# epilogues: 426 software RNE f32->bf16 pack sequences (bfe/add3/lshr/and_or) replaced by v_cvt_pk_bf16_f32 (bit-identical for finite values; baseline uses the same instruction in attention)
# speedup vs baseline: 1.0506x; 1.0033x over previous
; DI float siluf(float x) { return x * sigm(x); }
;     ...
; #pragma unroll
;   for (int n = 0; n < 4; ++n)
; #pragma unroll
;     for (int j = 0; j < 4; ++j) stg[(fq * 4 + j) * 68 + n * 16 + fr] = am[n][j];
;   asm volatile("s_waitcnt lgkmcnt(0)" ::: "memory");
;   const float* rp = stg + (lane >> 2) * 68 + (lane & 3) * 16;
; #pragma unroll
;   for (int i = 0; i < 4; ++i) { f32x4 t = *(const f32x4*)(rp + i * 4); v[4 * i] = t[0]; v[4 * i + 1] = t[1]; v[4 * i + 2] = t[2]; v[4 * i + 3] = t[3]; }
; DI void phase_inproj0(const Params& p) {
;     ...
;       float rs = r0[row];
; #pragma unroll
;       for (int i = 0; i < 16; ++i) v[i] *= rs;
;       if (col < 1024) store16_bf(u + (size_t)row * 1024 + col, v);
;       else if (col < 1728) store16_bf(lat + (size_t)row * 704 + col - 1024, v);
;       else if (col < 3776) {
; #pragma unroll
;         for (int i = 0; i < 16; ++i) v[i] = siluf(v[i]);
;         store16_bf(G0 + (size_t)row * 2048 + col - 1728, v); }
.LBB0_169:
	v_lshrrev_b32_e32 v2, 6, v150
	v_mul_lo_u32 v2, v2, s40
	s_add_i32 s6, 16, 0x10000
	v_add_u32_e32 v5, s6, v2
	v_lshrrev_b32_e32 v2, 2, v150
	v_and_b32_e32 v4, 15, v150
	v_and_b32_e32 v2, 12, v2
	v_lshlrev_b32_e32 v4, 2, v4
	v_mul_u32_u24_e32 v2, 0x110, v2
	v_add3_u32 v2, v5, v4, v2
	v_bfe_u32 v4, v150, 2, 4
	v_and_b32_e32 v137, 48, v151
	v_mul_u32_u24_e32 v134, 0x110, v4
	v_lshlrev_b32_e32 v135, 2, v137
	v_add3_u32 v144, v5, v134, v135
	v_ashrrev_i32_e32 v5, 1, v150
	v_and_b32_e32 v5, 0xffffff80, v5
	v_add_u32_e32 v5, s11, v5
	s_waitcnt vmcnt(0)
	s_barrier
	v_or_b32_e32 v134, v5, v4
	ds_write2_b32 v2, v130, v126 offset1:16
	ds_write2_b32 v2, v131, v127 offset0:68 offset1:84
	ds_write2_b32 v2, v132, v128 offset0:136 offset1:152
	ds_write2_b32 v2, v133, v129 offset0:204 offset1:220
	ds_write2_b32 v2, v122, v118 offset0:32 offset1:48
	ds_write2_b32 v2, v123, v119 offset0:100 offset1:116
	ds_write2_b32 v2, v124, v120 offset0:168 offset1:184
	ds_write2_b32 v2, v125, v121 offset0:236 offset1:252
	s_waitcnt lgkmcnt(0)
	v_ashrrev_i32_e32 v135, 31, v134
	ds_read_b128 v[120:123], v144
	ds_read_b128 v[124:127], v144 offset:16
	ds_read_b128 v[128:131], v144 offset:32
	ds_read_b128 v[146:149], v144 offset:48
	v_lshl_add_u64 v[4:5], v[134:135], 2, s[16:17]
	global_load_dword v136, v[4:5], off
	v_and_b32_e32 v4, 0xc0, v150
	v_or_b32_e32 v4, s10, v4
	v_mov_b32_e32 v119, v3
	v_or_b32_e32 v118, v4, v137
	s_waitcnt lgkmcnt(3)
	v_mov_b32_e32 v132, v120
	v_mov_b32_e32 v133, v122
	v_mov_b32_e32 v122, v121
	s_waitcnt lgkmcnt(2)
	v_mov_b32_e32 v120, v124
	v_mov_b32_e32 v121, v126
	v_mov_b32_e32 v126, v125
	s_waitcnt lgkmcnt(1)
	v_mov_b32_e32 v124, v128
	v_mov_b32_e32 v125, v130
	v_mov_b32_e32 v130, v129
	s_waitcnt lgkmcnt(0)
	v_mov_b32_e32 v128, v146
	v_mov_b32_e32 v129, v148
	v_mov_b32_e32 v148, v147
	v_cmp_lt_u32_e64 s[8:9], s42, v4
	v_cmp_gt_u32_e64 s[6:7], s43, v4
	v_cmp_lt_i32_e64 s[10:11], s41, v118
	v_lshl_add_u64 v[4:5], v[118:119], 1, s[12:13]
	s_waitcnt vmcnt(0)
	v_pk_mul_f32 v[142:143], v[132:133], v[136:137] op_sel_hi:[1,0]
	v_pk_mul_f32 v[140:141], v[122:123], v[136:137] op_sel_hi:[1,0]
	v_pk_mul_f32 v[138:139], v[120:121], v[136:137] op_sel_hi:[1,0]
	v_pk_mul_f32 v[132:133], v[126:127], v[136:137] op_sel_hi:[1,0]
	v_pk_mul_f32 v[126:127], v[124:125], v[136:137] op_sel_hi:[1,0]
	v_pk_mul_f32 v[124:125], v[130:131], v[136:137] op_sel_hi:[1,0]
	v_pk_mul_f32 v[122:123], v[128:129], v[136:137] op_sel_hi:[1,0]
	v_pk_mul_f32 v[120:121], v[148:149], v[136:137] op_sel_hi:[1,0]
	s_and_saveexec_b64 s[26:27], s[10:11]
	s_xor_b64 s[26:27], exec, s[26:27]
	s_cbranch_execz .LBB0_177
	s_and_saveexec_b64 s[36:37], s[8:9]
	s_xor_b64 s[36:37], exec, s[36:37]
	s_cbranch_execz .LBB0_174
	s_and_saveexec_b64 s[38:39], s[6:7]
	s_cbranch_execz .LBB0_173
	v_mul_f32_e32 v119, 0xbfb8aa3b, v142
	v_exp_f32_e32 v128, v119
	v_mul_f32_e32 v119, 0xbfb8aa3b, v140
	v_exp_f32_e32 v146, v119
	v_mul_f32_e32 v119, 0xbfb8aa3b, v143
	v_exp_f32_e32 v129, v119
	v_mul_f32_e32 v119, 0xbfb8aa3b, v141
	v_exp_f32_e32 v147, v119
	v_mul_f32_e32 v119, 0xbfb8aa3b, v138
	v_exp_f32_e32 v148, v119
	v_mul_f32_e32 v119, 0xbfb8aa3b, v132
	v_exp_f32_e32 v150, v119
	v_mul_f32_e32 v119, 0xbfb8aa3b, v139
	v_exp_f32_e32 v149, v119
	v_mul_f32_e32 v119, 0xbfb8aa3b, v133
	v_exp_f32_e32 v151, v119
	v_mul_f32_e32 v119, 0xbfb8aa3b, v126
	v_exp_f32_e32 v152, v119
	v_mul_f32_e32 v119, 0xbfb8aa3b, v124
	v_exp_f32_e32 v154, v119
	v_mul_f32_e32 v119, 0xbfb8aa3b, v127
	v_pk_add_f32 v[158:159], v[128:129], 1.0 op_sel_hi:[1,0]
	v_exp_f32_e32 v153, v119
	v_mul_f32_e32 v119, 0xbfb8aa3b, v125
	v_exp_f32_e32 v155, v119
	v_mul_f32_e32 v119, 0xbfb8aa3b, v122
	v_exp_f32_e32 v136, v119
	v_mul_f32_e32 v119, 0xbfb8aa3b, v120
	v_exp_f32_e32 v130, v119
	v_mul_f32_e32 v119, 0xbfb8aa3b, v123
	v_exp_f32_e32 v137, v119
	v_mul_f32_e32 v119, 0xbfb8aa3b, v121
	v_exp_f32_e32 v131, v119
	v_rcp_f32_e32 v159, v159
	v_pk_add_f32 v[146:147], v[146:147], 1.0 op_sel_hi:[1,0]
	v_rcp_f32_e32 v158, v158
	s_nop 0
	v_pk_mul_f32 v[142:143], v[142:143], v[158:159]
	v_rcp_f32_e32 v147, v147
	v_pk_add_f32 v[148:149], v[148:149], 1.0 op_sel_hi:[1,0]
	v_rcp_f32_e32 v146, v146
	s_nop 0
	v_pk_mul_f32 v[140:141], v[140:141], v[146:147]
	v_rcp_f32_e32 v147, v149
	v_pk_add_f32 v[150:151], v[150:151], 1.0 op_sel_hi:[1,0]
	v_rcp_f32_e32 v146, v148
	s_nop 0
	v_pk_mul_f32 v[138:139], v[138:139], v[146:147]
	v_rcp_f32_e32 v147, v151
	v_pk_add_f32 v[136:137], v[136:137], 1.0 op_sel_hi:[1,0]
	v_rcp_f32_e32 v146, v150
	s_nop 0
	v_pk_mul_f32 v[132:133], v[132:133], v[146:147]
	v_bfe_u32 v147, v140, 16, 1
	v_bfe_u32 v145, v132, 16, 1
	v_bfe_u32 v119, v133, 16, 1
	v_add3_u32 v147, v140, v147, s44
	v_add3_u32 v140, v132, v145, s44
	v_bfe_u32 v132, v142, 16, 1
	v_bfe_u32 v145, v139, 16, 1
	v_bfe_u32 v146, v141, 16, 1
	v_add3_u32 v119, v133, v119, s44
	v_bfe_u32 v133, v143, 16, 1
	v_add3_u32 v139, v139, v145, s44
	v_add3_u32 v132, v142, v132, s44
	v_add3_u32 v146, v141, v146, s44
	v_bfe_u32 v141, v138, 16, 1
	v_add3_u32 v133, v143, v133, s44
	v_lshrrev_b32_e32 v142, 16, v132
	v_lshrrev_b32_e32 v132, 16, v139
	v_add3_u32 v138, v138, v141, s44
	v_lshrrev_b32_e32 v143, 16, v133
	v_and_or_b32 v141, v119, s33, v132
	v_pk_add_f32 v[132:133], v[152:153], 1.0 op_sel_hi:[1,0]
	v_lshrrev_b32_e32 v138, 16, v138
	v_and_or_b32 v140, v140, s33, v138
	v_and_or_b32 v138, v147, s33, v142
	v_and_or_b32 v139, v146, s33, v143
	v_rcp_f32_e32 v133, v133
	v_pk_add_f32 v[130:131], v[130:131], 1.0 op_sel_hi:[1,0]
	v_pk_add_f32 v[142:143], v[154:155], 1.0 op_sel_hi:[1,0]
	v_rcp_f32_e32 v132, v132
	s_nop 0
	v_pk_mul_f32 v[126:127], v[126:127], v[132:133]
	v_rcp_f32_e32 v133, v143
	v_rcp_f32_e32 v132, v142
	s_nop 0
	v_pk_mul_f32 v[124:125], v[124:125], v[132:133]
	v_rcp_f32_e32 v133, v137
	v_lshlrev_b64 v[128:129], 12, v[134:135]
	v_rcp_f32_e32 v132, v136
	s_nop 0
	v_pk_mul_f32 v[122:123], v[122:123], v[132:133]
	v_div_scale_f32 v133, s[46:47], v130, v130, 1.0
	v_rcp_f32_e32 v136, v133
	v_rcp_f32_e32 v131, v131
	v_fma_f32 v119, -v133, v136, 1.0
	v_fmac_f32_e32 v136, v119, v136
	v_div_scale_f32 v119, vcc, 1.0, v130, 1.0
	v_mul_f32_e32 v132, v119, v136
	v_fma_f32 v137, -v133, v132, v119
	v_fmac_f32_e32 v132, v137, v136
	v_fma_f32 v119, -v133, v132, v119
	v_div_fmas_f32 v119, v119, v136, v132
	v_div_fixup_f32 v130, v119, v130, 1.0
	v_pk_mul_f32 v[120:121], v[120:121], v[130:131]
	v_bfe_u32 v119, v121, 16, 1
	v_add3_u32 v119, v121, v119, s44
	v_lshl_add_u64 v[128:129], v[4:5], 0, v[128:129]
	v_bfe_u32 v132, v123, 16, 1
	v_add3_u32 v123, v123, v132, s44
	v_cvt_pk_bf16_f32 v122, v122, v120
	v_cvt_pk_bf16_f32 v120, v126, v124
	v_add_co_u32_e32 v124, vcc, 0x13bfb000, v128
	v_lshrrev_b32_e32 v123, 16, v123
	v_cvt_pk_bf16_f32 v121, v127, v125
	v_addc_co_u32_e32 v125, vcc, 0, v129, vcc
	v_and_or_b32 v123, v119, s33, v123
	global_store_dwordx4 v[124:125], v[138:141], off offset:640
	global_store_dwordx4 v[124:125], v[120:123], off offset:656

; DI void phase_inproj0(const Params& p) {
;     ...
;       else if (col < 1728) store16_bf(lat + (size_t)row * 704 + col - 1024, v);
.LBB0_174:
	s_andn2_saveexec_b64 s[36:37], s[36:37]
	s_cbranch_execz .LBB0_176
	v_bfe_u32 v119, v133, 16, 1
	v_add3_u32 v119, v133, v119, s44
	v_bfe_u32 v133, v139, 16, 1
	v_bfe_u32 v128, v132, 16, 1
	v_add3_u32 v133, v139, v133, s44
	v_add3_u32 v128, v132, v128, s44
	v_bfe_u32 v132, v138, 16, 1
	v_lshrrev_b32_e32 v131, 16, v133
	v_add3_u32 v132, v138, v132, s44
	v_and_or_b32 v131, v119, s33, v131
	v_bfe_u32 v119, v121, 16, 1
	v_lshrrev_b32_e32 v130, 16, v132
	v_add3_u32 v119, v121, v119, s44
	v_and_or_b32 v130, v128, s33, v130
	v_cvt_pk_bf16_f32 v128, v142, v140
	v_mad_i64_i32 v[136:137], s[38:39], v134, s45, v[4:5]
	v_bfe_u32 v138, v123, 16, 1
	v_add3_u32 v123, v123, v138, s44
	v_cvt_pk_bf16_f32 v122, v122, v120
	v_cvt_pk_bf16_f32 v120, v126, v124
	v_add_co_u32_e32 v124, vcc, 0xf9fb000, v136
	v_cvt_pk_bf16_f32 v129, v143, v141
	v_lshrrev_b32_e32 v123, 16, v123
	v_cvt_pk_bf16_f32 v121, v127, v125
	v_addc_co_u32_e32 v125, vcc, 0, v137, vcc
	v_and_or_b32 v123, v119, s33, v123
	global_store_dwordx4 v[124:125], v[128:131], off offset:2048
	global_store_dwordx4 v[124:125], v[120:123], off offset:2064

; DI float siluf(float x) { return x * sigm(x); }
; DI void phase_inproj0(const Params& p) {
;     ...
;       float rs = r0[row];
; #pragma unroll
;       for (int i = 0; i < 16; ++i) v[i] *= rs;
;       if (col < 1024) store16_bf(u + (size_t)row * 1024 + col, v);
;       else if (col < 1728) store16_bf(lat + (size_t)row * 704 + col - 1024, v);
;       else if (col < 3776) {
; #pragma unroll
;         for (int i = 0; i < 16; ++i) v[i] = siluf(v[i]);
;         store16_bf(G0 + (size_t)row * 2048 + col - 1728, v); }
.LBB0_177:
	s_or_saveexec_b64 s[26:27], s[26:27]
	v_ashrrev_i32_e32 v119, 31, v118
	v_lshl_add_u64 v[118:119], v[118:119], 1, s[18:19]
	s_xor_b64 exec, exec, s[26:27]
	s_cbranch_execz .LBB0_179
	v_lshlrev_b64 v[128:129], 11, v[134:135]
	v_lshl_add_u64 v[136:137], v[118:119], 0, v[128:129]
	v_bfe_u32 v128, v133, 16, 1
	v_bfe_u32 v131, v140, 16, 1
	v_bfe_u32 v129, v132, 16, 1
	v_add3_u32 v135, v140, v131, s44
	v_add3_u32 v128, v133, v128, s44
	v_bfe_u32 v130, v142, 16, 1
	v_bfe_u32 v133, v139, 16, 1
	v_add3_u32 v129, v132, v129, s44
	v_bfe_u32 v132, v138, 16, 1
	v_add3_u32 v133, v139, v133, s44
	v_add3_u32 v130, v142, v130, s44
	v_add3_u32 v132, v138, v132, s44
	v_lshrrev_b32_e32 v138, 16, v130
	v_lshrrev_b32_e32 v131, 16, v133
	v_lshrrev_b32_e32 v130, 16, v132
	v_and_or_b32 v131, v128, s33, v131
	v_and_or_b32 v128, v135, s33, v138
	v_and_or_b32 v130, v129, s33, v130
	v_cvt_pk_bf16_f32 v129, v143, v141
	v_cvt_pk_bf16_f32 v123, v123, v121
	v_cvt_pk_bf16_f32 v122, v122, v120
	v_cvt_pk_bf16_f32 v121, v127, v125
	v_cvt_pk_bf16_f32 v120, v126, v124
	global_store_dwordx4 v[136:137], v[128:131], off
	global_store_dwordx4 v[136:137], v[120:123], off offset:16
.LBB0_179:
	s_or_b64 exec, exec, s[26:27]
	ds_write2_b32 v2, v114, v110 offset1:16
	ds_write2_b32 v2, v115, v111 offset0:68 offset1:84
	ds_write2_b32 v2, v116, v112 offset0:136 offset1:152
	ds_write2_b32 v2, v117, v113 offset0:204 offset1:220
	ds_write2_b32 v2, v106, v102 offset0:32 offset1:48
	ds_write2_b32 v2, v107, v103 offset0:100 offset1:116
	ds_write2_b32 v2, v108, v104 offset0:168 offset1:184
	ds_write2_b32 v2, v109, v105 offset0:236 offset1:252
	v_or_b32_e32 v110, 16, v134
	s_waitcnt lgkmcnt(0)
	v_ashrrev_i32_e32 v111, 31, v110
	ds_read_b128 v[102:105], v144
	ds_read_b128 v[106:109], v144 offset:16
	ds_read_b128 v[124:127], v144 offset:32
	ds_read_b128 v[128:131], v144 offset:48
	v_lshl_add_u64 v[112:113], v[110:111], 2, s[16:17]
	global_load_dword v112, v[112:113], off
	s_waitcnt lgkmcnt(3)
	v_mov_b32_e32 v114, v102
	v_mov_b32_e32 v115, v104
	v_mov_b32_e32 v104, v103
	s_waitcnt lgkmcnt(2)
	v_mov_b32_e32 v102, v106
	v_mov_b32_e32 v103, v108
	v_mov_b32_e32 v108, v107
	s_waitcnt lgkmcnt(1)
	v_mov_b32_e32 v106, v124
	v_mov_b32_e32 v107, v126
	v_mov_b32_e32 v126, v125
	s_waitcnt lgkmcnt(0)
	v_mov_b32_e32 v120, v128
	v_mov_b32_e32 v121, v130
	v_mov_b32_e32 v130, v129
	s_waitcnt vmcnt(0)
	v_pk_mul_f32 v[124:125], v[114:115], v[112:113] op_sel_hi:[1,0]
	v_pk_mul_f32 v[122:123], v[104:105], v[112:113] op_sel_hi:[1,0]
	v_pk_mul_f32 v[116:117], v[102:103], v[112:113] op_sel_hi:[1,0]
	v_pk_mul_f32 v[114:115], v[108:109], v[112:113] op_sel_hi:[1,0]
	v_pk_mul_f32 v[108:109], v[106:107], v[112:113] op_sel_hi:[1,0]
	v_pk_mul_f32 v[106:107], v[126:127], v[112:113] op_sel_hi:[1,0]
	v_pk_mul_f32 v[104:105], v[120:121], v[112:113] op_sel_hi:[1,0]
	v_pk_mul_f32 v[102:103], v[130:131], v[112:113] op_sel_hi:[1,0]
	s_and_saveexec_b64 s[26:27], s[10:11]
	s_xor_b64 s[26:27], exec, s[26:27]
	s_cbranch_execz .LBB0_187
	s_and_saveexec_b64 s[36:37], s[8:9]
	s_xor_b64 s[36:37], exec, s[36:37]
	s_cbranch_execz .LBB0_184
	s_and_saveexec_b64 s[38:39], s[6:7]
	s_cbranch_execz .LBB0_183
	v_mul_f32_e32 v112, 0xbfb8aa3b, v124
	v_exp_f32_e32 v126, v112
	v_mul_f32_e32 v112, 0xbfb8aa3b, v122
	v_exp_f32_e32 v128, v112
	v_mul_f32_e32 v112, 0xbfb8aa3b, v125
	v_exp_f32_e32 v127, v112
	v_mul_f32_e32 v112, 0xbfb8aa3b, v123
	v_exp_f32_e32 v129, v112
	v_mul_f32_e32 v112, 0xbfb8aa3b, v116
	v_pk_add_f32 v[126:127], v[126:127], 1.0 op_sel_hi:[1,0]
	v_exp_f32_e32 v130, v112
	v_pk_add_f32 v[128:129], v[128:129], 1.0 op_sel_hi:[1,0]
	v_mul_f32_e32 v112, 0xbfb8aa3b, v114
	v_exp_f32_e32 v132, v112
	v_rcp_f32_e32 v127, v127
	v_mul_f32_e32 v112, 0xbfb8aa3b, v117
	v_rcp_f32_e32 v126, v126
	s_nop 0
	v_pk_mul_f32 v[124:125], v[124:125], v[126:127]
	v_exp_f32_e32 v131, v112
	v_rcp_f32_e32 v127, v129
	v_pk_add_f32 v[130:131], v[130:131], 1.0 op_sel_hi:[1,0]
	v_rcp_f32_e32 v126, v128
	s_nop 0
	v_pk_mul_f32 v[122:123], v[122:123], v[126:127]
	v_mul_f32_e32 v112, 0xbfb8aa3b, v115
	v_rcp_f32_e32 v127, v131
	v_exp_f32_e32 v133, v112
	s_nop 0
	v_pk_add_f32 v[128:129], v[132:133], 1.0 op_sel_hi:[1,0]
	v_rcp_f32_e32 v126, v130
	s_nop 0
	v_pk_mul_f32 v[116:117], v[116:117], v[126:127]
	v_mul_f32_e32 v112, 0xbfb8aa3b, v108
	v_rcp_f32_e32 v127, v129
	v_exp_f32_e32 v136, v112
	v_mul_f32_e32 v112, 0xbfb8aa3b, v106
	v_exp_f32_e32 v138, v112
	v_mul_f32_e32 v112, 0xbfb8aa3b, v109
	v_exp_f32_e32 v137, v112
	v_rcp_f32_e32 v126, v128
	v_bfe_u32 v128, v123, 16, 1
	v_bfe_u32 v129, v122, 16, 1
	v_pk_mul_f32 v[114:115], v[114:115], v[126:127]
	v_add3_u32 v129, v122, v129, s44
	v_add3_u32 v128, v123, v128, s44
	v_bfe_u32 v122, v124, 16, 1
	v_bfe_u32 v123, v125, 16, 1
	v_add3_u32 v123, v125, v123, s44
	v_add3_u32 v122, v124, v122, s44
	v_lshrrev_b32_e32 v124, 16, v122
	v_lshrrev_b32_e32 v125, 16, v123
	v_pk_add_f32 v[122:123], v[136:137], 1.0 op_sel_hi:[1,0]
	v_cvt_pk_bf16_f32 v116, v116, v114
	v_and_or_b32 v114, v129, s33, v124
	v_cvt_pk_bf16_f32 v117, v117, v115
	v_and_or_b32 v115, v128, s33, v125
	v_mul_f32_e32 v112, 0xbfb8aa3b, v107
	v_rcp_f32_e32 v123, v123
	v_exp_f32_e32 v139, v112
	s_nop 0
	v_pk_add_f32 v[124:125], v[138:139], 1.0 op_sel_hi:[1,0]
	v_rcp_f32_e32 v122, v122
	s_nop 0
	v_pk_mul_f32 v[108:109], v[108:109], v[122:123]
	v_mul_f32_e32 v112, 0xbfb8aa3b, v104
	v_mul_f32_e32 v113, 0xbfb8aa3b, v105
	v_exp_f32_e32 v120, v112
	v_exp_f32_e32 v121, v113
	v_rcp_f32_e32 v123, v125
	v_pk_add_f32 v[120:121], v[120:121], 1.0 op_sel_hi:[1,0]
	v_rcp_f32_e32 v122, v124
	s_nop 0
	v_pk_mul_f32 v[106:107], v[106:107], v[122:123]
	v_mul_f32_e32 v112, 0xbfb8aa3b, v102
	v_mul_f32_e32 v113, 0xbfb8aa3b, v103
	v_exp_f32_e32 v112, v112
	v_exp_f32_e32 v113, v113
	v_rcp_f32_e32 v121, v121
	v_pk_add_f32 v[112:113], v[112:113], 1.0 op_sel_hi:[1,0]
	v_rcp_f32_e32 v120, v120
	s_nop 0
	v_pk_mul_f32 v[104:105], v[104:105], v[120:121]
	v_div_scale_f32 v122, s[46:47], v112, v112, 1.0
	v_rcp_f32_e32 v123, v122
	v_rcp_f32_e32 v113, v113
	v_fma_f32 v120, -v122, v123, 1.0
	v_fmac_f32_e32 v123, v120, v123
	v_div_scale_f32 v120, vcc, 1.0, v112, 1.0
	v_mul_f32_e32 v121, v120, v123
	v_fma_f32 v124, -v122, v121, v120
	v_fmac_f32_e32 v121, v124, v123
	v_fma_f32 v120, -v122, v121, v120
	v_div_fmas_f32 v120, v120, v123, v121
	v_div_fixup_f32 v112, v120, v112, 1.0
	v_pk_mul_f32 v[102:103], v[102:103], v[112:113]
	v_lshlrev_b64 v[110:111], 12, v[110:111]
	v_lshl_add_u64 v[110:111], v[4:5], 0, v[110:111]
	v_cvt_pk_bf16_f32 v104, v104, v102
	v_cvt_pk_bf16_f32 v102, v108, v106
	v_add_co_u32_e32 v106, vcc, 0x13bfb000, v110
	v_cvt_pk_bf16_f32 v105, v105, v103
	v_cvt_pk_bf16_f32 v103, v109, v107
	v_addc_co_u32_e32 v107, vcc, 0, v111, vcc
	global_store_dwordx4 v[106:107], v[114:117], off offset:640
	global_store_dwordx4 v[106:107], v[102:105], off offset:656

; DI void phase_inproj0(const Params& p) {
;     ...
;       else if (col < 1728) store16_bf(lat + (size_t)row * 704 + col - 1024, v);
.LBB0_184:
	s_andn2_saveexec_b64 s[36:37], s[36:37]
	s_cbranch_execz .LBB0_186
	v_mad_i64_i32 v[120:121], s[38:39], v110, s45, v[4:5]
	v_bfe_u32 v110, v115, 16, 1
	v_bfe_u32 v111, v114, 16, 1
	v_add3_u32 v110, v115, v110, s44
	v_bfe_u32 v115, v117, 16, 1
	v_add3_u32 v111, v114, v111, s44
	v_bfe_u32 v114, v116, 16, 1
	v_add3_u32 v115, v117, v115, s44
	v_add3_u32 v114, v116, v114, s44
	v_lshrrev_b32_e32 v113, 16, v115
	v_lshrrev_b32_e32 v112, 16, v114
	v_and_or_b32 v113, v110, s33, v113
	v_cvt_pk_bf16_f32 v110, v124, v122
	v_and_or_b32 v112, v111, s33, v112
	v_cvt_pk_bf16_f32 v111, v125, v123
	v_cvt_pk_bf16_f32 v104, v104, v102
	v_cvt_pk_bf16_f32 v102, v108, v106
	v_add_co_u32_e32 v106, vcc, 0xf9fb000, v120
	v_cvt_pk_bf16_f32 v105, v105, v103
	v_cvt_pk_bf16_f32 v103, v109, v107
	v_addc_co_u32_e32 v107, vcc, 0, v121, vcc
	global_store_dwordx4 v[106:107], v[110:113], off offset:2048
	global_store_dwordx4 v[106:107], v[102:105], off offset:2064

; DI float siluf(float x) { return x * sigm(x); }
; DI void phase_inproj0(const Params& p) {
;     ...
;       float rs = r0[row];
; #pragma unroll
;       for (int i = 0; i < 16; ++i) v[i] *= rs;
;       if (col < 1024) store16_bf(u + (size_t)row * 1024 + col, v);
;       else if (col < 1728) store16_bf(lat + (size_t)row * 704 + col - 1024, v);
;       else if (col < 3776) {
; #pragma unroll
;         for (int i = 0; i < 16; ++i) v[i] = siluf(v[i]);
;         store16_bf(G0 + (size_t)row * 2048 + col - 1728, v); }
.LBB0_187:
	s_andn2_saveexec_b64 s[26:27], s[26:27]
	s_cbranch_execz .LBB0_189
	v_lshlrev_b64 v[110:111], 11, v[110:111]
	v_lshl_add_u64 v[120:121], v[118:119], 0, v[110:111]
	v_bfe_u32 v110, v115, 16, 1
	v_bfe_u32 v111, v114, 16, 1
	v_add3_u32 v111, v114, v111, s44
	v_add3_u32 v110, v115, v110, s44
	v_bfe_u32 v114, v116, 16, 1
	v_bfe_u32 v115, v117, 16, 1
	v_add3_u32 v115, v117, v115, s44
	v_add3_u32 v114, v116, v114, s44
	v_lshrrev_b32_e32 v112, 16, v114
	v_lshrrev_b32_e32 v113, 16, v115
	v_and_or_b32 v113, v110, s33, v113
	v_and_or_b32 v112, v111, s33, v112
	v_cvt_pk_bf16_f32 v111, v125, v123
	v_cvt_pk_bf16_f32 v110, v124, v122
	v_cvt_pk_bf16_f32 v105, v105, v103
	v_cvt_pk_bf16_f32 v104, v104, v102
	v_cvt_pk_bf16_f32 v103, v109, v107
	v_cvt_pk_bf16_f32 v102, v108, v106
	global_store_dwordx4 v[120:121], v[110:113], off
	global_store_dwordx4 v[120:121], v[102:105], off offset:16
.LBB0_189:
	s_or_b64 exec, exec, s[26:27]
	ds_write2_b32 v2, v98, v94 offset1:16
	ds_write2_b32 v2, v99, v95 offset0:68 offset1:84
	ds_write2_b32 v2, v100, v96 offset0:136 offset1:152
	ds_write2_b32 v2, v101, v97 offset0:204 offset1:220
	ds_write2_b32 v2, v90, v86 offset0:32 offset1:48
	ds_write2_b32 v2, v91, v87 offset0:100 offset1:116
	ds_write2_b32 v2, v92, v88 offset0:168 offset1:184
	ds_write2_b32 v2, v93, v89 offset0:236 offset1:252
	v_or_b32_e32 v94, 32, v134
	s_waitcnt lgkmcnt(0)
	v_ashrrev_i32_e32 v95, 31, v94
	ds_read_b128 v[86:89], v144
	ds_read_b128 v[90:93], v144 offset:16
	ds_read_b128 v[100:103], v144 offset:32
	ds_read_b128 v[106:109], v144 offset:48
	v_lshl_add_u64 v[96:97], v[94:95], 2, s[16:17]
	global_load_dword v96, v[96:97], off
	s_waitcnt lgkmcnt(3)
	v_mov_b32_e32 v98, v86
	v_mov_b32_e32 v99, v88
	v_mov_b32_e32 v88, v87
	s_waitcnt lgkmcnt(2)
	v_mov_b32_e32 v86, v90
	v_mov_b32_e32 v87, v92
	v_mov_b32_e32 v92, v91
	s_waitcnt lgkmcnt(1)
	v_mov_b32_e32 v90, v100
	v_mov_b32_e32 v91, v102
	v_mov_b32_e32 v102, v101
	s_waitcnt lgkmcnt(0)
	v_mov_b32_e32 v110, v106
	v_mov_b32_e32 v111, v108
	v_mov_b32_e32 v108, v107
	s_waitcnt vmcnt(0)
	v_pk_mul_f32 v[106:107], v[98:99], v[96:97] op_sel_hi:[1,0]
	v_pk_mul_f32 v[104:105], v[88:89], v[96:97] op_sel_hi:[1,0]
	v_pk_mul_f32 v[100:101], v[86:87], v[96:97] op_sel_hi:[1,0]
	v_pk_mul_f32 v[98:99], v[92:93], v[96:97] op_sel_hi:[1,0]
	v_pk_mul_f32 v[92:93], v[90:91], v[96:97] op_sel_hi:[1,0]
	v_pk_mul_f32 v[90:91], v[102:103], v[96:97] op_sel_hi:[1,0]
	v_pk_mul_f32 v[88:89], v[110:111], v[96:97] op_sel_hi:[1,0]
	v_pk_mul_f32 v[86:87], v[108:109], v[96:97] op_sel_hi:[1,0]
	s_and_saveexec_b64 s[26:27], s[10:11]
	s_xor_b64 s[26:27], exec, s[26:27]
	s_cbranch_execz .LBB0_197
	s_and_saveexec_b64 s[36:37], s[8:9]
	s_xor_b64 s[36:37], exec, s[36:37]
	s_cbranch_execz .LBB0_194
	s_and_saveexec_b64 s[38:39], s[6:7]
	s_cbranch_execz .LBB0_193
	v_mul_f32_e32 v96, 0xbfb8aa3b, v106
	v_exp_f32_e32 v108, v96
	v_mul_f32_e32 v96, 0xbfb8aa3b, v104
	v_exp_f32_e32 v110, v96
	v_mul_f32_e32 v96, 0xbfb8aa3b, v107
	v_exp_f32_e32 v109, v96
	v_mul_f32_e32 v96, 0xbfb8aa3b, v105
	v_exp_f32_e32 v111, v96
	v_mul_f32_e32 v96, 0xbfb8aa3b, v100
	v_pk_add_f32 v[108:109], v[108:109], 1.0 op_sel_hi:[1,0]
	v_exp_f32_e32 v112, v96
	v_pk_add_f32 v[110:111], v[110:111], 1.0 op_sel_hi:[1,0]
	v_mul_f32_e32 v96, 0xbfb8aa3b, v98
	v_exp_f32_e32 v114, v96
	v_rcp_f32_e32 v109, v109
	v_mul_f32_e32 v96, 0xbfb8aa3b, v101
	v_rcp_f32_e32 v108, v108
	s_nop 0
	v_pk_mul_f32 v[106:107], v[106:107], v[108:109]
	v_exp_f32_e32 v113, v96
	v_rcp_f32_e32 v109, v111
	v_pk_add_f32 v[112:113], v[112:113], 1.0 op_sel_hi:[1,0]
	v_rcp_f32_e32 v108, v110
	s_nop 0
	v_pk_mul_f32 v[104:105], v[104:105], v[108:109]
	v_mul_f32_e32 v96, 0xbfb8aa3b, v99
	v_rcp_f32_e32 v109, v113
	v_exp_f32_e32 v115, v96
	s_nop 0
	v_pk_add_f32 v[110:111], v[114:115], 1.0 op_sel_hi:[1,0]
	v_rcp_f32_e32 v108, v112
	s_nop 0
	v_pk_mul_f32 v[100:101], v[100:101], v[108:109]
	v_mul_f32_e32 v96, 0xbfb8aa3b, v92
	v_rcp_f32_e32 v109, v111
	v_exp_f32_e32 v116, v96
	v_mul_f32_e32 v96, 0xbfb8aa3b, v90
	v_exp_f32_e32 v120, v96
	v_mul_f32_e32 v96, 0xbfb8aa3b, v93
	v_exp_f32_e32 v117, v96
	v_rcp_f32_e32 v108, v110
	v_bfe_u32 v110, v105, 16, 1
	v_bfe_u32 v111, v104, 16, 1
	v_pk_mul_f32 v[98:99], v[98:99], v[108:109]
	v_add3_u32 v111, v104, v111, s44
	v_add3_u32 v110, v105, v110, s44
	v_bfe_u32 v104, v106, 16, 1
	v_bfe_u32 v105, v107, 16, 1
	v_add3_u32 v105, v107, v105, s44
	v_add3_u32 v104, v106, v104, s44
	v_lshrrev_b32_e32 v106, 16, v104
	v_lshrrev_b32_e32 v107, 16, v105
	v_pk_add_f32 v[104:105], v[116:117], 1.0 op_sel_hi:[1,0]
	v_cvt_pk_bf16_f32 v100, v100, v98
	v_and_or_b32 v98, v111, s33, v106
	v_cvt_pk_bf16_f32 v101, v101, v99
	v_and_or_b32 v99, v110, s33, v107
	v_mul_f32_e32 v96, 0xbfb8aa3b, v91
	v_rcp_f32_e32 v105, v105
	v_exp_f32_e32 v121, v96
	s_nop 0
	v_pk_add_f32 v[106:107], v[120:121], 1.0 op_sel_hi:[1,0]
	v_rcp_f32_e32 v104, v104
	s_nop 0
	v_pk_mul_f32 v[92:93], v[92:93], v[104:105]
	v_mul_f32_e32 v96, 0xbfb8aa3b, v88
	v_mul_f32_e32 v97, 0xbfb8aa3b, v89
	v_exp_f32_e32 v102, v96
	v_exp_f32_e32 v103, v97
	v_rcp_f32_e32 v105, v107
	v_pk_add_f32 v[102:103], v[102:103], 1.0 op_sel_hi:[1,0]
	v_rcp_f32_e32 v104, v106
	s_nop 0
	v_pk_mul_f32 v[90:91], v[90:91], v[104:105]
	v_mul_f32_e32 v96, 0xbfb8aa3b, v86
	v_mul_f32_e32 v97, 0xbfb8aa3b, v87
	v_exp_f32_e32 v96, v96
	v_exp_f32_e32 v97, v97
	v_rcp_f32_e32 v103, v103
	v_pk_add_f32 v[96:97], v[96:97], 1.0 op_sel_hi:[1,0]
	v_rcp_f32_e32 v102, v102
	s_nop 0
	v_pk_mul_f32 v[88:89], v[88:89], v[102:103]
	v_div_scale_f32 v104, s[46:47], v96, v96, 1.0
	v_rcp_f32_e32 v105, v104
	v_rcp_f32_e32 v97, v97
	v_fma_f32 v102, -v104, v105, 1.0
	v_fmac_f32_e32 v105, v102, v105
	v_div_scale_f32 v102, vcc, 1.0, v96, 1.0
	v_mul_f32_e32 v103, v102, v105
	v_fma_f32 v106, -v104, v103, v102
	v_fmac_f32_e32 v103, v106, v105
	v_fma_f32 v102, -v104, v103, v102
	v_div_fmas_f32 v102, v102, v105, v103
	v_div_fixup_f32 v96, v102, v96, 1.0
	v_pk_mul_f32 v[86:87], v[86:87], v[96:97]
	v_lshlrev_b64 v[94:95], 12, v[94:95]
	v_lshl_add_u64 v[94:95], v[4:5], 0, v[94:95]
	v_cvt_pk_bf16_f32 v88, v88, v86
	v_cvt_pk_bf16_f32 v86, v92, v90
	v_add_co_u32_e32 v90, vcc, 0x13bfb000, v94
	v_cvt_pk_bf16_f32 v89, v89, v87
	v_cvt_pk_bf16_f32 v87, v93, v91
	v_addc_co_u32_e32 v91, vcc, 0, v95, vcc
	global_store_dwordx4 v[90:91], v[98:101], off offset:640
	global_store_dwordx4 v[90:91], v[86:89], off offset:656

; DI void phase_inproj0(const Params& p) {
;     ...
;       else if (col < 1728) store16_bf(lat + (size_t)row * 704 + col - 1024, v);
.LBB0_194:
	s_andn2_saveexec_b64 s[36:37], s[36:37]
	s_cbranch_execz .LBB0_196
	v_mad_i64_i32 v[102:103], s[38:39], v94, s45, v[4:5]
	v_bfe_u32 v94, v99, 16, 1
	v_bfe_u32 v95, v98, 16, 1
	v_add3_u32 v94, v99, v94, s44
	v_bfe_u32 v99, v101, 16, 1
	v_add3_u32 v95, v98, v95, s44
	v_bfe_u32 v98, v100, 16, 1
	v_add3_u32 v99, v101, v99, s44
	v_add3_u32 v98, v100, v98, s44
	v_lshrrev_b32_e32 v97, 16, v99
	v_lshrrev_b32_e32 v96, 16, v98
	v_and_or_b32 v97, v94, s33, v97
	v_cvt_pk_bf16_f32 v94, v106, v104
	v_and_or_b32 v96, v95, s33, v96
	v_cvt_pk_bf16_f32 v95, v107, v105
	v_cvt_pk_bf16_f32 v88, v88, v86
	v_cvt_pk_bf16_f32 v86, v92, v90
	v_add_co_u32_e32 v90, vcc, 0xf9fb000, v102
	v_cvt_pk_bf16_f32 v89, v89, v87
	v_cvt_pk_bf16_f32 v87, v93, v91
	v_addc_co_u32_e32 v91, vcc, 0, v103, vcc
	global_store_dwordx4 v[90:91], v[94:97], off offset:2048
	global_store_dwordx4 v[90:91], v[86:89], off offset:2064

; DI float siluf(float x) { return x * sigm(x); }
; DI void phase_inproj0(const Params& p) {
;     ...
;       float rs = r0[row];
; #pragma unroll
;       for (int i = 0; i < 16; ++i) v[i] *= rs;
;       if (col < 1024) store16_bf(u + (size_t)row * 1024 + col, v);
;       else if (col < 1728) store16_bf(lat + (size_t)row * 704 + col - 1024, v);
;       else if (col < 3776) {
; #pragma unroll
;         for (int i = 0; i < 16; ++i) v[i] = siluf(v[i]);
;         store16_bf(G0 + (size_t)row * 2048 + col - 1728, v); }
.LBB0_197:
	s_andn2_saveexec_b64 s[26:27], s[26:27]
	s_cbranch_execz .LBB0_199
	v_lshlrev_b64 v[94:95], 11, v[94:95]
	v_lshl_add_u64 v[102:103], v[118:119], 0, v[94:95]
	v_bfe_u32 v94, v99, 16, 1
	v_bfe_u32 v95, v98, 16, 1
	v_add3_u32 v95, v98, v95, s44
	v_add3_u32 v94, v99, v94, s44
	v_bfe_u32 v98, v100, 16, 1
	v_bfe_u32 v99, v101, 16, 1
	v_add3_u32 v99, v101, v99, s44
	v_add3_u32 v98, v100, v98, s44
	v_lshrrev_b32_e32 v96, 16, v98
	v_lshrrev_b32_e32 v97, 16, v99
	v_and_or_b32 v97, v94, s33, v97
	v_and_or_b32 v96, v95, s33, v96
	v_cvt_pk_bf16_f32 v95, v107, v105
	v_cvt_pk_bf16_f32 v94, v106, v104
	v_cvt_pk_bf16_f32 v89, v89, v87
	v_cvt_pk_bf16_f32 v88, v88, v86
	v_cvt_pk_bf16_f32 v87, v93, v91
	v_cvt_pk_bf16_f32 v86, v92, v90
	global_store_dwordx4 v[102:103], v[94:97], off
	global_store_dwordx4 v[102:103], v[86:89], off offset:16
.LBB0_199:
	s_or_b64 exec, exec, s[26:27]
	ds_write2_b32 v2, v82, v78 offset1:16
	ds_write2_b32 v2, v83, v79 offset0:68 offset1:84
	ds_write2_b32 v2, v84, v80 offset0:136 offset1:152
	ds_write2_b32 v2, v85, v81 offset0:204 offset1:220
	ds_write2_b32 v2, v74, v70 offset0:32 offset1:48
	ds_write2_b32 v2, v75, v71 offset0:100 offset1:116
	ds_write2_b32 v2, v76, v72 offset0:168 offset1:184
	ds_write2_b32 v2, v77, v73 offset0:236 offset1:252
	v_or_b32_e32 v78, 48, v134
	s_waitcnt lgkmcnt(0)
	v_ashrrev_i32_e32 v79, 31, v78
	ds_read_b128 v[70:73], v144
	ds_read_b128 v[74:77], v144 offset:16
	ds_read_b128 v[84:87], v144 offset:32
	ds_read_b128 v[90:93], v144 offset:48
	v_lshl_add_u64 v[80:81], v[78:79], 2, s[16:17]
	global_load_dword v80, v[80:81], off
	s_waitcnt lgkmcnt(3)
	v_mov_b32_e32 v82, v70
	v_mov_b32_e32 v83, v72
	v_mov_b32_e32 v72, v71
	s_waitcnt lgkmcnt(2)
	v_mov_b32_e32 v70, v74
	v_mov_b32_e32 v71, v76
	v_mov_b32_e32 v76, v75
	s_waitcnt lgkmcnt(1)
	v_mov_b32_e32 v74, v84
	v_mov_b32_e32 v75, v86
	v_mov_b32_e32 v86, v85
	s_waitcnt lgkmcnt(0)
	v_mov_b32_e32 v94, v90
	v_mov_b32_e32 v95, v92
	v_mov_b32_e32 v92, v91
	s_waitcnt vmcnt(0)
	v_pk_mul_f32 v[90:91], v[82:83], v[80:81] op_sel_hi:[1,0]
	v_pk_mul_f32 v[88:89], v[72:73], v[80:81] op_sel_hi:[1,0]
	v_pk_mul_f32 v[84:85], v[70:71], v[80:81] op_sel_hi:[1,0]
	v_pk_mul_f32 v[82:83], v[76:77], v[80:81] op_sel_hi:[1,0]
	v_pk_mul_f32 v[76:77], v[74:75], v[80:81] op_sel_hi:[1,0]
	v_pk_mul_f32 v[74:75], v[86:87], v[80:81] op_sel_hi:[1,0]
	v_pk_mul_f32 v[72:73], v[94:95], v[80:81] op_sel_hi:[1,0]
	v_pk_mul_f32 v[70:71], v[92:93], v[80:81] op_sel_hi:[1,0]
	s_and_saveexec_b64 s[26:27], s[10:11]
	s_xor_b64 s[26:27], exec, s[26:27]
	s_cbranch_execz .LBB0_207
	s_and_saveexec_b64 s[36:37], s[8:9]
	s_xor_b64 s[36:37], exec, s[36:37]
	s_cbranch_execz .LBB0_204
	s_and_saveexec_b64 s[38:39], s[6:7]
	s_cbranch_execz .LBB0_203
	v_mul_f32_e32 v80, 0xbfb8aa3b, v90
	v_exp_f32_e32 v92, v80
	v_mul_f32_e32 v80, 0xbfb8aa3b, v88
	v_exp_f32_e32 v94, v80
	v_mul_f32_e32 v80, 0xbfb8aa3b, v91
	v_exp_f32_e32 v93, v80
	v_mul_f32_e32 v80, 0xbfb8aa3b, v89
	v_exp_f32_e32 v95, v80
	v_mul_f32_e32 v80, 0xbfb8aa3b, v84
	v_pk_add_f32 v[92:93], v[92:93], 1.0 op_sel_hi:[1,0]
	v_exp_f32_e32 v96, v80
	v_pk_add_f32 v[94:95], v[94:95], 1.0 op_sel_hi:[1,0]
	v_mul_f32_e32 v80, 0xbfb8aa3b, v82
	v_exp_f32_e32 v98, v80
	v_rcp_f32_e32 v93, v93
	v_mul_f32_e32 v80, 0xbfb8aa3b, v85
	v_rcp_f32_e32 v92, v92
	s_nop 0
	v_pk_mul_f32 v[90:91], v[90:91], v[92:93]
	v_exp_f32_e32 v97, v80
	v_rcp_f32_e32 v93, v95
	v_pk_add_f32 v[96:97], v[96:97], 1.0 op_sel_hi:[1,0]
	v_rcp_f32_e32 v92, v94
	s_nop 0
	v_pk_mul_f32 v[88:89], v[88:89], v[92:93]
	v_mul_f32_e32 v80, 0xbfb8aa3b, v83
	v_rcp_f32_e32 v93, v97
	v_exp_f32_e32 v99, v80
	s_nop 0
	v_pk_add_f32 v[94:95], v[98:99], 1.0 op_sel_hi:[1,0]
	v_rcp_f32_e32 v92, v96
	s_nop 0
	v_pk_mul_f32 v[84:85], v[84:85], v[92:93]
	v_mul_f32_e32 v80, 0xbfb8aa3b, v76
	v_rcp_f32_e32 v93, v95
	v_exp_f32_e32 v100, v80
	v_mul_f32_e32 v80, 0xbfb8aa3b, v74
	v_exp_f32_e32 v102, v80
	v_mul_f32_e32 v80, 0xbfb8aa3b, v77
	v_exp_f32_e32 v101, v80
	v_rcp_f32_e32 v92, v94
	v_bfe_u32 v94, v89, 16, 1
	v_bfe_u32 v95, v88, 16, 1
	v_pk_mul_f32 v[82:83], v[82:83], v[92:93]
	v_add3_u32 v95, v88, v95, s44
	v_add3_u32 v94, v89, v94, s44
	v_bfe_u32 v88, v90, 16, 1
	v_bfe_u32 v89, v91, 16, 1
	v_add3_u32 v89, v91, v89, s44
	v_add3_u32 v88, v90, v88, s44
	v_lshrrev_b32_e32 v90, 16, v88
	v_lshrrev_b32_e32 v91, 16, v89
	v_pk_add_f32 v[88:89], v[100:101], 1.0 op_sel_hi:[1,0]
	v_cvt_pk_bf16_f32 v84, v84, v82
	v_and_or_b32 v82, v95, s33, v90
	v_cvt_pk_bf16_f32 v85, v85, v83
	v_and_or_b32 v83, v94, s33, v91
	v_mul_f32_e32 v80, 0xbfb8aa3b, v75
	v_rcp_f32_e32 v89, v89
	v_exp_f32_e32 v103, v80
	s_nop 0
	v_pk_add_f32 v[90:91], v[102:103], 1.0 op_sel_hi:[1,0]
	v_rcp_f32_e32 v88, v88
	s_nop 0
	v_pk_mul_f32 v[76:77], v[76:77], v[88:89]
	v_mul_f32_e32 v80, 0xbfb8aa3b, v72
	v_mul_f32_e32 v81, 0xbfb8aa3b, v73
	v_exp_f32_e32 v86, v80
	v_exp_f32_e32 v87, v81
	v_rcp_f32_e32 v89, v91
	v_pk_add_f32 v[86:87], v[86:87], 1.0 op_sel_hi:[1,0]
	v_rcp_f32_e32 v88, v90
	s_nop 0
	v_pk_mul_f32 v[74:75], v[74:75], v[88:89]
	v_mul_f32_e32 v80, 0xbfb8aa3b, v70
	v_mul_f32_e32 v81, 0xbfb8aa3b, v71
	v_exp_f32_e32 v80, v80
	v_exp_f32_e32 v81, v81
	v_rcp_f32_e32 v87, v87
	v_pk_add_f32 v[80:81], v[80:81], 1.0 op_sel_hi:[1,0]
	v_rcp_f32_e32 v86, v86
	s_nop 0
	v_pk_mul_f32 v[72:73], v[72:73], v[86:87]
	v_div_scale_f32 v88, s[46:47], v80, v80, 1.0
	v_rcp_f32_e32 v89, v88
	v_rcp_f32_e32 v81, v81
	v_fma_f32 v86, -v88, v89, 1.0
	v_fmac_f32_e32 v89, v86, v89
	v_div_scale_f32 v86, vcc, 1.0, v80, 1.0
	v_mul_f32_e32 v87, v86, v89
	v_fma_f32 v90, -v88, v87, v86
	v_fmac_f32_e32 v87, v90, v89
	v_fma_f32 v86, -v88, v87, v86
	v_div_fmas_f32 v86, v86, v89, v87
	v_div_fixup_f32 v80, v86, v80, 1.0
	v_pk_mul_f32 v[70:71], v[70:71], v[80:81]
	v_lshlrev_b64 v[78:79], 12, v[78:79]
	v_lshl_add_u64 v[78:79], v[4:5], 0, v[78:79]
	v_cvt_pk_bf16_f32 v72, v72, v70
	v_cvt_pk_bf16_f32 v70, v76, v74
	v_add_co_u32_e32 v74, vcc, 0x13bfb000, v78
	v_cvt_pk_bf16_f32 v73, v73, v71
	v_cvt_pk_bf16_f32 v71, v77, v75
	v_addc_co_u32_e32 v75, vcc, 0, v79, vcc
	global_store_dwordx4 v[74:75], v[82:85], off offset:640
	global_store_dwordx4 v[74:75], v[70:73], off offset:656

; DI void phase_inproj0(const Params& p) {
;     ...
;       else if (col < 1728) store16_bf(lat + (size_t)row * 704 + col - 1024, v);
.LBB0_204:
	s_andn2_saveexec_b64 s[36:37], s[36:37]
	s_cbranch_execz .LBB0_206
	v_mad_i64_i32 v[86:87], s[38:39], v78, s45, v[4:5]
	v_bfe_u32 v78, v83, 16, 1
	v_bfe_u32 v79, v82, 16, 1
	v_add3_u32 v78, v83, v78, s44
	v_bfe_u32 v83, v85, 16, 1
	v_add3_u32 v79, v82, v79, s44
	v_bfe_u32 v82, v84, 16, 1
	v_add3_u32 v83, v85, v83, s44
	v_add3_u32 v82, v84, v82, s44
	v_lshrrev_b32_e32 v81, 16, v83
	v_lshrrev_b32_e32 v80, 16, v82
	v_and_or_b32 v81, v78, s33, v81
	v_cvt_pk_bf16_f32 v78, v90, v88
	v_and_or_b32 v80, v79, s33, v80
	v_cvt_pk_bf16_f32 v79, v91, v89
	v_cvt_pk_bf16_f32 v72, v72, v70
	v_cvt_pk_bf16_f32 v70, v76, v74
	v_add_co_u32_e32 v74, vcc, 0xf9fb000, v86
	v_cvt_pk_bf16_f32 v73, v73, v71
	v_cvt_pk_bf16_f32 v71, v77, v75
	v_addc_co_u32_e32 v75, vcc, 0, v87, vcc
	global_store_dwordx4 v[74:75], v[78:81], off offset:2048
	global_store_dwordx4 v[74:75], v[70:73], off offset:2064

; DI float siluf(float x) { return x * sigm(x); }
; DI void phase_inproj0(const Params& p) {
;     ...
;       float rs = r0[row];
; #pragma unroll
;       for (int i = 0; i < 16; ++i) v[i] *= rs;
;       if (col < 1024) store16_bf(u + (size_t)row * 1024 + col, v);
;       else if (col < 1728) store16_bf(lat + (size_t)row * 704 + col - 1024, v);
;       else if (col < 3776) {
; #pragma unroll
;         for (int i = 0; i < 16; ++i) v[i] = siluf(v[i]);
;         store16_bf(G0 + (size_t)row * 2048 + col - 1728, v); }
.LBB0_207:
	s_andn2_saveexec_b64 s[26:27], s[26:27]
	s_cbranch_execz .LBB0_209
	v_lshlrev_b64 v[78:79], 11, v[78:79]
	v_lshl_add_u64 v[86:87], v[118:119], 0, v[78:79]
	v_bfe_u32 v78, v83, 16, 1
	v_bfe_u32 v79, v82, 16, 1
	v_add3_u32 v79, v82, v79, s44
	v_add3_u32 v78, v83, v78, s44
	v_bfe_u32 v82, v84, 16, 1
	v_bfe_u32 v83, v85, 16, 1
	v_add3_u32 v83, v85, v83, s44
	v_add3_u32 v82, v84, v82, s44
	v_lshrrev_b32_e32 v80, 16, v82
	v_lshrrev_b32_e32 v81, 16, v83
	v_and_or_b32 v81, v78, s33, v81
	v_and_or_b32 v80, v79, s33, v80
	v_cvt_pk_bf16_f32 v79, v91, v89
	v_cvt_pk_bf16_f32 v78, v90, v88
	v_cvt_pk_bf16_f32 v73, v73, v71
	v_cvt_pk_bf16_f32 v72, v72, v70
	v_cvt_pk_bf16_f32 v71, v77, v75
	v_cvt_pk_bf16_f32 v70, v76, v74
	global_store_dwordx4 v[86:87], v[78:81], off
	global_store_dwordx4 v[86:87], v[70:73], off offset:16
.LBB0_209:
	s_or_b64 exec, exec, s[26:27]
	ds_write2_b32 v2, v66, v62 offset1:16
	ds_write2_b32 v2, v67, v63 offset0:68 offset1:84
	ds_write2_b32 v2, v68, v64 offset0:136 offset1:152
	ds_write2_b32 v2, v69, v65 offset0:204 offset1:220
	ds_write2_b32 v2, v58, v54 offset0:32 offset1:48
	ds_write2_b32 v2, v59, v55 offset0:100 offset1:116
	ds_write2_b32 v2, v60, v56 offset0:168 offset1:184
	ds_write2_b32 v2, v61, v57 offset0:236 offset1:252
	v_or_b32_e32 v62, 64, v134
	s_waitcnt lgkmcnt(0)
	v_ashrrev_i32_e32 v63, 31, v62
	ds_read_b128 v[54:57], v144
	ds_read_b128 v[58:61], v144 offset:16
	ds_read_b128 v[68:71], v144 offset:32
	ds_read_b128 v[74:77], v144 offset:48
	v_lshl_add_u64 v[64:65], v[62:63], 2, s[16:17]
	global_load_dword v64, v[64:65], off
	s_waitcnt lgkmcnt(3)
	v_mov_b32_e32 v66, v54
	v_mov_b32_e32 v67, v56
	v_mov_b32_e32 v56, v55
	s_waitcnt lgkmcnt(2)
	v_mov_b32_e32 v54, v58
	v_mov_b32_e32 v55, v60
	v_mov_b32_e32 v60, v59
	s_waitcnt lgkmcnt(1)
	v_mov_b32_e32 v58, v68
	v_mov_b32_e32 v59, v70
	v_mov_b32_e32 v70, v69
	s_waitcnt lgkmcnt(0)
	v_mov_b32_e32 v78, v74
	v_mov_b32_e32 v79, v76
	v_mov_b32_e32 v76, v75
	s_waitcnt vmcnt(0)
	v_pk_mul_f32 v[74:75], v[66:67], v[64:65] op_sel_hi:[1,0]
	v_pk_mul_f32 v[72:73], v[56:57], v[64:65] op_sel_hi:[1,0]
	v_pk_mul_f32 v[68:69], v[54:55], v[64:65] op_sel_hi:[1,0]
	v_pk_mul_f32 v[66:67], v[60:61], v[64:65] op_sel_hi:[1,0]
	v_pk_mul_f32 v[60:61], v[58:59], v[64:65] op_sel_hi:[1,0]
	v_pk_mul_f32 v[58:59], v[70:71], v[64:65] op_sel_hi:[1,0]
	v_pk_mul_f32 v[56:57], v[78:79], v[64:65] op_sel_hi:[1,0]
	v_pk_mul_f32 v[54:55], v[76:77], v[64:65] op_sel_hi:[1,0]
	s_and_saveexec_b64 s[26:27], s[10:11]
	s_xor_b64 s[26:27], exec, s[26:27]
	s_cbranch_execz .LBB0_217
	s_and_saveexec_b64 s[36:37], s[8:9]
	s_xor_b64 s[36:37], exec, s[36:37]
	s_cbranch_execz .LBB0_214
	s_and_saveexec_b64 s[38:39], s[6:7]
	s_cbranch_execz .LBB0_213
	v_mul_f32_e32 v64, 0xbfb8aa3b, v74
	v_exp_f32_e32 v76, v64
	v_mul_f32_e32 v64, 0xbfb8aa3b, v72
	v_exp_f32_e32 v78, v64
	v_mul_f32_e32 v64, 0xbfb8aa3b, v75
	v_exp_f32_e32 v77, v64
	v_mul_f32_e32 v64, 0xbfb8aa3b, v73
	v_exp_f32_e32 v79, v64
	v_mul_f32_e32 v64, 0xbfb8aa3b, v68
	v_pk_add_f32 v[76:77], v[76:77], 1.0 op_sel_hi:[1,0]
	v_exp_f32_e32 v80, v64
	v_pk_add_f32 v[78:79], v[78:79], 1.0 op_sel_hi:[1,0]
	v_mul_f32_e32 v64, 0xbfb8aa3b, v66
	v_exp_f32_e32 v82, v64
	v_rcp_f32_e32 v77, v77
	v_mul_f32_e32 v64, 0xbfb8aa3b, v69
	v_rcp_f32_e32 v76, v76
	s_nop 0
	v_pk_mul_f32 v[74:75], v[74:75], v[76:77]
	v_exp_f32_e32 v81, v64
	v_rcp_f32_e32 v77, v79
	v_pk_add_f32 v[80:81], v[80:81], 1.0 op_sel_hi:[1,0]
	v_rcp_f32_e32 v76, v78
	s_nop 0
	v_pk_mul_f32 v[72:73], v[72:73], v[76:77]
	v_mul_f32_e32 v64, 0xbfb8aa3b, v67
	v_rcp_f32_e32 v77, v81
	v_exp_f32_e32 v83, v64
	s_nop 0
	v_pk_add_f32 v[78:79], v[82:83], 1.0 op_sel_hi:[1,0]
	v_rcp_f32_e32 v76, v80
	s_nop 0
	v_pk_mul_f32 v[68:69], v[68:69], v[76:77]
	v_mul_f32_e32 v64, 0xbfb8aa3b, v60
	v_rcp_f32_e32 v77, v79
	v_exp_f32_e32 v84, v64
	v_mul_f32_e32 v64, 0xbfb8aa3b, v58
	v_exp_f32_e32 v86, v64
	v_mul_f32_e32 v64, 0xbfb8aa3b, v61
	v_exp_f32_e32 v85, v64
	v_rcp_f32_e32 v76, v78
	v_bfe_u32 v78, v73, 16, 1
	v_bfe_u32 v79, v72, 16, 1
	v_pk_mul_f32 v[66:67], v[66:67], v[76:77]
	v_add3_u32 v79, v72, v79, s44
	v_add3_u32 v78, v73, v78, s44
	v_bfe_u32 v72, v74, 16, 1
	v_bfe_u32 v73, v75, 16, 1
	v_add3_u32 v73, v75, v73, s44
	v_add3_u32 v72, v74, v72, s44
	v_lshrrev_b32_e32 v74, 16, v72
	v_lshrrev_b32_e32 v75, 16, v73
	v_pk_add_f32 v[72:73], v[84:85], 1.0 op_sel_hi:[1,0]
	v_cvt_pk_bf16_f32 v68, v68, v66
	v_and_or_b32 v66, v79, s33, v74
	v_cvt_pk_bf16_f32 v69, v69, v67
	v_and_or_b32 v67, v78, s33, v75
	v_mul_f32_e32 v64, 0xbfb8aa3b, v59
	v_rcp_f32_e32 v73, v73
	v_exp_f32_e32 v87, v64
	s_nop 0
	v_pk_add_f32 v[74:75], v[86:87], 1.0 op_sel_hi:[1,0]
	v_rcp_f32_e32 v72, v72
	s_nop 0
	v_pk_mul_f32 v[60:61], v[60:61], v[72:73]
	v_mul_f32_e32 v64, 0xbfb8aa3b, v56
	v_mul_f32_e32 v65, 0xbfb8aa3b, v57
	v_exp_f32_e32 v70, v64
	v_exp_f32_e32 v71, v65
	v_rcp_f32_e32 v73, v75
	v_pk_add_f32 v[70:71], v[70:71], 1.0 op_sel_hi:[1,0]
	v_rcp_f32_e32 v72, v74
	s_nop 0
	v_pk_mul_f32 v[58:59], v[58:59], v[72:73]
	v_mul_f32_e32 v64, 0xbfb8aa3b, v54
	v_mul_f32_e32 v65, 0xbfb8aa3b, v55
	v_exp_f32_e32 v64, v64
	v_exp_f32_e32 v65, v65
	v_rcp_f32_e32 v71, v71
	v_pk_add_f32 v[64:65], v[64:65], 1.0 op_sel_hi:[1,0]
	v_rcp_f32_e32 v70, v70
	s_nop 0
	v_pk_mul_f32 v[56:57], v[56:57], v[70:71]
	v_div_scale_f32 v72, s[46:47], v64, v64, 1.0
	v_rcp_f32_e32 v73, v72
	v_rcp_f32_e32 v65, v65
	v_fma_f32 v70, -v72, v73, 1.0
	v_fmac_f32_e32 v73, v70, v73
	v_div_scale_f32 v70, vcc, 1.0, v64, 1.0
	v_mul_f32_e32 v71, v70, v73
	v_fma_f32 v74, -v72, v71, v70
	v_fmac_f32_e32 v71, v74, v73
	v_fma_f32 v70, -v72, v71, v70
	v_div_fmas_f32 v70, v70, v73, v71
	v_div_fixup_f32 v64, v70, v64, 1.0
	v_pk_mul_f32 v[54:55], v[54:55], v[64:65]
	v_lshlrev_b64 v[62:63], 12, v[62:63]
	v_lshl_add_u64 v[62:63], v[4:5], 0, v[62:63]
	v_cvt_pk_bf16_f32 v56, v56, v54
	v_cvt_pk_bf16_f32 v54, v60, v58
	v_add_co_u32_e32 v58, vcc, 0x13bfb000, v62
	v_cvt_pk_bf16_f32 v57, v57, v55
	v_cvt_pk_bf16_f32 v55, v61, v59
	v_addc_co_u32_e32 v59, vcc, 0, v63, vcc
	global_store_dwordx4 v[58:59], v[66:69], off offset:640
	global_store_dwordx4 v[58:59], v[54:57], off offset:656

; DI void phase_inproj0(const Params& p) {
;     ...
;       else if (col < 1728) store16_bf(lat + (size_t)row * 704 + col - 1024, v);
.LBB0_214:
	s_andn2_saveexec_b64 s[36:37], s[36:37]
	s_cbranch_execz .LBB0_216
	v_mad_i64_i32 v[70:71], s[38:39], v62, s45, v[4:5]
	v_bfe_u32 v62, v67, 16, 1
	v_bfe_u32 v63, v66, 16, 1
	v_add3_u32 v62, v67, v62, s44
	v_bfe_u32 v67, v69, 16, 1
	v_add3_u32 v63, v66, v63, s44
	v_bfe_u32 v66, v68, 16, 1
	v_add3_u32 v67, v69, v67, s44
	v_add3_u32 v66, v68, v66, s44
	v_lshrrev_b32_e32 v65, 16, v67
	v_lshrrev_b32_e32 v64, 16, v66
	v_and_or_b32 v65, v62, s33, v65
	v_cvt_pk_bf16_f32 v62, v74, v72
	v_and_or_b32 v64, v63, s33, v64
	v_cvt_pk_bf16_f32 v63, v75, v73
	v_cvt_pk_bf16_f32 v56, v56, v54
	v_cvt_pk_bf16_f32 v54, v60, v58
	v_add_co_u32_e32 v58, vcc, 0xf9fb000, v70
	v_cvt_pk_bf16_f32 v57, v57, v55
	v_cvt_pk_bf16_f32 v55, v61, v59
	v_addc_co_u32_e32 v59, vcc, 0, v71, vcc
	global_store_dwordx4 v[58:59], v[62:65], off offset:2048
	global_store_dwordx4 v[58:59], v[54:57], off offset:2064

; DI unsigned pack2(float a, float b) { return (unsigned)f2bf(a) | ((unsigned)f2bf(b) << 16); }
; DI float siluf(float x) { return x * sigm(x); }
;     ...
;     for (int j = 0; j < 4; ++j) stg[(fq * 4 + j) * 68 + n * 16 + fr] = am[n][j];
;   asm volatile("s_waitcnt lgkmcnt(0)" ::: "memory");
;   const float* rp = stg + (lane >> 2) * 68 + (lane & 3) * 16;
; #pragma unroll
;   for (int i = 0; i < 4; ++i) { f32x4 t = *(const f32x4*)(rp + i * 4); v[4 * i] = t[0]; v[4 * i + 1] = t[1]; v[4 * i + 2] = t[2]; v[4 * i + 3] = t[3]; }
;   asm volatile("" ::: "memory");
; }
; DI void store16_bf(bft* dst, const float (&v)[16]) {
;   u32x4 o0 = {pack2(v[0], v[1]), pack2(v[2], v[3]), pack2(v[4], v[5]), pack2(v[6], v[7])}, o1 = {pack2(v[8], v[9]), pack2(v[10], v[11]), pack2(v[12], v[13]), pack2(v[14], v[15])};
;   *(u32x4*)dst = o0; *(u32x4*)(dst + 8) = o1;
; DI void phase_inproj0(const Params& p) {
;     ...
;     EPI256_BEGIN
;       float rs = r0[row];
; #pragma unroll
;       for (int i = 0; i < 16; ++i) v[i] *= rs;
;       if (col < 1024) store16_bf(u + (size_t)row * 1024 + col, v);
;       else if (col < 1728) store16_bf(lat + (size_t)row * 704 + col - 1024, v);
;       else if (col < 3776) {
; #pragma unroll
;         for (int i = 0; i < 16; ++i) v[i] = siluf(v[i]);
;         store16_bf(G0 + (size_t)row * 2048 + col - 1728, v); }
.LBB0_217:
	s_andn2_saveexec_b64 s[26:27], s[26:27]
	s_cbranch_execz .LBB0_219
	v_lshlrev_b64 v[62:63], 11, v[62:63]
	v_lshl_add_u64 v[70:71], v[118:119], 0, v[62:63]
	v_bfe_u32 v62, v67, 16, 1
	v_bfe_u32 v63, v66, 16, 1
	v_add3_u32 v63, v66, v63, s44
	v_add3_u32 v62, v67, v62, s44
	v_bfe_u32 v66, v68, 16, 1
	v_bfe_u32 v67, v69, 16, 1
	v_add3_u32 v67, v69, v67, s44
	v_add3_u32 v66, v68, v66, s44
	v_lshrrev_b32_e32 v64, 16, v66
	v_lshrrev_b32_e32 v65, 16, v67
	v_and_or_b32 v65, v62, s33, v65
	v_and_or_b32 v64, v63, s33, v64
	v_cvt_pk_bf16_f32 v63, v75, v73
	v_cvt_pk_bf16_f32 v62, v74, v72
	v_cvt_pk_bf16_f32 v57, v57, v55
	v_cvt_pk_bf16_f32 v56, v56, v54
	v_cvt_pk_bf16_f32 v55, v61, v59
	v_cvt_pk_bf16_f32 v54, v60, v58
	global_store_dwordx4 v[70:71], v[62:65], off
	global_store_dwordx4 v[70:71], v[54:57], off offset:16
.LBB0_219:
	s_or_b64 exec, exec, s[26:27]
	ds_write2_b32 v2, v50, v46 offset1:16
	ds_write2_b32 v2, v51, v47 offset0:68 offset1:84
	ds_write2_b32 v2, v52, v48 offset0:136 offset1:152
	ds_write2_b32 v2, v53, v49 offset0:204 offset1:220
	ds_write2_b32 v2, v42, v38 offset0:32 offset1:48
	ds_write2_b32 v2, v43, v39 offset0:100 offset1:116
	ds_write2_b32 v2, v44, v40 offset0:168 offset1:184
	ds_write2_b32 v2, v45, v41 offset0:236 offset1:252
	v_or_b32_e32 v46, 0x50, v134
	s_waitcnt lgkmcnt(0)
	v_ashrrev_i32_e32 v47, 31, v46
	ds_read_b128 v[38:41], v144
	ds_read_b128 v[42:45], v144 offset:16
	ds_read_b128 v[52:55], v144 offset:32
	ds_read_b128 v[58:61], v144 offset:48
	v_lshl_add_u64 v[48:49], v[46:47], 2, s[16:17]
	global_load_dword v48, v[48:49], off
	s_waitcnt lgkmcnt(3)
	v_mov_b32_e32 v50, v38
	v_mov_b32_e32 v51, v40
	v_mov_b32_e32 v40, v39
	s_waitcnt lgkmcnt(2)
	v_mov_b32_e32 v38, v42
	v_mov_b32_e32 v39, v44
	v_mov_b32_e32 v44, v43
	s_waitcnt lgkmcnt(1)
	v_mov_b32_e32 v42, v52
	v_mov_b32_e32 v43, v54
	v_mov_b32_e32 v54, v53
	s_waitcnt lgkmcnt(0)
	v_mov_b32_e32 v62, v58
	v_mov_b32_e32 v63, v60
	v_mov_b32_e32 v60, v59
	s_waitcnt vmcnt(0)
	v_pk_mul_f32 v[58:59], v[50:51], v[48:49] op_sel_hi:[1,0]
	v_pk_mul_f32 v[56:57], v[40:41], v[48:49] op_sel_hi:[1,0]
	v_pk_mul_f32 v[52:53], v[38:39], v[48:49] op_sel_hi:[1,0]
	v_pk_mul_f32 v[50:51], v[44:45], v[48:49] op_sel_hi:[1,0]
	v_pk_mul_f32 v[44:45], v[42:43], v[48:49] op_sel_hi:[1,0]
	v_pk_mul_f32 v[42:43], v[54:55], v[48:49] op_sel_hi:[1,0]
	v_pk_mul_f32 v[40:41], v[62:63], v[48:49] op_sel_hi:[1,0]
	v_pk_mul_f32 v[38:39], v[60:61], v[48:49] op_sel_hi:[1,0]
	s_and_saveexec_b64 s[26:27], s[10:11]
	s_xor_b64 s[26:27], exec, s[26:27]
	s_cbranch_execz .LBB0_227
	s_and_saveexec_b64 s[36:37], s[8:9]
	s_xor_b64 s[36:37], exec, s[36:37]
	s_cbranch_execz .LBB0_224
	s_and_saveexec_b64 s[38:39], s[6:7]
	s_cbranch_execz .LBB0_223
	v_mul_f32_e32 v48, 0xbfb8aa3b, v58
	v_exp_f32_e32 v60, v48
	v_mul_f32_e32 v48, 0xbfb8aa3b, v56
	v_exp_f32_e32 v62, v48
	v_mul_f32_e32 v48, 0xbfb8aa3b, v59
	v_exp_f32_e32 v61, v48
	v_mul_f32_e32 v48, 0xbfb8aa3b, v57
	v_exp_f32_e32 v63, v48
	v_mul_f32_e32 v48, 0xbfb8aa3b, v52
	v_pk_add_f32 v[60:61], v[60:61], 1.0 op_sel_hi:[1,0]
	v_exp_f32_e32 v64, v48
	v_pk_add_f32 v[62:63], v[62:63], 1.0 op_sel_hi:[1,0]
	v_mul_f32_e32 v48, 0xbfb8aa3b, v50
	v_exp_f32_e32 v66, v48
	v_rcp_f32_e32 v61, v61
	v_mul_f32_e32 v48, 0xbfb8aa3b, v53
	v_rcp_f32_e32 v60, v60
	s_nop 0
	v_pk_mul_f32 v[58:59], v[58:59], v[60:61]
	v_exp_f32_e32 v65, v48
	v_rcp_f32_e32 v61, v63
	v_pk_add_f32 v[64:65], v[64:65], 1.0 op_sel_hi:[1,0]
	v_rcp_f32_e32 v60, v62
	s_nop 0
	v_pk_mul_f32 v[56:57], v[56:57], v[60:61]
	v_mul_f32_e32 v48, 0xbfb8aa3b, v51
	v_rcp_f32_e32 v61, v65
	v_exp_f32_e32 v67, v48
	s_nop 0
	v_pk_add_f32 v[62:63], v[66:67], 1.0 op_sel_hi:[1,0]
	v_rcp_f32_e32 v60, v64
	s_nop 0
	v_pk_mul_f32 v[52:53], v[52:53], v[60:61]
	v_mul_f32_e32 v48, 0xbfb8aa3b, v44
	v_rcp_f32_e32 v61, v63
	v_exp_f32_e32 v68, v48
	v_mul_f32_e32 v48, 0xbfb8aa3b, v42
	v_exp_f32_e32 v70, v48
	v_mul_f32_e32 v48, 0xbfb8aa3b, v45
	v_exp_f32_e32 v69, v48
	v_rcp_f32_e32 v60, v62
	v_bfe_u32 v62, v57, 16, 1
	v_bfe_u32 v63, v56, 16, 1
	v_pk_mul_f32 v[50:51], v[50:51], v[60:61]
	v_add3_u32 v63, v56, v63, s44
	v_add3_u32 v62, v57, v62, s44
	v_bfe_u32 v56, v58, 16, 1
	v_bfe_u32 v57, v59, 16, 1
	v_add3_u32 v57, v59, v57, s44
	v_add3_u32 v56, v58, v56, s44
	v_lshrrev_b32_e32 v58, 16, v56
	v_lshrrev_b32_e32 v59, 16, v57
	v_pk_add_f32 v[56:57], v[68:69], 1.0 op_sel_hi:[1,0]
	v_cvt_pk_bf16_f32 v52, v52, v50
	v_and_or_b32 v50, v63, s33, v58
	v_cvt_pk_bf16_f32 v53, v53, v51
	v_and_or_b32 v51, v62, s33, v59
	v_mul_f32_e32 v48, 0xbfb8aa3b, v43
	v_rcp_f32_e32 v57, v57
	v_exp_f32_e32 v71, v48
	s_nop 0
	v_pk_add_f32 v[58:59], v[70:71], 1.0 op_sel_hi:[1,0]
	v_rcp_f32_e32 v56, v56
	s_nop 0
	v_pk_mul_f32 v[44:45], v[44:45], v[56:57]
	v_mul_f32_e32 v48, 0xbfb8aa3b, v40
	v_mul_f32_e32 v49, 0xbfb8aa3b, v41
	v_exp_f32_e32 v54, v48
	v_exp_f32_e32 v55, v49
	v_rcp_f32_e32 v57, v59
	v_pk_add_f32 v[54:55], v[54:55], 1.0 op_sel_hi:[1,0]
	v_rcp_f32_e32 v56, v58
	s_nop 0
	v_pk_mul_f32 v[42:43], v[42:43], v[56:57]
	v_mul_f32_e32 v48, 0xbfb8aa3b, v38
	v_mul_f32_e32 v49, 0xbfb8aa3b, v39
	v_exp_f32_e32 v48, v48
	v_exp_f32_e32 v49, v49
	v_rcp_f32_e32 v55, v55
	v_pk_add_f32 v[48:49], v[48:49], 1.0 op_sel_hi:[1,0]
	v_rcp_f32_e32 v54, v54
	s_nop 0
	v_pk_mul_f32 v[40:41], v[40:41], v[54:55]
	v_div_scale_f32 v56, s[46:47], v48, v48, 1.0
	v_rcp_f32_e32 v57, v56
	v_rcp_f32_e32 v49, v49
	v_fma_f32 v54, -v56, v57, 1.0
	v_fmac_f32_e32 v57, v54, v57
	v_div_scale_f32 v54, vcc, 1.0, v48, 1.0
	v_mul_f32_e32 v55, v54, v57
	v_fma_f32 v58, -v56, v55, v54
	v_fmac_f32_e32 v55, v58, v57
	v_fma_f32 v54, -v56, v55, v54
	v_div_fmas_f32 v54, v54, v57, v55
	v_div_fixup_f32 v48, v54, v48, 1.0
	v_pk_mul_f32 v[38:39], v[38:39], v[48:49]
	v_lshlrev_b64 v[46:47], 12, v[46:47]
	v_lshl_add_u64 v[46:47], v[4:5], 0, v[46:47]
	v_cvt_pk_bf16_f32 v40, v40, v38
	v_cvt_pk_bf16_f32 v38, v44, v42
	v_add_co_u32_e32 v42, vcc, 0x13bfb000, v46
	v_cvt_pk_bf16_f32 v41, v41, v39
	v_cvt_pk_bf16_f32 v39, v45, v43
	v_addc_co_u32_e32 v43, vcc, 0, v47, vcc
	global_store_dwordx4 v[42:43], v[50:53], off offset:640
	global_store_dwordx4 v[42:43], v[38:41], off offset:656

; DI unsigned pack2(float a, float b) { return (unsigned)f2bf(a) | ((unsigned)f2bf(b) << 16); }
; DI void store16_bf(bft* dst, const float (&v)[16]) {
;   u32x4 o0 = {pack2(v[0], v[1]), pack2(v[2], v[3]), pack2(v[4], v[5]), pack2(v[6], v[7])}, o1 = {pack2(v[8], v[9]), pack2(v[10], v[11]), pack2(v[12], v[13]), pack2(v[14], v[15])};
;   *(u32x4*)dst = o0; *(u32x4*)(dst + 8) = o1;
; DI void phase_inproj0(const Params& p) {
;     ...
;       else if (col < 1728) store16_bf(lat + (size_t)row * 704 + col - 1024, v);
.LBB0_224:
	s_andn2_saveexec_b64 s[36:37], s[36:37]
	s_cbranch_execz .LBB0_226
	v_mad_i64_i32 v[54:55], s[38:39], v46, s45, v[4:5]
	v_bfe_u32 v46, v51, 16, 1
	v_bfe_u32 v47, v50, 16, 1
	v_add3_u32 v46, v51, v46, s44
	v_bfe_u32 v51, v53, 16, 1
	v_add3_u32 v47, v50, v47, s44
	v_bfe_u32 v50, v52, 16, 1
	v_add3_u32 v51, v53, v51, s44
	v_add3_u32 v50, v52, v50, s44
	v_lshrrev_b32_e32 v49, 16, v51
	v_lshrrev_b32_e32 v48, 16, v50
	v_and_or_b32 v49, v46, s33, v49
	v_cvt_pk_bf16_f32 v46, v58, v56
	v_and_or_b32 v48, v47, s33, v48
	v_cvt_pk_bf16_f32 v47, v59, v57
	v_cvt_pk_bf16_f32 v40, v40, v38
	v_cvt_pk_bf16_f32 v38, v44, v42
	v_add_co_u32_e32 v42, vcc, 0xf9fb000, v54
	v_cvt_pk_bf16_f32 v41, v41, v39
	v_cvt_pk_bf16_f32 v39, v45, v43
	v_addc_co_u32_e32 v43, vcc, 0, v55, vcc
	global_store_dwordx4 v[42:43], v[46:49], off offset:2048
	global_store_dwordx4 v[42:43], v[38:41], off offset:2064

; DI unsigned pack2(float a, float b) { return (unsigned)f2bf(a) | ((unsigned)f2bf(b) << 16); }
; DI float siluf(float x) { return x * sigm(x); }
;     ...
;     for (int j = 0; j < 4; ++j) stg[(fq * 4 + j) * 68 + n * 16 + fr] = am[n][j];
;   asm volatile("s_waitcnt lgkmcnt(0)" ::: "memory");
;   const float* rp = stg + (lane >> 2) * 68 + (lane & 3) * 16;
; #pragma unroll
;   for (int i = 0; i < 4; ++i) { f32x4 t = *(const f32x4*)(rp + i * 4); v[4 * i] = t[0]; v[4 * i + 1] = t[1]; v[4 * i + 2] = t[2]; v[4 * i + 3] = t[3]; }
;   asm volatile("" ::: "memory");
; }
; DI void store16_bf(bft* dst, const float (&v)[16]) {
;   u32x4 o0 = {pack2(v[0], v[1]), pack2(v[2], v[3]), pack2(v[4], v[5]), pack2(v[6], v[7])}, o1 = {pack2(v[8], v[9]), pack2(v[10], v[11]), pack2(v[12], v[13]), pack2(v[14], v[15])};
;   *(u32x4*)dst = o0; *(u32x4*)(dst + 8) = o1;
; DI void phase_inproj0(const Params& p) {
;     ...
;     EPI256_BEGIN
;       float rs = r0[row];
; #pragma unroll
;       for (int i = 0; i < 16; ++i) v[i] *= rs;
;       if (col < 1024) store16_bf(u + (size_t)row * 1024 + col, v);
;       else if (col < 1728) store16_bf(lat + (size_t)row * 704 + col - 1024, v);
;       else if (col < 3776) {
; #pragma unroll
;         for (int i = 0; i < 16; ++i) v[i] = siluf(v[i]);
;         store16_bf(G0 + (size_t)row * 2048 + col - 1728, v); }
.LBB0_227:
	s_andn2_saveexec_b64 s[26:27], s[26:27]
	s_cbranch_execz .LBB0_229
	v_lshlrev_b64 v[46:47], 11, v[46:47]
	v_lshl_add_u64 v[54:55], v[118:119], 0, v[46:47]
	v_bfe_u32 v46, v51, 16, 1
	v_bfe_u32 v47, v50, 16, 1
	v_add3_u32 v47, v50, v47, s44
	v_add3_u32 v46, v51, v46, s44
	v_bfe_u32 v50, v52, 16, 1
	v_bfe_u32 v51, v53, 16, 1
	v_add3_u32 v51, v53, v51, s44
	v_add3_u32 v50, v52, v50, s44
	v_lshrrev_b32_e32 v48, 16, v50
	v_lshrrev_b32_e32 v49, 16, v51
	v_and_or_b32 v49, v46, s33, v49
	v_and_or_b32 v48, v47, s33, v48
	v_cvt_pk_bf16_f32 v47, v59, v57
	v_cvt_pk_bf16_f32 v46, v58, v56
	v_cvt_pk_bf16_f32 v41, v41, v39
	v_cvt_pk_bf16_f32 v40, v40, v38
	v_cvt_pk_bf16_f32 v39, v45, v43
	v_cvt_pk_bf16_f32 v38, v44, v42
	global_store_dwordx4 v[54:55], v[46:49], off
	global_store_dwordx4 v[54:55], v[38:41], off offset:16
.LBB0_229:
	s_or_b64 exec, exec, s[26:27]
	ds_write2_b32 v2, v34, v30 offset1:16
	ds_write2_b32 v2, v35, v31 offset0:68 offset1:84
	ds_write2_b32 v2, v36, v32 offset0:136 offset1:152
	ds_write2_b32 v2, v37, v33 offset0:204 offset1:220
	ds_write2_b32 v2, v26, v22 offset0:32 offset1:48
	ds_write2_b32 v2, v27, v23 offset0:100 offset1:116
	ds_write2_b32 v2, v28, v24 offset0:168 offset1:184
	ds_write2_b32 v2, v29, v25 offset0:236 offset1:252
	v_or_b32_e32 v30, 0x60, v134
	s_waitcnt lgkmcnt(0)
	v_ashrrev_i32_e32 v31, 31, v30
	ds_read_b128 v[22:25], v144
	ds_read_b128 v[26:29], v144 offset:16
	ds_read_b128 v[36:39], v144 offset:32
	ds_read_b128 v[42:45], v144 offset:48
	v_lshl_add_u64 v[32:33], v[30:31], 2, s[16:17]
	global_load_dword v32, v[32:33], off
	s_waitcnt lgkmcnt(3)
	v_mov_b32_e32 v34, v22
	v_mov_b32_e32 v35, v24
	v_mov_b32_e32 v24, v23
	s_waitcnt lgkmcnt(2)
	v_mov_b32_e32 v22, v26
	v_mov_b32_e32 v23, v28
	v_mov_b32_e32 v28, v27
	s_waitcnt lgkmcnt(1)
	v_mov_b32_e32 v26, v36
	v_mov_b32_e32 v27, v38
	v_mov_b32_e32 v38, v37
	s_waitcnt lgkmcnt(0)
	v_mov_b32_e32 v46, v42
	v_mov_b32_e32 v47, v44
	v_mov_b32_e32 v44, v43
	s_waitcnt vmcnt(0)
	v_pk_mul_f32 v[42:43], v[34:35], v[32:33] op_sel_hi:[1,0]
	v_pk_mul_f32 v[40:41], v[24:25], v[32:33] op_sel_hi:[1,0]
	v_pk_mul_f32 v[36:37], v[22:23], v[32:33] op_sel_hi:[1,0]
	v_pk_mul_f32 v[34:35], v[28:29], v[32:33] op_sel_hi:[1,0]
	v_pk_mul_f32 v[28:29], v[26:27], v[32:33] op_sel_hi:[1,0]
	v_pk_mul_f32 v[26:27], v[38:39], v[32:33] op_sel_hi:[1,0]
	v_pk_mul_f32 v[24:25], v[46:47], v[32:33] op_sel_hi:[1,0]
	v_pk_mul_f32 v[22:23], v[44:45], v[32:33] op_sel_hi:[1,0]
	s_and_saveexec_b64 s[26:27], s[10:11]
	s_xor_b64 s[26:27], exec, s[26:27]
	s_cbranch_execz .LBB0_237
	s_and_saveexec_b64 s[36:37], s[8:9]
	s_xor_b64 s[36:37], exec, s[36:37]
	s_cbranch_execz .LBB0_234
	s_and_saveexec_b64 s[38:39], s[6:7]
	s_cbranch_execz .LBB0_233
	v_mul_f32_e32 v32, 0xbfb8aa3b, v42
	v_exp_f32_e32 v44, v32
	v_mul_f32_e32 v32, 0xbfb8aa3b, v40
	v_exp_f32_e32 v46, v32
	v_mul_f32_e32 v32, 0xbfb8aa3b, v43
	v_exp_f32_e32 v45, v32
	v_mul_f32_e32 v32, 0xbfb8aa3b, v41
	v_exp_f32_e32 v47, v32
	v_mul_f32_e32 v32, 0xbfb8aa3b, v36
	v_pk_add_f32 v[44:45], v[44:45], 1.0 op_sel_hi:[1,0]
	v_exp_f32_e32 v48, v32
	v_pk_add_f32 v[46:47], v[46:47], 1.0 op_sel_hi:[1,0]
	v_mul_f32_e32 v32, 0xbfb8aa3b, v34
	v_exp_f32_e32 v50, v32
	v_rcp_f32_e32 v45, v45
	v_mul_f32_e32 v32, 0xbfb8aa3b, v37
	v_rcp_f32_e32 v44, v44
	s_nop 0
	v_pk_mul_f32 v[42:43], v[42:43], v[44:45]
	v_exp_f32_e32 v49, v32
	v_rcp_f32_e32 v45, v47
	v_pk_add_f32 v[48:49], v[48:49], 1.0 op_sel_hi:[1,0]
	v_rcp_f32_e32 v44, v46
	s_nop 0
	v_pk_mul_f32 v[40:41], v[40:41], v[44:45]
	v_mul_f32_e32 v32, 0xbfb8aa3b, v35
	v_rcp_f32_e32 v45, v49
	v_exp_f32_e32 v51, v32
	s_nop 0
	v_pk_add_f32 v[46:47], v[50:51], 1.0 op_sel_hi:[1,0]
	v_rcp_f32_e32 v44, v48
	s_nop 0
	v_pk_mul_f32 v[36:37], v[36:37], v[44:45]
	v_mul_f32_e32 v32, 0xbfb8aa3b, v28
	v_rcp_f32_e32 v45, v47
	v_exp_f32_e32 v52, v32
	v_mul_f32_e32 v32, 0xbfb8aa3b, v26
	v_exp_f32_e32 v54, v32
	v_mul_f32_e32 v32, 0xbfb8aa3b, v29
	v_exp_f32_e32 v53, v32
	v_rcp_f32_e32 v44, v46
	v_bfe_u32 v46, v41, 16, 1
	v_bfe_u32 v47, v40, 16, 1
	v_pk_mul_f32 v[34:35], v[34:35], v[44:45]
	v_add3_u32 v47, v40, v47, s44
	v_add3_u32 v46, v41, v46, s44
	v_bfe_u32 v40, v42, 16, 1
	v_bfe_u32 v41, v43, 16, 1
	v_add3_u32 v41, v43, v41, s44
	v_add3_u32 v40, v42, v40, s44
	v_lshrrev_b32_e32 v42, 16, v40
	v_lshrrev_b32_e32 v43, 16, v41
	v_pk_add_f32 v[40:41], v[52:53], 1.0 op_sel_hi:[1,0]
	v_cvt_pk_bf16_f32 v36, v36, v34
	v_and_or_b32 v34, v47, s33, v42
	v_cvt_pk_bf16_f32 v37, v37, v35
	v_and_or_b32 v35, v46, s33, v43
	v_mul_f32_e32 v32, 0xbfb8aa3b, v27
	v_rcp_f32_e32 v41, v41
	v_exp_f32_e32 v55, v32
	s_nop 0
	v_pk_add_f32 v[42:43], v[54:55], 1.0 op_sel_hi:[1,0]
	v_rcp_f32_e32 v40, v40
	s_nop 0
	v_pk_mul_f32 v[28:29], v[28:29], v[40:41]
	v_mul_f32_e32 v32, 0xbfb8aa3b, v24
	v_mul_f32_e32 v33, 0xbfb8aa3b, v25
	v_exp_f32_e32 v38, v32
	v_exp_f32_e32 v39, v33
	v_rcp_f32_e32 v41, v43
	v_pk_add_f32 v[38:39], v[38:39], 1.0 op_sel_hi:[1,0]
	v_rcp_f32_e32 v40, v42
	s_nop 0
	v_pk_mul_f32 v[26:27], v[26:27], v[40:41]
	v_mul_f32_e32 v32, 0xbfb8aa3b, v22
	v_mul_f32_e32 v33, 0xbfb8aa3b, v23
	v_exp_f32_e32 v32, v32
	v_exp_f32_e32 v33, v33
	v_rcp_f32_e32 v39, v39
	v_pk_add_f32 v[32:33], v[32:33], 1.0 op_sel_hi:[1,0]
	v_rcp_f32_e32 v38, v38
	s_nop 0
	v_pk_mul_f32 v[24:25], v[24:25], v[38:39]
	v_div_scale_f32 v40, s[46:47], v32, v32, 1.0
	v_rcp_f32_e32 v41, v40
	v_rcp_f32_e32 v33, v33
	v_fma_f32 v38, -v40, v41, 1.0
	v_fmac_f32_e32 v41, v38, v41
	v_div_scale_f32 v38, vcc, 1.0, v32, 1.0
	v_mul_f32_e32 v39, v38, v41
	v_fma_f32 v42, -v40, v39, v38
	v_fmac_f32_e32 v39, v42, v41
	v_fma_f32 v38, -v40, v39, v38
	v_div_fmas_f32 v38, v38, v41, v39
	v_div_fixup_f32 v32, v38, v32, 1.0
	v_pk_mul_f32 v[22:23], v[22:23], v[32:33]
	v_lshlrev_b64 v[30:31], 12, v[30:31]
	v_lshl_add_u64 v[30:31], v[4:5], 0, v[30:31]
	v_cvt_pk_bf16_f32 v24, v24, v22
	v_cvt_pk_bf16_f32 v22, v28, v26
	v_add_co_u32_e32 v26, vcc, 0x13bfb000, v30
	v_cvt_pk_bf16_f32 v25, v25, v23
	v_cvt_pk_bf16_f32 v23, v29, v27
	v_addc_co_u32_e32 v27, vcc, 0, v31, vcc
	global_store_dwordx4 v[26:27], v[34:37], off offset:640
	global_store_dwordx4 v[26:27], v[22:25], off offset:656

; DI unsigned pack2(float a, float b) { return (unsigned)f2bf(a) | ((unsigned)f2bf(b) << 16); }
; DI void store16_bf(bft* dst, const float (&v)[16]) {
;   u32x4 o0 = {pack2(v[0], v[1]), pack2(v[2], v[3]), pack2(v[4], v[5]), pack2(v[6], v[7])}, o1 = {pack2(v[8], v[9]), pack2(v[10], v[11]), pack2(v[12], v[13]), pack2(v[14], v[15])};
;   *(u32x4*)dst = o0; *(u32x4*)(dst + 8) = o1;
; DI void phase_inproj0(const Params& p) {
;     ...
;       else if (col < 1728) store16_bf(lat + (size_t)row * 704 + col - 1024, v);
.LBB0_234:
	s_andn2_saveexec_b64 s[36:37], s[36:37]
	s_cbranch_execz .LBB0_236
	v_mad_i64_i32 v[38:39], s[38:39], v30, s45, v[4:5]
	v_bfe_u32 v30, v35, 16, 1
	v_bfe_u32 v31, v34, 16, 1
	v_add3_u32 v30, v35, v30, s44
	v_bfe_u32 v35, v37, 16, 1
	v_add3_u32 v31, v34, v31, s44
	v_bfe_u32 v34, v36, 16, 1
	v_add3_u32 v35, v37, v35, s44
	v_add3_u32 v34, v36, v34, s44
	v_lshrrev_b32_e32 v33, 16, v35
	v_lshrrev_b32_e32 v32, 16, v34
	v_and_or_b32 v33, v30, s33, v33
	v_cvt_pk_bf16_f32 v30, v42, v40
	v_and_or_b32 v32, v31, s33, v32
	v_cvt_pk_bf16_f32 v31, v43, v41
	v_cvt_pk_bf16_f32 v24, v24, v22
	v_cvt_pk_bf16_f32 v22, v28, v26
	v_add_co_u32_e32 v26, vcc, 0xf9fb000, v38
	v_cvt_pk_bf16_f32 v25, v25, v23
	v_cvt_pk_bf16_f32 v23, v29, v27
	v_addc_co_u32_e32 v27, vcc, 0, v39, vcc
	global_store_dwordx4 v[26:27], v[30:33], off offset:2048
	global_store_dwordx4 v[26:27], v[22:25], off offset:2064

; DI unsigned pack2(float a, float b) { return (unsigned)f2bf(a) | ((unsigned)f2bf(b) << 16); }
; DI float siluf(float x) { return x * sigm(x); }
;     ...
;     for (int j = 0; j < 4; ++j) stg[(fq * 4 + j) * 68 + n * 16 + fr] = am[n][j];
;   asm volatile("s_waitcnt lgkmcnt(0)" ::: "memory");
;   const float* rp = stg + (lane >> 2) * 68 + (lane & 3) * 16;
; #pragma unroll
;   for (int i = 0; i < 4; ++i) { f32x4 t = *(const f32x4*)(rp + i * 4); v[4 * i] = t[0]; v[4 * i + 1] = t[1]; v[4 * i + 2] = t[2]; v[4 * i + 3] = t[3]; }
;   asm volatile("" ::: "memory");
; }
; DI void store16_bf(bft* dst, const float (&v)[16]) {
;   u32x4 o0 = {pack2(v[0], v[1]), pack2(v[2], v[3]), pack2(v[4], v[5]), pack2(v[6], v[7])}, o1 = {pack2(v[8], v[9]), pack2(v[10], v[11]), pack2(v[12], v[13]), pack2(v[14], v[15])};
;   *(u32x4*)dst = o0; *(u32x4*)(dst + 8) = o1;
; DI void phase_inproj0(const Params& p) {
;     ...
;     EPI256_BEGIN
;       float rs = r0[row];
; #pragma unroll
;       for (int i = 0; i < 16; ++i) v[i] *= rs;
;       if (col < 1024) store16_bf(u + (size_t)row * 1024 + col, v);
;       else if (col < 1728) store16_bf(lat + (size_t)row * 704 + col - 1024, v);
;       else if (col < 3776) {
; #pragma unroll
;         for (int i = 0; i < 16; ++i) v[i] = siluf(v[i]);
;         store16_bf(G0 + (size_t)row * 2048 + col - 1728, v); }
.LBB0_237:
	s_andn2_saveexec_b64 s[26:27], s[26:27]
	s_cbranch_execz .LBB0_239
	v_lshlrev_b64 v[30:31], 11, v[30:31]
	v_lshl_add_u64 v[38:39], v[118:119], 0, v[30:31]
	v_bfe_u32 v30, v35, 16, 1
	v_bfe_u32 v31, v34, 16, 1
	v_add3_u32 v31, v34, v31, s44
	v_add3_u32 v30, v35, v30, s44
	v_bfe_u32 v34, v36, 16, 1
	v_bfe_u32 v35, v37, 16, 1
	v_add3_u32 v35, v37, v35, s44
	v_add3_u32 v34, v36, v34, s44
	v_lshrrev_b32_e32 v32, 16, v34
	v_lshrrev_b32_e32 v33, 16, v35
	v_and_or_b32 v33, v30, s33, v33
	v_and_or_b32 v32, v31, s33, v32
	v_cvt_pk_bf16_f32 v31, v43, v41
	v_cvt_pk_bf16_f32 v30, v42, v40
	v_cvt_pk_bf16_f32 v25, v25, v23
	v_cvt_pk_bf16_f32 v24, v24, v22
	v_cvt_pk_bf16_f32 v23, v29, v27
	v_cvt_pk_bf16_f32 v22, v28, v26
	global_store_dwordx4 v[38:39], v[30:33], off
	global_store_dwordx4 v[38:39], v[22:25], off offset:16
.LBB0_239:
	s_or_b64 exec, exec, s[26:27]
	ds_write2_b32 v2, v18, v14 offset1:16
	ds_write2_b32 v2, v19, v15 offset0:68 offset1:84
	ds_write2_b32 v2, v20, v16 offset0:136 offset1:152
	ds_write2_b32 v2, v21, v17 offset0:204 offset1:220
	ds_write2_b32 v2, v10, v6 offset0:32 offset1:48
	ds_write2_b32 v2, v11, v7 offset0:100 offset1:116
	ds_write2_b32 v2, v12, v8 offset0:168 offset1:184
	ds_write2_b32 v2, v13, v9 offset0:236 offset1:252
	v_or_b32_e32 v26, 0x70, v134
	s_waitcnt lgkmcnt(0)
	v_ashrrev_i32_e32 v27, 31, v26
	ds_read_b128 v[6:9], v144
	ds_read_b128 v[10:13], v144 offset:16
	ds_read_b128 v[18:21], v144 offset:32
	ds_read_b128 v[28:31], v144 offset:48
	v_lshl_add_u64 v[14:15], v[26:27], 2, s[16:17]
	global_load_dword v2, v[14:15], off
	s_waitcnt lgkmcnt(3)
	v_mov_b32_e32 v14, v6
	v_mov_b32_e32 v15, v8
	v_mov_b32_e32 v8, v7
	s_waitcnt lgkmcnt(2)
	v_mov_b32_e32 v6, v10
	v_mov_b32_e32 v7, v12
	v_mov_b32_e32 v12, v11
	s_waitcnt lgkmcnt(1)
	v_mov_b32_e32 v10, v18
	v_mov_b32_e32 v11, v20
	v_mov_b32_e32 v20, v19
	s_waitcnt lgkmcnt(0)
	v_mov_b32_e32 v32, v28
	v_mov_b32_e32 v33, v30
	v_mov_b32_e32 v30, v29
	s_waitcnt vmcnt(0)
	v_pk_mul_f32 v[24:25], v[14:15], v[2:3] op_sel_hi:[1,0]
	v_pk_mul_f32 v[22:23], v[8:9], v[2:3] op_sel_hi:[1,0]
	v_pk_mul_f32 v[18:19], v[6:7], v[2:3] op_sel_hi:[1,0]
	v_pk_mul_f32 v[16:17], v[12:13], v[2:3] op_sel_hi:[1,0]
	v_pk_mul_f32 v[12:13], v[10:11], v[2:3] op_sel_hi:[1,0]
	v_pk_mul_f32 v[10:11], v[20:21], v[2:3] op_sel_hi:[1,0]
	v_pk_mul_f32 v[8:9], v[32:33], v[2:3] op_sel_hi:[1,0]
	v_pk_mul_f32 v[6:7], v[30:31], v[2:3] op_sel_hi:[1,0]
	s_and_saveexec_b64 s[26:27], s[10:11]
	s_xor_b64 s[10:11], exec, s[26:27]
	s_cbranch_execz .LBB0_247
	s_and_saveexec_b64 s[26:27], s[8:9]
	s_xor_b64 s[8:9], exec, s[26:27]
	s_cbranch_execz .LBB0_244
	s_and_saveexec_b64 s[26:27], s[6:7]
	s_cbranch_execz .LBB0_243
	v_mul_f32_e32 v2, 0xbfb8aa3b, v24
	v_exp_f32_e32 v28, v2
	v_mul_f32_e32 v2, 0xbfb8aa3b, v22
	v_exp_f32_e32 v30, v2
	v_mul_f32_e32 v2, 0xbfb8aa3b, v25
	v_exp_f32_e32 v29, v2
	v_mul_f32_e32 v2, 0xbfb8aa3b, v23
	v_exp_f32_e32 v31, v2
	v_mul_f32_e32 v2, 0xbfb8aa3b, v18
	v_exp_f32_e32 v32, v2
	v_mul_f32_e32 v2, 0xbfb8aa3b, v16
	v_exp_f32_e32 v34, v2
	v_mul_f32_e32 v2, 0xbfb8aa3b, v19
	v_exp_f32_e32 v33, v2
	v_mul_f32_e32 v2, 0xbfb8aa3b, v17
	v_exp_f32_e32 v35, v2
	v_mul_f32_e32 v2, 0xbfb8aa3b, v12
	v_exp_f32_e32 v36, v2
	v_mul_f32_e32 v2, 0xbfb8aa3b, v10
	v_exp_f32_e32 v38, v2
	v_mul_f32_e32 v2, 0xbfb8aa3b, v13
	v_pk_add_f32 v[28:29], v[28:29], 1.0 op_sel_hi:[1,0]
	v_exp_f32_e32 v37, v2
	v_mul_f32_e32 v2, 0xbfb8aa3b, v11
	v_exp_f32_e32 v39, v2
	v_mul_f32_e32 v2, 0xbfb8aa3b, v8
	v_exp_f32_e32 v20, v2
	v_mul_f32_e32 v2, 0xbfb8aa3b, v6
	v_exp_f32_e32 v14, v2
	v_mul_f32_e32 v2, 0xbfb8aa3b, v9
	v_exp_f32_e32 v21, v2
	v_mul_f32_e32 v2, 0xbfb8aa3b, v7
	v_exp_f32_e32 v15, v2
	v_lshlrev_b64 v[26:27], 12, v[26:27]
	v_lshl_add_u64 v[4:5], v[4:5], 0, v[26:27]
	v_rcp_f32_e32 v27, v29
	v_pk_add_f32 v[30:31], v[30:31], 1.0 op_sel_hi:[1,0]
	v_rcp_f32_e32 v26, v28
	s_nop 0
	v_pk_mul_f32 v[24:25], v[24:25], v[26:27]
	v_rcp_f32_e32 v27, v31
	v_pk_add_f32 v[28:29], v[32:33], 1.0 op_sel_hi:[1,0]
	v_rcp_f32_e32 v26, v30
	s_nop 0
	v_pk_mul_f32 v[22:23], v[22:23], v[26:27]
	v_rcp_f32_e32 v27, v29
	v_pk_add_f32 v[30:31], v[34:35], 1.0 op_sel_hi:[1,0]
	v_rcp_f32_e32 v26, v28
	s_nop 0
	v_pk_mul_f32 v[18:19], v[18:19], v[26:27]
	v_rcp_f32_e32 v27, v31
	v_pk_add_f32 v[20:21], v[20:21], 1.0 op_sel_hi:[1,0]
	v_rcp_f32_e32 v26, v30
	s_nop 0
	v_pk_mul_f32 v[16:17], v[16:17], v[26:27]
	v_bfe_u32 v28, v22, 16, 1
	v_bfe_u32 v2, v17, 16, 1
	v_bfe_u32 v27, v23, 16, 1
	v_add3_u32 v28, v22, v28, s44
	v_add3_u32 v2, v17, v2, s44
	v_bfe_u32 v17, v24, 16, 1
	v_bfe_u32 v22, v25, 16, 1
	v_bfe_u32 v26, v19, 16, 1
	v_add3_u32 v27, v23, v27, s44
	v_add3_u32 v19, v19, v26, s44
	v_add3_u32 v22, v25, v22, s44
	v_add3_u32 v17, v24, v17, s44
	v_lshrrev_b32_e32 v24, 16, v17
	v_lshrrev_b32_e32 v17, 16, v22
	v_lshrrev_b32_e32 v19, 16, v19
	v_pk_add_f32 v[22:23], v[36:37], 1.0 op_sel_hi:[1,0]
	v_and_or_b32 v19, v2, s33, v19
	v_cvt_pk_bf16_f32 v18, v18, v16
	v_and_or_b32 v16, v28, s33, v24
	v_and_or_b32 v17, v27, s33, v17
	v_rcp_f32_e32 v23, v23
	v_pk_add_f32 v[14:15], v[14:15], 1.0 op_sel_hi:[1,0]
	v_pk_add_f32 v[24:25], v[38:39], 1.0 op_sel_hi:[1,0]
	v_rcp_f32_e32 v22, v22
	s_nop 0
	v_pk_mul_f32 v[12:13], v[12:13], v[22:23]
	v_rcp_f32_e32 v23, v25
	v_rcp_f32_e32 v22, v24
	s_nop 0
	v_pk_mul_f32 v[10:11], v[10:11], v[22:23]
	v_rcp_f32_e32 v21, v21
	v_rcp_f32_e32 v20, v20
	s_nop 0
	v_pk_mul_f32 v[8:9], v[8:9], v[20:21]
	v_div_scale_f32 v21, s[6:7], v14, v14, 1.0
	v_rcp_f32_e32 v22, v21
	v_rcp_f32_e32 v15, v15
	v_fma_f32 v2, -v21, v22, 1.0
	v_fmac_f32_e32 v22, v2, v22
	v_div_scale_f32 v2, vcc, 1.0, v14, 1.0
	v_mul_f32_e32 v20, v2, v22
	v_fma_f32 v23, -v21, v20, v2
	v_fmac_f32_e32 v20, v23, v22
	v_fma_f32 v2, -v21, v20, v2
	v_div_fmas_f32 v2, v2, v22, v20
	v_div_fixup_f32 v14, v2, v14, 1.0
	v_pk_mul_f32 v[6:7], v[6:7], v[14:15]
	v_bfe_u32 v2, v7, 16, 1
	v_add3_u32 v2, v7, v2, s44
	v_bfe_u32 v20, v9, 16, 1
	v_add3_u32 v9, v9, v20, s44
	v_add_co_u32_e32 v4, vcc, 0x13bfb000, v4
	v_lshrrev_b32_e32 v9, 16, v9
	v_addc_co_u32_e32 v5, vcc, 0, v5, vcc
	v_and_or_b32 v9, v2, s33, v9
	v_cvt_pk_bf16_f32 v8, v8, v6
	v_cvt_pk_bf16_f32 v7, v13, v11
	v_cvt_pk_bf16_f32 v6, v12, v10
	global_store_dwordx4 v[4:5], v[16:19], off offset:640
	global_store_dwordx4 v[4:5], v[6:9], off offset:656

; DI unsigned pack2(float a, float b) { return (unsigned)f2bf(a) | ((unsigned)f2bf(b) << 16); }
; DI void store16_bf(bft* dst, const float (&v)[16]) {
;   u32x4 o0 = {pack2(v[0], v[1]), pack2(v[2], v[3]), pack2(v[4], v[5]), pack2(v[6], v[7])}, o1 = {pack2(v[8], v[9]), pack2(v[10], v[11]), pack2(v[12], v[13]), pack2(v[14], v[15])};
;   *(u32x4*)dst = o0; *(u32x4*)(dst + 8) = o1;
; DI void phase_inproj0(const Params& p) {
;     ...
;       else if (col < 1728) store16_bf(lat + (size_t)row * 704 + col - 1024, v);
.LBB0_244:
	s_andn2_saveexec_b64 s[6:7], s[8:9]
	s_cbranch_execz .LBB0_246
	v_mad_i64_i32 v[20:21], s[8:9], v26, s45, v[4:5]
	v_bfe_u32 v2, v17, 16, 1
	v_bfe_u32 v4, v16, 16, 1
	v_bfe_u32 v14, v22, 16, 1
	v_add3_u32 v4, v16, v4, s44
	v_add3_u32 v2, v17, v2, s44
	v_bfe_u32 v15, v24, 16, 1
	v_bfe_u32 v17, v18, 16, 1
	v_add3_u32 v14, v22, v14, s44
	v_bfe_u32 v22, v19, 16, 1
	v_add3_u32 v17, v18, v17, s44
	v_add3_u32 v15, v24, v15, s44
	v_add3_u32 v19, v19, v22, s44
	v_lshrrev_b32_e32 v18, 16, v15
	v_lshrrev_b32_e32 v16, 16, v17
	v_lshrrev_b32_e32 v17, 16, v19
	v_and_or_b32 v16, v4, s33, v16
	v_cvt_pk_bf16_f32 v15, v25, v23
	v_bfe_u32 v4, v6, 16, 1
	v_bfe_u32 v5, v11, 16, 1
	v_and_or_b32 v17, v2, s33, v17
	v_and_or_b32 v14, v14, s33, v18
	v_bfe_u32 v2, v7, 16, 1
	v_bfe_u32 v18, v10, 16, 1
	v_add3_u32 v5, v11, v5, s44
	v_add3_u32 v4, v6, v4, s44
	v_bfe_u32 v6, v12, 16, 1
	v_bfe_u32 v11, v8, 16, 1
	v_add3_u32 v10, v10, v18, s44
	v_add3_u32 v2, v7, v2, s44
	v_bfe_u32 v7, v13, 16, 1
	v_bfe_u32 v18, v9, 16, 1
	v_add3_u32 v8, v8, v11, s44
	v_add3_u32 v6, v12, v6, s44
	v_add3_u32 v9, v9, v18, s44
	v_add3_u32 v7, v13, v7, s44
	v_lshrrev_b32_e32 v11, 16, v6
	v_lshrrev_b32_e32 v6, 16, v8
	v_add_co_u32_e32 v8, vcc, 0xf9fb000, v20
	v_lshrrev_b32_e32 v12, 16, v7
	v_lshrrev_b32_e32 v7, 16, v9
	v_addc_co_u32_e32 v9, vcc, 0, v21, vcc
	v_and_or_b32 v7, v2, s33, v7
	v_and_or_b32 v6, v4, s33, v6
	v_and_or_b32 v5, v5, s33, v12
	v_and_or_b32 v4, v10, s33, v11
	global_store_dwordx4 v[8:9], v[14:17], off offset:2048
	global_store_dwordx4 v[8:9], v[4:7], off offset:2064

; DI unsigned pack2(float a, float b) { return (unsigned)f2bf(a) | ((unsigned)f2bf(b) << 16); }
; DI void store16_bf(bft* dst, const float (&v)[16]) {
;   u32x4 o0 = {pack2(v[0], v[1]), pack2(v[2], v[3]), pack2(v[4], v[5]), pack2(v[6], v[7])}, o1 = {pack2(v[8], v[9]), pack2(v[10], v[11]), pack2(v[12], v[13]), pack2(v[14], v[15])};
;   *(u32x4*)dst = o0; *(u32x4*)(dst + 8) = o1;
; DI void phase_inproj0(const Params& p) {
;     ...
;       if (col < 1024) store16_bf(u + (size_t)row * 1024 + col, v);
.LBB0_247:
	s_andn2_saveexec_b64 s[6:7], s[10:11]
	s_cbranch_execz .LBB0_156
	v_lshlrev_b64 v[4:5], 11, v[26:27]
	v_lshl_add_u64 v[20:21], v[118:119], 0, v[4:5]
	v_bfe_u32 v2, v17, 16, 1
	v_bfe_u32 v4, v16, 16, 1
	v_bfe_u32 v14, v22, 16, 1
	v_add3_u32 v14, v22, v14, s44
	v_add3_u32 v4, v16, v4, s44
	v_add3_u32 v2, v17, v2, s44
	v_bfe_u32 v15, v24, 16, 1
	v_bfe_u32 v17, v18, 16, 1
	v_bfe_u32 v22, v19, 16, 1
	v_add3_u32 v19, v19, v22, s44
	v_add3_u32 v17, v18, v17, s44
	v_add3_u32 v15, v24, v15, s44
	v_lshrrev_b32_e32 v18, 16, v15
	v_lshrrev_b32_e32 v16, 16, v17
	v_lshrrev_b32_e32 v17, 16, v19
	v_and_or_b32 v17, v2, s33, v17
	v_and_or_b32 v16, v4, s33, v16
	v_cvt_pk_bf16_f32 v15, v25, v23
	v_and_or_b32 v14, v14, s33, v18
	v_bfe_u32 v2, v7, 16, 1
	v_bfe_u32 v4, v6, 16, 1
	v_bfe_u32 v5, v11, 16, 1
	v_bfe_u32 v18, v10, 16, 1
	v_add3_u32 v10, v10, v18, s44
	v_add3_u32 v5, v11, v5, s44
	v_add3_u32 v4, v6, v4, s44
	v_add3_u32 v2, v7, v2, s44
	v_bfe_u32 v6, v12, 16, 1
	v_bfe_u32 v7, v13, 16, 1
	v_bfe_u32 v11, v8, 16, 1
	v_bfe_u32 v18, v9, 16, 1
	v_add3_u32 v9, v9, v18, s44
	v_add3_u32 v8, v8, v11, s44
	v_add3_u32 v7, v13, v7, s44
	v_add3_u32 v6, v12, v6, s44
	v_lshrrev_b32_e32 v11, 16, v6
	v_lshrrev_b32_e32 v12, 16, v7
	v_lshrrev_b32_e32 v6, 16, v8
	v_lshrrev_b32_e32 v7, 16, v9
	v_and_or_b32 v7, v2, s33, v7
	v_and_or_b32 v6, v4, s33, v6
	v_and_or_b32 v5, v5, s33, v12
	v_and_or_b32 v4, v10, s33, v11
	global_store_dwordx4 v[20:21], v[14:17], off
	global_store_dwordx4 v[20:21], v[4:7], off offset:16
	s_branch .LBB0_156

; DI unsigned pack2(float a, float b) { return (unsigned)f2bf(a) | ((unsigned)f2bf(b) << 16); }
; DI void phase_s5gen(const Params& p) {
;     ...
;       u32x4 w = {pack2(v[0], v[1]), pack2(v[2], v[3]), pack2(v[4], v[5]), pack2(v[6], v[7])};
;       *(u32x4*)(Tm + ((size_t)g * 512 + n) * 768 + k8 * 8) = w; }
.LBB0_329:
	s_or_b64 exec, exec, s[64:65]
	s_waitcnt lgkmcnt(0)
	v_cvt_pk_bf16_f32 v0, v0, v1
	v_cvt_pk_bf16_f32 v1, v2, v3
	v_cvt_pk_bf16_f32 v2, v4, v5
	v_ashrrev_i32_e32 v13, 31, v12
	v_cvt_pk_bf16_f32 v3, v6, v7
	v_lshl_add_u64 v[4:5], s[60:61], 0, v[12:13]
	v_mov_b64_e32 v[6:7], s[0:1]
	v_mad_u64_u32 v[6:7], s[16:17], v4, s78, v[6:7]
	v_mad_i32_i24 v7, v5, s78, v7
	v_ashrrev_i32_e32 v15, 31, v14
	v_lshl_add_u64 v[4:5], v[14:15], 1, v[6:7]
	global_store_dwordx4 v[4:5], v[0:3], off
	v_cmp_lt_i32_e32 vcc, s79, v10
	v_add_u32_e32 v8, 0x1000, v8
	v_add_u32_e32 v0, 0x200, v10
	s_or_b64 s[62:63], vcc, s[62:63]
	v_mov_b32_e32 v10, v0
	s_andn2_b64 exec, exec, s[62:63]
	s_cbranch_execz .LBB0_413

; DI unsigned pack2(float a, float b) { return (unsigned)f2bf(a) | ((unsigned)f2bf(b) << 16); }
; DI void phase_s5gen(const Params& p) {
;     ...
;     for (int e = tid; e < 64 * 64; e += NTHR) { int n = q4 * 64 + (e >> 6), k8 = e & 63; int d = n >> 7, ri = (n >> 6) & 1, m = n & 63; float v[8];
; #pragma unroll
;       for (int j = 0; j < 8; ++j) { int k = k8 * 8 + j, tau = k >> 4, c2 = k & 15; int pwr = d == 0 ? 31 - tau : tau;
;         float2 V = cmul(pw[(d * 33 + pwr) * 64 + m], Bb[(d * 64 + m) * 16 + c2]); v[j] = ri == 0 ? V.x : V.y; }
;       u32x4 w = {pack2(v[0], v[1]), pack2(v[2], v[3]), pack2(v[4], v[5]), pack2(v[6], v[7])};
;       *(u32x4*)(W1 + ((size_t)g * 256 + n) * 512 + k8 * 8) = w; }
.LBB0_415:
	v_ashrrev_i32_e32 v3, 6, v2
	v_cmp_lt_i32_e32 vcc, s80, v2
	v_add_u32_e32 v4, s58, v3
	s_or_b64 s[18:19], vcc, s[18:19]
	v_ashrrev_i32_e32 v6, 7, v4
	v_cmp_gt_u32_e32 vcc, s3, v4
	v_add_u32_e32 v5, 0x200, v2
	v_and_b32_e32 v3, 63, v3
	v_cndmask_b32_e32 v7, v66, v67, vcc
	v_mul_i32_i24_e32 v9, 33, v6
	v_mov_b32_e32 v2, v5
	v_lshlrev_b32_e32 v8, 3, v3
	v_lshlrev_b32_e32 v3, 7, v3
	v_ashrrev_i32_e32 v5, 31, v4
	v_lshl_add_u32 v6, v6, 13, 16
	v_add_lshl_u32 v7, v9, v7, 9
	v_and_b32_e32 v50, 64, v4
	v_lshlrev_b64 v[4:5], 10, v[4:5]
	v_add3_u32 v3, v6, v3, v71
	v_add3_u32 v16, 16, v7, v8
	v_lshl_add_u64 v[20:21], v[0:1], 0, v[4:5]
	ds_read_b128 v[4:7], v3 offset:33808
	ds_read_b128 v[8:11], v3 offset:33824
	ds_read_b128 v[12:15], v3 offset:33840
	ds_read_b64 v[22:23], v16
	ds_read_b128 v[16:19], v3 offset:33792
	s_waitcnt lgkmcnt(4)
	v_mov_b32_e32 v25, v4
	v_mov_b32_e32 v27, v5
	v_mov_b32_e32 v29, v4
	v_mov_b32_e32 v31, v6
	v_mov_b32_e32 v37, v7
	v_mov_b32_e32 v39, v6
	s_waitcnt lgkmcnt(3)
	v_mov_b32_e32 v42, v9
	s_waitcnt lgkmcnt(2)
	v_mov_b32_e32 v43, v13
	v_mov_b32_e32 v44, v8
	v_mov_b32_e32 v45, v13
	v_mov_b32_e32 v46, v11
	v_mov_b32_e32 v47, v15
	s_waitcnt lgkmcnt(0)
	v_mov_b32_e32 v26, v17
	v_mov_b32_e32 v4, v16
	v_mov_b32_e32 v36, v19
	v_mov_b32_e32 v6, v18
	v_mov_b32_e32 v40, v8
	v_mov_b32_e32 v41, v12
	v_mov_b32_e32 v8, v9
	v_mov_b32_e32 v9, v12
	v_mov_b32_e32 v12, v10
	v_mov_b32_e32 v13, v14
	v_mov_b32_e32 v48, v10
	v_mov_b32_e32 v49, v15
	v_mov_b32_e32 v10, v11
	v_mov_b32_e32 v11, v14
	v_mov_b32_e32 v24, v16
	v_mov_b32_e32 v28, v17
	v_mov_b32_e32 v30, v18
	v_mov_b32_e32 v38, v19
	v_pk_mul_f32 v[14:15], v[22:23], v[42:43] op_sel:[1,0]
	v_pk_mul_f32 v[16:17], v[22:23], v[44:45] op_sel:[1,0] op_sel_hi:[0,1]
	v_pk_mul_f32 v[18:19], v[22:23], v[46:47] op_sel:[1,0]
	v_pk_mul_f32 v[26:27], v[22:23], v[26:27] op_sel:[1,0]
	v_pk_mul_f32 v[4:5], v[22:23], v[4:5] op_sel:[1,0] op_sel_hi:[0,1]
	v_pk_mul_f32 v[36:37], v[22:23], v[36:37] op_sel:[1,0]
	v_pk_mul_f32 v[6:7], v[22:23], v[6:7] op_sel:[1,0] op_sel_hi:[0,1]
	v_pk_mul_f32 v[42:43], v[22:23], v[48:49] op_sel:[1,0] op_sel_hi:[0,1]
	v_pk_fma_f32 v[14:15], v[22:23], v[40:41], v[14:15] op_sel_hi:[0,1,1] neg_lo:[0,0,1] neg_hi:[0,0,1]
	v_pk_fma_f32 v[8:9], v[22:23], v[8:9], v[16:17]
	v_pk_fma_f32 v[12:13], v[22:23], v[12:13], v[18:19] op_sel_hi:[0,1,1] neg_lo:[0,0,1] neg_hi:[0,0,1]
	v_pk_fma_f32 v[16:17], v[22:23], v[24:25], v[26:27] op_sel_hi:[0,1,1] neg_lo:[0,0,1] neg_hi:[0,0,1]
	v_pk_fma_f32 v[4:5], v[22:23], v[28:29], v[4:5]
	v_pk_fma_f32 v[18:19], v[22:23], v[30:31], v[36:37] op_sel_hi:[0,1,1] neg_lo:[0,0,1] neg_hi:[0,0,1]
	v_pk_fma_f32 v[6:7], v[22:23], v[38:39], v[6:7]
	v_cmp_eq_u32_e32 vcc, 0, v50
	v_pk_fma_f32 v[10:11], v[22:23], v[10:11], v[42:43]
	s_nop 0
	v_cndmask_b32_e32 v3, v5, v17, vcc
	v_cndmask_b32_e32 v4, v4, v16, vcc
	v_cndmask_b32_e32 v5, v6, v18, vcc
	v_cndmask_b32_e32 v6, v7, v19, vcc
	v_cndmask_b32_e32 v7, v9, v15, vcc
	v_cndmask_b32_e32 v8, v8, v14, vcc
	v_cndmask_b32_e32 v9, v10, v12, vcc
	v_cndmask_b32_e32 v10, v11, v13, vcc
	v_bfe_u32 v15, v4, 16, 1
	v_bfe_u32 v16, v3, 16, 1
	v_bfe_u32 v13, v6, 16, 1
	v_bfe_u32 v14, v5, 16, 1
	v_add3_u32 v3, v3, v16, s76
	v_add3_u32 v4, v4, v15, s76
	v_add3_u32 v14, v5, v14, s76
	v_add3_u32 v5, v6, v13, s76
	v_lshrrev_b32_e32 v4, 16, v4
	v_lshrrev_b32_e32 v3, 16, v3
	v_cvt_pk_bf16_f32 v7, v7, v10
	v_cvt_pk_bf16_f32 v6, v8, v9
	v_and_or_b32 v5, v5, s77, v3
	v_and_or_b32 v4, v14, s77, v4
	global_store_dwordx4 v[20:21], v[4:7], off
	s_andn2_b64 exec, exec, s[18:19]
	s_cbranch_execnz .LBB0_415
	s_branch .LBB0_318

; DI float geluf(float x) { float z = 0.7978845608028654f * (x + 0.044715f * x * x * x); float t = 1.f - 2.f / (1.f + __expf(2.f * z)); return 0.5f * x * (1.f + t); }
;     ...
; #pragma unroll
;   for (int n = 0; n < 4; ++n)
; #pragma unroll
;     for (int j = 0; j < 4; ++j) stg[(fq * 4 + j) * 68 + n * 16 + fr] = am[n][j];
;   asm volatile("s_waitcnt lgkmcnt(0)" ::: "memory");
;   const float* rp = stg + (lane >> 2) * 68 + (lane & 3) * 16;
; #pragma unroll
;   for (int i = 0; i < 4; ++i) { f32x4 t = *(const f32x4*)(rp + i * 4); v[4 * i] = t[0]; v[4 * i + 1] = t[1]; v[4 * i + 2] = t[2]; v[4 * i + 3] = t[3]; }
; DI void phase_s5step3(const Params& p) {
;     ...
;     EPI256_BEGIN
; #pragma unroll
;       for (int i = 0; i < 16; ++i) v[i] = geluf(v[i]);
;       store16_bf(ys + ((size_t)row * 32 + (col >> 4)) * LDP + g * 16, v);
.LBB0_592:
	v_lshrrev_b32_e32 v2, 6, v159
	v_lshrrev_b32_e32 v132, 2, v159
	v_and_b32_e32 v3, 15, v159
	v_mul_lo_u32 v2, v2, s31
	v_and_b32_e32 v132, 12, v132
	v_add_u32_e32 v2, s33, v2
	v_lshlrev_b32_e32 v3, 2, v3
	v_mul_u32_u24_e32 v132, 0x110, v132
	v_add3_u32 v140, v2, v3, v132
	v_bfe_u32 v3, v159, 2, 4
	v_and_b32_e32 v133, 48, v160
	s_waitcnt vmcnt(0)
	s_barrier
	v_mul_u32_u24_e32 v132, 0x110, v3
	v_lshlrev_b32_e32 v134, 2, v133
	ds_write2_b32 v140, v128, v124 offset1:16
	ds_write2_b32 v140, v129, v125 offset0:68 offset1:84
	ds_write2_b32 v140, v130, v126 offset0:136 offset1:152
	ds_write2_b32 v140, v131, v127 offset0:204 offset1:220
	ds_write2_b32 v140, v120, v116 offset0:32 offset1:48
	ds_write2_b32 v140, v121, v117 offset0:100 offset1:116
	ds_write2_b32 v140, v122, v118 offset0:168 offset1:184
	ds_write2_b32 v140, v123, v119 offset0:236 offset1:252
	v_add3_u32 v141, v2, v132, v134
	s_waitcnt lgkmcnt(0)
	ds_read_b128 v[142:145], v141
	ds_read_b128 v[124:127], v141 offset:16
	ds_read_b128 v[120:123], v141 offset:32
	ds_read_b128 v[116:119], v141 offset:48
	v_ashrrev_i32_e32 v2, 1, v159
	s_waitcnt lgkmcnt(3)
	v_mul_f32_e32 v128, 0x3d372713, v145
	v_mul_f32_e32 v128, v145, v128
	v_fma_f32 v128, v145, v128, v145
	v_mul_f32_e32 v128, 0x3f4c422a, v128
	v_add_f32_e32 v128, v128, v128
	v_mul_f32_e32 v128, 0x3fb8aa3b, v128
	v_exp_f32_e32 v147, v128
	s_waitcnt lgkmcnt(2)
	v_mul_f32_e32 v128, 0x3d372713, v124
	v_mul_f32_e32 v128, v124, v128
	v_fma_f32 v128, v124, v128, v124
	v_mul_f32_e32 v128, 0x3f4c422a, v128
	v_add_f32_e32 v128, v128, v128
	v_mul_f32_e32 v128, 0x3fb8aa3b, v128
	v_exp_f32_e32 v148, v128
	v_mul_f32_e32 v128, 0x3d372713, v125
	v_mul_f32_e32 v128, v125, v128
	v_fma_f32 v128, v125, v128, v125
	v_mul_f32_e32 v128, 0x3f4c422a, v128
	v_add_f32_e32 v128, v128, v128
	v_mul_f32_e32 v128, 0x3fb8aa3b, v128
	v_exp_f32_e32 v150, v128
	v_mul_f32_e32 v128, 0x3d372713, v126
	v_mul_f32_e32 v128, v126, v128
	v_fma_f32 v128, v126, v128, v126
	v_mul_f32_e32 v128, 0x3f4c422a, v128
	v_add_f32_e32 v128, v128, v128
	v_mul_f32_e32 v128, 0x3fb8aa3b, v128
	v_exp_f32_e32 v149, v128
	v_mul_f32_e32 v128, 0x3d372713, v127
	v_mul_f32_e32 v128, v127, v128
	v_fma_f32 v128, v127, v128, v127
	v_mul_f32_e32 v128, 0x3f4c422a, v128
	v_add_f32_e32 v128, v128, v128
	v_mul_f32_e32 v128, 0x3fb8aa3b, v128
	v_exp_f32_e32 v151, v128
	s_waitcnt lgkmcnt(1)
	v_mul_f32_e32 v128, 0x3d372713, v120
	v_mul_f32_e32 v128, v120, v128
	v_fma_f32 v128, v120, v128, v120
	v_mul_f32_e32 v128, 0x3f4c422a, v128
	v_add_f32_e32 v128, v128, v128
	v_mul_f32_e32 v128, 0x3fb8aa3b, v128
	v_exp_f32_e32 v138, v128
	v_mul_f32_e32 v128, 0x3d372713, v121
	v_mul_f32_e32 v128, v121, v128
	v_fma_f32 v128, v121, v128, v121
	v_mul_f32_e32 v128, 0x3f4c422a, v128
	v_add_f32_e32 v128, v128, v128
	v_mul_f32_e32 v128, 0x3fb8aa3b, v128
	v_exp_f32_e32 v136, v128
	v_mul_f32_e32 v128, 0x3d372713, v122
	v_mul_f32_e32 v128, v122, v128
	v_fma_f32 v128, v122, v128, v122
	v_mul_f32_e32 v128, 0x3f4c422a, v128
	v_add_f32_e32 v128, v128, v128
	v_mul_f32_e32 v128, 0x3fb8aa3b, v128
	v_exp_f32_e32 v139, v128
	v_mul_f32_e32 v128, 0x3d372713, v123
	v_mul_f32_e32 v128, v123, v128
	v_fma_f32 v128, v123, v128, v123
	v_mul_f32_e32 v128, 0x3f4c422a, v128
	v_add_f32_e32 v128, v128, v128
	v_mul_f32_e32 v128, 0x3fb8aa3b, v128
	v_exp_f32_e32 v137, v128
	s_waitcnt lgkmcnt(0)
	v_mul_f32_e32 v128, 0x3d372713, v116
	v_mul_f32_e32 v128, v116, v128
	v_fma_f32 v128, v116, v128, v116
	v_mul_f32_e32 v128, 0x3f4c422a, v128
	v_add_f32_e32 v128, v128, v128
	v_and_b32_e32 v2, 0xffffff80, v2
	v_mul_f32_e32 v128, 0x3fb8aa3b, v128
	v_add_u32_e32 v2, s39, v2
	v_exp_f32_e32 v134, v128
	v_mul_f32_e32 v128, 0x3d372713, v117
	v_or_b32_e32 v132, v2, v3
	v_mul_f32_e32 v3, 0x3d372713, v143
	v_mul_f32_e32 v128, v117, v128
	v_mul_f32_e32 v3, v143, v3
	v_fma_f32 v128, v117, v128, v117
	v_fma_f32 v3, v143, v3, v143
	v_mul_f32_e32 v128, 0x3f4c422a, v128
	v_mul_f32_e32 v3, 0x3f4c422a, v3
	v_add_f32_e32 v128, v128, v128
	v_add_f32_e32 v3, v3, v3
	v_mul_f32_e32 v128, 0x3fb8aa3b, v128
	v_mul_f32_e32 v3, 0x3fb8aa3b, v3
	v_exp_f32_e32 v130, v128
	v_mul_f32_e32 v128, 0x3d372713, v118
	v_mul_f32_e32 v2, 0x3d372713, v142
	v_exp_f32_e32 v146, v3
	v_mul_f32_e32 v3, 0x3d372713, v144
	v_mul_f32_e32 v128, v118, v128
	v_mul_f32_e32 v2, v142, v2
	v_mul_f32_e32 v3, v144, v3
	v_fma_f32 v128, v118, v128, v118
	v_fma_f32 v2, v142, v2, v142
	v_fma_f32 v3, v144, v3, v144
	v_mul_f32_e32 v128, 0x3f4c422a, v128
	v_mul_f32_e32 v2, 0x3f4c422a, v2
	v_mul_f32_e32 v3, 0x3f4c422a, v3
	v_add_f32_e32 v128, v128, v128
	v_add_f32_e32 v2, v2, v2
	v_add_f32_e32 v3, v3, v3
	v_mul_f32_e32 v128, 0x3fb8aa3b, v128
	v_mul_f32_e32 v2, 0x3fb8aa3b, v2
	v_mul_f32_e32 v3, 0x3fb8aa3b, v3
	v_exp_f32_e32 v135, v128
	v_mul_f32_e32 v128, 0x3d372713, v119
	v_exp_f32_e32 v2, v2
	v_exp_f32_e32 v3, v3
	v_mul_f32_e32 v128, v119, v128
	v_fma_f32 v128, v119, v128, v119
	v_and_b32_e32 v0, 0xc0, v159
	v_mul_f32_e32 v128, 0x3f4c422a, v128
	s_add_u32 s8, s5, s14
	v_or3_b32 v0, v0, s38, v133
	v_add_f32_e32 v128, v128, v128
	v_ashrrev_i32_e32 v133, 31, v132
	s_addc_u32 s9, s22, s15
	v_lshrrev_b32_e32 v0, 4, v0
	v_mul_f32_e32 v128, 0x3fb8aa3b, v128
	v_lshlrev_b64 v[152:153], 5, v[132:133]
	v_pk_add_f32 v[154:155], v[2:3], 1.0 op_sel_hi:[1,0]
	v_exp_f32_e32 v131, v128
	v_or_b32_e32 v133, v152, v0
	v_mov_b64_e32 v[128:129], s[8:9]
	v_mad_u64_u32 v[2:3], s[8:9], v133, s36, v[128:129]
	v_mad_i32_i24 v3, v153, s36, v3
	v_rcp_f32_e32 v153, v155
	s_nop 0
	v_add_f32_e32 v153, v153, v153
	v_pk_add_f32 v[146:147], v[146:147], 1.0 op_sel_hi:[1,0]
	v_rcp_f32_e32 v152, v154
	s_nop 0
	v_add_f32_e32 v152, v152, v152
	v_mov_b32_e32 v154, v142
; DI unsigned pack2(float a, float b) { return (unsigned)f2bf(a) | ((unsigned)f2bf(b) << 16); }
; DI float geluf(float x) { float z = 0.7978845608028654f * (x + 0.044715f * x * x * x); float t = 1.f - 2.f / (1.f + __expf(2.f * z)); return 0.5f * x * (1.f + t); }
;     ...
; #pragma unroll
;   for (int n = 0; n < 4; ++n)
; #pragma unroll
;     for (int j = 0; j < 4; ++j) stg[(fq * 4 + j) * 68 + n * 16 + fr] = am[n][j];
;   asm volatile("s_waitcnt lgkmcnt(0)" ::: "memory");
;   const float* rp = stg + (lane >> 2) * 68 + (lane & 3) * 16;
; #pragma unroll
;   for (int i = 0; i < 4; ++i) { f32x4 t = *(const f32x4*)(rp + i * 4); v[4 * i] = t[0]; v[4 * i + 1] = t[1]; v[4 * i + 2] = t[2]; v[4 * i + 3] = t[3]; }
; DI void store16_bf(bft* dst, const float (&v)[16]) {
;   u32x4 o0 = {pack2(v[0], v[1]), pack2(v[2], v[3]), pack2(v[4], v[5]), pack2(v[6], v[7])}, o1 = {pack2(v[8], v[9]), pack2(v[10], v[11]), pack2(v[12], v[13]), pack2(v[14], v[15])};
;   *(u32x4*)dst = o0; *(u32x4*)(dst + 8) = o1;
; DI void phase_s5step3(const Params& p) {
;     ...
;       for (int i = 0; i < 16; ++i) v[i] = geluf(v[i]);
;       store16_bf(ys + ((size_t)row * 32 + (col >> 4)) * LDP + g * 16, v);
	v_pk_add_f32 v[152:153], v[152:153], 1.0 op_sel_hi:[1,0] neg_lo:[1,0] neg_hi:[1,0]
	v_mov_b32_e32 v155, v144
	v_pk_mul_f32 v[154:155], v[154:155], 0.5 op_sel_hi:[1,0]
	v_pk_add_f32 v[152:153], v[152:153], 1.0 op_sel_hi:[1,0]
	v_pk_mul_f32 v[152:153], v[154:155], v[152:153]
	v_rcp_f32_e32 v147, v147
	s_nop 0
	v_add_f32_e32 v147, v147, v147
	v_pk_add_f32 v[138:139], v[138:139], 1.0 op_sel_hi:[1,0]
	v_mov_b32_e32 v144, v143
	v_pk_add_f32 v[142:143], v[148:149], 1.0 op_sel_hi:[1,0]
	v_rcp_f32_e32 v146, v146
	s_nop 0
	v_add_f32_e32 v146, v146, v146
	v_pk_add_f32 v[146:147], v[146:147], 1.0 op_sel_hi:[1,0] neg_lo:[1,0] neg_hi:[1,0]
	v_pk_mul_f32 v[144:145], v[144:145], 0.5 op_sel_hi:[1,0]
	v_pk_add_f32 v[146:147], v[146:147], 1.0 op_sel_hi:[1,0]
	v_pk_add_f32 v[136:137], v[136:137], 1.0 op_sel_hi:[1,0]
	v_pk_mul_f32 v[144:145], v[144:145], v[146:147]
	v_rcp_f32_e32 v143, v143
	s_nop 0
	v_add_f32_e32 v143, v143, v143
	v_pk_add_f32 v[130:131], v[130:131], 1.0 op_sel_hi:[1,0]
	v_pk_add_f32 v[148:149], v[150:151], 1.0 op_sel_hi:[1,0]
	v_mov_b32_e32 v146, v124
	v_mov_b32_e32 v147, v126
	v_rcp_f32_e32 v142, v142
	s_nop 0
	v_add_f32_e32 v142, v142, v142
	v_pk_add_f32 v[142:143], v[142:143], 1.0 op_sel_hi:[1,0] neg_lo:[1,0] neg_hi:[1,0]
	v_pk_mul_f32 v[146:147], v[146:147], 0.5 op_sel_hi:[1,0]
	v_pk_add_f32 v[142:143], v[142:143], 1.0 op_sel_hi:[1,0]
	v_pk_mul_f32 v[142:143], v[146:147], v[142:143]
	v_rcp_f32_e32 v147, v149
	s_nop 0
	v_add_f32_e32 v147, v147, v147
	v_rcp_f32_e32 v146, v148
	s_nop 0
	v_add_f32_e32 v146, v146, v146
	v_pk_add_f32 v[146:147], v[146:147], 1.0 op_sel_hi:[1,0] neg_lo:[1,0] neg_hi:[1,0]
	v_mov_b32_e32 v126, v125
	v_pk_mul_f32 v[124:125], v[126:127], 0.5 op_sel_hi:[1,0]
	v_pk_add_f32 v[126:127], v[146:147], 1.0 op_sel_hi:[1,0]
	v_bfe_u32 v133, v145, 16, 1
	v_pk_mul_f32 v[124:125], v[124:125], v[126:127]
	v_add3_u32 v133, v145, v133, s37
	v_bfe_u32 v127, v153, 16, 1
	v_add3_u32 v127, v153, v127, s37
	v_lshrrev_b32_e32 v146, 16, v127
	v_cvt_pk_bf16_f32 v127, v143, v125
	v_and_or_b32 v125, v133, s30, v146
	v_cvt_pk_bf16_f32 v126, v142, v124
	v_cvt_pk_bf16_f32 v124, v152, v144
	v_rcp_f32_e32 v139, v139
	s_nop 0
	v_add_f32_e32 v139, v139, v139
	s_add_i32 s23, s23, 1
	v_mov_b32_e32 v142, v120
	v_mov_b32_e32 v143, v122
	v_rcp_f32_e32 v138, v138
	s_nop 0
	v_add_f32_e32 v138, v138, v138
	v_pk_add_f32 v[138:139], v[138:139], 1.0 op_sel_hi:[1,0] neg_lo:[1,0] neg_hi:[1,0]
	v_pk_mul_f32 v[142:143], v[142:143], 0.5 op_sel_hi:[1,0]
	v_pk_add_f32 v[138:139], v[138:139], 1.0 op_sel_hi:[1,0]
	v_pk_mul_f32 v[138:139], v[142:143], v[138:139]
	v_rcp_f32_e32 v137, v137
	s_nop 0
	v_add_f32_e32 v137, v137, v137
	v_rcp_f32_e32 v136, v136
	s_nop 0
	v_add_f32_e32 v136, v136, v136
	v_mov_b32_e32 v122, v121
	v_pk_add_f32 v[120:121], v[134:135], 1.0 op_sel_hi:[1,0]
	v_pk_add_f32 v[136:137], v[136:137], 1.0 op_sel_hi:[1,0] neg_lo:[1,0] neg_hi:[1,0]
	v_pk_mul_f32 v[122:123], v[122:123], 0.5 op_sel_hi:[1,0]
	v_pk_add_f32 v[134:135], v[136:137], 1.0 op_sel_hi:[1,0]
	s_nop 0
	v_pk_mul_f32 v[122:123], v[122:123], v[134:135]
	v_rcp_f32_e32 v121, v121
	s_nop 0
	v_add_f32_e32 v121, v121, v121
	v_mov_b32_e32 v134, v116
	v_div_scale_f32 v116, s[8:9], v131, v131, 2.0
	v_mov_b32_e32 v135, v118
	v_rcp_f32_e32 v118, v116
	v_rcp_f32_e32 v120, v120
	s_nop 0
	v_add_f32_e32 v120, v120, v120
	v_pk_add_f32 v[120:121], v[120:121], 1.0 op_sel_hi:[1,0] neg_lo:[1,0] neg_hi:[1,0]
	v_pk_mul_f32 v[134:135], v[134:135], 0.5 op_sel_hi:[1,0]
	v_fma_f32 v133, -v116, v118, 1.0
	v_pk_add_f32 v[120:121], v[120:121], 1.0 op_sel_hi:[1,0]
	v_fmac_f32_e32 v118, v133, v118
	v_div_scale_f32 v133, vcc, 2.0, v131, 2.0
	v_pk_mul_f32 v[120:121], v[134:135], v[120:121]
	v_mul_f32_e32 v134, v133, v118
	v_fma_f32 v135, -v116, v134, v133
	v_fmac_f32_e32 v134, v135, v118
	v_fma_f32 v116, -v116, v134, v133
	v_div_scale_f32 v133, s[8:9], v130, v130, 2.0
	v_rcp_f32_e32 v135, v133
	v_div_fmas_f32 v116, v116, v118, v134
	v_div_fixup_f32 v131, v116, v131, 2.0
	v_fma_f32 v116, -v133, v135, 1.0
	v_fmac_f32_e32 v135, v116, v135
	v_div_scale_f32 v116, vcc, 2.0, v130, 2.0
	v_mul_f32_e32 v118, v116, v135
	v_fma_f32 v134, -v133, v118, v116
	v_fmac_f32_e32 v118, v134, v135
	v_fma_f32 v116, -v133, v118, v116
	v_div_fmas_f32 v116, v116, v135, v118
	v_div_fixup_f32 v130, v116, v130, 2.0
	v_pk_add_f32 v[130:131], v[130:131], 1.0 op_sel_hi:[1,0] neg_lo:[1,0] neg_hi:[1,0]
	v_mov_b32_e32 v118, v117
	v_pk_mul_f32 v[116:117], v[118:119], 0.5 op_sel_hi:[1,0]
	v_pk_add_f32 v[118:119], v[130:131], 1.0 op_sel_hi:[1,0]
	v_pk_mul_f32 v[116:117], v[116:117], v[118:119]
	v_cvt_pk_bf16_f32 v119, v121, v117
	v_cvt_pk_bf16_f32 v118, v120, v116
	v_cvt_pk_bf16_f32 v117, v139, v123
	v_cvt_pk_bf16_f32 v116, v138, v122
	global_store_dwordx4 v[2:3], v[124:127], off
	global_store_dwordx4 v[2:3], v[116:119], off offset:16
	ds_write2_b32 v140, v112, v108 offset1:16
	ds_write2_b32 v140, v113, v109 offset0:68 offset1:84
	ds_write2_b32 v140, v114, v110 offset0:136 offset1:152
	ds_write2_b32 v140, v115, v111 offset0:204 offset1:220
	ds_write2_b32 v140, v104, v100 offset0:32 offset1:48
	ds_write2_b32 v140, v105, v101 offset0:100 offset1:116
	ds_write2_b32 v140, v106, v102 offset0:168 offset1:184
	ds_write2_b32 v140, v107, v103 offset0:236 offset1:252
	s_waitcnt lgkmcnt(0)
	ds_read_b128 v[120:123], v141
	ds_read_b128 v[108:111], v141 offset:16
	ds_read_b128 v[104:107], v141 offset:32
	ds_read_b128 v[100:103], v141 offset:48
	v_or_b32_e32 v134, 16, v132
	s_waitcnt lgkmcnt(3)
; DI float geluf(float x) { float z = 0.7978845608028654f * (x + 0.044715f * x * x * x); float t = 1.f - 2.f / (1.f + __expf(2.f * z)); return 0.5f * x * (1.f + t); }
;     ...
; #pragma unroll
;   for (int n = 0; n < 4; ++n)
; #pragma unroll
;     for (int j = 0; j < 4; ++j) stg[(fq * 4 + j) * 68 + n * 16 + fr] = am[n][j];
;   asm volatile("s_waitcnt lgkmcnt(0)" ::: "memory");
;   const float* rp = stg + (lane >> 2) * 68 + (lane & 3) * 16;
; #pragma unroll
;   for (int i = 0; i < 4; ++i) { f32x4 t = *(const f32x4*)(rp + i * 4); v[4 * i] = t[0]; v[4 * i + 1] = t[1]; v[4 * i + 2] = t[2]; v[4 * i + 3] = t[3]; }
; DI void phase_s5step3(const Params& p) {
;     ...
;       for (int i = 0; i < 16; ++i) v[i] = geluf(v[i]);
	v_mul_f32_e32 v3, 0x3d372713, v121
	v_mul_f32_e32 v3, v121, v3
	v_fma_f32 v3, v121, v3, v121
	v_mul_f32_e32 v3, 0x3f4c422a, v3
	v_add_f32_e32 v3, v3, v3
	v_mul_f32_e32 v3, 0x3fb8aa3b, v3
	v_mul_f32_e32 v2, 0x3d372713, v120
	v_exp_f32_e32 v124, v3
	v_mul_f32_e32 v3, 0x3d372713, v122
	v_mul_f32_e32 v2, v120, v2
	v_mul_f32_e32 v3, v122, v3
	v_fma_f32 v2, v120, v2, v120
	v_fma_f32 v3, v122, v3, v122
	v_mul_f32_e32 v2, 0x3f4c422a, v2
	v_mul_f32_e32 v3, 0x3f4c422a, v3
	v_add_f32_e32 v2, v2, v2
	v_add_f32_e32 v3, v3, v3
	v_mul_f32_e32 v2, 0x3fb8aa3b, v2
	v_mul_f32_e32 v3, 0x3fb8aa3b, v3
	v_exp_f32_e32 v2, v2
	v_exp_f32_e32 v3, v3
	v_ashrrev_i32_e32 v135, 31, v134
	v_lshlrev_b64 v[134:135], 5, v[134:135]
	v_or_b32_e32 v133, v134, v0
	v_pk_add_f32 v[136:137], v[2:3], 1.0 op_sel_hi:[1,0]
	v_mad_u64_u32 v[2:3], s[8:9], v133, s36, v[128:129]
	v_mad_i32_i24 v3, v135, s36, v3
	v_mul_f32_e32 v112, 0x3d372713, v123
	v_mul_f32_e32 v112, v123, v112
	v_fma_f32 v112, v123, v112, v123
	v_mul_f32_e32 v112, 0x3f4c422a, v112
	v_add_f32_e32 v112, v112, v112
	v_rcp_f32_e32 v135, v137
	s_nop 0
	v_add_f32_e32 v135, v135, v135
	v_mul_f32_e32 v112, 0x3fb8aa3b, v112
	v_exp_f32_e32 v125, v112
	s_nop 0
	v_pk_add_f32 v[124:125], v[124:125], 1.0 op_sel_hi:[1,0]
	s_waitcnt lgkmcnt(2)
	v_mul_f32_e32 v112, 0x3d372713, v108
	v_rcp_f32_e32 v134, v136
	s_nop 0
	v_add_f32_e32 v134, v134, v134
	v_mov_b32_e32 v136, v120
	v_mul_f32_e32 v112, v108, v112
	v_mov_b32_e32 v137, v122
	v_fma_f32 v112, v108, v112, v108
	v_mul_f32_e32 v112, 0x3f4c422a, v112
	v_add_f32_e32 v112, v112, v112
	v_mul_f32_e32 v112, 0x3fb8aa3b, v112
	v_pk_add_f32 v[134:135], v[134:135], 1.0 op_sel_hi:[1,0] neg_lo:[1,0] neg_hi:[1,0]
	v_exp_f32_e32 v126, v112
	v_mul_f32_e32 v112, 0x3d372713, v109
	v_pk_mul_f32 v[136:137], v[136:137], 0.5 op_sel_hi:[1,0]
	v_pk_add_f32 v[134:135], v[134:135], 1.0 op_sel_hi:[1,0]
	v_mul_f32_e32 v112, v109, v112
	v_pk_mul_f32 v[134:135], v[136:137], v[134:135]
	v_fma_f32 v112, v109, v112, v109
	v_mul_f32_e32 v112, 0x3f4c422a, v112
	v_add_f32_e32 v112, v112, v112
	v_mul_f32_e32 v112, 0x3fb8aa3b, v112
	v_exp_f32_e32 v130, v112
	v_mul_f32_e32 v112, 0x3d372713, v110
	v_mul_f32_e32 v112, v110, v112
	v_fma_f32 v112, v110, v112, v110
	v_mul_f32_e32 v112, 0x3f4c422a, v112
	v_rcp_f32_e32 v125, v125
	s_nop 0
	v_add_f32_e32 v125, v125, v125
	v_add_f32_e32 v112, v112, v112
	v_mul_f32_e32 v112, 0x3fb8aa3b, v112
	v_exp_f32_e32 v127, v112
	v_rcp_f32_e32 v124, v124
	s_nop 0
	v_add_f32_e32 v124, v124, v124
	v_mov_b32_e32 v122, v121
	v_pk_add_f32 v[120:121], v[126:127], 1.0 op_sel_hi:[1,0]
	v_pk_add_f32 v[124:125], v[124:125], 1.0 op_sel_hi:[1,0] neg_lo:[1,0] neg_hi:[1,0]
	v_pk_mul_f32 v[122:123], v[122:123], 0.5 op_sel_hi:[1,0]
	v_pk_add_f32 v[124:125], v[124:125], 1.0 op_sel_hi:[1,0]
	v_mul_f32_e32 v112, 0x3d372713, v111
	v_pk_mul_f32 v[122:123], v[122:123], v[124:125]
	v_mul_f32_e32 v112, v111, v112
	v_fma_f32 v112, v111, v112, v111
	v_mul_f32_e32 v112, 0x3f4c422a, v112
	v_add_f32_e32 v112, v112, v112
	v_rcp_f32_e32 v121, v121
	s_nop 0
	v_add_f32_e32 v121, v121, v121
	v_mul_f32_e32 v112, 0x3fb8aa3b, v112
	v_exp_f32_e32 v131, v112
	s_nop 0
	v_pk_add_f32 v[126:127], v[130:131], 1.0 op_sel_hi:[1,0]
	v_rcp_f32_e32 v120, v120
	s_nop 0
	v_add_f32_e32 v120, v120, v120
	v_mov_b32_e32 v124, v108
	v_mov_b32_e32 v125, v110
	v_pk_add_f32 v[120:121], v[120:121], 1.0 op_sel_hi:[1,0] neg_lo:[1,0] neg_hi:[1,0]
	v_pk_mul_f32 v[124:125], v[124:125], 0.5 op_sel_hi:[1,0]
	v_pk_add_f32 v[120:121], v[120:121], 1.0 op_sel_hi:[1,0]
	s_waitcnt lgkmcnt(1)
	v_mul_f32_e32 v112, 0x3d372713, v104
	v_pk_mul_f32 v[120:121], v[124:125], v[120:121]
	v_mul_f32_e32 v112, v104, v112
	v_fma_f32 v112, v104, v112, v104
	v_mul_f32_e32 v112, 0x3f4c422a, v112
	v_add_f32_e32 v112, v112, v112
	v_mul_f32_e32 v112, 0x3fb8aa3b, v112
	v_exp_f32_e32 v118, v112
	v_mul_f32_e32 v112, 0x3d372713, v105
	v_mul_f32_e32 v112, v105, v112
	v_fma_f32 v112, v105, v112, v105
	v_mul_f32_e32 v112, 0x3f4c422a, v112
	v_rcp_f32_e32 v125, v127
	s_nop 0
	v_add_f32_e32 v125, v125, v125
	v_add_f32_e32 v112, v112, v112
	v_mul_f32_e32 v112, 0x3fb8aa3b, v112
	v_exp_f32_e32 v116, v112
	v_mul_f32_e32 v112, 0x3d372713, v106
	v_mul_f32_e32 v112, v106, v112
	v_fma_f32 v112, v106, v112, v106
	v_mul_f32_e32 v112, 0x3f4c422a, v112
	v_add_f32_e32 v112, v112, v112
	v_rcp_f32_e32 v124, v126
	s_nop 0
	v_add_f32_e32 v124, v124, v124
	v_mul_f32_e32 v112, 0x3fb8aa3b, v112
	v_pk_add_f32 v[124:125], v[124:125], 1.0 op_sel_hi:[1,0] neg_lo:[1,0] neg_hi:[1,0]
	v_mov_b32_e32 v110, v109
	v_exp_f32_e32 v119, v112
	v_pk_mul_f32 v[108:109], v[110:111], 0.5 op_sel_hi:[1,0]
	v_pk_add_f32 v[110:111], v[124:125], 1.0 op_sel_hi:[1,0]
	v_pk_mul_f32 v[108:109], v[108:109], v[110:111]
	v_pk_add_f32 v[118:119], v[118:119], 1.0 op_sel_hi:[1,0]
	v_cvt_pk_bf16_f32 v110, v120, v108
	v_cvt_pk_bf16_f32 v108, v134, v122
	v_cvt_pk_bf16_f32 v111, v121, v109
	v_cvt_pk_bf16_f32 v109, v135, v123
	v_mul_f32_e32 v112, 0x3d372713, v107
	v_mul_f32_e32 v112, v107, v112
	v_fma_f32 v112, v107, v112, v107
	v_mul_f32_e32 v112, 0x3f4c422a, v112
	v_add_f32_e32 v112, v112, v112
	v_rcp_f32_e32 v119, v119
	s_nop 0
	v_add_f32_e32 v119, v119, v119
	v_mul_f32_e32 v112, 0x3fb8aa3b, v112
	v_exp_f32_e32 v117, v112
	s_nop 0
	v_pk_add_f32 v[116:117], v[116:117], 1.0 op_sel_hi:[1,0]
	v_rcp_f32_e32 v118, v118
	s_nop 0
	v_add_f32_e32 v118, v118, v118
	v_mov_b32_e32 v120, v104
	v_mov_b32_e32 v121, v106
	v_pk_add_f32 v[118:119], v[118:119], 1.0 op_sel_hi:[1,0] neg_lo:[1,0] neg_hi:[1,0]
	v_pk_mul_f32 v[120:121], v[120:121], 0.5 op_sel_hi:[1,0]
	v_pk_add_f32 v[118:119], v[118:119], 1.0 op_sel_hi:[1,0]
	s_waitcnt lgkmcnt(0)
; DI unsigned pack2(float a, float b) { return (unsigned)f2bf(a) | ((unsigned)f2bf(b) << 16); }
; DI float geluf(float x) { float z = 0.7978845608028654f * (x + 0.044715f * x * x * x); float t = 1.f - 2.f / (1.f + __expf(2.f * z)); return 0.5f * x * (1.f + t); }
;     ...
; #pragma unroll
;   for (int n = 0; n < 4; ++n)
; #pragma unroll
;     for (int j = 0; j < 4; ++j) stg[(fq * 4 + j) * 68 + n * 16 + fr] = am[n][j];
;   asm volatile("s_waitcnt lgkmcnt(0)" ::: "memory");
;   const float* rp = stg + (lane >> 2) * 68 + (lane & 3) * 16;
; #pragma unroll
;   for (int i = 0; i < 4; ++i) { f32x4 t = *(const f32x4*)(rp + i * 4); v[4 * i] = t[0]; v[4 * i + 1] = t[1]; v[4 * i + 2] = t[2]; v[4 * i + 3] = t[3]; }
; DI void store16_bf(bft* dst, const float (&v)[16]) {
;   u32x4 o0 = {pack2(v[0], v[1]), pack2(v[2], v[3]), pack2(v[4], v[5]), pack2(v[6], v[7])}, o1 = {pack2(v[8], v[9]), pack2(v[10], v[11]), pack2(v[12], v[13]), pack2(v[14], v[15])};
;   *(u32x4*)dst = o0; *(u32x4*)(dst + 8) = o1;
; DI void phase_s5step3(const Params& p) {
;     ...
;       for (int i = 0; i < 16; ++i) v[i] = geluf(v[i]);
;       store16_bf(ys + ((size_t)row * 32 + (col >> 4)) * LDP + g * 16, v);
	v_mul_f32_e32 v112, 0x3d372713, v100
	v_pk_mul_f32 v[118:119], v[120:121], v[118:119]
	v_mul_f32_e32 v113, 0x3d372713, v102
	v_mul_f32_e32 v112, v100, v112
	v_mul_f32_e32 v113, v102, v113
	v_fma_f32 v112, v100, v112, v100
	v_fma_f32 v113, v102, v113, v102
	v_mul_f32_e32 v112, 0x3f4c422a, v112
	v_mul_f32_e32 v113, 0x3f4c422a, v113
	v_rcp_f32_e32 v117, v117
	s_nop 0
	v_add_f32_e32 v117, v117, v117
	v_add_f32_e32 v112, v112, v112
	v_add_f32_e32 v113, v113, v113
	v_mul_f32_e32 v112, 0x3fb8aa3b, v112
	v_mul_f32_e32 v113, 0x3fb8aa3b, v113
	v_exp_f32_e32 v114, v112
	v_exp_f32_e32 v115, v113
	v_rcp_f32_e32 v116, v116
	s_nop 0
	v_add_f32_e32 v116, v116, v116
	v_mov_b32_e32 v106, v105
	v_pk_add_f32 v[104:105], v[114:115], 1.0 op_sel_hi:[1,0]
	v_pk_add_f32 v[116:117], v[116:117], 1.0 op_sel_hi:[1,0] neg_lo:[1,0] neg_hi:[1,0]
	v_pk_mul_f32 v[106:107], v[106:107], 0.5 op_sel_hi:[1,0]
	v_pk_add_f32 v[114:115], v[116:117], 1.0 op_sel_hi:[1,0]
	v_mul_f32_e32 v112, 0x3d372713, v101
	v_pk_mul_f32 v[106:107], v[106:107], v[114:115]
	v_mul_f32_e32 v113, 0x3d372713, v103
	v_mul_f32_e32 v112, v101, v112
	v_mul_f32_e32 v113, v103, v113
	v_fma_f32 v112, v101, v112, v101
	v_fma_f32 v113, v103, v113, v103
	v_mul_f32_e32 v112, 0x3f4c422a, v112
	v_mul_f32_e32 v113, 0x3f4c422a, v113
	v_add_f32_e32 v112, v112, v112
	v_add_f32_e32 v113, v113, v113
	v_rcp_f32_e32 v105, v105
	s_nop 0
	v_add_f32_e32 v105, v105, v105
	v_mul_f32_e32 v112, 0x3fb8aa3b, v112
	v_mul_f32_e32 v113, 0x3fb8aa3b, v113
	v_exp_f32_e32 v112, v112
	v_exp_f32_e32 v113, v113
	s_nop 0
	v_pk_add_f32 v[112:113], v[112:113], 1.0 op_sel_hi:[1,0]
	v_rcp_f32_e32 v104, v104
	s_nop 0
	v_add_f32_e32 v104, v104, v104
	v_mov_b32_e32 v114, v100
	v_div_scale_f32 v100, s[8:9], v113, v113, 2.0
	v_mov_b32_e32 v115, v102
	v_rcp_f32_e32 v102, v100
	v_pk_add_f32 v[104:105], v[104:105], 1.0 op_sel_hi:[1,0] neg_lo:[1,0] neg_hi:[1,0]
	v_pk_mul_f32 v[114:115], v[114:115], 0.5 op_sel_hi:[1,0]
	v_pk_add_f32 v[104:105], v[104:105], 1.0 op_sel_hi:[1,0]
	s_nop 0
	v_pk_mul_f32 v[104:105], v[114:115], v[104:105]
	v_fma_f32 v114, -v100, v102, 1.0
	v_fmac_f32_e32 v102, v114, v102
	v_div_scale_f32 v114, vcc, 2.0, v113, 2.0
	v_mul_f32_e32 v115, v114, v102
	v_fma_f32 v116, -v100, v115, v114
	v_fmac_f32_e32 v115, v116, v102
	v_fma_f32 v100, -v100, v115, v114
	v_div_scale_f32 v114, s[8:9], v112, v112, 2.0
	v_rcp_f32_e32 v116, v114
	v_div_fmas_f32 v100, v100, v102, v115
	v_div_fixup_f32 v113, v100, v113, 2.0
	v_fma_f32 v100, -v114, v116, 1.0
	v_fmac_f32_e32 v116, v100, v116
	v_div_scale_f32 v100, vcc, 2.0, v112, 2.0
	v_mul_f32_e32 v102, v100, v116
	v_fma_f32 v115, -v114, v102, v100
	v_fmac_f32_e32 v102, v115, v116
	v_fma_f32 v100, -v114, v102, v100
	v_div_fmas_f32 v100, v100, v116, v102
	v_div_fixup_f32 v112, v100, v112, 2.0
	v_pk_add_f32 v[112:113], v[112:113], 1.0 op_sel_hi:[1,0] neg_lo:[1,0] neg_hi:[1,0]
	v_mov_b32_e32 v102, v101
	v_pk_mul_f32 v[100:101], v[102:103], 0.5 op_sel_hi:[1,0]
	v_pk_add_f32 v[102:103], v[112:113], 1.0 op_sel_hi:[1,0]
	v_pk_mul_f32 v[100:101], v[100:101], v[102:103]
	v_cvt_pk_bf16_f32 v103, v105, v101
	v_cvt_pk_bf16_f32 v102, v104, v100
	v_cvt_pk_bf16_f32 v101, v119, v107
	v_cvt_pk_bf16_f32 v100, v118, v106
	global_store_dwordx4 v[2:3], v[108:111], off
	global_store_dwordx4 v[2:3], v[100:103], off offset:16
	ds_write2_b32 v140, v96, v92 offset1:16
	ds_write2_b32 v140, v97, v93 offset0:68 offset1:84
	ds_write2_b32 v140, v98, v94 offset0:136 offset1:152
	ds_write2_b32 v140, v99, v95 offset0:204 offset1:220
	ds_write2_b32 v140, v88, v84 offset0:32 offset1:48
	ds_write2_b32 v140, v89, v85 offset0:100 offset1:116
	ds_write2_b32 v140, v90, v86 offset0:168 offset1:184
	ds_write2_b32 v140, v91, v87 offset0:236 offset1:252
	s_waitcnt lgkmcnt(0)
	ds_read_b128 v[104:107], v141
	ds_read_b128 v[92:95], v141 offset:16
	ds_read_b128 v[88:91], v141 offset:32
	ds_read_b128 v[84:87], v141 offset:48
	v_or_b32_e32 v114, 32, v132
	s_waitcnt lgkmcnt(3)
	v_mul_f32_e32 v3, 0x3d372713, v105
	v_mul_f32_e32 v3, v105, v3
	v_fma_f32 v3, v105, v3, v105
	v_mul_f32_e32 v3, 0x3f4c422a, v3
	v_add_f32_e32 v3, v3, v3
	v_mul_f32_e32 v3, 0x3fb8aa3b, v3
	v_mul_f32_e32 v2, 0x3d372713, v104
	v_exp_f32_e32 v108, v3
	v_mul_f32_e32 v3, 0x3d372713, v106
	v_mul_f32_e32 v2, v104, v2
	v_mul_f32_e32 v3, v106, v3
	v_fma_f32 v2, v104, v2, v104
	v_fma_f32 v3, v106, v3, v106
	v_mul_f32_e32 v2, 0x3f4c422a, v2
	v_mul_f32_e32 v3, 0x3f4c422a, v3
	v_add_f32_e32 v2, v2, v2
	v_add_f32_e32 v3, v3, v3
	v_mul_f32_e32 v2, 0x3fb8aa3b, v2
	v_mul_f32_e32 v3, 0x3fb8aa3b, v3
	v_exp_f32_e32 v2, v2
	v_exp_f32_e32 v3, v3
	v_ashrrev_i32_e32 v115, 31, v114
	v_lshlrev_b64 v[114:115], 5, v[114:115]
	v_or_b32_e32 v114, v114, v0
	v_pk_add_f32 v[116:117], v[2:3], 1.0 op_sel_hi:[1,0]
	v_mad_u64_u32 v[2:3], s[8:9], v114, s36, v[128:129]
	v_mad_i32_i24 v3, v115, s36, v3
	v_mul_f32_e32 v96, 0x3d372713, v107
	v_mul_f32_e32 v96, v107, v96
	v_fma_f32 v96, v107, v96, v107
	v_mul_f32_e32 v96, 0x3f4c422a, v96
	v_add_f32_e32 v96, v96, v96
	v_rcp_f32_e32 v115, v117
	s_nop 0
	v_add_f32_e32 v115, v115, v115
	v_mul_f32_e32 v96, 0x3fb8aa3b, v96
	v_exp_f32_e32 v109, v96
	s_nop 0
	v_pk_add_f32 v[108:109], v[108:109], 1.0 op_sel_hi:[1,0]
	s_waitcnt lgkmcnt(2)
; DI unsigned pack2(float a, float b) { return (unsigned)f2bf(a) | ((unsigned)f2bf(b) << 16); }
; DI float geluf(float x) { float z = 0.7978845608028654f * (x + 0.044715f * x * x * x); float t = 1.f - 2.f / (1.f + __expf(2.f * z)); return 0.5f * x * (1.f + t); }
; DI void store16_bf(bft* dst, const float (&v)[16]) {
;   u32x4 o0 = {pack2(v[0], v[1]), pack2(v[2], v[3]), pack2(v[4], v[5]), pack2(v[6], v[7])}, o1 = {pack2(v[8], v[9]), pack2(v[10], v[11]), pack2(v[12], v[13]), pack2(v[14], v[15])};
;   *(u32x4*)dst = o0; *(u32x4*)(dst + 8) = o1;
; DI void phase_s5step3(const Params& p) {
;     ...
;       for (int i = 0; i < 16; ++i) v[i] = geluf(v[i]);
	v_mul_f32_e32 v96, 0x3d372713, v92
	v_rcp_f32_e32 v114, v116
	s_nop 0
	v_add_f32_e32 v114, v114, v114
	v_mov_b32_e32 v116, v104
	v_mul_f32_e32 v96, v92, v96
	v_mov_b32_e32 v117, v106
	v_fma_f32 v96, v92, v96, v92
	v_mul_f32_e32 v96, 0x3f4c422a, v96
	v_pk_add_f32 v[114:115], v[114:115], 1.0 op_sel_hi:[1,0] neg_lo:[1,0] neg_hi:[1,0]
	v_add_f32_e32 v96, v96, v96
	v_pk_mul_f32 v[116:117], v[116:117], 0.5 op_sel_hi:[1,0]
	v_pk_add_f32 v[114:115], v[114:115], 1.0 op_sel_hi:[1,0]
	v_mul_f32_e32 v96, 0x3fb8aa3b, v96
	v_pk_mul_f32 v[114:115], v[116:117], v[114:115]
	v_exp_f32_e32 v110, v96
	v_mul_f32_e32 v96, 0x3d372713, v93
	v_mul_f32_e32 v96, v93, v96
	v_fma_f32 v96, v93, v96, v93
	v_mul_f32_e32 v96, 0x3f4c422a, v96
	v_add_f32_e32 v96, v96, v96
	v_mul_f32_e32 v96, 0x3fb8aa3b, v96
	v_exp_f32_e32 v112, v96
	v_mul_f32_e32 v96, 0x3d372713, v94
	v_mul_f32_e32 v96, v94, v96
	v_fma_f32 v96, v94, v96, v94
	v_mul_f32_e32 v96, 0x3f4c422a, v96
	v_rcp_f32_e32 v109, v109
	s_nop 0
	v_add_f32_e32 v109, v109, v109
	v_add_f32_e32 v96, v96, v96
	v_mul_f32_e32 v96, 0x3fb8aa3b, v96
	v_exp_f32_e32 v111, v96
	v_rcp_f32_e32 v108, v108
	s_nop 0
	v_add_f32_e32 v108, v108, v108
	v_mov_b32_e32 v106, v105
	v_pk_add_f32 v[104:105], v[110:111], 1.0 op_sel_hi:[1,0]
	v_pk_add_f32 v[108:109], v[108:109], 1.0 op_sel_hi:[1,0] neg_lo:[1,0] neg_hi:[1,0]
	v_pk_mul_f32 v[106:107], v[106:107], 0.5 op_sel_hi:[1,0]
	v_pk_add_f32 v[108:109], v[108:109], 1.0 op_sel_hi:[1,0]
	v_mul_f32_e32 v96, 0x3d372713, v95
	v_pk_mul_f32 v[106:107], v[106:107], v[108:109]
	v_mul_f32_e32 v96, v95, v96
	v_fma_f32 v96, v95, v96, v95
	v_mul_f32_e32 v96, 0x3f4c422a, v96
	v_add_f32_e32 v96, v96, v96
	v_rcp_f32_e32 v105, v105
	s_nop 0
	v_add_f32_e32 v105, v105, v105
	v_mul_f32_e32 v96, 0x3fb8aa3b, v96
	v_exp_f32_e32 v113, v96
	s_nop 0
	v_pk_add_f32 v[110:111], v[112:113], 1.0 op_sel_hi:[1,0]
	v_rcp_f32_e32 v104, v104
	s_nop 0
	v_add_f32_e32 v104, v104, v104
	v_mov_b32_e32 v108, v92
	v_mov_b32_e32 v109, v94
	v_pk_add_f32 v[104:105], v[104:105], 1.0 op_sel_hi:[1,0] neg_lo:[1,0] neg_hi:[1,0]
	v_pk_mul_f32 v[108:109], v[108:109], 0.5 op_sel_hi:[1,0]
	v_pk_add_f32 v[104:105], v[104:105], 1.0 op_sel_hi:[1,0]
	s_waitcnt lgkmcnt(1)
	v_mul_f32_e32 v96, 0x3d372713, v88
	v_pk_mul_f32 v[104:105], v[108:109], v[104:105]
	v_mul_f32_e32 v96, v88, v96
	v_fma_f32 v96, v88, v96, v88
	v_mul_f32_e32 v96, 0x3f4c422a, v96
	v_add_f32_e32 v96, v96, v96
	v_mul_f32_e32 v96, 0x3fb8aa3b, v96
	v_exp_f32_e32 v102, v96
	v_mul_f32_e32 v96, 0x3d372713, v89
	v_mul_f32_e32 v96, v89, v96
	v_fma_f32 v96, v89, v96, v89
	v_mul_f32_e32 v96, 0x3f4c422a, v96
	v_rcp_f32_e32 v109, v111
	s_nop 0
	v_add_f32_e32 v109, v109, v109
	v_add_f32_e32 v96, v96, v96
	v_mul_f32_e32 v96, 0x3fb8aa3b, v96
	v_exp_f32_e32 v100, v96
	v_mul_f32_e32 v96, 0x3d372713, v90
	v_mul_f32_e32 v96, v90, v96
	v_fma_f32 v96, v90, v96, v90
	v_mul_f32_e32 v96, 0x3f4c422a, v96
	v_add_f32_e32 v96, v96, v96
	v_rcp_f32_e32 v108, v110
	s_nop 0
	v_add_f32_e32 v108, v108, v108
	v_mul_f32_e32 v96, 0x3fb8aa3b, v96
	v_pk_add_f32 v[108:109], v[108:109], 1.0 op_sel_hi:[1,0] neg_lo:[1,0] neg_hi:[1,0]
	v_mov_b32_e32 v94, v93
	v_exp_f32_e32 v103, v96
	v_pk_mul_f32 v[92:93], v[94:95], 0.5 op_sel_hi:[1,0]
	v_pk_add_f32 v[94:95], v[108:109], 1.0 op_sel_hi:[1,0]
	v_pk_mul_f32 v[92:93], v[92:93], v[94:95]
	v_pk_add_f32 v[102:103], v[102:103], 1.0 op_sel_hi:[1,0]
	v_cvt_pk_bf16_f32 v94, v104, v92
	v_cvt_pk_bf16_f32 v92, v114, v106
	v_cvt_pk_bf16_f32 v95, v105, v93
	v_cvt_pk_bf16_f32 v93, v115, v107
	v_mul_f32_e32 v96, 0x3d372713, v91
	v_mul_f32_e32 v96, v91, v96
	v_fma_f32 v96, v91, v96, v91
	v_mul_f32_e32 v96, 0x3f4c422a, v96
	v_add_f32_e32 v96, v96, v96
	v_rcp_f32_e32 v103, v103
	s_nop 0
	v_add_f32_e32 v103, v103, v103
	v_mul_f32_e32 v96, 0x3fb8aa3b, v96
	v_exp_f32_e32 v101, v96
	s_nop 0
	v_pk_add_f32 v[100:101], v[100:101], 1.0 op_sel_hi:[1,0]
	v_rcp_f32_e32 v102, v102
	s_nop 0
	v_add_f32_e32 v102, v102, v102
	v_mov_b32_e32 v104, v88
	v_mov_b32_e32 v105, v90
	v_pk_add_f32 v[102:103], v[102:103], 1.0 op_sel_hi:[1,0] neg_lo:[1,0] neg_hi:[1,0]
	v_pk_mul_f32 v[104:105], v[104:105], 0.5 op_sel_hi:[1,0]
	v_pk_add_f32 v[102:103], v[102:103], 1.0 op_sel_hi:[1,0]
	s_waitcnt lgkmcnt(0)
	v_mul_f32_e32 v96, 0x3d372713, v84
	v_pk_mul_f32 v[102:103], v[104:105], v[102:103]
	v_mul_f32_e32 v97, 0x3d372713, v86
	v_mul_f32_e32 v96, v84, v96
	v_mul_f32_e32 v97, v86, v97
	v_fma_f32 v96, v84, v96, v84
	v_fma_f32 v97, v86, v97, v86
	v_mul_f32_e32 v96, 0x3f4c422a, v96
	v_mul_f32_e32 v97, 0x3f4c422a, v97
	v_rcp_f32_e32 v101, v101
	s_nop 0
	v_add_f32_e32 v101, v101, v101
	v_add_f32_e32 v96, v96, v96
	v_add_f32_e32 v97, v97, v97
	v_mul_f32_e32 v96, 0x3fb8aa3b, v96
	v_mul_f32_e32 v97, 0x3fb8aa3b, v97
	v_exp_f32_e32 v98, v96
	v_exp_f32_e32 v99, v97
	v_rcp_f32_e32 v100, v100
	s_nop 0
	v_add_f32_e32 v100, v100, v100
	v_mov_b32_e32 v90, v89
	v_pk_add_f32 v[88:89], v[98:99], 1.0 op_sel_hi:[1,0]
	v_pk_add_f32 v[100:101], v[100:101], 1.0 op_sel_hi:[1,0] neg_lo:[1,0] neg_hi:[1,0]
	v_pk_mul_f32 v[90:91], v[90:91], 0.5 op_sel_hi:[1,0]
	v_pk_add_f32 v[98:99], v[100:101], 1.0 op_sel_hi:[1,0]
	v_mul_f32_e32 v96, 0x3d372713, v85
	v_pk_mul_f32 v[90:91], v[90:91], v[98:99]
	v_mul_f32_e32 v97, 0x3d372713, v87
	v_mul_f32_e32 v96, v85, v96
	v_mul_f32_e32 v97, v87, v97
	v_fma_f32 v96, v85, v96, v85
	v_fma_f32 v97, v87, v97, v87
	v_mul_f32_e32 v96, 0x3f4c422a, v96
	v_mul_f32_e32 v97, 0x3f4c422a, v97
	v_add_f32_e32 v96, v96, v96
	v_add_f32_e32 v97, v97, v97
	v_rcp_f32_e32 v89, v89
	s_nop 0
	v_add_f32_e32 v89, v89, v89
	v_mul_f32_e32 v96, 0x3fb8aa3b, v96
	v_mul_f32_e32 v97, 0x3fb8aa3b, v97
	v_exp_f32_e32 v96, v96
	v_exp_f32_e32 v97, v97
	s_nop 0
; DI unsigned pack2(float a, float b) { return (unsigned)f2bf(a) | ((unsigned)f2bf(b) << 16); }
; DI float geluf(float x) { float z = 0.7978845608028654f * (x + 0.044715f * x * x * x); float t = 1.f - 2.f / (1.f + __expf(2.f * z)); return 0.5f * x * (1.f + t); }
;     ...
; #pragma unroll
;   for (int n = 0; n < 4; ++n)
; #pragma unroll
;     for (int j = 0; j < 4; ++j) stg[(fq * 4 + j) * 68 + n * 16 + fr] = am[n][j];
;   asm volatile("s_waitcnt lgkmcnt(0)" ::: "memory");
;   const float* rp = stg + (lane >> 2) * 68 + (lane & 3) * 16;
; #pragma unroll
;   for (int i = 0; i < 4; ++i) { f32x4 t = *(const f32x4*)(rp + i * 4); v[4 * i] = t[0]; v[4 * i + 1] = t[1]; v[4 * i + 2] = t[2]; v[4 * i + 3] = t[3]; }
; DI void store16_bf(bft* dst, const float (&v)[16]) {
;   u32x4 o0 = {pack2(v[0], v[1]), pack2(v[2], v[3]), pack2(v[4], v[5]), pack2(v[6], v[7])}, o1 = {pack2(v[8], v[9]), pack2(v[10], v[11]), pack2(v[12], v[13]), pack2(v[14], v[15])};
;   *(u32x4*)dst = o0; *(u32x4*)(dst + 8) = o1;
; DI void phase_s5step3(const Params& p) {
;     ...
;       for (int i = 0; i < 16; ++i) v[i] = geluf(v[i]);
;       store16_bf(ys + ((size_t)row * 32 + (col >> 4)) * LDP + g * 16, v);
	v_pk_add_f32 v[96:97], v[96:97], 1.0 op_sel_hi:[1,0]
	v_rcp_f32_e32 v88, v88
	s_nop 0
	v_add_f32_e32 v88, v88, v88
	v_mov_b32_e32 v98, v84
	v_div_scale_f32 v84, s[8:9], v97, v97, 2.0
	v_mov_b32_e32 v99, v86
	v_rcp_f32_e32 v86, v84
	v_pk_add_f32 v[88:89], v[88:89], 1.0 op_sel_hi:[1,0] neg_lo:[1,0] neg_hi:[1,0]
	v_pk_mul_f32 v[98:99], v[98:99], 0.5 op_sel_hi:[1,0]
	v_pk_add_f32 v[88:89], v[88:89], 1.0 op_sel_hi:[1,0]
	s_nop 0
	v_pk_mul_f32 v[88:89], v[98:99], v[88:89]
	v_fma_f32 v98, -v84, v86, 1.0
	v_fmac_f32_e32 v86, v98, v86
	v_div_scale_f32 v98, vcc, 2.0, v97, 2.0
	v_mul_f32_e32 v99, v98, v86
	v_fma_f32 v100, -v84, v99, v98
	v_fmac_f32_e32 v99, v100, v86
	v_fma_f32 v84, -v84, v99, v98
	v_div_scale_f32 v98, s[8:9], v96, v96, 2.0
	v_rcp_f32_e32 v100, v98
	v_div_fmas_f32 v84, v84, v86, v99
	v_div_fixup_f32 v97, v84, v97, 2.0
	v_fma_f32 v84, -v98, v100, 1.0
	v_fmac_f32_e32 v100, v84, v100
	v_div_scale_f32 v84, vcc, 2.0, v96, 2.0
	v_mul_f32_e32 v86, v84, v100
	v_fma_f32 v99, -v98, v86, v84
	v_fmac_f32_e32 v86, v99, v100
	v_fma_f32 v84, -v98, v86, v84
	v_div_fmas_f32 v84, v84, v100, v86
	v_div_fixup_f32 v96, v84, v96, 2.0
	v_pk_add_f32 v[96:97], v[96:97], 1.0 op_sel_hi:[1,0] neg_lo:[1,0] neg_hi:[1,0]
	v_mov_b32_e32 v86, v85
	v_pk_mul_f32 v[84:85], v[86:87], 0.5 op_sel_hi:[1,0]
	v_pk_add_f32 v[86:87], v[96:97], 1.0 op_sel_hi:[1,0]
	v_pk_mul_f32 v[84:85], v[84:85], v[86:87]
	v_cvt_pk_bf16_f32 v87, v89, v85
	v_cvt_pk_bf16_f32 v86, v88, v84
	v_cvt_pk_bf16_f32 v85, v103, v91
	v_cvt_pk_bf16_f32 v84, v102, v90
	global_store_dwordx4 v[2:3], v[92:95], off
	global_store_dwordx4 v[2:3], v[84:87], off offset:16
	ds_write2_b32 v140, v80, v76 offset1:16
	ds_write2_b32 v140, v81, v77 offset0:68 offset1:84
	ds_write2_b32 v140, v82, v78 offset0:136 offset1:152
	ds_write2_b32 v140, v83, v79 offset0:204 offset1:220
	ds_write2_b32 v140, v72, v68 offset0:32 offset1:48
	ds_write2_b32 v140, v73, v69 offset0:100 offset1:116
	ds_write2_b32 v140, v74, v70 offset0:168 offset1:184
	ds_write2_b32 v140, v75, v71 offset0:236 offset1:252
	s_waitcnt lgkmcnt(0)
	ds_read_b128 v[88:91], v141
	ds_read_b128 v[76:79], v141 offset:16
	ds_read_b128 v[72:75], v141 offset:32
	ds_read_b128 v[68:71], v141 offset:48
	v_or_b32_e32 v98, 48, v132
	s_waitcnt lgkmcnt(3)
	v_mul_f32_e32 v3, 0x3d372713, v89
	v_mul_f32_e32 v3, v89, v3
	v_fma_f32 v3, v89, v3, v89
	v_mul_f32_e32 v3, 0x3f4c422a, v3
	v_add_f32_e32 v3, v3, v3
	v_mul_f32_e32 v3, 0x3fb8aa3b, v3
	v_mul_f32_e32 v2, 0x3d372713, v88
	v_exp_f32_e32 v92, v3
	v_mul_f32_e32 v3, 0x3d372713, v90
	v_mul_f32_e32 v2, v88, v2
	v_mul_f32_e32 v3, v90, v3
	v_fma_f32 v2, v88, v2, v88
	v_fma_f32 v3, v90, v3, v90
	v_mul_f32_e32 v2, 0x3f4c422a, v2
	v_mul_f32_e32 v3, 0x3f4c422a, v3
	v_add_f32_e32 v2, v2, v2
	v_add_f32_e32 v3, v3, v3
	v_mul_f32_e32 v2, 0x3fb8aa3b, v2
	v_mul_f32_e32 v3, 0x3fb8aa3b, v3
	v_exp_f32_e32 v2, v2
	v_exp_f32_e32 v3, v3
	v_ashrrev_i32_e32 v99, 31, v98
	v_lshlrev_b64 v[98:99], 5, v[98:99]
	v_or_b32_e32 v98, v98, v0
	v_pk_add_f32 v[100:101], v[2:3], 1.0 op_sel_hi:[1,0]
	v_mad_u64_u32 v[2:3], s[8:9], v98, s36, v[128:129]
	v_mad_i32_i24 v3, v99, s36, v3
	v_mul_f32_e32 v80, 0x3d372713, v91
	v_mul_f32_e32 v80, v91, v80
	v_fma_f32 v80, v91, v80, v91
	v_mul_f32_e32 v80, 0x3f4c422a, v80
	v_add_f32_e32 v80, v80, v80
	v_rcp_f32_e32 v99, v101
	s_nop 0
	v_add_f32_e32 v99, v99, v99
	v_mul_f32_e32 v80, 0x3fb8aa3b, v80
	v_exp_f32_e32 v93, v80
	s_nop 0
	v_pk_add_f32 v[92:93], v[92:93], 1.0 op_sel_hi:[1,0]
	s_waitcnt lgkmcnt(2)
	v_mul_f32_e32 v80, 0x3d372713, v76
	v_rcp_f32_e32 v98, v100
	s_nop 0
	v_add_f32_e32 v98, v98, v98
	v_mov_b32_e32 v100, v88
	v_mul_f32_e32 v80, v76, v80
	v_mov_b32_e32 v101, v90
	v_fma_f32 v80, v76, v80, v76
	v_mul_f32_e32 v80, 0x3f4c422a, v80
	v_pk_add_f32 v[98:99], v[98:99], 1.0 op_sel_hi:[1,0] neg_lo:[1,0] neg_hi:[1,0]
	v_add_f32_e32 v80, v80, v80
	v_pk_mul_f32 v[100:101], v[100:101], 0.5 op_sel_hi:[1,0]
	v_pk_add_f32 v[98:99], v[98:99], 1.0 op_sel_hi:[1,0]
	v_mul_f32_e32 v80, 0x3fb8aa3b, v80
	v_pk_mul_f32 v[98:99], v[100:101], v[98:99]
	v_exp_f32_e32 v94, v80
	v_mul_f32_e32 v80, 0x3d372713, v77
	v_mul_f32_e32 v80, v77, v80
	v_fma_f32 v80, v77, v80, v77
	v_mul_f32_e32 v80, 0x3f4c422a, v80
	v_add_f32_e32 v80, v80, v80
	v_mul_f32_e32 v80, 0x3fb8aa3b, v80
	v_exp_f32_e32 v96, v80
	v_mul_f32_e32 v80, 0x3d372713, v78
	v_mul_f32_e32 v80, v78, v80
	v_fma_f32 v80, v78, v80, v78
	v_mul_f32_e32 v80, 0x3f4c422a, v80
	v_rcp_f32_e32 v93, v93
	s_nop 0
	v_add_f32_e32 v93, v93, v93
	v_add_f32_e32 v80, v80, v80
	v_mul_f32_e32 v80, 0x3fb8aa3b, v80
	v_exp_f32_e32 v95, v80
	v_rcp_f32_e32 v92, v92
	s_nop 0
	v_add_f32_e32 v92, v92, v92
	v_mov_b32_e32 v90, v89
	v_pk_add_f32 v[88:89], v[94:95], 1.0 op_sel_hi:[1,0]
	v_pk_add_f32 v[92:93], v[92:93], 1.0 op_sel_hi:[1,0] neg_lo:[1,0] neg_hi:[1,0]
	v_pk_mul_f32 v[90:91], v[90:91], 0.5 op_sel_hi:[1,0]
	v_pk_add_f32 v[92:93], v[92:93], 1.0 op_sel_hi:[1,0]
	v_mul_f32_e32 v80, 0x3d372713, v79
	v_pk_mul_f32 v[90:91], v[90:91], v[92:93]
	v_mul_f32_e32 v80, v79, v80
	v_fma_f32 v80, v79, v80, v79
	v_mul_f32_e32 v80, 0x3f4c422a, v80
	v_add_f32_e32 v80, v80, v80
	v_rcp_f32_e32 v89, v89
	s_nop 0
	v_add_f32_e32 v89, v89, v89
	v_mul_f32_e32 v80, 0x3fb8aa3b, v80
	v_exp_f32_e32 v97, v80
	s_nop 0
	v_pk_add_f32 v[94:95], v[96:97], 1.0 op_sel_hi:[1,0]
	v_rcp_f32_e32 v88, v88
	s_nop 0
	v_add_f32_e32 v88, v88, v88
	v_mov_b32_e32 v92, v76
	v_mov_b32_e32 v93, v78
	v_pk_add_f32 v[88:89], v[88:89], 1.0 op_sel_hi:[1,0] neg_lo:[1,0] neg_hi:[1,0]
	v_pk_mul_f32 v[92:93], v[92:93], 0.5 op_sel_hi:[1,0]
	v_pk_add_f32 v[88:89], v[88:89], 1.0 op_sel_hi:[1,0]
	s_waitcnt lgkmcnt(1)
; DI unsigned pack2(float a, float b) { return (unsigned)f2bf(a) | ((unsigned)f2bf(b) << 16); }
; DI float geluf(float x) { float z = 0.7978845608028654f * (x + 0.044715f * x * x * x); float t = 1.f - 2.f / (1.f + __expf(2.f * z)); return 0.5f * x * (1.f + t); }
;     ...
; #pragma unroll
;   for (int n = 0; n < 4; ++n)
; #pragma unroll
;     for (int j = 0; j < 4; ++j) stg[(fq * 4 + j) * 68 + n * 16 + fr] = am[n][j];
;   asm volatile("s_waitcnt lgkmcnt(0)" ::: "memory");
;   const float* rp = stg + (lane >> 2) * 68 + (lane & 3) * 16;
; #pragma unroll
;   for (int i = 0; i < 4; ++i) { f32x4 t = *(const f32x4*)(rp + i * 4); v[4 * i] = t[0]; v[4 * i + 1] = t[1]; v[4 * i + 2] = t[2]; v[4 * i + 3] = t[3]; }
; DI void store16_bf(bft* dst, const float (&v)[16]) {
;   u32x4 o0 = {pack2(v[0], v[1]), pack2(v[2], v[3]), pack2(v[4], v[5]), pack2(v[6], v[7])}, o1 = {pack2(v[8], v[9]), pack2(v[10], v[11]), pack2(v[12], v[13]), pack2(v[14], v[15])};
;   *(u32x4*)dst = o0; *(u32x4*)(dst + 8) = o1;
; DI void phase_s5step3(const Params& p) {
;     ...
;       for (int i = 0; i < 16; ++i) v[i] = geluf(v[i]);
;       store16_bf(ys + ((size_t)row * 32 + (col >> 4)) * LDP + g * 16, v);
	v_mul_f32_e32 v80, 0x3d372713, v72
	v_pk_mul_f32 v[88:89], v[92:93], v[88:89]
	v_mul_f32_e32 v80, v72, v80
	v_fma_f32 v80, v72, v80, v72
	v_mul_f32_e32 v80, 0x3f4c422a, v80
	v_add_f32_e32 v80, v80, v80
	v_mul_f32_e32 v80, 0x3fb8aa3b, v80
	v_exp_f32_e32 v86, v80
	v_mul_f32_e32 v80, 0x3d372713, v73
	v_mul_f32_e32 v80, v73, v80
	v_fma_f32 v80, v73, v80, v73
	v_mul_f32_e32 v80, 0x3f4c422a, v80
	v_rcp_f32_e32 v93, v95
	s_nop 0
	v_add_f32_e32 v93, v93, v93
	v_add_f32_e32 v80, v80, v80
	v_mul_f32_e32 v80, 0x3fb8aa3b, v80
	v_exp_f32_e32 v84, v80
	v_mul_f32_e32 v80, 0x3d372713, v74
	v_mul_f32_e32 v80, v74, v80
	v_fma_f32 v80, v74, v80, v74
	v_mul_f32_e32 v80, 0x3f4c422a, v80
	v_add_f32_e32 v80, v80, v80
	v_rcp_f32_e32 v92, v94
	s_nop 0
	v_add_f32_e32 v92, v92, v92
	v_mul_f32_e32 v80, 0x3fb8aa3b, v80
	v_pk_add_f32 v[92:93], v[92:93], 1.0 op_sel_hi:[1,0] neg_lo:[1,0] neg_hi:[1,0]
	v_mov_b32_e32 v78, v77
	v_exp_f32_e32 v87, v80
	v_pk_mul_f32 v[76:77], v[78:79], 0.5 op_sel_hi:[1,0]
	v_pk_add_f32 v[78:79], v[92:93], 1.0 op_sel_hi:[1,0]
	v_pk_mul_f32 v[76:77], v[76:77], v[78:79]
	v_pk_add_f32 v[86:87], v[86:87], 1.0 op_sel_hi:[1,0]
	v_cvt_pk_bf16_f32 v78, v88, v76
	v_cvt_pk_bf16_f32 v76, v98, v90
	v_cvt_pk_bf16_f32 v79, v89, v77
	v_cvt_pk_bf16_f32 v77, v99, v91
	v_mul_f32_e32 v80, 0x3d372713, v75
	v_mul_f32_e32 v80, v75, v80
	v_fma_f32 v80, v75, v80, v75
	v_mul_f32_e32 v80, 0x3f4c422a, v80
	v_add_f32_e32 v80, v80, v80
	v_rcp_f32_e32 v87, v87
	s_nop 0
	v_add_f32_e32 v87, v87, v87
	v_mul_f32_e32 v80, 0x3fb8aa3b, v80
	v_exp_f32_e32 v85, v80
	s_nop 0
	v_pk_add_f32 v[84:85], v[84:85], 1.0 op_sel_hi:[1,0]
	v_rcp_f32_e32 v86, v86
	s_nop 0
	v_add_f32_e32 v86, v86, v86
	v_mov_b32_e32 v88, v72
	v_mov_b32_e32 v89, v74
	v_pk_add_f32 v[86:87], v[86:87], 1.0 op_sel_hi:[1,0] neg_lo:[1,0] neg_hi:[1,0]
	v_pk_mul_f32 v[88:89], v[88:89], 0.5 op_sel_hi:[1,0]
	v_pk_add_f32 v[86:87], v[86:87], 1.0 op_sel_hi:[1,0]
	s_waitcnt lgkmcnt(0)
	v_mul_f32_e32 v80, 0x3d372713, v68
	v_pk_mul_f32 v[86:87], v[88:89], v[86:87]
	v_mul_f32_e32 v81, 0x3d372713, v70
	v_mul_f32_e32 v80, v68, v80
	v_mul_f32_e32 v81, v70, v81
	v_fma_f32 v80, v68, v80, v68
	v_fma_f32 v81, v70, v81, v70
	v_mul_f32_e32 v80, 0x3f4c422a, v80
	v_mul_f32_e32 v81, 0x3f4c422a, v81
	v_rcp_f32_e32 v85, v85
	s_nop 0
	v_add_f32_e32 v85, v85, v85
	v_add_f32_e32 v80, v80, v80
	v_add_f32_e32 v81, v81, v81
	v_mul_f32_e32 v80, 0x3fb8aa3b, v80
	v_mul_f32_e32 v81, 0x3fb8aa3b, v81
	v_exp_f32_e32 v82, v80
	v_exp_f32_e32 v83, v81
	v_rcp_f32_e32 v84, v84
	s_nop 0
	v_add_f32_e32 v84, v84, v84
	v_mov_b32_e32 v74, v73
	v_pk_add_f32 v[72:73], v[82:83], 1.0 op_sel_hi:[1,0]
	v_pk_add_f32 v[84:85], v[84:85], 1.0 op_sel_hi:[1,0] neg_lo:[1,0] neg_hi:[1,0]
	v_pk_mul_f32 v[74:75], v[74:75], 0.5 op_sel_hi:[1,0]
	v_pk_add_f32 v[82:83], v[84:85], 1.0 op_sel_hi:[1,0]
	v_mul_f32_e32 v80, 0x3d372713, v69
	v_pk_mul_f32 v[74:75], v[74:75], v[82:83]
	v_mul_f32_e32 v81, 0x3d372713, v71
	v_mul_f32_e32 v80, v69, v80
	v_mul_f32_e32 v81, v71, v81
	v_fma_f32 v80, v69, v80, v69
	v_fma_f32 v81, v71, v81, v71
	v_mul_f32_e32 v80, 0x3f4c422a, v80
	v_mul_f32_e32 v81, 0x3f4c422a, v81
	v_add_f32_e32 v80, v80, v80
	v_add_f32_e32 v81, v81, v81
	v_rcp_f32_e32 v73, v73
	s_nop 0
	v_add_f32_e32 v73, v73, v73
	v_mul_f32_e32 v80, 0x3fb8aa3b, v80
	v_mul_f32_e32 v81, 0x3fb8aa3b, v81
	v_exp_f32_e32 v80, v80
	v_exp_f32_e32 v81, v81
	s_nop 0
	v_pk_add_f32 v[80:81], v[80:81], 1.0 op_sel_hi:[1,0]
	v_rcp_f32_e32 v72, v72
	s_nop 0
	v_add_f32_e32 v72, v72, v72
	v_mov_b32_e32 v82, v68
	v_div_scale_f32 v68, s[8:9], v81, v81, 2.0
	v_mov_b32_e32 v83, v70
	v_rcp_f32_e32 v70, v68
	v_pk_add_f32 v[72:73], v[72:73], 1.0 op_sel_hi:[1,0] neg_lo:[1,0] neg_hi:[1,0]
	v_pk_mul_f32 v[82:83], v[82:83], 0.5 op_sel_hi:[1,0]
	v_pk_add_f32 v[72:73], v[72:73], 1.0 op_sel_hi:[1,0]
	s_nop 0
	v_pk_mul_f32 v[72:73], v[82:83], v[72:73]
	v_fma_f32 v82, -v68, v70, 1.0
	v_fmac_f32_e32 v70, v82, v70
	v_div_scale_f32 v82, vcc, 2.0, v81, 2.0
	v_mul_f32_e32 v83, v82, v70
	v_fma_f32 v84, -v68, v83, v82
	v_fmac_f32_e32 v83, v84, v70
	v_fma_f32 v68, -v68, v83, v82
	v_div_scale_f32 v82, s[8:9], v80, v80, 2.0
	v_rcp_f32_e32 v84, v82
	v_div_fmas_f32 v68, v68, v70, v83
	v_div_fixup_f32 v81, v68, v81, 2.0
	v_fma_f32 v68, -v82, v84, 1.0
	v_fmac_f32_e32 v84, v68, v84
	v_div_scale_f32 v68, vcc, 2.0, v80, 2.0
	v_mul_f32_e32 v70, v68, v84
	v_fma_f32 v83, -v82, v70, v68
	v_fmac_f32_e32 v70, v83, v84
	v_fma_f32 v68, -v82, v70, v68
	v_div_fmas_f32 v68, v68, v84, v70
	v_div_fixup_f32 v80, v68, v80, 2.0
	v_pk_add_f32 v[80:81], v[80:81], 1.0 op_sel_hi:[1,0] neg_lo:[1,0] neg_hi:[1,0]
	v_mov_b32_e32 v70, v69
	v_pk_mul_f32 v[68:69], v[70:71], 0.5 op_sel_hi:[1,0]
	v_pk_add_f32 v[70:71], v[80:81], 1.0 op_sel_hi:[1,0]
	v_pk_mul_f32 v[68:69], v[68:69], v[70:71]
	v_cvt_pk_bf16_f32 v71, v73, v69
	v_cvt_pk_bf16_f32 v70, v72, v68
	v_cvt_pk_bf16_f32 v69, v87, v75
	v_cvt_pk_bf16_f32 v68, v86, v74
	global_store_dwordx4 v[2:3], v[76:79], off
	global_store_dwordx4 v[2:3], v[68:71], off offset:16
	ds_write2_b32 v140, v64, v60 offset1:16
	ds_write2_b32 v140, v65, v61 offset0:68 offset1:84
	ds_write2_b32 v140, v66, v62 offset0:136 offset1:152
	ds_write2_b32 v140, v67, v63 offset0:204 offset1:220
	ds_write2_b32 v140, v56, v52 offset0:32 offset1:48
	ds_write2_b32 v140, v57, v53 offset0:100 offset1:116
	ds_write2_b32 v140, v58, v54 offset0:168 offset1:184
	ds_write2_b32 v140, v59, v55 offset0:236 offset1:252
	s_waitcnt lgkmcnt(0)
	ds_read_b128 v[72:75], v141
	ds_read_b128 v[60:63], v141 offset:16
	ds_read_b128 v[56:59], v141 offset:32
	ds_read_b128 v[52:55], v141 offset:48
	v_or_b32_e32 v82, 64, v132
	s_waitcnt lgkmcnt(3)
; DI float geluf(float x) { float z = 0.7978845608028654f * (x + 0.044715f * x * x * x); float t = 1.f - 2.f / (1.f + __expf(2.f * z)); return 0.5f * x * (1.f + t); }
;     ...
; #pragma unroll
;   for (int n = 0; n < 4; ++n)
; #pragma unroll
;     for (int j = 0; j < 4; ++j) stg[(fq * 4 + j) * 68 + n * 16 + fr] = am[n][j];
;   asm volatile("s_waitcnt lgkmcnt(0)" ::: "memory");
;   const float* rp = stg + (lane >> 2) * 68 + (lane & 3) * 16;
; #pragma unroll
;   for (int i = 0; i < 4; ++i) { f32x4 t = *(const f32x4*)(rp + i * 4); v[4 * i] = t[0]; v[4 * i + 1] = t[1]; v[4 * i + 2] = t[2]; v[4 * i + 3] = t[3]; }
; DI void phase_s5step3(const Params& p) {
;     ...
;       for (int i = 0; i < 16; ++i) v[i] = geluf(v[i]);
	v_mul_f32_e32 v3, 0x3d372713, v73
	v_mul_f32_e32 v3, v73, v3
	v_fma_f32 v3, v73, v3, v73
	v_mul_f32_e32 v3, 0x3f4c422a, v3
	v_add_f32_e32 v3, v3, v3
	v_mul_f32_e32 v3, 0x3fb8aa3b, v3
	v_mul_f32_e32 v2, 0x3d372713, v72
	v_exp_f32_e32 v76, v3
	v_mul_f32_e32 v3, 0x3d372713, v74
	v_mul_f32_e32 v2, v72, v2
	v_mul_f32_e32 v3, v74, v3
	v_fma_f32 v2, v72, v2, v72
	v_fma_f32 v3, v74, v3, v74
	v_mul_f32_e32 v2, 0x3f4c422a, v2
	v_mul_f32_e32 v3, 0x3f4c422a, v3
	v_add_f32_e32 v2, v2, v2
	v_add_f32_e32 v3, v3, v3
	v_mul_f32_e32 v2, 0x3fb8aa3b, v2
	v_mul_f32_e32 v3, 0x3fb8aa3b, v3
	v_exp_f32_e32 v2, v2
	v_exp_f32_e32 v3, v3
	v_ashrrev_i32_e32 v83, 31, v82
	v_lshlrev_b64 v[82:83], 5, v[82:83]
	v_or_b32_e32 v82, v82, v0
	v_pk_add_f32 v[84:85], v[2:3], 1.0 op_sel_hi:[1,0]
	v_mad_u64_u32 v[2:3], s[8:9], v82, s36, v[128:129]
	v_mad_i32_i24 v3, v83, s36, v3
	v_mul_f32_e32 v64, 0x3d372713, v75
	v_mul_f32_e32 v64, v75, v64
	v_fma_f32 v64, v75, v64, v75
	v_mul_f32_e32 v64, 0x3f4c422a, v64
	v_add_f32_e32 v64, v64, v64
	v_rcp_f32_e32 v83, v85
	s_nop 0
	v_add_f32_e32 v83, v83, v83
	v_mul_f32_e32 v64, 0x3fb8aa3b, v64
	v_exp_f32_e32 v77, v64
	s_nop 0
	v_pk_add_f32 v[76:77], v[76:77], 1.0 op_sel_hi:[1,0]
	s_waitcnt lgkmcnt(2)
	v_mul_f32_e32 v64, 0x3d372713, v60
	v_rcp_f32_e32 v82, v84
	s_nop 0
	v_add_f32_e32 v82, v82, v82
	v_mov_b32_e32 v84, v72
	v_mul_f32_e32 v64, v60, v64
	v_mov_b32_e32 v85, v74
	v_fma_f32 v64, v60, v64, v60
	v_mul_f32_e32 v64, 0x3f4c422a, v64
	v_pk_add_f32 v[82:83], v[82:83], 1.0 op_sel_hi:[1,0] neg_lo:[1,0] neg_hi:[1,0]
	v_add_f32_e32 v64, v64, v64
	v_pk_mul_f32 v[84:85], v[84:85], 0.5 op_sel_hi:[1,0]
	v_pk_add_f32 v[82:83], v[82:83], 1.0 op_sel_hi:[1,0]
	v_mul_f32_e32 v64, 0x3fb8aa3b, v64
	v_pk_mul_f32 v[82:83], v[84:85], v[82:83]
	v_exp_f32_e32 v78, v64
	v_mul_f32_e32 v64, 0x3d372713, v61
	v_mul_f32_e32 v64, v61, v64
	v_fma_f32 v64, v61, v64, v61
	v_mul_f32_e32 v64, 0x3f4c422a, v64
	v_add_f32_e32 v64, v64, v64
	v_mul_f32_e32 v64, 0x3fb8aa3b, v64
	v_exp_f32_e32 v80, v64
	v_mul_f32_e32 v64, 0x3d372713, v62
	v_mul_f32_e32 v64, v62, v64
	v_fma_f32 v64, v62, v64, v62
	v_mul_f32_e32 v64, 0x3f4c422a, v64
	v_rcp_f32_e32 v77, v77
	s_nop 0
	v_add_f32_e32 v77, v77, v77
	v_add_f32_e32 v64, v64, v64
	v_mul_f32_e32 v64, 0x3fb8aa3b, v64
	v_exp_f32_e32 v79, v64
	v_rcp_f32_e32 v76, v76
	s_nop 0
	v_add_f32_e32 v76, v76, v76
	v_mov_b32_e32 v74, v73
	v_pk_add_f32 v[72:73], v[78:79], 1.0 op_sel_hi:[1,0]
	v_pk_add_f32 v[76:77], v[76:77], 1.0 op_sel_hi:[1,0] neg_lo:[1,0] neg_hi:[1,0]
	v_pk_mul_f32 v[74:75], v[74:75], 0.5 op_sel_hi:[1,0]
	v_pk_add_f32 v[76:77], v[76:77], 1.0 op_sel_hi:[1,0]
	v_mul_f32_e32 v64, 0x3d372713, v63
	v_pk_mul_f32 v[74:75], v[74:75], v[76:77]
	v_mul_f32_e32 v64, v63, v64
	v_fma_f32 v64, v63, v64, v63
	v_mul_f32_e32 v64, 0x3f4c422a, v64
	v_add_f32_e32 v64, v64, v64
	v_rcp_f32_e32 v73, v73
	s_nop 0
	v_add_f32_e32 v73, v73, v73
	v_mul_f32_e32 v64, 0x3fb8aa3b, v64
	v_exp_f32_e32 v81, v64
	s_nop 0
	v_pk_add_f32 v[78:79], v[80:81], 1.0 op_sel_hi:[1,0]
	v_rcp_f32_e32 v72, v72
	s_nop 0
	v_add_f32_e32 v72, v72, v72
	v_mov_b32_e32 v76, v60
	v_mov_b32_e32 v77, v62
	v_pk_add_f32 v[72:73], v[72:73], 1.0 op_sel_hi:[1,0] neg_lo:[1,0] neg_hi:[1,0]
	v_pk_mul_f32 v[76:77], v[76:77], 0.5 op_sel_hi:[1,0]
	v_pk_add_f32 v[72:73], v[72:73], 1.0 op_sel_hi:[1,0]
	s_waitcnt lgkmcnt(1)
	v_mul_f32_e32 v64, 0x3d372713, v56
	v_pk_mul_f32 v[72:73], v[76:77], v[72:73]
	v_mul_f32_e32 v64, v56, v64
	v_fma_f32 v64, v56, v64, v56
	v_mul_f32_e32 v64, 0x3f4c422a, v64
	v_add_f32_e32 v64, v64, v64
	v_mul_f32_e32 v64, 0x3fb8aa3b, v64
	v_exp_f32_e32 v70, v64
	v_mul_f32_e32 v64, 0x3d372713, v57
	v_mul_f32_e32 v64, v57, v64
	v_fma_f32 v64, v57, v64, v57
	v_mul_f32_e32 v64, 0x3f4c422a, v64
	v_rcp_f32_e32 v77, v79
	s_nop 0
	v_add_f32_e32 v77, v77, v77
	v_add_f32_e32 v64, v64, v64
	v_mul_f32_e32 v64, 0x3fb8aa3b, v64
	v_exp_f32_e32 v68, v64
	v_mul_f32_e32 v64, 0x3d372713, v58
	v_mul_f32_e32 v64, v58, v64
	v_fma_f32 v64, v58, v64, v58
	v_mul_f32_e32 v64, 0x3f4c422a, v64
	v_add_f32_e32 v64, v64, v64
	v_rcp_f32_e32 v76, v78
	s_nop 0
	v_add_f32_e32 v76, v76, v76
	v_mul_f32_e32 v64, 0x3fb8aa3b, v64
	v_pk_add_f32 v[76:77], v[76:77], 1.0 op_sel_hi:[1,0] neg_lo:[1,0] neg_hi:[1,0]
	v_mov_b32_e32 v62, v61
	v_exp_f32_e32 v71, v64
	v_pk_mul_f32 v[60:61], v[62:63], 0.5 op_sel_hi:[1,0]
	v_pk_add_f32 v[62:63], v[76:77], 1.0 op_sel_hi:[1,0]
	v_pk_mul_f32 v[60:61], v[60:61], v[62:63]
	v_pk_add_f32 v[70:71], v[70:71], 1.0 op_sel_hi:[1,0]
	v_cvt_pk_bf16_f32 v62, v72, v60
	v_cvt_pk_bf16_f32 v60, v82, v74
	v_cvt_pk_bf16_f32 v63, v73, v61
	v_cvt_pk_bf16_f32 v61, v83, v75
	v_mul_f32_e32 v64, 0x3d372713, v59
	v_mul_f32_e32 v64, v59, v64
	v_fma_f32 v64, v59, v64, v59
	v_mul_f32_e32 v64, 0x3f4c422a, v64
	v_add_f32_e32 v64, v64, v64
	v_rcp_f32_e32 v71, v71
	s_nop 0
	v_add_f32_e32 v71, v71, v71
	v_mul_f32_e32 v64, 0x3fb8aa3b, v64
	v_exp_f32_e32 v69, v64
	s_nop 0
	v_pk_add_f32 v[68:69], v[68:69], 1.0 op_sel_hi:[1,0]
	v_rcp_f32_e32 v70, v70
	s_nop 0
	v_add_f32_e32 v70, v70, v70
	v_mov_b32_e32 v72, v56
	v_mov_b32_e32 v73, v58
	v_pk_add_f32 v[70:71], v[70:71], 1.0 op_sel_hi:[1,0] neg_lo:[1,0] neg_hi:[1,0]
	v_pk_mul_f32 v[72:73], v[72:73], 0.5 op_sel_hi:[1,0]
	v_pk_add_f32 v[70:71], v[70:71], 1.0 op_sel_hi:[1,0]
	s_waitcnt lgkmcnt(0)
; DI unsigned pack2(float a, float b) { return (unsigned)f2bf(a) | ((unsigned)f2bf(b) << 16); }
; DI float geluf(float x) { float z = 0.7978845608028654f * (x + 0.044715f * x * x * x); float t = 1.f - 2.f / (1.f + __expf(2.f * z)); return 0.5f * x * (1.f + t); }
;     ...
; #pragma unroll
;   for (int n = 0; n < 4; ++n)
; #pragma unroll
;     for (int j = 0; j < 4; ++j) stg[(fq * 4 + j) * 68 + n * 16 + fr] = am[n][j];
;   asm volatile("s_waitcnt lgkmcnt(0)" ::: "memory");
;   const float* rp = stg + (lane >> 2) * 68 + (lane & 3) * 16;
; #pragma unroll
;   for (int i = 0; i < 4; ++i) { f32x4 t = *(const f32x4*)(rp + i * 4); v[4 * i] = t[0]; v[4 * i + 1] = t[1]; v[4 * i + 2] = t[2]; v[4 * i + 3] = t[3]; }
; DI void store16_bf(bft* dst, const float (&v)[16]) {
;   u32x4 o0 = {pack2(v[0], v[1]), pack2(v[2], v[3]), pack2(v[4], v[5]), pack2(v[6], v[7])}, o1 = {pack2(v[8], v[9]), pack2(v[10], v[11]), pack2(v[12], v[13]), pack2(v[14], v[15])};
;   *(u32x4*)dst = o0; *(u32x4*)(dst + 8) = o1;
; DI void phase_s5step3(const Params& p) {
;     ...
;       for (int i = 0; i < 16; ++i) v[i] = geluf(v[i]);
;       store16_bf(ys + ((size_t)row * 32 + (col >> 4)) * LDP + g * 16, v);
	v_mul_f32_e32 v64, 0x3d372713, v52
	v_pk_mul_f32 v[70:71], v[72:73], v[70:71]
	v_mul_f32_e32 v65, 0x3d372713, v54
	v_mul_f32_e32 v64, v52, v64
	v_mul_f32_e32 v65, v54, v65
	v_fma_f32 v64, v52, v64, v52
	v_fma_f32 v65, v54, v65, v54
	v_mul_f32_e32 v64, 0x3f4c422a, v64
	v_mul_f32_e32 v65, 0x3f4c422a, v65
	v_rcp_f32_e32 v69, v69
	s_nop 0
	v_add_f32_e32 v69, v69, v69
	v_add_f32_e32 v64, v64, v64
	v_add_f32_e32 v65, v65, v65
	v_mul_f32_e32 v64, 0x3fb8aa3b, v64
	v_mul_f32_e32 v65, 0x3fb8aa3b, v65
	v_exp_f32_e32 v66, v64
	v_exp_f32_e32 v67, v65
	v_rcp_f32_e32 v68, v68
	s_nop 0
	v_add_f32_e32 v68, v68, v68
	v_mov_b32_e32 v58, v57
	v_pk_add_f32 v[56:57], v[66:67], 1.0 op_sel_hi:[1,0]
	v_pk_add_f32 v[68:69], v[68:69], 1.0 op_sel_hi:[1,0] neg_lo:[1,0] neg_hi:[1,0]
	v_pk_mul_f32 v[58:59], v[58:59], 0.5 op_sel_hi:[1,0]
	v_pk_add_f32 v[66:67], v[68:69], 1.0 op_sel_hi:[1,0]
	v_mul_f32_e32 v64, 0x3d372713, v53
	v_pk_mul_f32 v[58:59], v[58:59], v[66:67]
	v_mul_f32_e32 v65, 0x3d372713, v55
	v_mul_f32_e32 v64, v53, v64
	v_mul_f32_e32 v65, v55, v65
	v_fma_f32 v64, v53, v64, v53
	v_fma_f32 v65, v55, v65, v55
	v_mul_f32_e32 v64, 0x3f4c422a, v64
	v_mul_f32_e32 v65, 0x3f4c422a, v65
	v_add_f32_e32 v64, v64, v64
	v_add_f32_e32 v65, v65, v65
	v_rcp_f32_e32 v57, v57
	s_nop 0
	v_add_f32_e32 v57, v57, v57
	v_mul_f32_e32 v64, 0x3fb8aa3b, v64
	v_mul_f32_e32 v65, 0x3fb8aa3b, v65
	v_exp_f32_e32 v64, v64
	v_exp_f32_e32 v65, v65
	s_nop 0
	v_pk_add_f32 v[64:65], v[64:65], 1.0 op_sel_hi:[1,0]
	v_rcp_f32_e32 v56, v56
	s_nop 0
	v_add_f32_e32 v56, v56, v56
	v_mov_b32_e32 v66, v52
	v_div_scale_f32 v52, s[8:9], v65, v65, 2.0
	v_mov_b32_e32 v67, v54
	v_rcp_f32_e32 v54, v52
	v_pk_add_f32 v[56:57], v[56:57], 1.0 op_sel_hi:[1,0] neg_lo:[1,0] neg_hi:[1,0]
	v_pk_mul_f32 v[66:67], v[66:67], 0.5 op_sel_hi:[1,0]
	v_pk_add_f32 v[56:57], v[56:57], 1.0 op_sel_hi:[1,0]
	s_nop 0
	v_pk_mul_f32 v[56:57], v[66:67], v[56:57]
	v_fma_f32 v66, -v52, v54, 1.0
	v_fmac_f32_e32 v54, v66, v54
	v_div_scale_f32 v66, vcc, 2.0, v65, 2.0
	v_mul_f32_e32 v67, v66, v54
	v_fma_f32 v68, -v52, v67, v66
	v_fmac_f32_e32 v67, v68, v54
	v_fma_f32 v52, -v52, v67, v66
	v_div_scale_f32 v66, s[8:9], v64, v64, 2.0
	v_rcp_f32_e32 v68, v66
	v_div_fmas_f32 v52, v52, v54, v67
	v_div_fixup_f32 v65, v52, v65, 2.0
	v_fma_f32 v52, -v66, v68, 1.0
	v_fmac_f32_e32 v68, v52, v68
	v_div_scale_f32 v52, vcc, 2.0, v64, 2.0
	v_mul_f32_e32 v54, v52, v68
	v_fma_f32 v67, -v66, v54, v52
	v_fmac_f32_e32 v54, v67, v68
	v_fma_f32 v52, -v66, v54, v52
	v_div_fmas_f32 v52, v52, v68, v54
	v_div_fixup_f32 v64, v52, v64, 2.0
	v_pk_add_f32 v[64:65], v[64:65], 1.0 op_sel_hi:[1,0] neg_lo:[1,0] neg_hi:[1,0]
	v_mov_b32_e32 v54, v53
	v_pk_mul_f32 v[52:53], v[54:55], 0.5 op_sel_hi:[1,0]
	v_pk_add_f32 v[54:55], v[64:65], 1.0 op_sel_hi:[1,0]
	v_pk_mul_f32 v[52:53], v[52:53], v[54:55]
	v_cvt_pk_bf16_f32 v55, v57, v53
	v_cvt_pk_bf16_f32 v54, v56, v52
	v_cvt_pk_bf16_f32 v53, v71, v59
	v_cvt_pk_bf16_f32 v52, v70, v58
	global_store_dwordx4 v[2:3], v[60:63], off
	global_store_dwordx4 v[2:3], v[52:55], off offset:16
	ds_write2_b32 v140, v48, v44 offset1:16
	ds_write2_b32 v140, v49, v45 offset0:68 offset1:84
	ds_write2_b32 v140, v50, v46 offset0:136 offset1:152
	ds_write2_b32 v140, v51, v47 offset0:204 offset1:220
	ds_write2_b32 v140, v40, v36 offset0:32 offset1:48
	ds_write2_b32 v140, v41, v37 offset0:100 offset1:116
	ds_write2_b32 v140, v42, v38 offset0:168 offset1:184
	ds_write2_b32 v140, v43, v39 offset0:236 offset1:252
	s_waitcnt lgkmcnt(0)
	ds_read_b128 v[56:59], v141
	ds_read_b128 v[44:47], v141 offset:16
	ds_read_b128 v[40:43], v141 offset:32
	ds_read_b128 v[36:39], v141 offset:48
	v_or_b32_e32 v66, 0x50, v132
	s_waitcnt lgkmcnt(3)
	v_mul_f32_e32 v3, 0x3d372713, v57
	v_mul_f32_e32 v3, v57, v3
	v_fma_f32 v3, v57, v3, v57
	v_mul_f32_e32 v3, 0x3f4c422a, v3
	v_add_f32_e32 v3, v3, v3
	v_mul_f32_e32 v3, 0x3fb8aa3b, v3
	v_mul_f32_e32 v2, 0x3d372713, v56
	v_exp_f32_e32 v60, v3
	v_mul_f32_e32 v3, 0x3d372713, v58
	v_mul_f32_e32 v2, v56, v2
	v_mul_f32_e32 v3, v58, v3
	v_fma_f32 v2, v56, v2, v56
	v_fma_f32 v3, v58, v3, v58
	v_mul_f32_e32 v2, 0x3f4c422a, v2
	v_mul_f32_e32 v3, 0x3f4c422a, v3
	v_add_f32_e32 v2, v2, v2
	v_add_f32_e32 v3, v3, v3
	v_mul_f32_e32 v2, 0x3fb8aa3b, v2
	v_mul_f32_e32 v3, 0x3fb8aa3b, v3
	v_exp_f32_e32 v2, v2
	v_exp_f32_e32 v3, v3
	v_ashrrev_i32_e32 v67, 31, v66
	v_lshlrev_b64 v[66:67], 5, v[66:67]
	v_or_b32_e32 v66, v66, v0
	v_pk_add_f32 v[68:69], v[2:3], 1.0 op_sel_hi:[1,0]
	v_mad_u64_u32 v[2:3], s[8:9], v66, s36, v[128:129]
	v_mad_i32_i24 v3, v67, s36, v3
	v_mul_f32_e32 v48, 0x3d372713, v59
	v_mul_f32_e32 v48, v59, v48
	v_fma_f32 v48, v59, v48, v59
	v_mul_f32_e32 v48, 0x3f4c422a, v48
	v_add_f32_e32 v48, v48, v48
	v_rcp_f32_e32 v67, v69
	s_nop 0
	v_add_f32_e32 v67, v67, v67
	v_mul_f32_e32 v48, 0x3fb8aa3b, v48
	v_exp_f32_e32 v61, v48
	s_nop 0
	v_pk_add_f32 v[60:61], v[60:61], 1.0 op_sel_hi:[1,0]
	s_waitcnt lgkmcnt(2)
; DI unsigned pack2(float a, float b) { return (unsigned)f2bf(a) | ((unsigned)f2bf(b) << 16); }
; DI float geluf(float x) { float z = 0.7978845608028654f * (x + 0.044715f * x * x * x); float t = 1.f - 2.f / (1.f + __expf(2.f * z)); return 0.5f * x * (1.f + t); }
; DI void store16_bf(bft* dst, const float (&v)[16]) {
;   u32x4 o0 = {pack2(v[0], v[1]), pack2(v[2], v[3]), pack2(v[4], v[5]), pack2(v[6], v[7])}, o1 = {pack2(v[8], v[9]), pack2(v[10], v[11]), pack2(v[12], v[13]), pack2(v[14], v[15])};
;   *(u32x4*)dst = o0; *(u32x4*)(dst + 8) = o1;
; DI void phase_s5step3(const Params& p) {
;     ...
;       for (int i = 0; i < 16; ++i) v[i] = geluf(v[i]);
	v_mul_f32_e32 v48, 0x3d372713, v44
	v_rcp_f32_e32 v66, v68
	s_nop 0
	v_add_f32_e32 v66, v66, v66
	v_mov_b32_e32 v68, v56
	v_mul_f32_e32 v48, v44, v48
	v_mov_b32_e32 v69, v58
	v_fma_f32 v48, v44, v48, v44
	v_mul_f32_e32 v48, 0x3f4c422a, v48
	v_pk_add_f32 v[66:67], v[66:67], 1.0 op_sel_hi:[1,0] neg_lo:[1,0] neg_hi:[1,0]
	v_add_f32_e32 v48, v48, v48
	v_pk_mul_f32 v[68:69], v[68:69], 0.5 op_sel_hi:[1,0]
	v_pk_add_f32 v[66:67], v[66:67], 1.0 op_sel_hi:[1,0]
	v_mul_f32_e32 v48, 0x3fb8aa3b, v48
	v_pk_mul_f32 v[66:67], v[68:69], v[66:67]
	v_exp_f32_e32 v62, v48
	v_mul_f32_e32 v48, 0x3d372713, v45
	v_mul_f32_e32 v48, v45, v48
	v_fma_f32 v48, v45, v48, v45
	v_mul_f32_e32 v48, 0x3f4c422a, v48
	v_add_f32_e32 v48, v48, v48
	v_mul_f32_e32 v48, 0x3fb8aa3b, v48
	v_exp_f32_e32 v64, v48
	v_mul_f32_e32 v48, 0x3d372713, v46
	v_mul_f32_e32 v48, v46, v48
	v_fma_f32 v48, v46, v48, v46
	v_mul_f32_e32 v48, 0x3f4c422a, v48
	v_rcp_f32_e32 v61, v61
	s_nop 0
	v_add_f32_e32 v61, v61, v61
	v_add_f32_e32 v48, v48, v48
	v_mul_f32_e32 v48, 0x3fb8aa3b, v48
	v_exp_f32_e32 v63, v48
	v_rcp_f32_e32 v60, v60
	s_nop 0
	v_add_f32_e32 v60, v60, v60
	v_mov_b32_e32 v58, v57
	v_pk_add_f32 v[56:57], v[62:63], 1.0 op_sel_hi:[1,0]
	v_pk_add_f32 v[60:61], v[60:61], 1.0 op_sel_hi:[1,0] neg_lo:[1,0] neg_hi:[1,0]
	v_pk_mul_f32 v[58:59], v[58:59], 0.5 op_sel_hi:[1,0]
	v_pk_add_f32 v[60:61], v[60:61], 1.0 op_sel_hi:[1,0]
	v_mul_f32_e32 v48, 0x3d372713, v47
	v_pk_mul_f32 v[58:59], v[58:59], v[60:61]
	v_mul_f32_e32 v48, v47, v48
	v_fma_f32 v48, v47, v48, v47
	v_mul_f32_e32 v48, 0x3f4c422a, v48
	v_add_f32_e32 v48, v48, v48
	v_rcp_f32_e32 v57, v57
	s_nop 0
	v_add_f32_e32 v57, v57, v57
	v_mul_f32_e32 v48, 0x3fb8aa3b, v48
	v_exp_f32_e32 v65, v48
	s_nop 0
	v_pk_add_f32 v[62:63], v[64:65], 1.0 op_sel_hi:[1,0]
	v_rcp_f32_e32 v56, v56
	s_nop 0
	v_add_f32_e32 v56, v56, v56
	v_mov_b32_e32 v60, v44
	v_mov_b32_e32 v61, v46
	v_pk_add_f32 v[56:57], v[56:57], 1.0 op_sel_hi:[1,0] neg_lo:[1,0] neg_hi:[1,0]
	v_pk_mul_f32 v[60:61], v[60:61], 0.5 op_sel_hi:[1,0]
	v_pk_add_f32 v[56:57], v[56:57], 1.0 op_sel_hi:[1,0]
	s_waitcnt lgkmcnt(1)
	v_mul_f32_e32 v48, 0x3d372713, v40
	v_pk_mul_f32 v[56:57], v[60:61], v[56:57]
	v_mul_f32_e32 v48, v40, v48
	v_fma_f32 v48, v40, v48, v40
	v_mul_f32_e32 v48, 0x3f4c422a, v48
	v_add_f32_e32 v48, v48, v48
	v_mul_f32_e32 v48, 0x3fb8aa3b, v48
	v_exp_f32_e32 v54, v48
	v_mul_f32_e32 v48, 0x3d372713, v41
	v_mul_f32_e32 v48, v41, v48
	v_fma_f32 v48, v41, v48, v41
	v_mul_f32_e32 v48, 0x3f4c422a, v48
	v_rcp_f32_e32 v61, v63
	s_nop 0
	v_add_f32_e32 v61, v61, v61
	v_add_f32_e32 v48, v48, v48
	v_mul_f32_e32 v48, 0x3fb8aa3b, v48
	v_exp_f32_e32 v52, v48
	v_mul_f32_e32 v48, 0x3d372713, v42
	v_mul_f32_e32 v48, v42, v48
	v_fma_f32 v48, v42, v48, v42
	v_mul_f32_e32 v48, 0x3f4c422a, v48
	v_add_f32_e32 v48, v48, v48
	v_rcp_f32_e32 v60, v62
	s_nop 0
	v_add_f32_e32 v60, v60, v60
	v_mul_f32_e32 v48, 0x3fb8aa3b, v48
	v_pk_add_f32 v[60:61], v[60:61], 1.0 op_sel_hi:[1,0] neg_lo:[1,0] neg_hi:[1,0]
	v_mov_b32_e32 v46, v45
	v_exp_f32_e32 v55, v48
	v_pk_mul_f32 v[44:45], v[46:47], 0.5 op_sel_hi:[1,0]
	v_pk_add_f32 v[46:47], v[60:61], 1.0 op_sel_hi:[1,0]
	v_pk_mul_f32 v[44:45], v[44:45], v[46:47]
	v_pk_add_f32 v[54:55], v[54:55], 1.0 op_sel_hi:[1,0]
	v_cvt_pk_bf16_f32 v46, v56, v44
	v_cvt_pk_bf16_f32 v44, v66, v58
	v_cvt_pk_bf16_f32 v47, v57, v45
	v_cvt_pk_bf16_f32 v45, v67, v59
	v_mul_f32_e32 v48, 0x3d372713, v43
	v_mul_f32_e32 v48, v43, v48
	v_fma_f32 v48, v43, v48, v43
	v_mul_f32_e32 v48, 0x3f4c422a, v48
	v_add_f32_e32 v48, v48, v48
	v_rcp_f32_e32 v55, v55
	s_nop 0
	v_add_f32_e32 v55, v55, v55
	v_mul_f32_e32 v48, 0x3fb8aa3b, v48
	v_exp_f32_e32 v53, v48
	s_nop 0
	v_pk_add_f32 v[52:53], v[52:53], 1.0 op_sel_hi:[1,0]
	v_rcp_f32_e32 v54, v54
	s_nop 0
	v_add_f32_e32 v54, v54, v54
	v_mov_b32_e32 v56, v40
	v_mov_b32_e32 v57, v42
	v_pk_add_f32 v[54:55], v[54:55], 1.0 op_sel_hi:[1,0] neg_lo:[1,0] neg_hi:[1,0]
	v_pk_mul_f32 v[56:57], v[56:57], 0.5 op_sel_hi:[1,0]
	v_pk_add_f32 v[54:55], v[54:55], 1.0 op_sel_hi:[1,0]
	s_waitcnt lgkmcnt(0)
	v_mul_f32_e32 v48, 0x3d372713, v36
	v_pk_mul_f32 v[54:55], v[56:57], v[54:55]
	v_mul_f32_e32 v49, 0x3d372713, v38
	v_mul_f32_e32 v48, v36, v48
	v_mul_f32_e32 v49, v38, v49
	v_fma_f32 v48, v36, v48, v36
	v_fma_f32 v49, v38, v49, v38
	v_mul_f32_e32 v48, 0x3f4c422a, v48
	v_mul_f32_e32 v49, 0x3f4c422a, v49
	v_rcp_f32_e32 v53, v53
	s_nop 0
	v_add_f32_e32 v53, v53, v53
	v_add_f32_e32 v48, v48, v48
	v_add_f32_e32 v49, v49, v49
	v_mul_f32_e32 v48, 0x3fb8aa3b, v48
	v_mul_f32_e32 v49, 0x3fb8aa3b, v49
	v_exp_f32_e32 v50, v48
	v_exp_f32_e32 v51, v49
	v_rcp_f32_e32 v52, v52
	s_nop 0
	v_add_f32_e32 v52, v52, v52
	v_mov_b32_e32 v42, v41
	v_pk_add_f32 v[40:41], v[50:51], 1.0 op_sel_hi:[1,0]
	v_pk_add_f32 v[52:53], v[52:53], 1.0 op_sel_hi:[1,0] neg_lo:[1,0] neg_hi:[1,0]
	v_pk_mul_f32 v[42:43], v[42:43], 0.5 op_sel_hi:[1,0]
	v_pk_add_f32 v[50:51], v[52:53], 1.0 op_sel_hi:[1,0]
	v_mul_f32_e32 v48, 0x3d372713, v37
	v_pk_mul_f32 v[42:43], v[42:43], v[50:51]
	v_mul_f32_e32 v49, 0x3d372713, v39
	v_mul_f32_e32 v48, v37, v48
	v_mul_f32_e32 v49, v39, v49
	v_fma_f32 v48, v37, v48, v37
	v_fma_f32 v49, v39, v49, v39
	v_mul_f32_e32 v48, 0x3f4c422a, v48
	v_mul_f32_e32 v49, 0x3f4c422a, v49
	v_add_f32_e32 v48, v48, v48
	v_add_f32_e32 v49, v49, v49
	v_rcp_f32_e32 v41, v41
	s_nop 0
	v_add_f32_e32 v41, v41, v41
	v_mul_f32_e32 v48, 0x3fb8aa3b, v48
	v_mul_f32_e32 v49, 0x3fb8aa3b, v49
	v_exp_f32_e32 v48, v48
	v_exp_f32_e32 v49, v49
	s_nop 0
	v_pk_add_f32 v[48:49], v[48:49], 1.0 op_sel_hi:[1,0]
	v_rcp_f32_e32 v40, v40
	s_nop 0
	v_add_f32_e32 v40, v40, v40
	v_mov_b32_e32 v50, v36
	v_div_scale_f32 v36, s[8:9], v49, v49, 2.0
; DI unsigned pack2(float a, float b) { return (unsigned)f2bf(a) | ((unsigned)f2bf(b) << 16); }
; DI float geluf(float x) { float z = 0.7978845608028654f * (x + 0.044715f * x * x * x); float t = 1.f - 2.f / (1.f + __expf(2.f * z)); return 0.5f * x * (1.f + t); }
;     ...
; #pragma unroll
;   for (int n = 0; n < 4; ++n)
; #pragma unroll
;     for (int j = 0; j < 4; ++j) stg[(fq * 4 + j) * 68 + n * 16 + fr] = am[n][j];
;   asm volatile("s_waitcnt lgkmcnt(0)" ::: "memory");
;   const float* rp = stg + (lane >> 2) * 68 + (lane & 3) * 16;
; #pragma unroll
;   for (int i = 0; i < 4; ++i) { f32x4 t = *(const f32x4*)(rp + i * 4); v[4 * i] = t[0]; v[4 * i + 1] = t[1]; v[4 * i + 2] = t[2]; v[4 * i + 3] = t[3]; }
; DI void store16_bf(bft* dst, const float (&v)[16]) {
;   u32x4 o0 = {pack2(v[0], v[1]), pack2(v[2], v[3]), pack2(v[4], v[5]), pack2(v[6], v[7])}, o1 = {pack2(v[8], v[9]), pack2(v[10], v[11]), pack2(v[12], v[13]), pack2(v[14], v[15])};
;   *(u32x4*)dst = o0; *(u32x4*)(dst + 8) = o1;
; DI void phase_s5step3(const Params& p) {
;     ...
;       for (int i = 0; i < 16; ++i) v[i] = geluf(v[i]);
;       store16_bf(ys + ((size_t)row * 32 + (col >> 4)) * LDP + g * 16, v);
	v_mov_b32_e32 v51, v38
	v_rcp_f32_e32 v38, v36
	v_pk_add_f32 v[40:41], v[40:41], 1.0 op_sel_hi:[1,0] neg_lo:[1,0] neg_hi:[1,0]
	v_pk_mul_f32 v[50:51], v[50:51], 0.5 op_sel_hi:[1,0]
	v_pk_add_f32 v[40:41], v[40:41], 1.0 op_sel_hi:[1,0]
	s_nop 0
	v_pk_mul_f32 v[40:41], v[50:51], v[40:41]
	v_fma_f32 v50, -v36, v38, 1.0
	v_fmac_f32_e32 v38, v50, v38
	v_div_scale_f32 v50, vcc, 2.0, v49, 2.0
	v_mul_f32_e32 v51, v50, v38
	v_fma_f32 v52, -v36, v51, v50
	v_fmac_f32_e32 v51, v52, v38
	v_fma_f32 v36, -v36, v51, v50
	v_div_scale_f32 v50, s[8:9], v48, v48, 2.0
	v_rcp_f32_e32 v52, v50
	v_div_fmas_f32 v36, v36, v38, v51
	v_div_fixup_f32 v49, v36, v49, 2.0
	v_fma_f32 v36, -v50, v52, 1.0
	v_fmac_f32_e32 v52, v36, v52
	v_div_scale_f32 v36, vcc, 2.0, v48, 2.0
	v_mul_f32_e32 v38, v36, v52
	v_fma_f32 v51, -v50, v38, v36
	v_fmac_f32_e32 v38, v51, v52
	v_fma_f32 v36, -v50, v38, v36
	v_div_fmas_f32 v36, v36, v52, v38
	v_div_fixup_f32 v48, v36, v48, 2.0
	v_pk_add_f32 v[48:49], v[48:49], 1.0 op_sel_hi:[1,0] neg_lo:[1,0] neg_hi:[1,0]
	v_mov_b32_e32 v38, v37
	v_pk_mul_f32 v[36:37], v[38:39], 0.5 op_sel_hi:[1,0]
	v_pk_add_f32 v[38:39], v[48:49], 1.0 op_sel_hi:[1,0]
	v_pk_mul_f32 v[36:37], v[36:37], v[38:39]
	v_cvt_pk_bf16_f32 v39, v41, v37
	v_cvt_pk_bf16_f32 v38, v40, v36
	v_cvt_pk_bf16_f32 v37, v55, v43
	v_cvt_pk_bf16_f32 v36, v54, v42
	global_store_dwordx4 v[2:3], v[44:47], off
	global_store_dwordx4 v[2:3], v[36:39], off offset:16
	ds_write2_b32 v140, v32, v28 offset1:16
	ds_write2_b32 v140, v33, v29 offset0:68 offset1:84
	ds_write2_b32 v140, v34, v30 offset0:136 offset1:152
	ds_write2_b32 v140, v35, v31 offset0:204 offset1:220
	ds_write2_b32 v140, v24, v20 offset0:32 offset1:48
	ds_write2_b32 v140, v25, v21 offset0:100 offset1:116
	ds_write2_b32 v140, v26, v22 offset0:168 offset1:184
	ds_write2_b32 v140, v27, v23 offset0:236 offset1:252
	s_waitcnt lgkmcnt(0)
	ds_read_b128 v[40:43], v141
	ds_read_b128 v[28:31], v141 offset:16
	ds_read_b128 v[24:27], v141 offset:32
	ds_read_b128 v[20:23], v141 offset:48
	v_or_b32_e32 v50, 0x60, v132
	s_waitcnt lgkmcnt(3)
	v_mul_f32_e32 v3, 0x3d372713, v41
	v_mul_f32_e32 v3, v41, v3
	v_fma_f32 v3, v41, v3, v41
	v_mul_f32_e32 v3, 0x3f4c422a, v3
	v_add_f32_e32 v3, v3, v3
	v_mul_f32_e32 v3, 0x3fb8aa3b, v3
	v_mul_f32_e32 v2, 0x3d372713, v40
	v_exp_f32_e32 v44, v3
	v_mul_f32_e32 v3, 0x3d372713, v42
	v_mul_f32_e32 v2, v40, v2
	v_mul_f32_e32 v3, v42, v3
	v_fma_f32 v2, v40, v2, v40
	v_fma_f32 v3, v42, v3, v42
	v_mul_f32_e32 v2, 0x3f4c422a, v2
	v_mul_f32_e32 v3, 0x3f4c422a, v3
	v_add_f32_e32 v2, v2, v2
	v_add_f32_e32 v3, v3, v3
	v_mul_f32_e32 v2, 0x3fb8aa3b, v2
	v_mul_f32_e32 v3, 0x3fb8aa3b, v3
	v_exp_f32_e32 v2, v2
	v_exp_f32_e32 v3, v3
	v_ashrrev_i32_e32 v51, 31, v50
	v_lshlrev_b64 v[50:51], 5, v[50:51]
	v_or_b32_e32 v50, v50, v0
	v_pk_add_f32 v[52:53], v[2:3], 1.0 op_sel_hi:[1,0]
	v_mad_u64_u32 v[2:3], s[8:9], v50, s36, v[128:129]
	v_mad_i32_i24 v3, v51, s36, v3
	v_mul_f32_e32 v32, 0x3d372713, v43
	v_mul_f32_e32 v32, v43, v32
	v_fma_f32 v32, v43, v32, v43
	v_mul_f32_e32 v32, 0x3f4c422a, v32
	v_add_f32_e32 v32, v32, v32
	v_rcp_f32_e32 v51, v53
	s_nop 0
	v_add_f32_e32 v51, v51, v51
	v_mul_f32_e32 v32, 0x3fb8aa3b, v32
	v_exp_f32_e32 v45, v32
	s_nop 0
	v_pk_add_f32 v[44:45], v[44:45], 1.0 op_sel_hi:[1,0]
	s_waitcnt lgkmcnt(2)
	v_mul_f32_e32 v32, 0x3d372713, v28
	v_rcp_f32_e32 v50, v52
	s_nop 0
	v_add_f32_e32 v50, v50, v50
	v_mov_b32_e32 v52, v40
	v_mul_f32_e32 v32, v28, v32
	v_mov_b32_e32 v53, v42
	v_fma_f32 v32, v28, v32, v28
	v_mul_f32_e32 v32, 0x3f4c422a, v32
	v_pk_add_f32 v[50:51], v[50:51], 1.0 op_sel_hi:[1,0] neg_lo:[1,0] neg_hi:[1,0]
	v_add_f32_e32 v32, v32, v32
	v_pk_mul_f32 v[52:53], v[52:53], 0.5 op_sel_hi:[1,0]
	v_pk_add_f32 v[50:51], v[50:51], 1.0 op_sel_hi:[1,0]
	v_mul_f32_e32 v32, 0x3fb8aa3b, v32
	v_pk_mul_f32 v[50:51], v[52:53], v[50:51]
	v_exp_f32_e32 v46, v32
	v_mul_f32_e32 v32, 0x3d372713, v29
	v_mul_f32_e32 v32, v29, v32
	v_fma_f32 v32, v29, v32, v29
	v_mul_f32_e32 v32, 0x3f4c422a, v32
	v_add_f32_e32 v32, v32, v32
	v_mul_f32_e32 v32, 0x3fb8aa3b, v32
	v_exp_f32_e32 v48, v32
	v_mul_f32_e32 v32, 0x3d372713, v30
	v_mul_f32_e32 v32, v30, v32
	v_fma_f32 v32, v30, v32, v30
	v_mul_f32_e32 v32, 0x3f4c422a, v32
	v_rcp_f32_e32 v45, v45
	s_nop 0
	v_add_f32_e32 v45, v45, v45
	v_add_f32_e32 v32, v32, v32
	v_mul_f32_e32 v32, 0x3fb8aa3b, v32
	v_exp_f32_e32 v47, v32
	v_rcp_f32_e32 v44, v44
	s_nop 0
	v_add_f32_e32 v44, v44, v44
	v_mov_b32_e32 v42, v41
	v_pk_add_f32 v[40:41], v[46:47], 1.0 op_sel_hi:[1,0]
	v_pk_add_f32 v[44:45], v[44:45], 1.0 op_sel_hi:[1,0] neg_lo:[1,0] neg_hi:[1,0]
	v_pk_mul_f32 v[42:43], v[42:43], 0.5 op_sel_hi:[1,0]
	v_pk_add_f32 v[44:45], v[44:45], 1.0 op_sel_hi:[1,0]
	v_mul_f32_e32 v32, 0x3d372713, v31
	v_pk_mul_f32 v[42:43], v[42:43], v[44:45]
	v_mul_f32_e32 v32, v31, v32
	v_fma_f32 v32, v31, v32, v31
	v_mul_f32_e32 v32, 0x3f4c422a, v32
	v_add_f32_e32 v32, v32, v32
	v_rcp_f32_e32 v41, v41
	s_nop 0
	v_add_f32_e32 v41, v41, v41
	v_mul_f32_e32 v32, 0x3fb8aa3b, v32
	v_exp_f32_e32 v49, v32
	s_nop 0
	v_pk_add_f32 v[46:47], v[48:49], 1.0 op_sel_hi:[1,0]
	v_rcp_f32_e32 v40, v40
	s_nop 0
	v_add_f32_e32 v40, v40, v40
	v_mov_b32_e32 v44, v28
	v_mov_b32_e32 v45, v30
	v_pk_add_f32 v[40:41], v[40:41], 1.0 op_sel_hi:[1,0] neg_lo:[1,0] neg_hi:[1,0]
	v_pk_mul_f32 v[44:45], v[44:45], 0.5 op_sel_hi:[1,0]
	v_pk_add_f32 v[40:41], v[40:41], 1.0 op_sel_hi:[1,0]
	s_waitcnt lgkmcnt(1)
; DI unsigned pack2(float a, float b) { return (unsigned)f2bf(a) | ((unsigned)f2bf(b) << 16); }
; DI float geluf(float x) { float z = 0.7978845608028654f * (x + 0.044715f * x * x * x); float t = 1.f - 2.f / (1.f + __expf(2.f * z)); return 0.5f * x * (1.f + t); }
;     ...
; #pragma unroll
;   for (int n = 0; n < 4; ++n)
; #pragma unroll
;     for (int j = 0; j < 4; ++j) stg[(fq * 4 + j) * 68 + n * 16 + fr] = am[n][j];
;   asm volatile("s_waitcnt lgkmcnt(0)" ::: "memory");
;   const float* rp = stg + (lane >> 2) * 68 + (lane & 3) * 16;
; #pragma unroll
;   for (int i = 0; i < 4; ++i) { f32x4 t = *(const f32x4*)(rp + i * 4); v[4 * i] = t[0]; v[4 * i + 1] = t[1]; v[4 * i + 2] = t[2]; v[4 * i + 3] = t[3]; }
; DI void store16_bf(bft* dst, const float (&v)[16]) {
;   u32x4 o0 = {pack2(v[0], v[1]), pack2(v[2], v[3]), pack2(v[4], v[5]), pack2(v[6], v[7])}, o1 = {pack2(v[8], v[9]), pack2(v[10], v[11]), pack2(v[12], v[13]), pack2(v[14], v[15])};
;   *(u32x4*)dst = o0; *(u32x4*)(dst + 8) = o1;
; DI void phase_s5step3(const Params& p) {
;     ...
;       for (int i = 0; i < 16; ++i) v[i] = geluf(v[i]);
;       store16_bf(ys + ((size_t)row * 32 + (col >> 4)) * LDP + g * 16, v);
	v_mul_f32_e32 v32, 0x3d372713, v24
	v_pk_mul_f32 v[40:41], v[44:45], v[40:41]
	v_mul_f32_e32 v32, v24, v32
	v_fma_f32 v32, v24, v32, v24
	v_mul_f32_e32 v32, 0x3f4c422a, v32
	v_add_f32_e32 v32, v32, v32
	v_mul_f32_e32 v32, 0x3fb8aa3b, v32
	v_exp_f32_e32 v38, v32
	v_mul_f32_e32 v32, 0x3d372713, v25
	v_mul_f32_e32 v32, v25, v32
	v_fma_f32 v32, v25, v32, v25
	v_mul_f32_e32 v32, 0x3f4c422a, v32
	v_rcp_f32_e32 v45, v47
	s_nop 0
	v_add_f32_e32 v45, v45, v45
	v_add_f32_e32 v32, v32, v32
	v_mul_f32_e32 v32, 0x3fb8aa3b, v32
	v_exp_f32_e32 v36, v32
	v_mul_f32_e32 v32, 0x3d372713, v26
	v_mul_f32_e32 v32, v26, v32
	v_fma_f32 v32, v26, v32, v26
	v_mul_f32_e32 v32, 0x3f4c422a, v32
	v_add_f32_e32 v32, v32, v32
	v_rcp_f32_e32 v44, v46
	s_nop 0
	v_add_f32_e32 v44, v44, v44
	v_mul_f32_e32 v32, 0x3fb8aa3b, v32
	v_pk_add_f32 v[44:45], v[44:45], 1.0 op_sel_hi:[1,0] neg_lo:[1,0] neg_hi:[1,0]
	v_mov_b32_e32 v30, v29
	v_exp_f32_e32 v39, v32
	v_pk_mul_f32 v[28:29], v[30:31], 0.5 op_sel_hi:[1,0]
	v_pk_add_f32 v[30:31], v[44:45], 1.0 op_sel_hi:[1,0]
	v_pk_mul_f32 v[28:29], v[28:29], v[30:31]
	v_pk_add_f32 v[38:39], v[38:39], 1.0 op_sel_hi:[1,0]
	v_cvt_pk_bf16_f32 v30, v40, v28
	v_cvt_pk_bf16_f32 v28, v50, v42
	v_cvt_pk_bf16_f32 v31, v41, v29
	v_cvt_pk_bf16_f32 v29, v51, v43
	v_mul_f32_e32 v32, 0x3d372713, v27
	v_mul_f32_e32 v32, v27, v32
	v_fma_f32 v32, v27, v32, v27
	v_mul_f32_e32 v32, 0x3f4c422a, v32
	v_add_f32_e32 v32, v32, v32
	v_rcp_f32_e32 v39, v39
	s_nop 0
	v_add_f32_e32 v39, v39, v39
	v_mul_f32_e32 v32, 0x3fb8aa3b, v32
	v_exp_f32_e32 v37, v32
	s_nop 0
	v_pk_add_f32 v[36:37], v[36:37], 1.0 op_sel_hi:[1,0]
	v_rcp_f32_e32 v38, v38
	s_nop 0
	v_add_f32_e32 v38, v38, v38
	v_mov_b32_e32 v40, v24
	v_mov_b32_e32 v41, v26
	v_pk_add_f32 v[38:39], v[38:39], 1.0 op_sel_hi:[1,0] neg_lo:[1,0] neg_hi:[1,0]
	v_pk_mul_f32 v[40:41], v[40:41], 0.5 op_sel_hi:[1,0]
	v_pk_add_f32 v[38:39], v[38:39], 1.0 op_sel_hi:[1,0]
	s_waitcnt lgkmcnt(0)
	v_mul_f32_e32 v32, 0x3d372713, v20
	v_pk_mul_f32 v[38:39], v[40:41], v[38:39]
	v_mul_f32_e32 v33, 0x3d372713, v22
	v_mul_f32_e32 v32, v20, v32
	v_mul_f32_e32 v33, v22, v33
	v_fma_f32 v32, v20, v32, v20
	v_fma_f32 v33, v22, v33, v22
	v_mul_f32_e32 v32, 0x3f4c422a, v32
	v_mul_f32_e32 v33, 0x3f4c422a, v33
	v_rcp_f32_e32 v37, v37
	s_nop 0
	v_add_f32_e32 v37, v37, v37
	v_add_f32_e32 v32, v32, v32
	v_add_f32_e32 v33, v33, v33
	v_mul_f32_e32 v32, 0x3fb8aa3b, v32
	v_mul_f32_e32 v33, 0x3fb8aa3b, v33
	v_exp_f32_e32 v34, v32
	v_exp_f32_e32 v35, v33
	v_rcp_f32_e32 v36, v36
	s_nop 0
	v_add_f32_e32 v36, v36, v36
	v_mov_b32_e32 v26, v25
	v_pk_add_f32 v[24:25], v[34:35], 1.0 op_sel_hi:[1,0]
	v_pk_add_f32 v[36:37], v[36:37], 1.0 op_sel_hi:[1,0] neg_lo:[1,0] neg_hi:[1,0]
	v_pk_mul_f32 v[26:27], v[26:27], 0.5 op_sel_hi:[1,0]
	v_pk_add_f32 v[34:35], v[36:37], 1.0 op_sel_hi:[1,0]
	v_mul_f32_e32 v32, 0x3d372713, v21
	v_pk_mul_f32 v[26:27], v[26:27], v[34:35]
	v_mul_f32_e32 v33, 0x3d372713, v23
	v_mul_f32_e32 v32, v21, v32
	v_mul_f32_e32 v33, v23, v33
	v_fma_f32 v32, v21, v32, v21
	v_fma_f32 v33, v23, v33, v23
	v_mul_f32_e32 v32, 0x3f4c422a, v32
	v_mul_f32_e32 v33, 0x3f4c422a, v33
	v_add_f32_e32 v32, v32, v32
	v_add_f32_e32 v33, v33, v33
	v_rcp_f32_e32 v25, v25
	s_nop 0
	v_add_f32_e32 v25, v25, v25
	v_mul_f32_e32 v32, 0x3fb8aa3b, v32
	v_mul_f32_e32 v33, 0x3fb8aa3b, v33
	v_exp_f32_e32 v32, v32
	v_exp_f32_e32 v33, v33
	s_nop 0
	v_pk_add_f32 v[32:33], v[32:33], 1.0 op_sel_hi:[1,0]
	v_rcp_f32_e32 v24, v24
	s_nop 0
	v_add_f32_e32 v24, v24, v24
	v_mov_b32_e32 v34, v20
	v_div_scale_f32 v20, s[8:9], v33, v33, 2.0
	v_mov_b32_e32 v35, v22
	v_rcp_f32_e32 v22, v20
	v_pk_add_f32 v[24:25], v[24:25], 1.0 op_sel_hi:[1,0] neg_lo:[1,0] neg_hi:[1,0]
	v_pk_mul_f32 v[34:35], v[34:35], 0.5 op_sel_hi:[1,0]
	v_pk_add_f32 v[24:25], v[24:25], 1.0 op_sel_hi:[1,0]
	s_nop 0
	v_pk_mul_f32 v[24:25], v[34:35], v[24:25]
	v_fma_f32 v34, -v20, v22, 1.0
	v_fmac_f32_e32 v22, v34, v22
	v_div_scale_f32 v34, vcc, 2.0, v33, 2.0
	v_mul_f32_e32 v35, v34, v22
	v_fma_f32 v36, -v20, v35, v34
	v_fmac_f32_e32 v35, v36, v22
	v_fma_f32 v20, -v20, v35, v34
	v_div_scale_f32 v34, s[8:9], v32, v32, 2.0
	v_rcp_f32_e32 v36, v34
	v_div_fmas_f32 v20, v20, v22, v35
	v_div_fixup_f32 v33, v20, v33, 2.0
	v_fma_f32 v20, -v34, v36, 1.0
	v_fmac_f32_e32 v36, v20, v36
	v_div_scale_f32 v20, vcc, 2.0, v32, 2.0
	v_mul_f32_e32 v22, v20, v36
	v_fma_f32 v35, -v34, v22, v20
	v_fmac_f32_e32 v22, v35, v36
	v_fma_f32 v20, -v34, v22, v20
	v_div_fmas_f32 v20, v20, v36, v22
	v_div_fixup_f32 v32, v20, v32, 2.0
	v_pk_add_f32 v[32:33], v[32:33], 1.0 op_sel_hi:[1,0] neg_lo:[1,0] neg_hi:[1,0]
	v_mov_b32_e32 v22, v21
	v_pk_mul_f32 v[20:21], v[22:23], 0.5 op_sel_hi:[1,0]
	v_pk_add_f32 v[22:23], v[32:33], 1.0 op_sel_hi:[1,0]
	v_pk_mul_f32 v[20:21], v[20:21], v[22:23]
	v_cvt_pk_bf16_f32 v23, v25, v21
	v_cvt_pk_bf16_f32 v22, v24, v20
	v_cvt_pk_bf16_f32 v21, v39, v27
	v_cvt_pk_bf16_f32 v20, v38, v26
	global_store_dwordx4 v[2:3], v[28:31], off
	global_store_dwordx4 v[2:3], v[20:23], off offset:16
	ds_write2_b32 v140, v16, v12 offset1:16
	ds_write2_b32 v140, v17, v13 offset0:68 offset1:84
	ds_write2_b32 v140, v18, v14 offset0:136 offset1:152
	ds_write2_b32 v140, v19, v15 offset0:204 offset1:220
	ds_write2_b32 v140, v8, v4 offset0:32 offset1:48
	ds_write2_b32 v140, v9, v5 offset0:100 offset1:116
	ds_write2_b32 v140, v10, v6 offset0:168 offset1:184
	ds_write2_b32 v140, v11, v7 offset0:236 offset1:252
	s_waitcnt lgkmcnt(0)
	ds_read_b128 v[24:27], v141
	ds_read_b128 v[10:13], v141 offset:16
	ds_read_b128 v[6:9], v141 offset:32
	ds_read_b128 v[2:5], v141 offset:48
	v_or_b32_e32 v34, 0x70, v132
	s_waitcnt lgkmcnt(3)
; DI float geluf(float x) { float z = 0.7978845608028654f * (x + 0.044715f * x * x * x); float t = 1.f - 2.f / (1.f + __expf(2.f * z)); return 0.5f * x * (1.f + t); }
;     ...
; #pragma unroll
;   for (int n = 0; n < 4; ++n)
; #pragma unroll
;     for (int j = 0; j < 4; ++j) stg[(fq * 4 + j) * 68 + n * 16 + fr] = am[n][j];
;   asm volatile("s_waitcnt lgkmcnt(0)" ::: "memory");
;   const float* rp = stg + (lane >> 2) * 68 + (lane & 3) * 16;
; #pragma unroll
;   for (int i = 0; i < 4; ++i) { f32x4 t = *(const f32x4*)(rp + i * 4); v[4 * i] = t[0]; v[4 * i + 1] = t[1]; v[4 * i + 2] = t[2]; v[4 * i + 3] = t[3]; }
; DI void phase_s5step3(const Params& p) {
;     ...
;       for (int i = 0; i < 16; ++i) v[i] = geluf(v[i]);
	v_mul_f32_e32 v15, 0x3d372713, v25
	v_mul_f32_e32 v15, v25, v15
	v_fma_f32 v15, v25, v15, v25
	v_mul_f32_e32 v15, 0x3f4c422a, v15
	v_add_f32_e32 v15, v15, v15
	v_mul_f32_e32 v15, 0x3fb8aa3b, v15
	v_mul_f32_e32 v14, 0x3d372713, v24
	v_exp_f32_e32 v28, v15
	v_mul_f32_e32 v15, 0x3d372713, v26
	v_mul_f32_e32 v14, v24, v14
	v_mul_f32_e32 v15, v26, v15
	v_fma_f32 v14, v24, v14, v24
	v_fma_f32 v15, v26, v15, v26
	v_mul_f32_e32 v14, 0x3f4c422a, v14
	v_mul_f32_e32 v15, 0x3f4c422a, v15
	v_add_f32_e32 v14, v14, v14
	v_add_f32_e32 v15, v15, v15
	v_mul_f32_e32 v14, 0x3fb8aa3b, v14
	v_mul_f32_e32 v15, 0x3fb8aa3b, v15
	v_exp_f32_e32 v14, v14
	v_exp_f32_e32 v15, v15
	v_ashrrev_i32_e32 v35, 31, v34
	v_lshlrev_b64 v[34:35], 5, v[34:35]
	v_or_b32_e32 v0, v34, v0
	v_pk_add_f32 v[36:37], v[14:15], 1.0 op_sel_hi:[1,0]
	v_mad_u64_u32 v[14:15], s[8:9], v0, s36, v[128:129]
	v_mad_i32_i24 v15, v35, s36, v15
	v_mul_f32_e32 v16, 0x3d372713, v27
	v_mul_f32_e32 v16, v27, v16
	v_fma_f32 v16, v27, v16, v27
	v_mul_f32_e32 v16, 0x3f4c422a, v16
	v_add_f32_e32 v16, v16, v16
	v_rcp_f32_e32 v35, v37
	s_nop 0
	v_add_f32_e32 v35, v35, v35
	v_mul_f32_e32 v16, 0x3fb8aa3b, v16
	v_exp_f32_e32 v29, v16
	s_waitcnt lgkmcnt(2)
	v_mul_f32_e32 v16, 0x3d372713, v10
	v_pk_add_f32 v[28:29], v[28:29], 1.0 op_sel_hi:[1,0]
	v_mul_f32_e32 v16, v10, v16
	v_rcp_f32_e32 v34, v36
	s_nop 0
	v_add_f32_e32 v34, v34, v34
	v_fma_f32 v16, v10, v16, v10
	v_mov_b32_e32 v36, v24
	v_mul_f32_e32 v16, 0x3f4c422a, v16
	v_add_f32_e32 v16, v16, v16
	v_mul_f32_e32 v16, 0x3fb8aa3b, v16
	v_exp_f32_e32 v30, v16
	v_mul_f32_e32 v16, 0x3d372713, v11
	v_pk_add_f32 v[34:35], v[34:35], 1.0 op_sel_hi:[1,0] neg_lo:[1,0] neg_hi:[1,0]
	v_mov_b32_e32 v37, v26
	v_mul_f32_e32 v16, v11, v16
	v_pk_mul_f32 v[36:37], v[36:37], 0.5 op_sel_hi:[1,0]
	v_pk_add_f32 v[34:35], v[34:35], 1.0 op_sel_hi:[1,0]
	v_fma_f32 v16, v11, v16, v11
	v_pk_mul_f32 v[34:35], v[36:37], v[34:35]
	v_mul_f32_e32 v16, 0x3f4c422a, v16
	v_add_f32_e32 v16, v16, v16
	v_mul_f32_e32 v16, 0x3fb8aa3b, v16
	v_exp_f32_e32 v32, v16
	v_mul_f32_e32 v16, 0x3d372713, v12
	v_mul_f32_e32 v16, v12, v16
	v_fma_f32 v16, v12, v16, v12
	v_mul_f32_e32 v16, 0x3f4c422a, v16
	v_add_f32_e32 v16, v16, v16
	v_rcp_f32_e32 v29, v29
	s_nop 0
	v_add_f32_e32 v29, v29, v29
	v_mul_f32_e32 v16, 0x3fb8aa3b, v16
	v_exp_f32_e32 v31, v16
	v_mov_b32_e32 v26, v25
	v_pk_add_f32 v[24:25], v[30:31], 1.0 op_sel_hi:[1,0]
	v_rcp_f32_e32 v28, v28
	s_nop 0
	v_add_f32_e32 v28, v28, v28
	v_pk_add_f32 v[28:29], v[28:29], 1.0 op_sel_hi:[1,0] neg_lo:[1,0] neg_hi:[1,0]
	v_pk_mul_f32 v[26:27], v[26:27], 0.5 op_sel_hi:[1,0]
	v_pk_add_f32 v[28:29], v[28:29], 1.0 op_sel_hi:[1,0]
	v_mul_f32_e32 v16, 0x3d372713, v13
	v_pk_mul_f32 v[26:27], v[26:27], v[28:29]
	v_mul_f32_e32 v16, v13, v16
	v_fma_f32 v16, v13, v16, v13
	v_mul_f32_e32 v16, 0x3f4c422a, v16
	v_add_f32_e32 v16, v16, v16
	v_rcp_f32_e32 v25, v25
	s_nop 0
	v_add_f32_e32 v25, v25, v25
	v_mul_f32_e32 v16, 0x3fb8aa3b, v16
	v_exp_f32_e32 v33, v16
	s_nop 0
	v_pk_add_f32 v[30:31], v[32:33], 1.0 op_sel_hi:[1,0]
	v_rcp_f32_e32 v24, v24
	s_nop 0
	v_add_f32_e32 v24, v24, v24
	v_mov_b32_e32 v28, v10
	v_pk_add_f32 v[24:25], v[24:25], 1.0 op_sel_hi:[1,0] neg_lo:[1,0] neg_hi:[1,0]
	v_mov_b32_e32 v29, v12
	v_pk_mul_f32 v[28:29], v[28:29], 0.5 op_sel_hi:[1,0]
	v_pk_add_f32 v[24:25], v[24:25], 1.0 op_sel_hi:[1,0]
	s_waitcnt lgkmcnt(1)
; DI unsigned pack2(float a, float b) { return (unsigned)f2bf(a) | ((unsigned)f2bf(b) << 16); }
; DI float geluf(float x) { float z = 0.7978845608028654f * (x + 0.044715f * x * x * x); float t = 1.f - 2.f / (1.f + __expf(2.f * z)); return 0.5f * x * (1.f + t); }
; DI void store16_bf(bft* dst, const float (&v)[16]) {
;   u32x4 o0 = {pack2(v[0], v[1]), pack2(v[2], v[3]), pack2(v[4], v[5]), pack2(v[6], v[7])}, o1 = {pack2(v[8], v[9]), pack2(v[10], v[11]), pack2(v[12], v[13]), pack2(v[14], v[15])};
;   *(u32x4*)dst = o0; *(u32x4*)(dst + 8) = o1;
; DI void phase_s5step3(const Params& p) {
;     ...
;       for (int i = 0; i < 16; ++i) v[i] = geluf(v[i]);
;       store16_bf(ys + ((size_t)row * 32 + (col >> 4)) * LDP + g * 16, v);
	v_mul_f32_e32 v16, 0x3d372713, v6
	v_pk_mul_f32 v[24:25], v[28:29], v[24:25]
	v_mul_f32_e32 v16, v6, v16
	v_fma_f32 v16, v6, v16, v6
	v_mul_f32_e32 v16, 0x3f4c422a, v16
	v_add_f32_e32 v16, v16, v16
	v_mul_f32_e32 v16, 0x3fb8aa3b, v16
	v_exp_f32_e32 v22, v16
	v_mul_f32_e32 v16, 0x3d372713, v7
	v_mul_f32_e32 v16, v7, v16
	v_fma_f32 v16, v7, v16, v7
	v_rcp_f32_e32 v29, v31
	s_nop 0
	v_add_f32_e32 v29, v29, v29
	v_mul_f32_e32 v16, 0x3f4c422a, v16
	v_add_f32_e32 v16, v16, v16
	v_mul_f32_e32 v16, 0x3fb8aa3b, v16
	v_exp_f32_e32 v20, v16
	v_mul_f32_e32 v16, 0x3d372713, v8
	v_mul_f32_e32 v16, v8, v16
	v_fma_f32 v16, v8, v16, v8
	v_mul_f32_e32 v16, 0x3f4c422a, v16
	v_rcp_f32_e32 v28, v30
	s_nop 0
	v_add_f32_e32 v28, v28, v28
	v_add_f32_e32 v16, v16, v16
	v_pk_add_f32 v[28:29], v[28:29], 1.0 op_sel_hi:[1,0] neg_lo:[1,0] neg_hi:[1,0]
	v_mov_b32_e32 v12, v11
	v_mul_f32_e32 v16, 0x3fb8aa3b, v16
	v_pk_mul_f32 v[10:11], v[12:13], 0.5 op_sel_hi:[1,0]
	v_pk_add_f32 v[12:13], v[28:29], 1.0 op_sel_hi:[1,0]
	v_exp_f32_e32 v23, v16
	v_pk_mul_f32 v[10:11], v[10:11], v[12:13]
	v_bfe_u32 v0, v11, 16, 1
	v_bfe_u32 v12, v10, 16, 1
	v_add3_u32 v10, v10, v12, s37
	v_add3_u32 v0, v11, v0, s37
	v_bfe_u32 v13, v24, 16, 1
	v_bfe_u32 v28, v25, 16, 1
	v_add3_u32 v25, v25, v28, s37
	v_add3_u32 v13, v24, v13, s37
	v_lshrrev_b32_e32 v12, 16, v13
	v_lshrrev_b32_e32 v13, 16, v25
	v_pk_add_f32 v[22:23], v[22:23], 1.0 op_sel_hi:[1,0]
	v_and_or_b32 v13, v0, s30, v13
	v_and_or_b32 v12, v10, s30, v12
	v_cvt_pk_bf16_f32 v10, v34, v26
	v_cvt_pk_bf16_f32 v11, v35, v27
	v_mul_f32_e32 v16, 0x3d372713, v9
	v_mul_f32_e32 v16, v9, v16
	v_fma_f32 v16, v9, v16, v9
	v_mul_f32_e32 v16, 0x3f4c422a, v16
	v_add_f32_e32 v16, v16, v16
	v_rcp_f32_e32 v23, v23
	s_nop 0
	v_add_f32_e32 v23, v23, v23
	v_mul_f32_e32 v16, 0x3fb8aa3b, v16
	v_exp_f32_e32 v21, v16
	s_nop 0
	v_pk_add_f32 v[20:21], v[20:21], 1.0 op_sel_hi:[1,0]
	v_rcp_f32_e32 v22, v22
	s_nop 0
	v_add_f32_e32 v22, v22, v22
	v_mov_b32_e32 v24, v6
	v_pk_add_f32 v[22:23], v[22:23], 1.0 op_sel_hi:[1,0] neg_lo:[1,0] neg_hi:[1,0]
	v_mov_b32_e32 v25, v8
	v_pk_mul_f32 v[24:25], v[24:25], 0.5 op_sel_hi:[1,0]
	v_pk_add_f32 v[22:23], v[22:23], 1.0 op_sel_hi:[1,0]
	v_pk_mul_f32 v[22:23], v[24:25], v[22:23]
	s_waitcnt lgkmcnt(0)
	v_mul_f32_e32 v16, 0x3d372713, v2
	v_mul_f32_e32 v17, 0x3d372713, v4
	v_mul_f32_e32 v16, v2, v16
	v_mul_f32_e32 v17, v4, v17
	v_fma_f32 v16, v2, v16, v2
	v_fma_f32 v17, v4, v17, v4
	v_mul_f32_e32 v16, 0x3f4c422a, v16
	v_mul_f32_e32 v17, 0x3f4c422a, v17
	v_add_f32_e32 v16, v16, v16
	v_add_f32_e32 v17, v17, v17
	v_rcp_f32_e32 v21, v21
	s_nop 0
	v_add_f32_e32 v21, v21, v21
	v_mul_f32_e32 v16, 0x3fb8aa3b, v16
	v_mul_f32_e32 v17, 0x3fb8aa3b, v17
	v_exp_f32_e32 v18, v16
	v_exp_f32_e32 v19, v17
	v_mov_b32_e32 v8, v7
	v_pk_add_f32 v[6:7], v[18:19], 1.0 op_sel_hi:[1,0]
	v_rcp_f32_e32 v20, v20
	s_nop 0
	v_add_f32_e32 v20, v20, v20
	v_pk_add_f32 v[20:21], v[20:21], 1.0 op_sel_hi:[1,0] neg_lo:[1,0] neg_hi:[1,0]
	v_pk_mul_f32 v[8:9], v[8:9], 0.5 op_sel_hi:[1,0]
	v_pk_add_f32 v[18:19], v[20:21], 1.0 op_sel_hi:[1,0]
	v_mul_f32_e32 v16, 0x3d372713, v3
	v_pk_mul_f32 v[8:9], v[8:9], v[18:19]
	v_mul_f32_e32 v17, 0x3d372713, v5
	v_mul_f32_e32 v16, v3, v16
	v_mul_f32_e32 v17, v5, v17
	v_fma_f32 v16, v3, v16, v3
	v_fma_f32 v17, v5, v17, v5
	v_mul_f32_e32 v16, 0x3f4c422a, v16
	v_mul_f32_e32 v17, 0x3f4c422a, v17
	v_add_f32_e32 v16, v16, v16
	v_add_f32_e32 v17, v17, v17
	v_rcp_f32_e32 v7, v7
	s_nop 0
	v_add_f32_e32 v7, v7, v7
	v_mul_f32_e32 v16, 0x3fb8aa3b, v16
	v_mul_f32_e32 v17, 0x3fb8aa3b, v17
	v_exp_f32_e32 v16, v16
	v_exp_f32_e32 v17, v17
	s_nop 0
	v_pk_add_f32 v[16:17], v[16:17], 1.0 op_sel_hi:[1,0]
	v_rcp_f32_e32 v6, v6
	s_nop 0
	v_add_f32_e32 v6, v6, v6
	v_mov_b32_e32 v18, v2
	v_pk_add_f32 v[6:7], v[6:7], 1.0 op_sel_hi:[1,0] neg_lo:[1,0] neg_hi:[1,0]
	v_mov_b32_e32 v19, v4
	v_pk_mul_f32 v[18:19], v[18:19], 0.5 op_sel_hi:[1,0]
	v_pk_add_f32 v[6:7], v[6:7], 1.0 op_sel_hi:[1,0]
	v_pk_mul_f32 v[6:7], v[18:19], v[6:7]
	v_div_scale_f32 v4, s[8:9], v16, v16, 2.0
	v_rcp_f32_e32 v19, v4
	v_rcp_f32_e32 v17, v17
	s_nop 0
	v_add_f32_e32 v17, v17, v17
	v_fma_f32 v0, -v4, v19, 1.0
	v_fmac_f32_e32 v19, v0, v19
	v_div_scale_f32 v0, vcc, 2.0, v16, 2.0
	v_mul_f32_e32 v2, v0, v19
	v_fma_f32 v18, -v4, v2, v0
	v_fmac_f32_e32 v2, v18, v19
	v_fma_f32 v0, -v4, v2, v0
	v_div_fmas_f32 v0, v0, v19, v2
	v_div_fixup_f32 v16, v0, v16, 2.0
	v_pk_add_f32 v[16:17], v[16:17], 1.0 op_sel_hi:[1,0] neg_lo:[1,0] neg_hi:[1,0]
	v_mov_b32_e32 v4, v3
	v_pk_mul_f32 v[2:3], v[4:5], 0.5 op_sel_hi:[1,0]
	v_pk_add_f32 v[4:5], v[16:17], 1.0 op_sel_hi:[1,0]
	v_pk_mul_f32 v[2:3], v[2:3], v[4:5]
	v_bfe_u32 v0, v3, 16, 1
	v_bfe_u32 v4, v2, 16, 1
	v_add3_u32 v2, v2, v4, s37
	v_add3_u32 v0, v3, v0, s37
	v_bfe_u32 v5, v6, 16, 1
	v_bfe_u32 v16, v7, 16, 1
	v_add3_u32 v7, v7, v16, s37
	v_add3_u32 v5, v6, v5, s37
	v_lshrrev_b32_e32 v4, 16, v5
	v_lshrrev_b32_e32 v5, 16, v7
	s_mov_b64 s[8:9], 0
	v_and_or_b32 v5, v0, s30, v5
	v_and_or_b32 v4, v2, s30, v4
	v_cvt_pk_bf16_f32 v3, v23, v9
	v_cvt_pk_bf16_f32 v2, v22, v8
	global_store_dwordx4 v[14:15], v[10:13], off
	global_store_dwordx4 v[14:15], v[2:5], off offset:16

; DI unsigned pack2(float a, float b) { return (unsigned)f2bf(a) | ((unsigned)f2bf(b) << 16); }
; DI void store16_bf(bft* dst, const float (&v)[16]) {
;   u32x4 o0 = {pack2(v[0], v[1]), pack2(v[2], v[3]), pack2(v[4], v[5]), pack2(v[6], v[7])}, o1 = {pack2(v[8], v[9]), pack2(v[10], v[11]), pack2(v[12], v[13]), pack2(v[14], v[15])};
;   *(u32x4*)dst = o0; *(u32x4*)(dst + 8) = o1;
; DI void phase_upproj(const Params& p, int sg) {
;     ...
;       EPI256_BEGIN
;         const int cw = bcol + wc * 64; const bool is_rope = (cw % 192) == 128;
;         if (is_rope) { int pos = tok_pos(sg * 16384 + row); const int cg = lane & 3; const float* rp = rt + pos * 64 + (cg & 1) * 16;
; #pragma unroll
;           for (int i = 0; i < 16; ++i) { float c = rp[i], s = rp[32 + i]; float xo = __shfl_xor(v[i], 2); v[i] = cg < 2 ? v[i] * c - xo * s : xo * s + v[i] * c; } }
;         store16_bf(Q + (size_t)row * 1536 + col, v);
.LBB0_693:
	s_or_b64 exec, exec, s[0:1]
	s_waitcnt lgkmcnt(3)
	s_waitcnt lgkmcnt(2)
	v_cvt_pk_bf16_f32 v11, v10, v11
	v_cvt_pk_bf16_f32 v10, v8, v9
	v_cvt_pk_bf16_f32 v9, v14, v15
	v_cvt_pk_bf16_f32 v8, v12, v13
	s_waitcnt lgkmcnt(1)
	s_waitcnt lgkmcnt(0)
	v_mad_i64_i32 v[16:17], s[0:1], v32, s95, v[132:133]
	v_cvt_pk_bf16_f32 v3, v2, v3
	v_cvt_pk_bf16_f32 v2, v0, v1
	v_cvt_pk_bf16_f32 v1, v6, v7
	v_cvt_pk_bf16_f32 v0, v4, v5
	global_store_dwordx4 v[16:17], v[8:11], off
	global_store_dwordx4 v[16:17], v[0:3], off offset:16

; DI unsigned pack2(float a, float b) { return (unsigned)f2bf(a) | ((unsigned)f2bf(b) << 16); }
;   const int lane = tid & 63, wid = tid >> 6, fr = lane & 15, fq = lane >> 4;
;   float* stg = (float*)(smem + PATCH) + wid * (16 * 68);
;   asm volatile("" ::: "memory");
; #pragma unroll
;   for (int n = 0; n < 4; ++n)
; #pragma unroll
;     for (int j = 0; j < 4; ++j) stg[(fq * 4 + j) * 68 + n * 16 + fr] = am[n][j];
;   asm volatile("s_waitcnt lgkmcnt(0)" ::: "memory");
;   const float* rp = stg + (lane >> 2) * 68 + (lane & 3) * 16;
; #pragma unroll
;   for (int i = 0; i < 4; ++i) { f32x4 t = *(const f32x4*)(rp + i * 4); v[4 * i] = t[0]; v[4 * i + 1] = t[1]; v[4 * i + 2] = t[2]; v[4 * i + 3] = t[3]; }
;   asm volatile("" ::: "memory");
; }
; DI void store16_bf(bft* dst, const float (&v)[16]) {
;   u32x4 o0 = {pack2(v[0], v[1]), pack2(v[2], v[3]), pack2(v[4], v[5]), pack2(v[6], v[7])}, o1 = {pack2(v[8], v[9]), pack2(v[10], v[11]), pack2(v[12], v[13]), pack2(v[14], v[15])};
;   *(u32x4*)dst = o0; *(u32x4*)(dst + 8) = o1;
; DI void phase_upproj(const Params& p, int sg) {
;     ...
;       EPI256_BEGIN
;         const int cw = bcol + wc * 64; const bool is_rope = (cw % 192) == 128;
;         if (is_rope) { int pos = tok_pos(sg * 16384 + row); const int cg = lane & 3; const float* rp = rt + pos * 64 + (cg & 1) * 16;
; #pragma unroll
;           for (int i = 0; i < 16; ++i) { float c = rp[i], s = rp[32 + i]; float xo = __shfl_xor(v[i], 2); v[i] = cg < 2 ? v[i] * c - xo * s : xo * s + v[i] * c; } }
;         store16_bf(Q + (size_t)row * 1536 + col, v);
.LBB0_757:
	s_or_b64 exec, exec, s[0:1]
	s_waitcnt lgkmcnt(3)
	v_bfe_u32 v96, v128, 16, 1
	s_waitcnt lgkmcnt(2)
	v_add3_u32 v96, v128, v96, s96
	v_bfe_u32 v136, v129, 16, 1
	v_lshl_or_b32 v98, v99, 4, v98
	v_lshrrev_b32_e32 v96, 16, v96
	v_add3_u32 v129, v129, v136, s96
	v_cvt_pk_bf16_f32 v127, v126, v127
	v_cvt_pk_bf16_f32 v126, v124, v125
	v_cvt_pk_bf16_f32 v125, v130, v131
	s_waitcnt lgkmcnt(1)
	v_ashrrev_i32_e32 v99, 31, v98
	v_and_or_b32 v124, v129, s92, v96
	s_waitcnt lgkmcnt(0)
	v_lshl_add_u64 v[132:133], v[98:99], 1, s[16:17]
	v_mad_i64_i32 v[98:99], s[0:1], v152, s95, v[132:133]
	v_cvt_pk_bf16_f32 v119, v118, v119
	v_cvt_pk_bf16_f32 v118, v116, v117
	v_cvt_pk_bf16_f32 v117, v122, v123
	v_cvt_pk_bf16_f32 v116, v120, v121
	global_store_dwordx4 v[98:99], v[124:127], off
	global_store_dwordx4 v[98:99], v[116:119], off offset:16
	ds_write2_b32 v153, v112, v108 offset1:16
	ds_write2_b32 v153, v113, v109 offset0:68 offset1:84
	ds_write2_b32 v153, v114, v110 offset0:136 offset1:152
	ds_write2_b32 v153, v115, v111 offset0:204 offset1:220
	ds_write2_b32 v153, v104, v100 offset0:32 offset1:48
	ds_write2_b32 v153, v105, v101 offset0:100 offset1:116
	ds_write2_b32 v153, v106, v102 offset0:168 offset1:184
	ds_write2_b32 v153, v107, v103 offset0:236 offset1:252
	s_waitcnt lgkmcnt(0)
	ds_read_b128 v[110:113], v154
	ds_read_b128 v[106:109], v154 offset:16
	ds_read_b128 v[102:105], v154 offset:32
	ds_read_b128 v[98:101], v154 offset:48
	v_or_b32_e32 v130, 16, v152
	s_and_saveexec_b64 s[0:1], s[10:11]
	s_cbranch_execz .LBB0_759
	v_add_u32_e32 v96, s86, v130
	v_cmp_gt_i32_e64 s[12:13], s69, v96
	s_nop 1
	v_cndmask_b32_e64 v114, v185, v186, s[12:13]
	v_and_b32_e32 v96, v114, v96
	v_lshlrev_b32_e32 v96, 8, v96
	v_and_b32_e32 v114, 64, v181
	v_lshl_add_u64 v[146:147], v[148:149], 0, v[96:97]
	v_xor_b32_e32 v96, 2, v181
	v_add_u32_e32 v114, 64, v114
	v_cmp_lt_i32_e64 s[12:13], v96, v114
	global_load_dwordx4 v[114:117], v[146:147], off offset:48
	global_load_dwordx4 v[122:125], v[146:147], off offset:32
	global_load_dwordx4 v[134:137], v[146:147], off offset:16
	global_load_dwordx4 v[138:141], v[146:147], off
	global_load_dwordx4 v[118:121], v[146:147], off offset:176
	global_load_dwordx4 v[126:129], v[146:147], off offset:160
	global_load_dwordx4 v[142:145], v[146:147], off offset:144
	global_load_dwordx4 v[156:159], v[146:147], off offset:128
	v_cndmask_b32_e64 v96, v181, v96, s[12:13]
	v_lshlrev_b32_e32 v96, 2, v96
	s_waitcnt lgkmcnt(3)
	ds_bpermute_b32 v160, v96, v110
	ds_bpermute_b32 v161, v96, v111
	s_waitcnt vmcnt(0) lgkmcnt(0)
	v_pk_mul_f32 v[146:147], v[156:157], v[160:161]
	s_nop 0
	v_cndmask_b32_e64 v147, v147, -v147, vcc
	v_cndmask_b32_e64 v146, v146, -v146, vcc
	v_pk_fma_f32 v[110:111], v[110:111], v[138:139], v[146:147]
	ds_bpermute_b32 v138, v96, v112
	ds_bpermute_b32 v139, v96, v113
	s_waitcnt lgkmcnt(0)
	v_pk_mul_f32 v[138:139], v[158:159], v[138:139]
	s_nop 0
	v_cndmask_b32_e64 v139, v139, -v139, vcc
	v_cndmask_b32_e64 v138, v138, -v138, vcc
	v_pk_fma_f32 v[112:113], v[112:113], v[140:141], v[138:139]
	ds_bpermute_b32 v138, v96, v106
	ds_bpermute_b32 v139, v96, v107
	s_waitcnt lgkmcnt(0)
	v_pk_mul_f32 v[138:139], v[142:143], v[138:139]
	s_nop 0
	v_cndmask_b32_e64 v139, v139, -v139, vcc
	v_cndmask_b32_e64 v138, v138, -v138, vcc
	v_pk_fma_f32 v[106:107], v[106:107], v[134:135], v[138:139]
	ds_bpermute_b32 v134, v96, v108
	ds_bpermute_b32 v135, v96, v109
	s_waitcnt lgkmcnt(0)
	v_pk_mul_f32 v[134:135], v[144:145], v[134:135]
	s_nop 0
	v_cndmask_b32_e64 v135, v135, -v135, vcc
	v_cndmask_b32_e64 v134, v134, -v134, vcc
	v_pk_fma_f32 v[108:109], v[108:109], v[136:137], v[134:135]
	ds_bpermute_b32 v134, v96, v102
	ds_bpermute_b32 v135, v96, v103
	s_waitcnt lgkmcnt(0)
	v_pk_mul_f32 v[126:127], v[126:127], v[134:135]
	s_nop 0
	v_cndmask_b32_e64 v127, v127, -v127, vcc
	v_cndmask_b32_e64 v126, v126, -v126, vcc
	v_pk_fma_f32 v[102:103], v[102:103], v[122:123], v[126:127]
	ds_bpermute_b32 v122, v96, v104
	ds_bpermute_b32 v123, v96, v105
	s_waitcnt lgkmcnt(0)
	v_pk_mul_f32 v[122:123], v[128:129], v[122:123]
	s_nop 0
	v_cndmask_b32_e64 v123, v123, -v123, vcc
	v_cndmask_b32_e64 v122, v122, -v122, vcc
	v_pk_fma_f32 v[104:105], v[104:105], v[124:125], v[122:123]
	ds_bpermute_b32 v122, v96, v98
	ds_bpermute_b32 v123, v96, v99
	s_waitcnt lgkmcnt(0)
	v_pk_mul_f32 v[118:119], v[118:119], v[122:123]
	s_nop 0
	v_cndmask_b32_e64 v119, v119, -v119, vcc
	v_cndmask_b32_e64 v118, v118, -v118, vcc
	v_pk_fma_f32 v[98:99], v[98:99], v[114:115], v[118:119]
	ds_bpermute_b32 v114, v96, v100
	ds_bpermute_b32 v115, v96, v101
	s_waitcnt lgkmcnt(0)
	v_pk_mul_f32 v[114:115], v[120:121], v[114:115]
	s_nop 0
	v_cndmask_b32_e64 v115, v115, -v115, vcc
	v_cndmask_b32_e64 v114, v114, -v114, vcc
	v_pk_fma_f32 v[100:101], v[100:101], v[116:117], v[114:115]
; DI unsigned pack2(float a, float b) { return (unsigned)f2bf(a) | ((unsigned)f2bf(b) << 16); }
;   const int lane = tid & 63, wid = tid >> 6, fr = lane & 15, fq = lane >> 4;
;   float* stg = (float*)(smem + PATCH) + wid * (16 * 68);
;   asm volatile("" ::: "memory");
; #pragma unroll
;   for (int n = 0; n < 4; ++n)
; #pragma unroll
;     for (int j = 0; j < 4; ++j) stg[(fq * 4 + j) * 68 + n * 16 + fr] = am[n][j];
;   asm volatile("s_waitcnt lgkmcnt(0)" ::: "memory");
;   const float* rp = stg + (lane >> 2) * 68 + (lane & 3) * 16;
; #pragma unroll
;   for (int i = 0; i < 4; ++i) { f32x4 t = *(const f32x4*)(rp + i * 4); v[4 * i] = t[0]; v[4 * i + 1] = t[1]; v[4 * i + 2] = t[2]; v[4 * i + 3] = t[3]; }
;   asm volatile("" ::: "memory");
; }
; DI void store16_bf(bft* dst, const float (&v)[16]) {
;   u32x4 o0 = {pack2(v[0], v[1]), pack2(v[2], v[3]), pack2(v[4], v[5]), pack2(v[6], v[7])}, o1 = {pack2(v[8], v[9]), pack2(v[10], v[11]), pack2(v[12], v[13]), pack2(v[14], v[15])};
;   *(u32x4*)dst = o0; *(u32x4*)(dst + 8) = o1;
; DI void phase_upproj(const Params& p, int sg) {
;     ...
;       EPI256_BEGIN
;         const int cw = bcol + wc * 64; const bool is_rope = (cw % 192) == 128;
;         if (is_rope) { int pos = tok_pos(sg * 16384 + row); const int cg = lane & 3; const float* rp = rt + pos * 64 + (cg & 1) * 16;
; #pragma unroll
;           for (int i = 0; i < 16; ++i) { float c = rp[i], s = rp[32 + i]; float xo = __shfl_xor(v[i], 2); v[i] = cg < 2 ? v[i] * c - xo * s : xo * s + v[i] * c; } }
;         store16_bf(Q + (size_t)row * 1536 + col, v);
.LBB0_759:
	s_or_b64 exec, exec, s[0:1]
	s_waitcnt lgkmcnt(3)
	v_bfe_u32 v96, v110, 16, 1
	s_waitcnt lgkmcnt(2)
	v_add3_u32 v96, v110, v96, s96
	v_bfe_u32 v118, v111, 16, 1
	v_lshrrev_b32_e32 v96, 16, v96
	v_add3_u32 v111, v111, v118, s96
	v_cvt_pk_bf16_f32 v109, v108, v109
	v_cvt_pk_bf16_f32 v108, v106, v107
	v_cvt_pk_bf16_f32 v107, v112, v113
	s_waitcnt lgkmcnt(1)
	v_and_or_b32 v106, v111, s92, v96
	s_waitcnt lgkmcnt(0)
	v_mad_i64_i32 v[114:115], s[0:1], v130, s95, v[132:133]
	v_cvt_pk_bf16_f32 v101, v100, v101
	v_cvt_pk_bf16_f32 v100, v98, v99
	v_cvt_pk_bf16_f32 v99, v104, v105
	v_cvt_pk_bf16_f32 v98, v102, v103
	global_store_dwordx4 v[114:115], v[106:109], off
	global_store_dwordx4 v[114:115], v[98:101], off offset:16
	ds_write2_b32 v153, v92, v88 offset1:16
	ds_write2_b32 v153, v93, v89 offset0:68 offset1:84
	ds_write2_b32 v153, v94, v90 offset0:136 offset1:152
	ds_write2_b32 v153, v95, v91 offset0:204 offset1:220
	ds_write2_b32 v153, v84, v80 offset0:32 offset1:48
	ds_write2_b32 v153, v85, v81 offset0:100 offset1:116
	ds_write2_b32 v153, v86, v82 offset0:168 offset1:184
	ds_write2_b32 v153, v87, v83 offset0:236 offset1:252
	s_waitcnt lgkmcnt(0)
	ds_read_b128 v[92:95], v154
	ds_read_b128 v[88:91], v154 offset:16
	ds_read_b128 v[84:87], v154 offset:32
	ds_read_b128 v[80:83], v154 offset:48
	v_or_b32_e32 v114, 32, v152
	s_and_saveexec_b64 s[0:1], s[10:11]
	s_cbranch_execz .LBB0_761
	v_add_u32_e32 v96, s86, v114
	v_cmp_gt_i32_e64 s[12:13], s69, v96
	s_nop 1
	v_cndmask_b32_e64 v98, v187, v188, s[12:13]
	v_and_b32_e32 v96, v98, v96
	v_lshlrev_b32_e32 v96, 8, v96
	v_and_b32_e32 v98, 64, v181
	v_lshl_add_u64 v[128:129], v[148:149], 0, v[96:97]
	v_xor_b32_e32 v96, 2, v181
	v_add_u32_e32 v98, 64, v98
	v_cmp_lt_i32_e64 s[12:13], v96, v98
	global_load_dwordx4 v[98:101], v[128:129], off offset:48
	global_load_dwordx4 v[106:109], v[128:129], off offset:32
	global_load_dwordx4 v[116:119], v[128:129], off offset:16
	global_load_dwordx4 v[120:123], v[128:129], off
	global_load_dwordx4 v[102:105], v[128:129], off offset:176
	global_load_dwordx4 v[110:113], v[128:129], off offset:160
	global_load_dwordx4 v[124:127], v[128:129], off offset:144
	s_nop 0
	global_load_dwordx4 v[128:131], v[128:129], off offset:128
	v_cndmask_b32_e64 v96, v181, v96, s[12:13]
	v_lshlrev_b32_e32 v96, 2, v96
	s_waitcnt lgkmcnt(3)
	ds_bpermute_b32 v134, v96, v92
	ds_bpermute_b32 v135, v96, v93
	s_waitcnt vmcnt(0) lgkmcnt(0)
	v_pk_mul_f32 v[128:129], v[128:129], v[134:135]
	s_nop 0
	v_cndmask_b32_e64 v129, v129, -v129, vcc
	v_cndmask_b32_e64 v128, v128, -v128, vcc
	v_pk_fma_f32 v[92:93], v[92:93], v[120:121], v[128:129]
	ds_bpermute_b32 v120, v96, v94
	ds_bpermute_b32 v121, v96, v95
	s_waitcnt lgkmcnt(0)
	v_pk_mul_f32 v[120:121], v[130:131], v[120:121]
	s_nop 0
	v_cndmask_b32_e64 v121, v121, -v121, vcc
	v_cndmask_b32_e64 v120, v120, -v120, vcc
	v_pk_fma_f32 v[94:95], v[94:95], v[122:123], v[120:121]
	ds_bpermute_b32 v120, v96, v88
	ds_bpermute_b32 v121, v96, v89
	s_waitcnt lgkmcnt(0)
	v_pk_mul_f32 v[120:121], v[124:125], v[120:121]
	s_nop 0
	v_cndmask_b32_e64 v121, v121, -v121, vcc
	v_cndmask_b32_e64 v120, v120, -v120, vcc
	v_pk_fma_f32 v[88:89], v[88:89], v[116:117], v[120:121]
	ds_bpermute_b32 v116, v96, v90
	ds_bpermute_b32 v117, v96, v91
	s_waitcnt lgkmcnt(0)
	v_pk_mul_f32 v[116:117], v[126:127], v[116:117]
	s_nop 0
	v_cndmask_b32_e64 v117, v117, -v117, vcc
	v_cndmask_b32_e64 v116, v116, -v116, vcc
	v_pk_fma_f32 v[90:91], v[90:91], v[118:119], v[116:117]
	ds_bpermute_b32 v116, v96, v84
	ds_bpermute_b32 v117, v96, v85
	s_waitcnt lgkmcnt(0)
	v_pk_mul_f32 v[110:111], v[110:111], v[116:117]
	s_nop 0
	v_cndmask_b32_e64 v111, v111, -v111, vcc
	v_cndmask_b32_e64 v110, v110, -v110, vcc
	v_pk_fma_f32 v[84:85], v[84:85], v[106:107], v[110:111]
	ds_bpermute_b32 v106, v96, v86
	ds_bpermute_b32 v107, v96, v87
	s_waitcnt lgkmcnt(0)
	v_pk_mul_f32 v[106:107], v[112:113], v[106:107]
	s_nop 0
	v_cndmask_b32_e64 v107, v107, -v107, vcc
	v_cndmask_b32_e64 v106, v106, -v106, vcc
	v_pk_fma_f32 v[86:87], v[86:87], v[108:109], v[106:107]
	ds_bpermute_b32 v106, v96, v80
	ds_bpermute_b32 v107, v96, v81
	s_waitcnt lgkmcnt(0)
	v_pk_mul_f32 v[102:103], v[102:103], v[106:107]
	s_nop 0
	v_cndmask_b32_e64 v103, v103, -v103, vcc
	v_cndmask_b32_e64 v102, v102, -v102, vcc
	v_pk_fma_f32 v[80:81], v[80:81], v[98:99], v[102:103]
	ds_bpermute_b32 v98, v96, v82
	ds_bpermute_b32 v99, v96, v83
	s_waitcnt lgkmcnt(0)
	v_pk_mul_f32 v[98:99], v[104:105], v[98:99]
	s_nop 0
	v_cndmask_b32_e64 v99, v99, -v99, vcc
	v_cndmask_b32_e64 v98, v98, -v98, vcc
	v_pk_fma_f32 v[82:83], v[82:83], v[100:101], v[98:99]
; DI unsigned pack2(float a, float b) { return (unsigned)f2bf(a) | ((unsigned)f2bf(b) << 16); }
;   const int lane = tid & 63, wid = tid >> 6, fr = lane & 15, fq = lane >> 4;
;   float* stg = (float*)(smem + PATCH) + wid * (16 * 68);
;   asm volatile("" ::: "memory");
; #pragma unroll
;   for (int n = 0; n < 4; ++n)
; #pragma unroll
;     for (int j = 0; j < 4; ++j) stg[(fq * 4 + j) * 68 + n * 16 + fr] = am[n][j];
;   asm volatile("s_waitcnt lgkmcnt(0)" ::: "memory");
;   const float* rp = stg + (lane >> 2) * 68 + (lane & 3) * 16;
; #pragma unroll
;   for (int i = 0; i < 4; ++i) { f32x4 t = *(const f32x4*)(rp + i * 4); v[4 * i] = t[0]; v[4 * i + 1] = t[1]; v[4 * i + 2] = t[2]; v[4 * i + 3] = t[3]; }
;   asm volatile("" ::: "memory");
; }
; DI void store16_bf(bft* dst, const float (&v)[16]) {
;   u32x4 o0 = {pack2(v[0], v[1]), pack2(v[2], v[3]), pack2(v[4], v[5]), pack2(v[6], v[7])}, o1 = {pack2(v[8], v[9]), pack2(v[10], v[11]), pack2(v[12], v[13]), pack2(v[14], v[15])};
;   *(u32x4*)dst = o0; *(u32x4*)(dst + 8) = o1;
; DI void phase_upproj(const Params& p, int sg) {
;     ...
;       EPI256_BEGIN
;         const int cw = bcol + wc * 64; const bool is_rope = (cw % 192) == 128;
;         if (is_rope) { int pos = tok_pos(sg * 16384 + row); const int cg = lane & 3; const float* rp = rt + pos * 64 + (cg & 1) * 16;
; #pragma unroll
;           for (int i = 0; i < 16; ++i) { float c = rp[i], s = rp[32 + i]; float xo = __shfl_xor(v[i], 2); v[i] = cg < 2 ? v[i] * c - xo * s : xo * s + v[i] * c; } }
;         store16_bf(Q + (size_t)row * 1536 + col, v);
.LBB0_761:
	s_or_b64 exec, exec, s[0:1]
	s_waitcnt lgkmcnt(3)
	s_waitcnt lgkmcnt(2)
	v_cvt_pk_bf16_f32 v91, v90, v91
	v_cvt_pk_bf16_f32 v90, v88, v89
	v_cvt_pk_bf16_f32 v89, v94, v95
	v_cvt_pk_bf16_f32 v88, v92, v93
	s_waitcnt lgkmcnt(1)
	s_waitcnt lgkmcnt(0)
	v_mad_i64_i32 v[98:99], s[0:1], v114, s95, v[132:133]
	v_cvt_pk_bf16_f32 v83, v82, v83
	v_cvt_pk_bf16_f32 v82, v80, v81
	v_cvt_pk_bf16_f32 v81, v86, v87
	v_cvt_pk_bf16_f32 v80, v84, v85
	global_store_dwordx4 v[98:99], v[88:91], off
	global_store_dwordx4 v[98:99], v[80:83], off offset:16
	ds_write2_b32 v153, v76, v72 offset1:16
	ds_write2_b32 v153, v77, v73 offset0:68 offset1:84
	ds_write2_b32 v153, v78, v74 offset0:136 offset1:152
	ds_write2_b32 v153, v79, v75 offset0:204 offset1:220
	ds_write2_b32 v153, v68, v64 offset0:32 offset1:48
	ds_write2_b32 v153, v69, v65 offset0:100 offset1:116
	ds_write2_b32 v153, v70, v66 offset0:168 offset1:184
	ds_write2_b32 v153, v71, v67 offset0:236 offset1:252
	s_waitcnt lgkmcnt(0)
	ds_read_b128 v[76:79], v154
	ds_read_b128 v[72:75], v154 offset:16
	ds_read_b128 v[68:71], v154 offset:32
	ds_read_b128 v[64:67], v154 offset:48
	v_or_b32_e32 v98, 48, v152
	s_and_saveexec_b64 s[0:1], s[10:11]
	s_cbranch_execz .LBB0_763
	v_add_u32_e32 v80, s86, v98
	v_cmp_gt_i32_e64 s[12:13], s69, v80
	s_nop 1
	v_cndmask_b32_e64 v81, v189, v190, s[12:13]
	v_and_b32_e32 v80, v81, v80
	v_and_b32_e32 v81, 64, v181
	v_lshlrev_b32_e32 v96, 8, v80
	v_xor_b32_e32 v80, 2, v181
	v_add_u32_e32 v81, 64, v81
	v_cmp_lt_i32_e64 s[12:13], v80, v81
	v_lshl_add_u64 v[112:113], v[148:149], 0, v[96:97]
	s_nop 0
	v_cndmask_b32_e64 v80, v181, v80, s[12:13]
	v_lshlrev_b32_e32 v96, 2, v80
	global_load_dwordx4 v[80:83], v[112:113], off offset:48
	global_load_dwordx4 v[88:91], v[112:113], off offset:32
	global_load_dwordx4 v[100:103], v[112:113], off offset:16
	global_load_dwordx4 v[104:107], v[112:113], off
	global_load_dwordx4 v[84:87], v[112:113], off offset:176
	global_load_dwordx4 v[92:95], v[112:113], off offset:160
	global_load_dwordx4 v[108:111], v[112:113], off offset:144
	s_nop 0
	global_load_dwordx4 v[112:115], v[112:113], off offset:128
	s_waitcnt lgkmcnt(3)
	ds_bpermute_b32 v116, v96, v76
	ds_bpermute_b32 v117, v96, v77
	s_waitcnt vmcnt(0) lgkmcnt(0)
	v_pk_mul_f32 v[112:113], v[112:113], v[116:117]
	s_nop 0
	v_cndmask_b32_e64 v113, v113, -v113, vcc
	v_cndmask_b32_e64 v112, v112, -v112, vcc
	v_pk_fma_f32 v[76:77], v[76:77], v[104:105], v[112:113]
	ds_bpermute_b32 v104, v96, v78
	ds_bpermute_b32 v105, v96, v79
	s_waitcnt lgkmcnt(0)
	v_pk_mul_f32 v[104:105], v[114:115], v[104:105]
	s_nop 0
	v_cndmask_b32_e64 v105, v105, -v105, vcc
	v_cndmask_b32_e64 v104, v104, -v104, vcc
	v_pk_fma_f32 v[78:79], v[78:79], v[106:107], v[104:105]
	ds_bpermute_b32 v104, v96, v72
	ds_bpermute_b32 v105, v96, v73
	s_waitcnt lgkmcnt(0)
	v_pk_mul_f32 v[104:105], v[108:109], v[104:105]
	s_nop 0
	v_cndmask_b32_e64 v105, v105, -v105, vcc
	v_cndmask_b32_e64 v104, v104, -v104, vcc
	v_pk_fma_f32 v[72:73], v[72:73], v[100:101], v[104:105]
	ds_bpermute_b32 v100, v96, v74
	ds_bpermute_b32 v101, v96, v75
	s_waitcnt lgkmcnt(0)
	v_pk_mul_f32 v[100:101], v[110:111], v[100:101]
	s_nop 0
	v_cndmask_b32_e64 v101, v101, -v101, vcc
	v_cndmask_b32_e64 v100, v100, -v100, vcc
	v_pk_fma_f32 v[74:75], v[74:75], v[102:103], v[100:101]
	ds_bpermute_b32 v100, v96, v68
	ds_bpermute_b32 v101, v96, v69
	s_waitcnt lgkmcnt(0)
	v_pk_mul_f32 v[92:93], v[92:93], v[100:101]
	s_nop 0
	v_cndmask_b32_e64 v93, v93, -v93, vcc
	v_cndmask_b32_e64 v92, v92, -v92, vcc
	v_pk_fma_f32 v[68:69], v[68:69], v[88:89], v[92:93]
	ds_bpermute_b32 v88, v96, v70
	ds_bpermute_b32 v89, v96, v71
	s_waitcnt lgkmcnt(0)
	v_pk_mul_f32 v[88:89], v[94:95], v[88:89]
	s_nop 0
	v_cndmask_b32_e64 v89, v89, -v89, vcc
	v_cndmask_b32_e64 v88, v88, -v88, vcc
	v_pk_fma_f32 v[70:71], v[70:71], v[90:91], v[88:89]
	ds_bpermute_b32 v88, v96, v64
	ds_bpermute_b32 v89, v96, v65
	s_waitcnt lgkmcnt(0)
	v_pk_mul_f32 v[84:85], v[84:85], v[88:89]
	s_nop 0
	v_cndmask_b32_e64 v85, v85, -v85, vcc
	v_cndmask_b32_e64 v84, v84, -v84, vcc
	v_pk_fma_f32 v[64:65], v[64:65], v[80:81], v[84:85]
	ds_bpermute_b32 v80, v96, v66
	ds_bpermute_b32 v81, v96, v67
	s_waitcnt lgkmcnt(0)
	v_pk_mul_f32 v[80:81], v[86:87], v[80:81]
	s_nop 0
	v_cndmask_b32_e64 v81, v81, -v81, vcc
	v_cndmask_b32_e64 v80, v80, -v80, vcc
	v_pk_fma_f32 v[66:67], v[66:67], v[82:83], v[80:81]
; DI unsigned pack2(float a, float b) { return (unsigned)f2bf(a) | ((unsigned)f2bf(b) << 16); }
;   const int lane = tid & 63, wid = tid >> 6, fr = lane & 15, fq = lane >> 4;
;   float* stg = (float*)(smem + PATCH) + wid * (16 * 68);
;   asm volatile("" ::: "memory");
; #pragma unroll
;   for (int n = 0; n < 4; ++n)
; #pragma unroll
;     for (int j = 0; j < 4; ++j) stg[(fq * 4 + j) * 68 + n * 16 + fr] = am[n][j];
;   asm volatile("s_waitcnt lgkmcnt(0)" ::: "memory");
;   const float* rp = stg + (lane >> 2) * 68 + (lane & 3) * 16;
; #pragma unroll
;   for (int i = 0; i < 4; ++i) { f32x4 t = *(const f32x4*)(rp + i * 4); v[4 * i] = t[0]; v[4 * i + 1] = t[1]; v[4 * i + 2] = t[2]; v[4 * i + 3] = t[3]; }
;   asm volatile("" ::: "memory");
; }
; DI void store16_bf(bft* dst, const float (&v)[16]) {
;   u32x4 o0 = {pack2(v[0], v[1]), pack2(v[2], v[3]), pack2(v[4], v[5]), pack2(v[6], v[7])}, o1 = {pack2(v[8], v[9]), pack2(v[10], v[11]), pack2(v[12], v[13]), pack2(v[14], v[15])};
;   *(u32x4*)dst = o0; *(u32x4*)(dst + 8) = o1;
; DI void phase_upproj(const Params& p, int sg) {
;     ...
;       EPI256_BEGIN
;         const int cw = bcol + wc * 64; const bool is_rope = (cw % 192) == 128;
;         if (is_rope) { int pos = tok_pos(sg * 16384 + row); const int cg = lane & 3; const float* rp = rt + pos * 64 + (cg & 1) * 16;
; #pragma unroll
;           for (int i = 0; i < 16; ++i) { float c = rp[i], s = rp[32 + i]; float xo = __shfl_xor(v[i], 2); v[i] = cg < 2 ? v[i] * c - xo * s : xo * s + v[i] * c; } }
;         store16_bf(Q + (size_t)row * 1536 + col, v);
.LBB0_763:
	s_or_b64 exec, exec, s[0:1]
	s_waitcnt lgkmcnt(3)
	s_waitcnt lgkmcnt(2)
	v_cvt_pk_bf16_f32 v75, v74, v75
	v_cvt_pk_bf16_f32 v74, v72, v73
	v_cvt_pk_bf16_f32 v73, v78, v79
	v_cvt_pk_bf16_f32 v72, v76, v77
	s_waitcnt lgkmcnt(1)
	s_waitcnt lgkmcnt(0)
	v_mad_i64_i32 v[80:81], s[0:1], v98, s95, v[132:133]
	v_cvt_pk_bf16_f32 v67, v66, v67
	v_cvt_pk_bf16_f32 v66, v64, v65
	v_cvt_pk_bf16_f32 v65, v70, v71
	v_cvt_pk_bf16_f32 v64, v68, v69
	global_store_dwordx4 v[80:81], v[72:75], off
	global_store_dwordx4 v[80:81], v[64:67], off offset:16
	ds_write2_b32 v153, v60, v56 offset1:16
	ds_write2_b32 v153, v61, v57 offset0:68 offset1:84
	ds_write2_b32 v153, v62, v58 offset0:136 offset1:152
	ds_write2_b32 v153, v63, v59 offset0:204 offset1:220
	ds_write2_b32 v153, v52, v48 offset0:32 offset1:48
	ds_write2_b32 v153, v53, v49 offset0:100 offset1:116
	ds_write2_b32 v153, v54, v50 offset0:168 offset1:184
	ds_write2_b32 v153, v55, v51 offset0:236 offset1:252
	s_waitcnt lgkmcnt(0)
	ds_read_b128 v[60:63], v154
	ds_read_b128 v[56:59], v154 offset:16
	ds_read_b128 v[52:55], v154 offset:32
	ds_read_b128 v[48:51], v154 offset:48
	v_or_b32_e32 v80, 64, v152
	s_and_saveexec_b64 s[0:1], s[10:11]
	s_cbranch_execz .LBB0_765
	v_add_u32_e32 v64, s86, v80
	v_cmp_gt_i32_e64 s[12:13], s69, v64
	s_nop 1
	v_cndmask_b32_e64 v65, v191, v192, s[12:13]
	v_and_b32_e32 v64, v65, v64
	v_and_b32_e32 v65, 64, v181
	v_lshlrev_b32_e32 v96, 8, v64
	v_xor_b32_e32 v64, 2, v181
	v_add_u32_e32 v65, 64, v65
	v_cmp_lt_i32_e64 s[12:13], v64, v65
	v_lshl_add_u64 v[94:95], v[148:149], 0, v[96:97]
	s_nop 0
	v_cndmask_b32_e64 v64, v181, v64, s[12:13]
	v_lshlrev_b32_e32 v81, 2, v64
	global_load_dwordx4 v[64:67], v[94:95], off offset:48
	global_load_dwordx4 v[72:75], v[94:95], off offset:32
	global_load_dwordx4 v[82:85], v[94:95], off offset:16
	global_load_dwordx4 v[86:89], v[94:95], off
	global_load_dwordx4 v[68:71], v[94:95], off offset:176
	global_load_dwordx4 v[76:79], v[94:95], off offset:160
	global_load_dwordx4 v[90:93], v[94:95], off offset:144
	global_load_dwordx4 v[98:101], v[94:95], off offset:128
	s_waitcnt lgkmcnt(3)
	ds_bpermute_b32 v102, v81, v60
	ds_bpermute_b32 v103, v81, v61
	s_waitcnt vmcnt(0) lgkmcnt(0)
	v_pk_mul_f32 v[94:95], v[98:99], v[102:103]
	s_nop 0
	v_cndmask_b32_e64 v95, v95, -v95, vcc
	v_cndmask_b32_e64 v94, v94, -v94, vcc
	v_pk_fma_f32 v[60:61], v[60:61], v[86:87], v[94:95]
	ds_bpermute_b32 v86, v81, v62
	ds_bpermute_b32 v87, v81, v63
	s_waitcnt lgkmcnt(0)
	v_pk_mul_f32 v[86:87], v[100:101], v[86:87]
	s_nop 0
	v_cndmask_b32_e64 v87, v87, -v87, vcc
	v_cndmask_b32_e64 v86, v86, -v86, vcc
	v_pk_fma_f32 v[62:63], v[62:63], v[88:89], v[86:87]
	ds_bpermute_b32 v86, v81, v56
	ds_bpermute_b32 v87, v81, v57
	s_waitcnt lgkmcnt(0)
	v_pk_mul_f32 v[86:87], v[90:91], v[86:87]
	s_nop 0
	v_cndmask_b32_e64 v87, v87, -v87, vcc
	v_cndmask_b32_e64 v86, v86, -v86, vcc
	v_pk_fma_f32 v[56:57], v[56:57], v[82:83], v[86:87]
	ds_bpermute_b32 v82, v81, v58
	ds_bpermute_b32 v83, v81, v59
	s_waitcnt lgkmcnt(0)
	v_pk_mul_f32 v[82:83], v[92:93], v[82:83]
	s_nop 0
	v_cndmask_b32_e64 v83, v83, -v83, vcc
	v_cndmask_b32_e64 v82, v82, -v82, vcc
	v_pk_fma_f32 v[58:59], v[58:59], v[84:85], v[82:83]
	ds_bpermute_b32 v82, v81, v52
	ds_bpermute_b32 v83, v81, v53
	s_waitcnt lgkmcnt(0)
	v_pk_mul_f32 v[76:77], v[76:77], v[82:83]
	s_nop 0
	v_cndmask_b32_e64 v77, v77, -v77, vcc
	v_cndmask_b32_e64 v76, v76, -v76, vcc
	v_pk_fma_f32 v[52:53], v[52:53], v[72:73], v[76:77]
	ds_bpermute_b32 v72, v81, v54
	ds_bpermute_b32 v73, v81, v55
	s_waitcnt lgkmcnt(0)
	v_pk_mul_f32 v[72:73], v[78:79], v[72:73]
	s_nop 0
	v_cndmask_b32_e64 v73, v73, -v73, vcc
	v_cndmask_b32_e64 v72, v72, -v72, vcc
	v_pk_fma_f32 v[54:55], v[54:55], v[74:75], v[72:73]
	ds_bpermute_b32 v72, v81, v48
	ds_bpermute_b32 v73, v81, v49
	s_waitcnt lgkmcnt(0)
	v_pk_mul_f32 v[68:69], v[68:69], v[72:73]
	s_nop 0
	v_cndmask_b32_e64 v69, v69, -v69, vcc
	v_cndmask_b32_e64 v68, v68, -v68, vcc
	v_pk_fma_f32 v[48:49], v[48:49], v[64:65], v[68:69]
	ds_bpermute_b32 v64, v81, v50
	ds_bpermute_b32 v65, v81, v51
	s_waitcnt lgkmcnt(0)
	v_pk_mul_f32 v[64:65], v[70:71], v[64:65]
	s_nop 0
	v_cndmask_b32_e64 v65, v65, -v65, vcc
	v_cndmask_b32_e64 v64, v64, -v64, vcc
	v_pk_fma_f32 v[50:51], v[50:51], v[66:67], v[64:65]
; DI unsigned pack2(float a, float b) { return (unsigned)f2bf(a) | ((unsigned)f2bf(b) << 16); }
;   const int lane = tid & 63, wid = tid >> 6, fr = lane & 15, fq = lane >> 4;
;   float* stg = (float*)(smem + PATCH) + wid * (16 * 68);
;   asm volatile("" ::: "memory");
; #pragma unroll
;   for (int n = 0; n < 4; ++n)
; #pragma unroll
;     for (int j = 0; j < 4; ++j) stg[(fq * 4 + j) * 68 + n * 16 + fr] = am[n][j];
;   asm volatile("s_waitcnt lgkmcnt(0)" ::: "memory");
;   const float* rp = stg + (lane >> 2) * 68 + (lane & 3) * 16;
; #pragma unroll
;   for (int i = 0; i < 4; ++i) { f32x4 t = *(const f32x4*)(rp + i * 4); v[4 * i] = t[0]; v[4 * i + 1] = t[1]; v[4 * i + 2] = t[2]; v[4 * i + 3] = t[3]; }
;   asm volatile("" ::: "memory");
; }
; DI void store16_bf(bft* dst, const float (&v)[16]) {
;   u32x4 o0 = {pack2(v[0], v[1]), pack2(v[2], v[3]), pack2(v[4], v[5]), pack2(v[6], v[7])}, o1 = {pack2(v[8], v[9]), pack2(v[10], v[11]), pack2(v[12], v[13]), pack2(v[14], v[15])};
;   *(u32x4*)dst = o0; *(u32x4*)(dst + 8) = o1;
; DI void phase_upproj(const Params& p, int sg) {
;     ...
;       EPI256_BEGIN
;         const int cw = bcol + wc * 64; const bool is_rope = (cw % 192) == 128;
;         if (is_rope) { int pos = tok_pos(sg * 16384 + row); const int cg = lane & 3; const float* rp = rt + pos * 64 + (cg & 1) * 16;
; #pragma unroll
;           for (int i = 0; i < 16; ++i) { float c = rp[i], s = rp[32 + i]; float xo = __shfl_xor(v[i], 2); v[i] = cg < 2 ? v[i] * c - xo * s : xo * s + v[i] * c; } }
;         store16_bf(Q + (size_t)row * 1536 + col, v);
.LBB0_765:
	s_or_b64 exec, exec, s[0:1]
	s_waitcnt lgkmcnt(3)
	s_waitcnt lgkmcnt(2)
	v_cvt_pk_bf16_f32 v59, v58, v59
	v_cvt_pk_bf16_f32 v58, v56, v57
	v_cvt_pk_bf16_f32 v57, v62, v63
	v_cvt_pk_bf16_f32 v56, v60, v61
	s_waitcnt lgkmcnt(1)
	s_waitcnt lgkmcnt(0)
	v_mad_i64_i32 v[64:65], s[0:1], v80, s95, v[132:133]
	v_cvt_pk_bf16_f32 v51, v50, v51
	v_cvt_pk_bf16_f32 v50, v48, v49
	v_cvt_pk_bf16_f32 v49, v54, v55
	v_cvt_pk_bf16_f32 v48, v52, v53
	global_store_dwordx4 v[64:65], v[56:59], off
	global_store_dwordx4 v[64:65], v[48:51], off offset:16
	ds_write2_b32 v153, v44, v40 offset1:16
	ds_write2_b32 v153, v45, v41 offset0:68 offset1:84
	ds_write2_b32 v153, v46, v42 offset0:136 offset1:152
	ds_write2_b32 v153, v47, v43 offset0:204 offset1:220
	ds_write2_b32 v153, v36, v32 offset0:32 offset1:48
	ds_write2_b32 v153, v37, v33 offset0:100 offset1:116
	ds_write2_b32 v153, v38, v34 offset0:168 offset1:184
	ds_write2_b32 v153, v39, v35 offset0:236 offset1:252
	s_waitcnt lgkmcnt(0)
	ds_read_b128 v[44:47], v154
	ds_read_b128 v[40:43], v154 offset:16
	ds_read_b128 v[36:39], v154 offset:32
	ds_read_b128 v[32:35], v154 offset:48
	v_or_b32_e32 v64, 0x50, v152
	s_and_saveexec_b64 s[0:1], s[10:11]
	s_cbranch_execz .LBB0_767
	v_add_u32_e32 v48, s86, v64
	v_cmp_gt_i32_e64 s[12:13], s69, v48
	s_nop 1
	v_cndmask_b32_e64 v49, v193, v194, s[12:13]
	v_and_b32_e32 v48, v49, v48
	v_and_b32_e32 v49, 64, v181
	v_lshlrev_b32_e32 v96, 8, v48
	v_xor_b32_e32 v48, 2, v181
	v_add_u32_e32 v49, 64, v49
	v_cmp_lt_i32_e64 s[12:13], v48, v49
	v_lshl_add_u64 v[78:79], v[148:149], 0, v[96:97]
	s_nop 0
	v_cndmask_b32_e64 v48, v181, v48, s[12:13]
	v_lshlrev_b32_e32 v65, 2, v48
	global_load_dwordx4 v[48:51], v[78:79], off offset:48
	global_load_dwordx4 v[56:59], v[78:79], off offset:32
	global_load_dwordx4 v[66:69], v[78:79], off offset:16
	global_load_dwordx4 v[70:73], v[78:79], off
	global_load_dwordx4 v[52:55], v[78:79], off offset:176
	global_load_dwordx4 v[60:63], v[78:79], off offset:160
	global_load_dwordx4 v[74:77], v[78:79], off offset:144
	s_nop 0
	global_load_dwordx4 v[78:81], v[78:79], off offset:128
	s_waitcnt lgkmcnt(3)
	ds_bpermute_b32 v82, v65, v44
	ds_bpermute_b32 v83, v65, v45
	s_waitcnt vmcnt(0) lgkmcnt(0)
	v_pk_mul_f32 v[78:79], v[78:79], v[82:83]
	s_nop 0
	v_cndmask_b32_e64 v79, v79, -v79, vcc
	v_cndmask_b32_e64 v78, v78, -v78, vcc
	v_pk_fma_f32 v[44:45], v[44:45], v[70:71], v[78:79]
	ds_bpermute_b32 v70, v65, v46
	ds_bpermute_b32 v71, v65, v47
	s_waitcnt lgkmcnt(0)
	v_pk_mul_f32 v[70:71], v[80:81], v[70:71]
	s_nop 0
	v_cndmask_b32_e64 v71, v71, -v71, vcc
	v_cndmask_b32_e64 v70, v70, -v70, vcc
	v_pk_fma_f32 v[46:47], v[46:47], v[72:73], v[70:71]
	ds_bpermute_b32 v70, v65, v40
	ds_bpermute_b32 v71, v65, v41
	s_waitcnt lgkmcnt(0)
	v_pk_mul_f32 v[70:71], v[74:75], v[70:71]
	s_nop 0
	v_cndmask_b32_e64 v71, v71, -v71, vcc
	v_cndmask_b32_e64 v70, v70, -v70, vcc
	v_pk_fma_f32 v[40:41], v[40:41], v[66:67], v[70:71]
	ds_bpermute_b32 v66, v65, v42
	ds_bpermute_b32 v67, v65, v43
	s_waitcnt lgkmcnt(0)
	v_pk_mul_f32 v[66:67], v[76:77], v[66:67]
	s_nop 0
	v_cndmask_b32_e64 v67, v67, -v67, vcc
	v_cndmask_b32_e64 v66, v66, -v66, vcc
	v_pk_fma_f32 v[42:43], v[42:43], v[68:69], v[66:67]
	ds_bpermute_b32 v66, v65, v36
	ds_bpermute_b32 v67, v65, v37
	s_waitcnt lgkmcnt(0)
	v_pk_mul_f32 v[60:61], v[60:61], v[66:67]
	s_nop 0
	v_cndmask_b32_e64 v61, v61, -v61, vcc
	v_cndmask_b32_e64 v60, v60, -v60, vcc
	v_pk_fma_f32 v[36:37], v[36:37], v[56:57], v[60:61]
	ds_bpermute_b32 v56, v65, v38
	ds_bpermute_b32 v57, v65, v39
	s_waitcnt lgkmcnt(0)
	v_pk_mul_f32 v[56:57], v[62:63], v[56:57]
	s_nop 0
	v_cndmask_b32_e64 v57, v57, -v57, vcc
	v_cndmask_b32_e64 v56, v56, -v56, vcc
	v_pk_fma_f32 v[38:39], v[38:39], v[58:59], v[56:57]
	ds_bpermute_b32 v56, v65, v32
	ds_bpermute_b32 v57, v65, v33
	s_waitcnt lgkmcnt(0)
	v_pk_mul_f32 v[52:53], v[52:53], v[56:57]
	s_nop 0
	v_cndmask_b32_e64 v53, v53, -v53, vcc
	v_cndmask_b32_e64 v52, v52, -v52, vcc
	v_pk_fma_f32 v[32:33], v[32:33], v[48:49], v[52:53]
	ds_bpermute_b32 v48, v65, v34
	ds_bpermute_b32 v49, v65, v35
	s_waitcnt lgkmcnt(0)
	v_pk_mul_f32 v[48:49], v[54:55], v[48:49]
	s_nop 0
	v_cndmask_b32_e64 v49, v49, -v49, vcc
	v_cndmask_b32_e64 v48, v48, -v48, vcc
	v_pk_fma_f32 v[34:35], v[34:35], v[50:51], v[48:49]
; DI unsigned pack2(float a, float b) { return (unsigned)f2bf(a) | ((unsigned)f2bf(b) << 16); }
;   const int lane = tid & 63, wid = tid >> 6, fr = lane & 15, fq = lane >> 4;
;   float* stg = (float*)(smem + PATCH) + wid * (16 * 68);
;   asm volatile("" ::: "memory");
; #pragma unroll
;   for (int n = 0; n < 4; ++n)
; #pragma unroll
;     for (int j = 0; j < 4; ++j) stg[(fq * 4 + j) * 68 + n * 16 + fr] = am[n][j];
;   asm volatile("s_waitcnt lgkmcnt(0)" ::: "memory");
;   const float* rp = stg + (lane >> 2) * 68 + (lane & 3) * 16;
; #pragma unroll
;   for (int i = 0; i < 4; ++i) { f32x4 t = *(const f32x4*)(rp + i * 4); v[4 * i] = t[0]; v[4 * i + 1] = t[1]; v[4 * i + 2] = t[2]; v[4 * i + 3] = t[3]; }
;   asm volatile("" ::: "memory");
; }
; DI void store16_bf(bft* dst, const float (&v)[16]) {
;   u32x4 o0 = {pack2(v[0], v[1]), pack2(v[2], v[3]), pack2(v[4], v[5]), pack2(v[6], v[7])}, o1 = {pack2(v[8], v[9]), pack2(v[10], v[11]), pack2(v[12], v[13]), pack2(v[14], v[15])};
;   *(u32x4*)dst = o0; *(u32x4*)(dst + 8) = o1;
; DI void phase_upproj(const Params& p, int sg) {
;     ...
;       EPI256_BEGIN
;         const int cw = bcol + wc * 64; const bool is_rope = (cw % 192) == 128;
;         if (is_rope) { int pos = tok_pos(sg * 16384 + row); const int cg = lane & 3; const float* rp = rt + pos * 64 + (cg & 1) * 16;
; #pragma unroll
;           for (int i = 0; i < 16; ++i) { float c = rp[i], s = rp[32 + i]; float xo = __shfl_xor(v[i], 2); v[i] = cg < 2 ? v[i] * c - xo * s : xo * s + v[i] * c; } }
;         store16_bf(Q + (size_t)row * 1536 + col, v);
.LBB0_767:
	s_or_b64 exec, exec, s[0:1]
	s_waitcnt lgkmcnt(3)
	s_waitcnt lgkmcnt(2)
	v_cvt_pk_bf16_f32 v43, v42, v43
	v_cvt_pk_bf16_f32 v42, v40, v41
	v_cvt_pk_bf16_f32 v41, v46, v47
	v_cvt_pk_bf16_f32 v40, v44, v45
	s_waitcnt lgkmcnt(1)
	s_waitcnt lgkmcnt(0)
	v_mad_i64_i32 v[48:49], s[0:1], v64, s95, v[132:133]
	v_cvt_pk_bf16_f32 v35, v34, v35
	v_cvt_pk_bf16_f32 v34, v32, v33
	v_cvt_pk_bf16_f32 v33, v38, v39
	v_cvt_pk_bf16_f32 v32, v36, v37
	global_store_dwordx4 v[48:49], v[40:43], off
	global_store_dwordx4 v[48:49], v[32:35], off offset:16
	ds_write2_b32 v153, v28, v24 offset1:16
	ds_write2_b32 v153, v29, v25 offset0:68 offset1:84
	ds_write2_b32 v153, v30, v26 offset0:136 offset1:152
	ds_write2_b32 v153, v31, v27 offset0:204 offset1:220
	ds_write2_b32 v153, v20, v16 offset0:32 offset1:48
	ds_write2_b32 v153, v21, v17 offset0:100 offset1:116
	ds_write2_b32 v153, v22, v18 offset0:168 offset1:184
	ds_write2_b32 v153, v23, v19 offset0:236 offset1:252
	s_waitcnt lgkmcnt(0)
	ds_read_b128 v[28:31], v154
	ds_read_b128 v[24:27], v154 offset:16
	ds_read_b128 v[20:23], v154 offset:32
	ds_read_b128 v[16:19], v154 offset:48
	v_or_b32_e32 v48, 0x60, v152
	s_and_saveexec_b64 s[0:1], s[10:11]
	s_cbranch_execz .LBB0_769
	v_add_u32_e32 v32, s86, v48
	v_cmp_gt_i32_e64 s[12:13], s69, v32
	s_nop 1
	v_cndmask_b32_e64 v33, v195, v196, s[12:13]
	v_and_b32_e32 v32, v33, v32
	v_and_b32_e32 v33, 64, v181
	v_lshlrev_b32_e32 v96, 8, v32
	v_xor_b32_e32 v32, 2, v181
	v_add_u32_e32 v33, 64, v33
	v_cmp_lt_i32_e64 s[12:13], v32, v33
	v_lshl_add_u64 v[62:63], v[148:149], 0, v[96:97]
	s_nop 0
	v_cndmask_b32_e64 v32, v181, v32, s[12:13]
	v_lshlrev_b32_e32 v49, 2, v32
	global_load_dwordx4 v[32:35], v[62:63], off offset:48
	global_load_dwordx4 v[40:43], v[62:63], off offset:32
	global_load_dwordx4 v[50:53], v[62:63], off offset:16
	global_load_dwordx4 v[54:57], v[62:63], off
	global_load_dwordx4 v[36:39], v[62:63], off offset:176
	global_load_dwordx4 v[44:47], v[62:63], off offset:160
	global_load_dwordx4 v[58:61], v[62:63], off offset:144
	s_nop 0
	global_load_dwordx4 v[62:65], v[62:63], off offset:128
	s_waitcnt lgkmcnt(3)
	ds_bpermute_b32 v66, v49, v28
	ds_bpermute_b32 v67, v49, v29
	s_waitcnt vmcnt(0) lgkmcnt(0)
	v_pk_mul_f32 v[62:63], v[62:63], v[66:67]
	s_nop 0
	v_cndmask_b32_e64 v63, v63, -v63, vcc
	v_cndmask_b32_e64 v62, v62, -v62, vcc
	v_pk_fma_f32 v[28:29], v[28:29], v[54:55], v[62:63]
	ds_bpermute_b32 v54, v49, v30
	ds_bpermute_b32 v55, v49, v31
	s_waitcnt lgkmcnt(0)
	v_pk_mul_f32 v[54:55], v[64:65], v[54:55]
	s_nop 0
	v_cndmask_b32_e64 v55, v55, -v55, vcc
	v_cndmask_b32_e64 v54, v54, -v54, vcc
	v_pk_fma_f32 v[30:31], v[30:31], v[56:57], v[54:55]
	ds_bpermute_b32 v54, v49, v24
	ds_bpermute_b32 v55, v49, v25
	s_waitcnt lgkmcnt(0)
	v_pk_mul_f32 v[54:55], v[58:59], v[54:55]
	s_nop 0
	v_cndmask_b32_e64 v55, v55, -v55, vcc
	v_cndmask_b32_e64 v54, v54, -v54, vcc
	v_pk_fma_f32 v[24:25], v[24:25], v[50:51], v[54:55]
	ds_bpermute_b32 v50, v49, v26
	ds_bpermute_b32 v51, v49, v27
	s_waitcnt lgkmcnt(0)
	v_pk_mul_f32 v[50:51], v[60:61], v[50:51]
	s_nop 0
	v_cndmask_b32_e64 v51, v51, -v51, vcc
	v_cndmask_b32_e64 v50, v50, -v50, vcc
	v_pk_fma_f32 v[26:27], v[26:27], v[52:53], v[50:51]
	ds_bpermute_b32 v50, v49, v20
	ds_bpermute_b32 v51, v49, v21
	s_waitcnt lgkmcnt(0)
	v_pk_mul_f32 v[44:45], v[44:45], v[50:51]
	s_nop 0
	v_cndmask_b32_e64 v45, v45, -v45, vcc
	v_cndmask_b32_e64 v44, v44, -v44, vcc
	v_pk_fma_f32 v[20:21], v[20:21], v[40:41], v[44:45]
	ds_bpermute_b32 v40, v49, v22
	ds_bpermute_b32 v41, v49, v23
	s_waitcnt lgkmcnt(0)
	v_pk_mul_f32 v[40:41], v[46:47], v[40:41]
	s_nop 0
	v_cndmask_b32_e64 v41, v41, -v41, vcc
	v_cndmask_b32_e64 v40, v40, -v40, vcc
	v_pk_fma_f32 v[22:23], v[22:23], v[42:43], v[40:41]
	ds_bpermute_b32 v40, v49, v16
	ds_bpermute_b32 v41, v49, v17
	s_waitcnt lgkmcnt(0)
	v_pk_mul_f32 v[36:37], v[36:37], v[40:41]
	s_nop 0
	v_cndmask_b32_e64 v37, v37, -v37, vcc
	v_cndmask_b32_e64 v36, v36, -v36, vcc
	v_pk_fma_f32 v[16:17], v[16:17], v[32:33], v[36:37]
	ds_bpermute_b32 v32, v49, v18
	ds_bpermute_b32 v33, v49, v19
	s_waitcnt lgkmcnt(0)
	v_pk_mul_f32 v[32:33], v[38:39], v[32:33]
	s_nop 0
	v_cndmask_b32_e64 v33, v33, -v33, vcc
	v_cndmask_b32_e64 v32, v32, -v32, vcc
	v_pk_fma_f32 v[18:19], v[18:19], v[34:35], v[32:33]
; DI unsigned pack2(float a, float b) { return (unsigned)f2bf(a) | ((unsigned)f2bf(b) << 16); }
;   const int lane = tid & 63, wid = tid >> 6, fr = lane & 15, fq = lane >> 4;
;   float* stg = (float*)(smem + PATCH) + wid * (16 * 68);
;   asm volatile("" ::: "memory");
; #pragma unroll
;   for (int n = 0; n < 4; ++n)
; #pragma unroll
;     for (int j = 0; j < 4; ++j) stg[(fq * 4 + j) * 68 + n * 16 + fr] = am[n][j];
;   asm volatile("s_waitcnt lgkmcnt(0)" ::: "memory");
;   const float* rp = stg + (lane >> 2) * 68 + (lane & 3) * 16;
; #pragma unroll
;   for (int i = 0; i < 4; ++i) { f32x4 t = *(const f32x4*)(rp + i * 4); v[4 * i] = t[0]; v[4 * i + 1] = t[1]; v[4 * i + 2] = t[2]; v[4 * i + 3] = t[3]; }
;   asm volatile("" ::: "memory");
; }
; DI void store16_bf(bft* dst, const float (&v)[16]) {
;   u32x4 o0 = {pack2(v[0], v[1]), pack2(v[2], v[3]), pack2(v[4], v[5]), pack2(v[6], v[7])}, o1 = {pack2(v[8], v[9]), pack2(v[10], v[11]), pack2(v[12], v[13]), pack2(v[14], v[15])};
;   *(u32x4*)dst = o0; *(u32x4*)(dst + 8) = o1;
; DI void phase_upproj(const Params& p, int sg) {
;     ...
;       EPI256_BEGIN
;         const int cw = bcol + wc * 64; const bool is_rope = (cw % 192) == 128;
;         if (is_rope) { int pos = tok_pos(sg * 16384 + row); const int cg = lane & 3; const float* rp = rt + pos * 64 + (cg & 1) * 16;
; #pragma unroll
;           for (int i = 0; i < 16; ++i) { float c = rp[i], s = rp[32 + i]; float xo = __shfl_xor(v[i], 2); v[i] = cg < 2 ? v[i] * c - xo * s : xo * s + v[i] * c; } }
;         store16_bf(Q + (size_t)row * 1536 + col, v);
.LBB0_769:
	s_or_b64 exec, exec, s[0:1]
	s_waitcnt lgkmcnt(3)
	s_waitcnt lgkmcnt(2)
	v_cvt_pk_bf16_f32 v27, v26, v27
	v_cvt_pk_bf16_f32 v26, v24, v25
	v_cvt_pk_bf16_f32 v25, v30, v31
	v_cvt_pk_bf16_f32 v24, v28, v29
	s_waitcnt lgkmcnt(1)
	s_waitcnt lgkmcnt(0)
	v_mad_i64_i32 v[32:33], s[0:1], v48, s95, v[132:133]
	v_cvt_pk_bf16_f32 v19, v18, v19
	v_cvt_pk_bf16_f32 v18, v16, v17
	v_cvt_pk_bf16_f32 v17, v22, v23
	v_cvt_pk_bf16_f32 v16, v20, v21
	global_store_dwordx4 v[32:33], v[24:27], off
	global_store_dwordx4 v[32:33], v[16:19], off offset:16
	ds_write2_b32 v153, v12, v8 offset1:16
	ds_write2_b32 v153, v13, v9 offset0:68 offset1:84
	ds_write2_b32 v153, v14, v10 offset0:136 offset1:152
	ds_write2_b32 v153, v15, v11 offset0:204 offset1:220
	ds_write2_b32 v153, v4, v0 offset0:32 offset1:48
	ds_write2_b32 v153, v5, v1 offset0:100 offset1:116
	ds_write2_b32 v153, v6, v2 offset0:168 offset1:184
	ds_write2_b32 v153, v7, v3 offset0:236 offset1:252
	s_waitcnt lgkmcnt(0)
	ds_read_b128 v[12:15], v154
	ds_read_b128 v[8:11], v154 offset:16
	ds_read_b128 v[4:7], v154 offset:32
	ds_read_b128 v[0:3], v154 offset:48
	v_or_b32_e32 v32, 0x70, v152
	s_and_saveexec_b64 s[0:1], s[10:11]
	s_cbranch_execz .LBB0_693
	v_add_u32_e32 v16, s86, v32
	v_cmp_gt_i32_e64 s[10:11], s69, v16
	s_nop 1
	v_cndmask_b32_e64 v17, v197, v198, s[10:11]
	v_and_b32_e32 v16, v17, v16
	v_and_b32_e32 v17, 64, v181
	v_lshlrev_b32_e32 v96, 8, v16
	v_xor_b32_e32 v16, 2, v181
	v_add_u32_e32 v17, 64, v17
	v_cmp_lt_i32_e64 s[10:11], v16, v17
	v_lshl_add_u64 v[46:47], v[148:149], 0, v[96:97]
	s_nop 0
	v_cndmask_b32_e64 v16, v181, v16, s[10:11]
	v_lshlrev_b32_e32 v33, 2, v16
	global_load_dwordx4 v[16:19], v[46:47], off offset:48
	global_load_dwordx4 v[24:27], v[46:47], off offset:32
	global_load_dwordx4 v[34:37], v[46:47], off offset:16
	global_load_dwordx4 v[38:41], v[46:47], off
	global_load_dwordx4 v[20:23], v[46:47], off offset:176
	global_load_dwordx4 v[28:31], v[46:47], off offset:160
	global_load_dwordx4 v[42:45], v[46:47], off offset:144
	s_nop 0
	global_load_dwordx4 v[46:49], v[46:47], off offset:128
	s_waitcnt lgkmcnt(3)
	ds_bpermute_b32 v50, v33, v12
	ds_bpermute_b32 v51, v33, v13
	s_waitcnt vmcnt(0) lgkmcnt(0)
	v_pk_mul_f32 v[46:47], v[46:47], v[50:51]
	s_nop 0
	v_cndmask_b32_e64 v47, v47, -v47, vcc
	v_cndmask_b32_e64 v46, v46, -v46, vcc
	v_pk_fma_f32 v[12:13], v[12:13], v[38:39], v[46:47]
	ds_bpermute_b32 v38, v33, v14
	ds_bpermute_b32 v39, v33, v15
	s_waitcnt lgkmcnt(0)
	v_pk_mul_f32 v[38:39], v[48:49], v[38:39]
	s_nop 0
	v_cndmask_b32_e64 v39, v39, -v39, vcc
	v_cndmask_b32_e64 v38, v38, -v38, vcc
	v_pk_fma_f32 v[14:15], v[14:15], v[40:41], v[38:39]
	ds_bpermute_b32 v38, v33, v8
	ds_bpermute_b32 v39, v33, v9
	s_waitcnt lgkmcnt(0)
	v_pk_mul_f32 v[38:39], v[42:43], v[38:39]
	s_nop 0
	v_cndmask_b32_e64 v39, v39, -v39, vcc
	v_cndmask_b32_e64 v38, v38, -v38, vcc
	v_pk_fma_f32 v[8:9], v[8:9], v[34:35], v[38:39]
	ds_bpermute_b32 v34, v33, v10
	ds_bpermute_b32 v35, v33, v11
	s_waitcnt lgkmcnt(0)
	v_pk_mul_f32 v[34:35], v[44:45], v[34:35]
	s_nop 0
	v_cndmask_b32_e64 v35, v35, -v35, vcc
	v_cndmask_b32_e64 v34, v34, -v34, vcc
	v_pk_fma_f32 v[10:11], v[10:11], v[36:37], v[34:35]
	ds_bpermute_b32 v34, v33, v4
	ds_bpermute_b32 v35, v33, v5
	s_waitcnt lgkmcnt(0)
	v_pk_mul_f32 v[28:29], v[28:29], v[34:35]
	s_nop 0
	v_cndmask_b32_e64 v29, v29, -v29, vcc
	v_cndmask_b32_e64 v28, v28, -v28, vcc
	v_pk_fma_f32 v[4:5], v[4:5], v[24:25], v[28:29]
	ds_bpermute_b32 v24, v33, v6
	ds_bpermute_b32 v25, v33, v7
	s_waitcnt lgkmcnt(0)
	v_pk_mul_f32 v[24:25], v[30:31], v[24:25]
	s_nop 0
	v_cndmask_b32_e64 v25, v25, -v25, vcc
	v_cndmask_b32_e64 v24, v24, -v24, vcc
	v_pk_fma_f32 v[6:7], v[6:7], v[26:27], v[24:25]
	ds_bpermute_b32 v24, v33, v0
	ds_bpermute_b32 v25, v33, v1
	s_waitcnt lgkmcnt(0)
	v_pk_mul_f32 v[20:21], v[20:21], v[24:25]
	s_nop 0
	v_cndmask_b32_e64 v21, v21, -v21, vcc
	v_cndmask_b32_e64 v20, v20, -v20, vcc
	v_pk_fma_f32 v[0:1], v[0:1], v[16:17], v[20:21]
	ds_bpermute_b32 v16, v33, v2
	ds_bpermute_b32 v17, v33, v3
	s_waitcnt lgkmcnt(0)
	v_pk_mul_f32 v[16:17], v[22:23], v[16:17]
	s_nop 0
	v_cndmask_b32_e64 v17, v17, -v17, vcc
	v_cndmask_b32_e64 v16, v16, -v16, vcc
	v_pk_fma_f32 v[2:3], v[2:3], v[18:19], v[16:17]
	s_branch .LBB0_693

; DI unsigned pack2(float a, float b) { return (unsigned)f2bf(a) | ((unsigned)f2bf(b) << 16); }
; DI float sigm(float x) { return 1.f / (1.f + __expf(-x)); }
;   const int lane = tid & 63, wid = tid >> 6, fr = lane & 15, fq = lane >> 4;
;   float* stg = (float*)(smem + PATCH) + wid * (16 * 68);
;   asm volatile("" ::: "memory");
; #pragma unroll
;   for (int n = 0; n < 4; ++n)
; #pragma unroll
;     for (int j = 0; j < 4; ++j) stg[(fq * 4 + j) * 68 + n * 16 + fr] = am[n][j];
;   asm volatile("s_waitcnt lgkmcnt(0)" ::: "memory");
;   const float* rp = stg + (lane >> 2) * 68 + (lane & 3) * 16;
; #pragma unroll
;   for (int i = 0; i < 4; ++i) { f32x4 t = *(const f32x4*)(rp + i * 4); v[4 * i] = t[0]; v[4 * i + 1] = t[1]; v[4 * i + 2] = t[2]; v[4 * i + 3] = t[3]; }
;   asm volatile("" ::: "memory");
; }
; DI void store16_bf(bft* dst, const float (&v)[16]) {
;   u32x4 o0 = {pack2(v[0], v[1]), pack2(v[2], v[3]), pack2(v[4], v[5]), pack2(v[6], v[7])}, o1 = {pack2(v[8], v[9]), pack2(v[10], v[11]), pack2(v[12], v[13]), pack2(v[14], v[15])};
;   *(u32x4*)dst = o0; *(u32x4*)(dst + 8) = o1;
; }
; DI void load16_bf(const bft* src, float (&v)[16]) {
;   u32x4 w0 = *(const u32x4*)src, w1 = *(const u32x4*)(src + 8);
; #pragma unroll
;   for (int i = 0; i < 4; ++i) { v[2 * i] = __uint_as_float(w0[i] << 16); v[2 * i + 1] = __uint_as_float(w0[i] & 0xffff0000u); v[8 + 2 * i] = __uint_as_float(w1[i] << 16); v[8 + 2 * i + 1] = __uint_as_float(w1[i] & 0xffff0000u); }
; }
; DI void phase_glu(const Params& p) {
;     ...
;     float b[16]; load16_f(p.s5_glu_b + bcol + ((tid >> 6) & 3) * 64 + (tid & 3) * 16, b);
;     EPI256_BEGIN
;       float y[16], g[16]; load16_bf(ys + (size_t)row * LDP + col, y); bft* gp = G0 + (size_t)row * 2048 + col; load16_bf(gp, g);
; #pragma unroll
;       for (int i = 0; i < 16; ++i) v[i] = y[i] * sigm(v[i] + b[i]) * g[i];
;       store16_bf(gp, v);
.LBB0_892:
	s_lshl_b32 s0, s26, 2
	s_add_u32 s0, s6, s0
	v_and_b32_e32 v148, 0xc0, v165
	s_addc_u32 s1, s7, 0
	v_lshlrev_b32_e32 v0, 2, v148
	v_and_b32_e32 v149, 48, v166
	v_lshl_add_u64 v[2:3], s[0:1], 0, v[0:1]
	v_lshlrev_b32_e32 v0, 2, v149
	v_lshl_add_u64 v[2:3], v[2:3], 0, v[0:1]
	s_waitcnt vmcnt(0)
	s_barrier
	global_load_dwordx4 v[48:51], v[2:3], off
	global_load_dwordx4 v[44:47], v[2:3], off offset:16
	global_load_dwordx4 v[24:27], v[2:3], off offset:32
	global_load_dwordx4 v[20:23], v[2:3], off offset:48
	v_lshrrev_b32_e32 v2, 6, v165
	v_lshrrev_b32_e32 v150, 2, v165
	v_and_b32_e32 v3, 15, v165
	v_mul_lo_u32 v2, v2, s23
	v_and_b32_e32 v150, 12, v150
	v_bfe_u32 v151, v165, 2, 4
	v_ashrrev_i32_e32 v152, 1, v165
	v_lshlrev_b32_e32 v3, 2, v3
	v_or3_b32 v148, v148, s26, v149
	v_add_u32_e32 v149, s33, v2
	v_mul_u32_u24_e32 v2, 0x110, v150
	v_mul_u32_u24_e32 v153, 0x110, v151
	v_and_b32_e32 v152, 0xffffff80, v152
	v_add3_u32 v155, v149, v3, v2
	v_add_u32_e32 v150, s25, v152
	v_add3_u32 v154, v149, v0, v153
	v_lshlrev_b32_e32 v0, 1, v148
	ds_write2_b32 v155, v144, v140 offset1:16
	ds_write2_b32 v155, v145, v141 offset0:68 offset1:84
	ds_write2_b32 v155, v146, v142 offset0:136 offset1:152
	ds_write2_b32 v155, v147, v143 offset0:204 offset1:220
	ds_write2_b32 v155, v136, v132 offset0:32 offset1:48
	ds_write2_b32 v155, v137, v133 offset0:100 offset1:116
	ds_write2_b32 v155, v138, v134 offset0:168 offset1:184
	ds_write2_b32 v155, v139, v135 offset0:236 offset1:252
	v_or_b32_e32 v2, v150, v151
	v_lshl_add_u64 v[148:149], s[8:9], 0, v[0:1]
	s_waitcnt lgkmcnt(0)
	v_ashrrev_i32_e32 v3, 31, v2
	v_mad_i64_i32 v[132:133], s[0:1], v2, s4, v[148:149]
	ds_read_b128 v[144:147], v154
	ds_read_b128 v[150:153], v154 offset:16
	ds_read_b128 v[156:159], v154 offset:32
	ds_read_b128 v[160:163], v154 offset:48
	global_load_dwordx4 v[166:169], v[132:133], off
	v_lshl_add_u64 v[140:141], s[10:11], 0, v[0:1]
	v_lshlrev_b64 v[134:135], 12, v[2:3]
	v_lshl_add_u64 v[142:143], v[140:141], 0, v[134:135]
	global_load_dwordx4 v[170:173], v[142:143], off
	global_load_dwordx4 v[136:139], v[132:133], off offset:16
	s_nop 0
	global_load_dwordx4 v[132:135], v[142:143], off offset:16
	s_add_i32 s2, s2, 1
	s_add_i32 s3, s3, 1
	s_waitcnt vmcnt(7) lgkmcnt(3)
	v_add_f32_e32 v0, v48, v144
	v_add_f32_e32 v3, v49, v145
	v_add_f32_e32 v144, v50, v146
	v_add_f32_e32 v145, v51, v147
	s_waitcnt vmcnt(6) lgkmcnt(2)
	v_add_f32_e32 v146, v44, v150
	v_add_f32_e32 v147, v45, v151
	v_add_f32_e32 v150, v46, v152
	v_add_f32_e32 v151, v47, v153
	s_waitcnt vmcnt(5) lgkmcnt(1)
	v_add_f32_e32 v153, v25, v157
	v_mul_f32_e32 v0, 0xbfb8aa3b, v0
	v_add_f32_e32 v152, v24, v156
	v_mul_f32_e32 v150, 0xbfb8aa3b, v150
	v_exp_f32_e32 v156, v0
	v_mul_f32_e32 v0, 0xbfb8aa3b, v153
	v_exp_f32_e32 v177, v150
	v_exp_f32_e32 v150, v0
	v_add_f32_e32 v0, v26, v158
	v_mul_f32_e32 v0, 0xbfb8aa3b, v0
	v_exp_f32_e32 v153, v0
	v_add_f32_e32 v0, v27, v159
	v_mul_f32_e32 v151, 0xbfb8aa3b, v151
	v_mul_f32_e32 v0, 0xbfb8aa3b, v0
	v_exp_f32_e32 v179, v151
	v_exp_f32_e32 v151, v0
	s_waitcnt vmcnt(4) lgkmcnt(0)
	v_add_f32_e32 v0, v20, v160
	v_mul_f32_e32 v146, 0xbfb8aa3b, v146
	v_mul_f32_e32 v0, 0xbfb8aa3b, v0
	v_mul_f32_e32 v144, 0xbfb8aa3b, v144
	v_exp_f32_e32 v176, v146
	v_exp_f32_e32 v146, v0
	v_add_f32_e32 v0, v21, v161
	v_exp_f32_e32 v157, v144
	v_mul_f32_e32 v0, 0xbfb8aa3b, v0
	v_exp_f32_e32 v144, v0
	v_add_f32_e32 v0, v22, v162
	v_mul_f32_e32 v147, 0xbfb8aa3b, v147
	v_mul_f32_e32 v0, 0xbfb8aa3b, v0
	v_exp_f32_e32 v178, v147
	v_exp_f32_e32 v147, v0
	v_add_f32_e32 v0, v23, v163
	v_mul_f32_e32 v145, 0xbfb8aa3b, v145
	v_mul_f32_e32 v0, 0xbfb8aa3b, v0
	v_pk_add_f32 v[156:157], v[156:157], 1.0 op_sel_hi:[1,0]
	v_mul_f32_e32 v3, 0xbfb8aa3b, v3
	v_exp_f32_e32 v175, v145
	v_exp_f32_e32 v145, v0
	v_exp_f32_e32 v174, v3
	s_waitcnt vmcnt(3)
	v_lshlrev_b32_e32 v158, 16, v166
	v_and_b32_e32 v160, 0xffff0000, v166
	s_waitcnt vmcnt(2)
	v_lshlrev_b32_e32 v162, 16, v170
	v_and_b32_e32 v166, 0xffff0000, v170
	v_lshlrev_b32_e32 v159, 16, v167
	v_and_b32_e32 v161, 0xffff0000, v167
	v_lshlrev_b32_e32 v163, 16, v171
	v_and_b32_e32 v167, 0xffff0000, v171
	v_rcp_f32_e32 v157, v157
	v_mul_f32_e32 v152, 0xbfb8aa3b, v152
	v_pk_add_f32 v[170:171], v[174:175], 1.0 op_sel_hi:[1,0]
	v_rcp_f32_e32 v156, v156
	s_nop 0
	v_pk_mul_f32 v[156:157], v[156:157], v[158:159]
	v_exp_f32_e32 v152, v152
	v_pk_mul_f32 v[156:157], v[156:157], v[162:163]
	v_rcp_f32_e32 v159, v171
	v_and_b32_e32 v171, 0xffff0000, v173
	v_rcp_f32_e32 v158, v170
	s_nop 0
	v_pk_mul_f32 v[158:159], v[158:159], v[160:161]
	v_lshlrev_b32_e32 v161, 16, v169
	v_lshlrev_b32_e32 v160, 16, v168
	v_and_b32_e32 v163, 0xffff0000, v169
	v_and_b32_e32 v162, 0xffff0000, v168
	v_pk_add_f32 v[168:169], v[176:177], 1.0 op_sel_hi:[1,0]
	v_pk_mul_f32 v[158:159], v[158:159], v[166:167]
	v_lshlrev_b32_e32 v166, 16, v172
	v_and_b32_e32 v170, 0xffff0000, v172
	v_lshlrev_b32_e32 v167, 16, v173
	v_rcp_f32_e32 v169, v169
	v_pk_add_f32 v[152:153], v[152:153], 1.0 op_sel_hi:[1,0]
	v_pk_add_f32 v[172:173], v[178:179], 1.0 op_sel_hi:[1,0]
	v_rcp_f32_e32 v168, v168
	s_nop 0
	v_pk_mul_f32 v[160:161], v[168:169], v[160:161]
	v_pk_add_f32 v[150:151], v[150:151], 1.0 op_sel_hi:[1,0]
	v_pk_mul_f32 v[160:161], v[160:161], v[166:167]
	v_rcp_f32_e32 v167, v173
	v_pk_add_f32 v[146:147], v[146:147], 1.0 op_sel_hi:[1,0]
	v_rcp_f32_e32 v166, v172
	s_nop 0
	v_pk_mul_f32 v[162:163], v[166:167], v[162:163]
	v_bfe_u32 v165, v159, 16, 1
	v_pk_mul_f32 v[162:163], v[162:163], v[170:171]
	v_bfe_u32 v166, v158, 16, 1
	v_add3_u32 v165, v159, v165, s24
	v_bfe_u32 v159, v157, 16, 1
	v_add3_u32 v166, v158, v166, s24
	v_bfe_u32 v158, v156, 16, 1
	v_add3_u32 v157, v157, v159, s24
	v_add3_u32 v156, v156, v158, s24
	v_cvt_pk_bf16_f32 v159, v161, v163
	v_cvt_pk_bf16_f32 v158, v160, v162
	v_lshrrev_b32_e32 v157, 16, v157
	v_and_or_b32 v157, v165, s22, v157
	v_lshrrev_b32_e32 v156, 16, v156
	v_and_or_b32 v156, v166, s22, v156
	v_rcp_f32_e32 v153, v153
	s_waitcnt vmcnt(1)
; DI unsigned pack2(float a, float b) { return (unsigned)f2bf(a) | ((unsigned)f2bf(b) << 16); }
; DI float sigm(float x) { return 1.f / (1.f + __expf(-x)); }
; DI void store16_bf(bft* dst, const float (&v)[16]) {
;   u32x4 o0 = {pack2(v[0], v[1]), pack2(v[2], v[3]), pack2(v[4], v[5]), pack2(v[6], v[7])}, o1 = {pack2(v[8], v[9]), pack2(v[10], v[11]), pack2(v[12], v[13]), pack2(v[14], v[15])};
;   *(u32x4*)dst = o0; *(u32x4*)(dst + 8) = o1;
; }
; DI void load16_bf(const bft* src, float (&v)[16]) {
;   u32x4 w0 = *(const u32x4*)src, w1 = *(const u32x4*)(src + 8);
; #pragma unroll
;   for (int i = 0; i < 4; ++i) { v[2 * i] = __uint_as_float(w0[i] << 16); v[2 * i + 1] = __uint_as_float(w0[i] & 0xffff0000u); v[8 + 2 * i] = __uint_as_float(w1[i] << 16); v[8 + 2 * i + 1] = __uint_as_float(w1[i] & 0xffff0000u); }
; }
; DI void phase_glu(const Params& p) {
;     ...
;     float b[16]; load16_f(p.s5_glu_b + bcol + ((tid >> 6) & 3) * 64 + (tid & 3) * 16, b);
;     EPI256_BEGIN
;       float y[16], g[16]; load16_bf(ys + (size_t)row * LDP + col, y); bft* gp = G0 + (size_t)row * 2048 + col; load16_bf(gp, g);
; #pragma unroll
;       for (int i = 0; i < 16; ++i) v[i] = y[i] * sigm(v[i] + b[i]) * g[i];
;       store16_bf(gp, v);
	v_lshlrev_b32_e32 v161, 16, v137
	v_rcp_f32_e32 v152, v152
	v_lshlrev_b32_e32 v160, 16, v136
	v_pk_mul_f32 v[152:153], v[152:153], v[160:161]
	v_rcp_f32_e32 v151, v151
	s_waitcnt vmcnt(0)
	v_lshlrev_b32_e32 v163, 16, v133
	v_lshlrev_b32_e32 v162, 16, v132
	v_pk_mul_f32 v[152:153], v[152:153], v[162:163]
	v_rcp_f32_e32 v150, v150
	v_pk_add_f32 v[144:145], v[144:145], 1.0 op_sel_hi:[1,0]
	v_and_b32_e32 v137, 0xffff0000, v137
	v_and_b32_e32 v136, 0xffff0000, v136
	v_rcp_f32_e32 v147, v147
	v_and_b32_e32 v133, 0xffff0000, v133
	v_div_scale_f32 v3, s[0:1], v145, v145, 1.0
	v_rcp_f32_e32 v160, v3
	v_and_b32_e32 v132, 0xffff0000, v132
	v_pk_mul_f32 v[136:137], v[150:151], v[136:137]
	v_rcp_f32_e32 v146, v146
	v_fma_f32 v0, -v3, v160, 1.0
	v_pk_mul_f32 v[132:133], v[136:137], v[132:133]
	v_lshlrev_b32_e32 v137, 16, v139
	v_lshlrev_b32_e32 v136, 16, v138
	v_fmac_f32_e32 v160, v0, v160
	v_div_scale_f32 v0, vcc, 1.0, v145, 1.0
	v_pk_mul_f32 v[136:137], v[146:147], v[136:137]
	v_mul_f32_e32 v146, v0, v160
	v_fma_f32 v147, -v3, v146, v0
	v_fmac_f32_e32 v146, v147, v160
	v_fma_f32 v0, -v3, v146, v0
	v_div_scale_f32 v3, s[0:1], v144, v144, 1.0
	v_rcp_f32_e32 v147, v3
	v_div_fmas_f32 v0, v0, v160, v146
	v_div_fixup_f32 v145, v0, v145, 1.0
	v_lshlrev_b32_e32 v151, 16, v135
	v_fma_f32 v0, -v3, v147, 1.0
	v_fmac_f32_e32 v147, v0, v147
	v_div_scale_f32 v0, vcc, 1.0, v144, 1.0
	v_lshlrev_b32_e32 v150, 16, v134
	v_mul_f32_e32 v146, v0, v147
	v_pk_mul_f32 v[136:137], v[136:137], v[150:151]
	v_fma_f32 v150, -v3, v146, v0
	v_fmac_f32_e32 v146, v150, v147
	v_fma_f32 v0, -v3, v146, v0
	v_div_fmas_f32 v0, v0, v147, v146
	v_and_b32_e32 v139, 0xffff0000, v139
	v_and_b32_e32 v138, 0xffff0000, v138
	v_div_fixup_f32 v144, v0, v144, 1.0
	v_and_b32_e32 v135, 0xffff0000, v135
	v_and_b32_e32 v134, 0xffff0000, v134
	v_pk_mul_f32 v[138:139], v[144:145], v[138:139]
	s_nop 0
	v_pk_mul_f32 v[134:135], v[138:139], v[134:135]
	v_bfe_u32 v0, v135, 16, 1
	v_bfe_u32 v3, v134, 16, 1
	v_add3_u32 v3, v134, v3, s24
	v_add3_u32 v0, v135, v0, s24
	v_bfe_u32 v138, v136, 16, 1
	v_bfe_u32 v139, v137, 16, 1
	v_add3_u32 v137, v137, v139, s24
	v_add3_u32 v136, v136, v138, s24
	v_lshrrev_b32_e32 v134, 16, v136
	v_lshrrev_b32_e32 v135, 16, v137
	v_and_or_b32 v135, v0, s22, v135
	v_and_or_b32 v134, v3, s22, v134
	v_cvt_pk_bf16_f32 v133, v153, v133
	v_cvt_pk_bf16_f32 v132, v152, v132
	global_store_dwordx4 v[142:143], v[156:159], off
	global_store_dwordx4 v[142:143], v[132:135], off offset:16
	ds_write2_b32 v155, v128, v124 offset1:16
	ds_write2_b32 v155, v129, v125 offset0:68 offset1:84
	ds_write2_b32 v155, v130, v126 offset0:136 offset1:152
	ds_write2_b32 v155, v131, v127 offset0:204 offset1:220
	ds_write2_b32 v155, v120, v116 offset0:32 offset1:48
	ds_write2_b32 v155, v121, v117 offset0:100 offset1:116
	ds_write2_b32 v155, v122, v118 offset0:168 offset1:184
	ds_write2_b32 v155, v123, v119 offset0:236 offset1:252
	s_waitcnt lgkmcnt(0)
	v_or_b32_e32 v116, 16, v2
	ds_read_b128 v[126:129], v154
	ds_read_b128 v[130:133], v154 offset:16
	ds_read_b128 v[134:137], v154 offset:32
	ds_read_b128 v[142:145], v154 offset:48
	v_mad_i64_i32 v[118:119], s[0:1], v116, s4, v[148:149]
	global_load_dwordx4 v[150:153], v[118:119], off
	v_ashrrev_i32_e32 v117, 31, v116
	v_lshlrev_b64 v[116:117], 12, v[116:117]
	v_lshl_add_u64 v[124:125], v[140:141], 0, v[116:117]
	global_load_dwordx4 v[156:159], v[124:125], off
	global_load_dwordx4 v[120:123], v[118:119], off offset:16
	s_nop 0
	global_load_dwordx4 v[116:119], v[124:125], off offset:16
	s_waitcnt lgkmcnt(3)
	v_add_f32_e32 v0, v48, v126
	v_mul_f32_e32 v0, 0xbfb8aa3b, v0
	v_exp_f32_e32 v138, v0
	v_add_f32_e32 v0, v49, v127
	v_mul_f32_e32 v0, 0xbfb8aa3b, v0
	v_exp_f32_e32 v146, v0
	v_add_f32_e32 v0, v50, v128
	v_mul_f32_e32 v0, 0xbfb8aa3b, v0
	v_exp_f32_e32 v139, v0
	v_add_f32_e32 v0, v51, v129
	v_mul_f32_e32 v0, 0xbfb8aa3b, v0
	v_exp_f32_e32 v147, v0
	s_waitcnt lgkmcnt(2)
	v_add_f32_e32 v0, v44, v130
	v_mul_f32_e32 v0, 0xbfb8aa3b, v0
	v_exp_f32_e32 v160, v0
	v_add_f32_e32 v0, v45, v131
	v_mul_f32_e32 v0, 0xbfb8aa3b, v0
	v_exp_f32_e32 v162, v0
	v_add_f32_e32 v0, v46, v132
	v_mul_f32_e32 v0, 0xbfb8aa3b, v0
	v_exp_f32_e32 v161, v0
	v_add_f32_e32 v0, v47, v133
	v_mul_f32_e32 v0, 0xbfb8aa3b, v0
	v_exp_f32_e32 v163, v0
	s_waitcnt lgkmcnt(1)
	v_add_f32_e32 v0, v24, v134
	v_mul_f32_e32 v0, 0xbfb8aa3b, v0
	v_exp_f32_e32 v132, v0
	v_add_f32_e32 v0, v25, v135
	v_mul_f32_e32 v0, 0xbfb8aa3b, v0
	v_exp_f32_e32 v130, v0
	v_add_f32_e32 v0, v26, v136
	v_mul_f32_e32 v0, 0xbfb8aa3b, v0
	v_exp_f32_e32 v133, v0
	v_add_f32_e32 v0, v27, v137
	v_mul_f32_e32 v0, 0xbfb8aa3b, v0
	v_exp_f32_e32 v131, v0
	s_waitcnt lgkmcnt(0)
	v_add_f32_e32 v0, v20, v142
	v_mul_f32_e32 v0, 0xbfb8aa3b, v0
	v_exp_f32_e32 v128, v0
	v_add_f32_e32 v0, v21, v143
	v_mul_f32_e32 v0, 0xbfb8aa3b, v0
	v_exp_f32_e32 v126, v0
	v_add_f32_e32 v0, v22, v144
	v_mul_f32_e32 v0, 0xbfb8aa3b, v0
	v_exp_f32_e32 v129, v0
	v_add_f32_e32 v0, v23, v145
	v_mul_f32_e32 v0, 0xbfb8aa3b, v0
	v_pk_add_f32 v[138:139], v[138:139], 1.0 op_sel_hi:[1,0]
	v_exp_f32_e32 v127, v0
	v_pk_add_f32 v[146:147], v[146:147], 1.0 op_sel_hi:[1,0]
	v_pk_add_f32 v[132:133], v[132:133], 1.0 op_sel_hi:[1,0]
	v_pk_add_f32 v[130:131], v[130:131], 1.0 op_sel_hi:[1,0]
	v_pk_add_f32 v[128:129], v[128:129], 1.0 op_sel_hi:[1,0]
	v_pk_add_f32 v[126:127], v[126:127], 1.0 op_sel_hi:[1,0]
	s_waitcnt vmcnt(3)
	v_lshlrev_b32_e32 v134, 16, v150
	v_and_b32_e32 v136, 0xffff0000, v150
	v_lshlrev_b32_e32 v135, 16, v151
	v_and_b32_e32 v137, 0xffff0000, v151
	s_waitcnt vmcnt(2)
; DI unsigned pack2(float a, float b) { return (unsigned)f2bf(a) | ((unsigned)f2bf(b) << 16); }
; DI float sigm(float x) { return 1.f / (1.f + __expf(-x)); }
; DI void store16_bf(bft* dst, const float (&v)[16]) {
;   u32x4 o0 = {pack2(v[0], v[1]), pack2(v[2], v[3]), pack2(v[4], v[5]), pack2(v[6], v[7])}, o1 = {pack2(v[8], v[9]), pack2(v[10], v[11]), pack2(v[12], v[13]), pack2(v[14], v[15])};
;   *(u32x4*)dst = o0; *(u32x4*)(dst + 8) = o1;
; }
; DI void load16_bf(const bft* src, float (&v)[16]) {
;   u32x4 w0 = *(const u32x4*)src, w1 = *(const u32x4*)(src + 8);
; #pragma unroll
;   for (int i = 0; i < 4; ++i) { v[2 * i] = __uint_as_float(w0[i] << 16); v[2 * i + 1] = __uint_as_float(w0[i] & 0xffff0000u); v[8 + 2 * i] = __uint_as_float(w1[i] << 16); v[8 + 2 * i + 1] = __uint_as_float(w1[i] & 0xffff0000u); }
; }
; DI void phase_glu(const Params& p) {
;     ...
;     float b[16]; load16_f(p.s5_glu_b + bcol + ((tid >> 6) & 3) * 64 + (tid & 3) * 16, b);
;     EPI256_BEGIN
;       float y[16], g[16]; load16_bf(ys + (size_t)row * LDP + col, y); bft* gp = G0 + (size_t)row * 2048 + col; load16_bf(gp, g);
; #pragma unroll
;       for (int i = 0; i < 16; ++i) v[i] = y[i] * sigm(v[i] + b[i]) * g[i];
;       store16_bf(gp, v);
	v_lshlrev_b32_e32 v142, 16, v156
	v_and_b32_e32 v144, 0xffff0000, v156
	v_rcp_f32_e32 v139, v139
	v_lshlrev_b32_e32 v143, 16, v157
	v_rcp_f32_e32 v138, v138
	s_nop 0
	v_pk_mul_f32 v[134:135], v[138:139], v[134:135]
	v_and_b32_e32 v145, 0xffff0000, v157
	v_pk_mul_f32 v[134:135], v[134:135], v[142:143]
	v_rcp_f32_e32 v139, v147
	v_and_b32_e32 v151, 0xffff0000, v159
	v_rcp_f32_e32 v138, v146
	v_pk_add_f32 v[146:147], v[160:161], 1.0 op_sel_hi:[1,0]
	v_pk_mul_f32 v[136:137], v[138:139], v[136:137]
	v_lshlrev_b32_e32 v138, 16, v152
	v_and_b32_e32 v142, 0xffff0000, v152
	v_lshlrev_b32_e32 v139, 16, v153
	v_and_b32_e32 v143, 0xffff0000, v153
	v_rcp_f32_e32 v147, v147
	v_pk_mul_f32 v[136:137], v[136:137], v[144:145]
	v_pk_add_f32 v[152:153], v[162:163], 1.0 op_sel_hi:[1,0]
	v_rcp_f32_e32 v146, v146
	v_lshlrev_b32_e32 v145, 16, v159
	v_lshlrev_b32_e32 v144, 16, v158
	v_pk_mul_f32 v[138:139], v[146:147], v[138:139]
	v_pk_mul_f32 v[138:139], v[138:139], v[144:145]
	v_rcp_f32_e32 v145, v153
	v_and_b32_e32 v150, 0xffff0000, v158
	v_rcp_f32_e32 v144, v152
	s_nop 0
	v_pk_mul_f32 v[142:143], v[144:145], v[142:143]
	v_bfe_u32 v144, v137, 16, 1
	v_pk_mul_f32 v[142:143], v[142:143], v[150:151]
	v_bfe_u32 v145, v136, 16, 1
	v_add3_u32 v144, v137, v144, s24
	v_bfe_u32 v137, v135, 16, 1
	v_add3_u32 v145, v136, v145, s24
	v_bfe_u32 v136, v134, 16, 1
	v_add3_u32 v135, v135, v137, s24
	v_add3_u32 v134, v134, v136, s24
	v_cvt_pk_bf16_f32 v137, v139, v143
	v_cvt_pk_bf16_f32 v136, v138, v142
	v_lshrrev_b32_e32 v135, 16, v135
	v_and_or_b32 v135, v144, s22, v135
	v_lshrrev_b32_e32 v134, 16, v134
	v_and_or_b32 v134, v145, s22, v134
	v_rcp_f32_e32 v133, v133
	s_waitcnt vmcnt(1)
	v_lshlrev_b32_e32 v139, 16, v121
	v_rcp_f32_e32 v132, v132
	v_lshlrev_b32_e32 v138, 16, v120
	v_pk_mul_f32 v[132:133], v[132:133], v[138:139]
	v_rcp_f32_e32 v131, v131
	s_waitcnt vmcnt(0)
	v_lshlrev_b32_e32 v143, 16, v117
	v_lshlrev_b32_e32 v142, 16, v116
	v_pk_mul_f32 v[132:133], v[132:133], v[142:143]
	v_rcp_f32_e32 v130, v130
	v_and_b32_e32 v121, 0xffff0000, v121
	v_and_b32_e32 v120, 0xffff0000, v120
	v_and_b32_e32 v117, 0xffff0000, v117
	v_rcp_f32_e32 v129, v129
	v_and_b32_e32 v116, 0xffff0000, v116
	v_div_scale_f32 v3, s[0:1], v127, v127, 1.0
	v_rcp_f32_e32 v138, v3
	v_pk_mul_f32 v[120:121], v[130:131], v[120:121]
	v_rcp_f32_e32 v128, v128
	v_pk_mul_f32 v[116:117], v[120:121], v[116:117]
	v_fma_f32 v0, -v3, v138, 1.0
	v_lshlrev_b32_e32 v121, 16, v123
	v_lshlrev_b32_e32 v120, 16, v122
	v_fmac_f32_e32 v138, v0, v138
	v_div_scale_f32 v0, vcc, 1.0, v127, 1.0
	v_pk_mul_f32 v[120:121], v[128:129], v[120:121]
	v_mul_f32_e32 v128, v0, v138
	v_fma_f32 v129, -v3, v128, v0
	v_fmac_f32_e32 v128, v129, v138
	v_fma_f32 v0, -v3, v128, v0
	v_div_scale_f32 v3, s[0:1], v126, v126, 1.0
	v_rcp_f32_e32 v129, v3
	v_div_fmas_f32 v0, v0, v138, v128
	v_div_fixup_f32 v127, v0, v127, 1.0
	v_lshlrev_b32_e32 v131, 16, v119
	v_fma_f32 v0, -v3, v129, 1.0
	v_fmac_f32_e32 v129, v0, v129
	v_div_scale_f32 v0, vcc, 1.0, v126, 1.0
	v_lshlrev_b32_e32 v130, 16, v118
	v_mul_f32_e32 v128, v0, v129
	v_pk_mul_f32 v[120:121], v[120:121], v[130:131]
	v_fma_f32 v130, -v3, v128, v0
	v_fmac_f32_e32 v128, v130, v129
	v_fma_f32 v0, -v3, v128, v0
	v_div_fmas_f32 v0, v0, v129, v128
	v_and_b32_e32 v123, 0xffff0000, v123
	v_and_b32_e32 v122, 0xffff0000, v122
	v_div_fixup_f32 v126, v0, v126, 1.0
	v_and_b32_e32 v119, 0xffff0000, v119
	v_and_b32_e32 v118, 0xffff0000, v118
	v_pk_mul_f32 v[122:123], v[126:127], v[122:123]
	s_nop 0
	v_pk_mul_f32 v[118:119], v[122:123], v[118:119]
	v_bfe_u32 v0, v119, 16, 1
	v_bfe_u32 v3, v118, 16, 1
	v_add3_u32 v3, v118, v3, s24
	v_add3_u32 v0, v119, v0, s24
	v_bfe_u32 v122, v120, 16, 1
	v_bfe_u32 v123, v121, 16, 1
	v_add3_u32 v121, v121, v123, s24
	v_add3_u32 v120, v120, v122, s24
	v_lshrrev_b32_e32 v118, 16, v120
	v_lshrrev_b32_e32 v119, 16, v121
	v_and_or_b32 v119, v0, s22, v119
	v_and_or_b32 v118, v3, s22, v118
	v_cvt_pk_bf16_f32 v117, v133, v117
	v_cvt_pk_bf16_f32 v116, v132, v116
	global_store_dwordx4 v[124:125], v[134:137], off
	global_store_dwordx4 v[124:125], v[116:119], off offset:16
	ds_write2_b32 v155, v112, v108 offset1:16
	ds_write2_b32 v155, v113, v109 offset0:68 offset1:84
	ds_write2_b32 v155, v114, v110 offset0:136 offset1:152
	ds_write2_b32 v155, v115, v111 offset0:204 offset1:220
	ds_write2_b32 v155, v104, v100 offset0:32 offset1:48
	ds_write2_b32 v155, v105, v101 offset0:100 offset1:116
	ds_write2_b32 v155, v106, v102 offset0:168 offset1:184
	ds_write2_b32 v155, v107, v103 offset0:236 offset1:252
	s_waitcnt lgkmcnt(0)
	v_or_b32_e32 v100, 32, v2
	ds_read_b128 v[110:113], v154
	ds_read_b128 v[114:117], v154 offset:16
	ds_read_b128 v[118:121], v154 offset:32
	ds_read_b128 v[122:125], v154 offset:48
	v_mad_i64_i32 v[102:103], s[0:1], v100, s4, v[148:149]
	v_ashrrev_i32_e32 v101, 31, v100
	global_load_dwordx4 v[126:129], v[102:103], off
	v_lshlrev_b64 v[100:101], 12, v[100:101]
	v_lshl_add_u64 v[108:109], v[140:141], 0, v[100:101]
	global_load_dwordx4 v[130:133], v[108:109], off
	global_load_dwordx4 v[104:107], v[102:103], off offset:16
	s_nop 0
	global_load_dwordx4 v[100:103], v[108:109], off offset:16
	s_waitcnt lgkmcnt(3)
	v_add_f32_e32 v0, v48, v110
	v_mul_f32_e32 v0, 0xbfb8aa3b, v0
	v_exp_f32_e32 v134, v0
	v_add_f32_e32 v0, v49, v111
	v_mul_f32_e32 v0, 0xbfb8aa3b, v0
	v_exp_f32_e32 v136, v0
	v_add_f32_e32 v0, v50, v112
	v_mul_f32_e32 v0, 0xbfb8aa3b, v0
	v_exp_f32_e32 v135, v0
	v_add_f32_e32 v0, v51, v113
	v_mul_f32_e32 v0, 0xbfb8aa3b, v0
	v_exp_f32_e32 v137, v0
	s_waitcnt lgkmcnt(2)
; DI unsigned pack2(float a, float b) { return (unsigned)f2bf(a) | ((unsigned)f2bf(b) << 16); }
; DI float sigm(float x) { return 1.f / (1.f + __expf(-x)); }
; DI void store16_bf(bft* dst, const float (&v)[16]) {
;   u32x4 o0 = {pack2(v[0], v[1]), pack2(v[2], v[3]), pack2(v[4], v[5]), pack2(v[6], v[7])}, o1 = {pack2(v[8], v[9]), pack2(v[10], v[11]), pack2(v[12], v[13]), pack2(v[14], v[15])};
;   *(u32x4*)dst = o0; *(u32x4*)(dst + 8) = o1;
; }
; DI void load16_bf(const bft* src, float (&v)[16]) {
;   u32x4 w0 = *(const u32x4*)src, w1 = *(const u32x4*)(src + 8);
; #pragma unroll
;   for (int i = 0; i < 4; ++i) { v[2 * i] = __uint_as_float(w0[i] << 16); v[2 * i + 1] = __uint_as_float(w0[i] & 0xffff0000u); v[8 + 2 * i] = __uint_as_float(w1[i] << 16); v[8 + 2 * i + 1] = __uint_as_float(w1[i] & 0xffff0000u); }
; }
; DI void phase_glu(const Params& p) {
;     ...
;     float b[16]; load16_f(p.s5_glu_b + bcol + ((tid >> 6) & 3) * 64 + (tid & 3) * 16, b);
;     EPI256_BEGIN
;       float y[16], g[16]; load16_bf(ys + (size_t)row * LDP + col, y); bft* gp = G0 + (size_t)row * 2048 + col; load16_bf(gp, g);
; #pragma unroll
;       for (int i = 0; i < 16; ++i) v[i] = y[i] * sigm(v[i] + b[i]) * g[i];
;       store16_bf(gp, v);
	v_add_f32_e32 v0, v44, v114
	v_mul_f32_e32 v0, 0xbfb8aa3b, v0
	v_exp_f32_e32 v138, v0
	v_add_f32_e32 v0, v45, v115
	v_mul_f32_e32 v0, 0xbfb8aa3b, v0
	v_exp_f32_e32 v142, v0
	v_add_f32_e32 v0, v46, v116
	v_mul_f32_e32 v0, 0xbfb8aa3b, v0
	v_exp_f32_e32 v139, v0
	v_add_f32_e32 v0, v47, v117
	v_mul_f32_e32 v0, 0xbfb8aa3b, v0
	v_exp_f32_e32 v143, v0
	s_waitcnt lgkmcnt(1)
	v_add_f32_e32 v0, v24, v118
	v_mul_f32_e32 v0, 0xbfb8aa3b, v0
	v_exp_f32_e32 v116, v0
	v_add_f32_e32 v0, v25, v119
	v_mul_f32_e32 v0, 0xbfb8aa3b, v0
	v_exp_f32_e32 v114, v0
	v_add_f32_e32 v0, v26, v120
	v_mul_f32_e32 v0, 0xbfb8aa3b, v0
	v_exp_f32_e32 v117, v0
	v_add_f32_e32 v0, v27, v121
	v_mul_f32_e32 v0, 0xbfb8aa3b, v0
	v_exp_f32_e32 v115, v0
	s_waitcnt lgkmcnt(0)
	v_add_f32_e32 v0, v20, v122
	v_mul_f32_e32 v0, 0xbfb8aa3b, v0
	v_exp_f32_e32 v112, v0
	v_add_f32_e32 v0, v21, v123
	v_mul_f32_e32 v0, 0xbfb8aa3b, v0
	v_exp_f32_e32 v110, v0
	v_add_f32_e32 v0, v22, v124
	v_mul_f32_e32 v0, 0xbfb8aa3b, v0
	v_exp_f32_e32 v113, v0
	v_add_f32_e32 v0, v23, v125
	v_mul_f32_e32 v0, 0xbfb8aa3b, v0
	v_pk_add_f32 v[124:125], v[134:135], 1.0 op_sel_hi:[1,0]
	v_exp_f32_e32 v111, v0
	v_pk_add_f32 v[116:117], v[116:117], 1.0 op_sel_hi:[1,0]
	v_pk_add_f32 v[114:115], v[114:115], 1.0 op_sel_hi:[1,0]
	v_pk_add_f32 v[112:113], v[112:113], 1.0 op_sel_hi:[1,0]
	v_pk_add_f32 v[110:111], v[110:111], 1.0 op_sel_hi:[1,0]
	s_waitcnt vmcnt(3)
	v_lshlrev_b32_e32 v118, 16, v126
	v_and_b32_e32 v120, 0xffff0000, v126
	s_waitcnt vmcnt(2)
	v_lshlrev_b32_e32 v122, 16, v130
	v_and_b32_e32 v126, 0xffff0000, v130
	v_lshlrev_b32_e32 v119, 16, v127
	v_and_b32_e32 v121, 0xffff0000, v127
	v_lshlrev_b32_e32 v123, 16, v131
	v_and_b32_e32 v127, 0xffff0000, v131
	v_rcp_f32_e32 v125, v125
	v_pk_add_f32 v[130:131], v[136:137], 1.0 op_sel_hi:[1,0]
	v_rcp_f32_e32 v124, v124
	s_nop 0
	v_pk_mul_f32 v[118:119], v[124:125], v[118:119]
	v_pk_mul_f32 v[118:119], v[118:119], v[122:123]
	v_rcp_f32_e32 v123, v131
	v_and_b32_e32 v131, 0xffff0000, v133
	v_rcp_f32_e32 v122, v130
	s_nop 0
	v_pk_mul_f32 v[120:121], v[122:123], v[120:121]
	v_lshlrev_b32_e32 v123, 16, v129
	v_lshlrev_b32_e32 v122, 16, v128
	v_and_b32_e32 v125, 0xffff0000, v129
	v_and_b32_e32 v124, 0xffff0000, v128
	v_pk_add_f32 v[128:129], v[138:139], 1.0 op_sel_hi:[1,0]
	v_pk_mul_f32 v[120:121], v[120:121], v[126:127]
	v_lshlrev_b32_e32 v126, 16, v132
	v_and_b32_e32 v130, 0xffff0000, v132
	v_lshlrev_b32_e32 v127, 16, v133
	v_rcp_f32_e32 v129, v129
	v_pk_add_f32 v[132:133], v[142:143], 1.0 op_sel_hi:[1,0]
	v_rcp_f32_e32 v128, v128
	s_nop 0
	v_pk_mul_f32 v[122:123], v[128:129], v[122:123]
	v_pk_mul_f32 v[122:123], v[122:123], v[126:127]
	v_rcp_f32_e32 v127, v133
	v_rcp_f32_e32 v126, v132
	s_nop 0
	v_pk_mul_f32 v[124:125], v[126:127], v[124:125]
	v_bfe_u32 v126, v121, 16, 1
	v_pk_mul_f32 v[124:125], v[124:125], v[130:131]
	v_bfe_u32 v127, v120, 16, 1
	v_add3_u32 v126, v121, v126, s24
	v_bfe_u32 v121, v119, 16, 1
	v_add3_u32 v127, v120, v127, s24
	v_bfe_u32 v120, v118, 16, 1
	v_add3_u32 v119, v119, v121, s24
	v_add3_u32 v118, v118, v120, s24
	v_cvt_pk_bf16_f32 v121, v123, v125
	v_cvt_pk_bf16_f32 v120, v122, v124
	v_lshrrev_b32_e32 v119, 16, v119
	v_and_or_b32 v119, v126, s22, v119
	v_lshrrev_b32_e32 v118, 16, v118
	v_and_or_b32 v118, v127, s22, v118
	v_rcp_f32_e32 v117, v117
	s_waitcnt vmcnt(1)
	v_lshlrev_b32_e32 v123, 16, v105
	v_rcp_f32_e32 v116, v116
	v_lshlrev_b32_e32 v122, 16, v104
	v_pk_mul_f32 v[116:117], v[116:117], v[122:123]
	v_rcp_f32_e32 v115, v115
	s_waitcnt vmcnt(0)
	v_lshlrev_b32_e32 v125, 16, v101
	v_lshlrev_b32_e32 v124, 16, v100
	v_pk_mul_f32 v[116:117], v[116:117], v[124:125]
	v_rcp_f32_e32 v114, v114
	v_and_b32_e32 v105, 0xffff0000, v105
	v_and_b32_e32 v104, 0xffff0000, v104
	v_and_b32_e32 v101, 0xffff0000, v101
	v_rcp_f32_e32 v113, v113
	v_and_b32_e32 v100, 0xffff0000, v100
	v_div_scale_f32 v3, s[0:1], v111, v111, 1.0
	v_rcp_f32_e32 v122, v3
	v_pk_mul_f32 v[104:105], v[114:115], v[104:105]
	v_rcp_f32_e32 v112, v112
	v_pk_mul_f32 v[100:101], v[104:105], v[100:101]
	v_fma_f32 v0, -v3, v122, 1.0
	v_lshlrev_b32_e32 v105, 16, v107
	v_lshlrev_b32_e32 v104, 16, v106
	v_fmac_f32_e32 v122, v0, v122
	v_div_scale_f32 v0, vcc, 1.0, v111, 1.0
	v_pk_mul_f32 v[104:105], v[112:113], v[104:105]
	v_mul_f32_e32 v112, v0, v122
	v_fma_f32 v113, -v3, v112, v0
	v_fmac_f32_e32 v112, v113, v122
	v_fma_f32 v0, -v3, v112, v0
	v_div_scale_f32 v3, s[0:1], v110, v110, 1.0
	v_rcp_f32_e32 v113, v3
	v_div_fmas_f32 v0, v0, v122, v112
	v_div_fixup_f32 v111, v0, v111, 1.0
	v_lshlrev_b32_e32 v115, 16, v103
	v_fma_f32 v0, -v3, v113, 1.0
	v_fmac_f32_e32 v113, v0, v113
	v_div_scale_f32 v0, vcc, 1.0, v110, 1.0
	v_lshlrev_b32_e32 v114, 16, v102
	v_mul_f32_e32 v112, v0, v113
	v_pk_mul_f32 v[104:105], v[104:105], v[114:115]
	v_fma_f32 v114, -v3, v112, v0
	v_fmac_f32_e32 v112, v114, v113
	v_fma_f32 v0, -v3, v112, v0
	v_div_fmas_f32 v0, v0, v113, v112
	v_and_b32_e32 v107, 0xffff0000, v107
	v_and_b32_e32 v106, 0xffff0000, v106
	v_div_fixup_f32 v110, v0, v110, 1.0
	v_and_b32_e32 v103, 0xffff0000, v103
	v_and_b32_e32 v102, 0xffff0000, v102
	v_pk_mul_f32 v[106:107], v[110:111], v[106:107]
	s_nop 0
	v_pk_mul_f32 v[102:103], v[106:107], v[102:103]
	v_bfe_u32 v0, v103, 16, 1
	v_bfe_u32 v3, v102, 16, 1
	v_add3_u32 v3, v102, v3, s24
	v_add3_u32 v0, v103, v0, s24
	v_bfe_u32 v106, v104, 16, 1
	v_bfe_u32 v107, v105, 16, 1
	v_add3_u32 v105, v105, v107, s24
	v_add3_u32 v104, v104, v106, s24
	v_lshrrev_b32_e32 v102, 16, v104
	v_lshrrev_b32_e32 v103, 16, v105
	v_and_or_b32 v103, v0, s22, v103
	v_and_or_b32 v102, v3, s22, v102
	v_cvt_pk_bf16_f32 v101, v117, v101
	v_cvt_pk_bf16_f32 v100, v116, v100
	global_store_dwordx4 v[108:109], v[118:121], off
	global_store_dwordx4 v[108:109], v[100:103], off offset:16
	ds_write2_b32 v155, v96, v92 offset1:16
	ds_write2_b32 v155, v97, v93 offset0:68 offset1:84
	ds_write2_b32 v155, v98, v94 offset0:136 offset1:152
	ds_write2_b32 v155, v99, v95 offset0:204 offset1:220
	ds_write2_b32 v155, v88, v84 offset0:32 offset1:48
	ds_write2_b32 v155, v89, v85 offset0:100 offset1:116
	ds_write2_b32 v155, v90, v86 offset0:168 offset1:184
	ds_write2_b32 v155, v91, v87 offset0:236 offset1:252
	s_waitcnt lgkmcnt(0)
; DI unsigned pack2(float a, float b) { return (unsigned)f2bf(a) | ((unsigned)f2bf(b) << 16); }
; DI float sigm(float x) { return 1.f / (1.f + __expf(-x)); }
; DI void store16_bf(bft* dst, const float (&v)[16]) {
;   u32x4 o0 = {pack2(v[0], v[1]), pack2(v[2], v[3]), pack2(v[4], v[5]), pack2(v[6], v[7])}, o1 = {pack2(v[8], v[9]), pack2(v[10], v[11]), pack2(v[12], v[13]), pack2(v[14], v[15])};
;   *(u32x4*)dst = o0; *(u32x4*)(dst + 8) = o1;
; }
; DI void load16_bf(const bft* src, float (&v)[16]) {
;   u32x4 w0 = *(const u32x4*)src, w1 = *(const u32x4*)(src + 8);
; #pragma unroll
;   for (int i = 0; i < 4; ++i) { v[2 * i] = __uint_as_float(w0[i] << 16); v[2 * i + 1] = __uint_as_float(w0[i] & 0xffff0000u); v[8 + 2 * i] = __uint_as_float(w1[i] << 16); v[8 + 2 * i + 1] = __uint_as_float(w1[i] & 0xffff0000u); }
; }
; DI void phase_glu(const Params& p) {
;     ...
;     float b[16]; load16_f(p.s5_glu_b + bcol + ((tid >> 6) & 3) * 64 + (tid & 3) * 16, b);
;     EPI256_BEGIN
;       float y[16], g[16]; load16_bf(ys + (size_t)row * LDP + col, y); bft* gp = G0 + (size_t)row * 2048 + col; load16_bf(gp, g);
; #pragma unroll
;       for (int i = 0; i < 16; ++i) v[i] = y[i] * sigm(v[i] + b[i]) * g[i];
;       store16_bf(gp, v);
	v_or_b32_e32 v84, 48, v2
	ds_read_b128 v[94:97], v154
	ds_read_b128 v[98:101], v154 offset:16
	ds_read_b128 v[102:105], v154 offset:32
	ds_read_b128 v[106:109], v154 offset:48
	v_mad_i64_i32 v[86:87], s[0:1], v84, s4, v[148:149]
	v_ashrrev_i32_e32 v85, 31, v84
	global_load_dwordx4 v[110:113], v[86:87], off
	v_lshlrev_b64 v[84:85], 12, v[84:85]
	v_lshl_add_u64 v[92:93], v[140:141], 0, v[84:85]
	global_load_dwordx4 v[114:117], v[92:93], off
	global_load_dwordx4 v[88:91], v[86:87], off offset:16
	s_nop 0
	global_load_dwordx4 v[84:87], v[92:93], off offset:16
	s_waitcnt lgkmcnt(3)
	v_add_f32_e32 v0, v48, v94
	v_mul_f32_e32 v0, 0xbfb8aa3b, v0
	v_exp_f32_e32 v118, v0
	v_add_f32_e32 v0, v49, v95
	v_mul_f32_e32 v0, 0xbfb8aa3b, v0
	v_exp_f32_e32 v120, v0
	v_add_f32_e32 v0, v50, v96
	v_mul_f32_e32 v0, 0xbfb8aa3b, v0
	v_exp_f32_e32 v119, v0
	v_add_f32_e32 v0, v51, v97
	v_mul_f32_e32 v0, 0xbfb8aa3b, v0
	v_exp_f32_e32 v121, v0
	s_waitcnt lgkmcnt(2)
	v_add_f32_e32 v0, v44, v98
	v_mul_f32_e32 v0, 0xbfb8aa3b, v0
	v_exp_f32_e32 v122, v0
	v_add_f32_e32 v0, v45, v99
	v_mul_f32_e32 v0, 0xbfb8aa3b, v0
	v_exp_f32_e32 v124, v0
	v_add_f32_e32 v0, v46, v100
	v_mul_f32_e32 v0, 0xbfb8aa3b, v0
	v_exp_f32_e32 v123, v0
	v_add_f32_e32 v0, v47, v101
	v_mul_f32_e32 v0, 0xbfb8aa3b, v0
	v_exp_f32_e32 v125, v0
	s_waitcnt lgkmcnt(1)
	v_add_f32_e32 v0, v24, v102
	v_mul_f32_e32 v0, 0xbfb8aa3b, v0
	v_exp_f32_e32 v100, v0
	v_add_f32_e32 v0, v25, v103
	v_mul_f32_e32 v0, 0xbfb8aa3b, v0
	v_exp_f32_e32 v98, v0
	v_add_f32_e32 v0, v26, v104
	v_mul_f32_e32 v0, 0xbfb8aa3b, v0
	v_exp_f32_e32 v101, v0
	v_add_f32_e32 v0, v27, v105
	v_mul_f32_e32 v0, 0xbfb8aa3b, v0
	v_exp_f32_e32 v99, v0
	s_waitcnt lgkmcnt(0)
	v_add_f32_e32 v0, v20, v106
	v_mul_f32_e32 v0, 0xbfb8aa3b, v0
	v_exp_f32_e32 v96, v0
	v_add_f32_e32 v0, v21, v107
	v_mul_f32_e32 v0, 0xbfb8aa3b, v0
	v_exp_f32_e32 v94, v0
	v_add_f32_e32 v0, v22, v108
	v_mul_f32_e32 v0, 0xbfb8aa3b, v0
	v_exp_f32_e32 v97, v0
	v_add_f32_e32 v0, v23, v109
	v_mul_f32_e32 v0, 0xbfb8aa3b, v0
	v_pk_add_f32 v[108:109], v[118:119], 1.0 op_sel_hi:[1,0]
	v_exp_f32_e32 v95, v0
	v_pk_add_f32 v[100:101], v[100:101], 1.0 op_sel_hi:[1,0]
	v_pk_add_f32 v[98:99], v[98:99], 1.0 op_sel_hi:[1,0]
	v_pk_add_f32 v[96:97], v[96:97], 1.0 op_sel_hi:[1,0]
	v_pk_add_f32 v[94:95], v[94:95], 1.0 op_sel_hi:[1,0]
	s_waitcnt vmcnt(3)
	v_lshlrev_b32_e32 v102, 16, v110
	v_and_b32_e32 v104, 0xffff0000, v110
	s_waitcnt vmcnt(2)
	v_lshlrev_b32_e32 v106, 16, v114
	v_and_b32_e32 v110, 0xffff0000, v114
	v_lshlrev_b32_e32 v103, 16, v111
	v_and_b32_e32 v105, 0xffff0000, v111
	v_lshlrev_b32_e32 v107, 16, v115
	v_and_b32_e32 v111, 0xffff0000, v115
	v_rcp_f32_e32 v109, v109
	v_pk_add_f32 v[114:115], v[120:121], 1.0 op_sel_hi:[1,0]
	v_rcp_f32_e32 v108, v108
	s_nop 0
	v_pk_mul_f32 v[102:103], v[108:109], v[102:103]
	v_pk_mul_f32 v[102:103], v[102:103], v[106:107]
	v_rcp_f32_e32 v107, v115
	v_and_b32_e32 v115, 0xffff0000, v117
	v_rcp_f32_e32 v106, v114
	s_nop 0
	v_pk_mul_f32 v[104:105], v[106:107], v[104:105]
	v_lshlrev_b32_e32 v107, 16, v113
	v_lshlrev_b32_e32 v106, 16, v112
	v_and_b32_e32 v109, 0xffff0000, v113
	v_and_b32_e32 v108, 0xffff0000, v112
	v_pk_add_f32 v[112:113], v[122:123], 1.0 op_sel_hi:[1,0]
	v_pk_mul_f32 v[104:105], v[104:105], v[110:111]
	v_lshlrev_b32_e32 v110, 16, v116
	v_and_b32_e32 v114, 0xffff0000, v116
	v_lshlrev_b32_e32 v111, 16, v117
	v_rcp_f32_e32 v113, v113
	v_pk_add_f32 v[116:117], v[124:125], 1.0 op_sel_hi:[1,0]
	v_rcp_f32_e32 v112, v112
	s_nop 0
	v_pk_mul_f32 v[106:107], v[112:113], v[106:107]
	v_pk_mul_f32 v[106:107], v[106:107], v[110:111]
	v_rcp_f32_e32 v111, v117
	v_rcp_f32_e32 v110, v116
	s_nop 0
	v_pk_mul_f32 v[108:109], v[110:111], v[108:109]
	v_bfe_u32 v110, v105, 16, 1
	v_pk_mul_f32 v[108:109], v[108:109], v[114:115]
	v_bfe_u32 v111, v104, 16, 1
	v_add3_u32 v110, v105, v110, s24
	v_bfe_u32 v105, v103, 16, 1
	v_add3_u32 v111, v104, v111, s24
	v_bfe_u32 v104, v102, 16, 1
	v_add3_u32 v103, v103, v105, s24
	v_add3_u32 v102, v102, v104, s24
	v_cvt_pk_bf16_f32 v105, v107, v109
	v_cvt_pk_bf16_f32 v104, v106, v108
	v_lshrrev_b32_e32 v103, 16, v103
	v_and_or_b32 v103, v110, s22, v103
	v_lshrrev_b32_e32 v102, 16, v102
	v_and_or_b32 v102, v111, s22, v102
	v_rcp_f32_e32 v101, v101
	s_waitcnt vmcnt(1)
	v_lshlrev_b32_e32 v107, 16, v89
	v_rcp_f32_e32 v100, v100
	v_lshlrev_b32_e32 v106, 16, v88
	v_pk_mul_f32 v[100:101], v[100:101], v[106:107]
	v_rcp_f32_e32 v99, v99
	s_waitcnt vmcnt(0)
; DI unsigned pack2(float a, float b) { return (unsigned)f2bf(a) | ((unsigned)f2bf(b) << 16); }
; DI float sigm(float x) { return 1.f / (1.f + __expf(-x)); }
; DI void store16_bf(bft* dst, const float (&v)[16]) {
;   u32x4 o0 = {pack2(v[0], v[1]), pack2(v[2], v[3]), pack2(v[4], v[5]), pack2(v[6], v[7])}, o1 = {pack2(v[8], v[9]), pack2(v[10], v[11]), pack2(v[12], v[13]), pack2(v[14], v[15])};
;   *(u32x4*)dst = o0; *(u32x4*)(dst + 8) = o1;
; }
; DI void load16_bf(const bft* src, float (&v)[16]) {
;   u32x4 w0 = *(const u32x4*)src, w1 = *(const u32x4*)(src + 8);
; #pragma unroll
;   for (int i = 0; i < 4; ++i) { v[2 * i] = __uint_as_float(w0[i] << 16); v[2 * i + 1] = __uint_as_float(w0[i] & 0xffff0000u); v[8 + 2 * i] = __uint_as_float(w1[i] << 16); v[8 + 2 * i + 1] = __uint_as_float(w1[i] & 0xffff0000u); }
; }
; DI void phase_glu(const Params& p) {
;     ...
;     float b[16]; load16_f(p.s5_glu_b + bcol + ((tid >> 6) & 3) * 64 + (tid & 3) * 16, b);
;     EPI256_BEGIN
;       float y[16], g[16]; load16_bf(ys + (size_t)row * LDP + col, y); bft* gp = G0 + (size_t)row * 2048 + col; load16_bf(gp, g);
; #pragma unroll
;       for (int i = 0; i < 16; ++i) v[i] = y[i] * sigm(v[i] + b[i]) * g[i];
;       store16_bf(gp, v);
	v_lshlrev_b32_e32 v109, 16, v85
	v_lshlrev_b32_e32 v108, 16, v84
	v_pk_mul_f32 v[100:101], v[100:101], v[108:109]
	v_rcp_f32_e32 v98, v98
	v_and_b32_e32 v89, 0xffff0000, v89
	v_and_b32_e32 v88, 0xffff0000, v88
	v_and_b32_e32 v85, 0xffff0000, v85
	v_rcp_f32_e32 v97, v97
	v_and_b32_e32 v84, 0xffff0000, v84
	v_div_scale_f32 v3, s[0:1], v95, v95, 1.0
	v_rcp_f32_e32 v106, v3
	v_pk_mul_f32 v[88:89], v[98:99], v[88:89]
	v_rcp_f32_e32 v96, v96
	v_pk_mul_f32 v[84:85], v[88:89], v[84:85]
	v_fma_f32 v0, -v3, v106, 1.0
	v_lshlrev_b32_e32 v89, 16, v91
	v_lshlrev_b32_e32 v88, 16, v90
	v_fmac_f32_e32 v106, v0, v106
	v_div_scale_f32 v0, vcc, 1.0, v95, 1.0
	v_pk_mul_f32 v[88:89], v[96:97], v[88:89]
	v_mul_f32_e32 v96, v0, v106
	v_fma_f32 v97, -v3, v96, v0
	v_fmac_f32_e32 v96, v97, v106
	v_fma_f32 v0, -v3, v96, v0
	v_div_scale_f32 v3, s[0:1], v94, v94, 1.0
	v_rcp_f32_e32 v97, v3
	v_div_fmas_f32 v0, v0, v106, v96
	v_div_fixup_f32 v95, v0, v95, 1.0
	v_lshlrev_b32_e32 v99, 16, v87
	v_fma_f32 v0, -v3, v97, 1.0
	v_fmac_f32_e32 v97, v0, v97
	v_div_scale_f32 v0, vcc, 1.0, v94, 1.0
	v_lshlrev_b32_e32 v98, 16, v86
	v_mul_f32_e32 v96, v0, v97
	v_pk_mul_f32 v[88:89], v[88:89], v[98:99]
	v_fma_f32 v98, -v3, v96, v0
	v_fmac_f32_e32 v96, v98, v97
	v_fma_f32 v0, -v3, v96, v0
	v_div_fmas_f32 v0, v0, v97, v96
	v_and_b32_e32 v91, 0xffff0000, v91
	v_and_b32_e32 v90, 0xffff0000, v90
	v_div_fixup_f32 v94, v0, v94, 1.0
	v_and_b32_e32 v87, 0xffff0000, v87
	v_and_b32_e32 v86, 0xffff0000, v86
	v_pk_mul_f32 v[90:91], v[94:95], v[90:91]
	s_nop 0
	v_pk_mul_f32 v[86:87], v[90:91], v[86:87]
	v_bfe_u32 v0, v87, 16, 1
	v_bfe_u32 v3, v86, 16, 1
	v_add3_u32 v3, v86, v3, s24
	v_add3_u32 v0, v87, v0, s24
	v_bfe_u32 v90, v88, 16, 1
	v_bfe_u32 v91, v89, 16, 1
	v_add3_u32 v89, v89, v91, s24
	v_add3_u32 v88, v88, v90, s24
	v_lshrrev_b32_e32 v86, 16, v88
	v_lshrrev_b32_e32 v87, 16, v89
	v_and_or_b32 v87, v0, s22, v87
	v_and_or_b32 v86, v3, s22, v86
	v_cvt_pk_bf16_f32 v85, v101, v85
	v_cvt_pk_bf16_f32 v84, v100, v84
	global_store_dwordx4 v[92:93], v[102:105], off
	global_store_dwordx4 v[92:93], v[84:87], off offset:16
	ds_write2_b32 v155, v76, v80 offset1:16
	ds_write2_b32 v155, v77, v81 offset0:68 offset1:84
	ds_write2_b32 v155, v78, v82 offset0:136 offset1:152
	ds_write2_b32 v155, v79, v83 offset0:204 offset1:220
	ds_write2_b32 v155, v68, v72 offset0:32 offset1:48
	ds_write2_b32 v155, v69, v73 offset0:100 offset1:116
	ds_write2_b32 v155, v70, v74 offset0:168 offset1:184
	ds_write2_b32 v155, v71, v75 offset0:236 offset1:252
	s_waitcnt lgkmcnt(0)
	v_or_b32_e32 v68, 64, v2
	ds_read_b128 v[78:81], v154
	ds_read_b128 v[82:85], v154 offset:16
	ds_read_b128 v[86:89], v154 offset:32
	ds_read_b128 v[90:93], v154 offset:48
	v_mad_i64_i32 v[70:71], s[0:1], v68, s4, v[148:149]
	v_ashrrev_i32_e32 v69, 31, v68
	global_load_dwordx4 v[94:97], v[70:71], off
	v_lshlrev_b64 v[68:69], 12, v[68:69]
	v_lshl_add_u64 v[76:77], v[140:141], 0, v[68:69]
	global_load_dwordx4 v[98:101], v[76:77], off
	global_load_dwordx4 v[72:75], v[70:71], off offset:16
	s_nop 0
	global_load_dwordx4 v[68:71], v[76:77], off offset:16
	s_waitcnt lgkmcnt(3)
	v_add_f32_e32 v0, v48, v78
	v_mul_f32_e32 v0, 0xbfb8aa3b, v0
	v_exp_f32_e32 v102, v0
	v_add_f32_e32 v0, v49, v79
	v_mul_f32_e32 v0, 0xbfb8aa3b, v0
	v_exp_f32_e32 v104, v0
	v_add_f32_e32 v0, v50, v80
	v_mul_f32_e32 v0, 0xbfb8aa3b, v0
	v_exp_f32_e32 v103, v0
	v_add_f32_e32 v0, v51, v81
	v_mul_f32_e32 v0, 0xbfb8aa3b, v0
	v_exp_f32_e32 v105, v0
	s_waitcnt lgkmcnt(2)
	v_add_f32_e32 v0, v44, v82
	v_mul_f32_e32 v0, 0xbfb8aa3b, v0
	v_exp_f32_e32 v106, v0
	v_add_f32_e32 v0, v45, v83
	v_mul_f32_e32 v0, 0xbfb8aa3b, v0
	v_exp_f32_e32 v108, v0
	v_add_f32_e32 v0, v46, v84
	v_mul_f32_e32 v0, 0xbfb8aa3b, v0
	v_exp_f32_e32 v107, v0
	v_add_f32_e32 v0, v47, v85
	v_mul_f32_e32 v0, 0xbfb8aa3b, v0
	v_exp_f32_e32 v109, v0
	s_waitcnt lgkmcnt(1)
	v_add_f32_e32 v0, v24, v86
	v_mul_f32_e32 v0, 0xbfb8aa3b, v0
	v_exp_f32_e32 v84, v0
	v_add_f32_e32 v0, v25, v87
	v_mul_f32_e32 v0, 0xbfb8aa3b, v0
	v_exp_f32_e32 v82, v0
	v_add_f32_e32 v0, v26, v88
	v_mul_f32_e32 v0, 0xbfb8aa3b, v0
	v_exp_f32_e32 v85, v0
	v_add_f32_e32 v0, v27, v89
	v_mul_f32_e32 v0, 0xbfb8aa3b, v0
	v_exp_f32_e32 v83, v0
	s_waitcnt lgkmcnt(0)
	v_add_f32_e32 v0, v20, v90
	v_mul_f32_e32 v0, 0xbfb8aa3b, v0
	v_exp_f32_e32 v80, v0
	v_add_f32_e32 v0, v21, v91
	v_mul_f32_e32 v0, 0xbfb8aa3b, v0
	v_exp_f32_e32 v78, v0
	v_add_f32_e32 v0, v22, v92
	v_mul_f32_e32 v0, 0xbfb8aa3b, v0
	v_exp_f32_e32 v81, v0
	v_add_f32_e32 v0, v23, v93
	v_mul_f32_e32 v0, 0xbfb8aa3b, v0
	v_pk_add_f32 v[92:93], v[102:103], 1.0 op_sel_hi:[1,0]
	v_exp_f32_e32 v79, v0
	v_pk_add_f32 v[84:85], v[84:85], 1.0 op_sel_hi:[1,0]
	v_pk_add_f32 v[82:83], v[82:83], 1.0 op_sel_hi:[1,0]
	v_pk_add_f32 v[80:81], v[80:81], 1.0 op_sel_hi:[1,0]
	v_pk_add_f32 v[78:79], v[78:79], 1.0 op_sel_hi:[1,0]
	s_waitcnt vmcnt(3)
	v_lshlrev_b32_e32 v86, 16, v94
	v_and_b32_e32 v88, 0xffff0000, v94
	s_waitcnt vmcnt(2)
; DI unsigned pack2(float a, float b) { return (unsigned)f2bf(a) | ((unsigned)f2bf(b) << 16); }
; DI float sigm(float x) { return 1.f / (1.f + __expf(-x)); }
; DI void store16_bf(bft* dst, const float (&v)[16]) {
;   u32x4 o0 = {pack2(v[0], v[1]), pack2(v[2], v[3]), pack2(v[4], v[5]), pack2(v[6], v[7])}, o1 = {pack2(v[8], v[9]), pack2(v[10], v[11]), pack2(v[12], v[13]), pack2(v[14], v[15])};
;   *(u32x4*)dst = o0; *(u32x4*)(dst + 8) = o1;
; }
; DI void load16_bf(const bft* src, float (&v)[16]) {
;   u32x4 w0 = *(const u32x4*)src, w1 = *(const u32x4*)(src + 8);
; #pragma unroll
;   for (int i = 0; i < 4; ++i) { v[2 * i] = __uint_as_float(w0[i] << 16); v[2 * i + 1] = __uint_as_float(w0[i] & 0xffff0000u); v[8 + 2 * i] = __uint_as_float(w1[i] << 16); v[8 + 2 * i + 1] = __uint_as_float(w1[i] & 0xffff0000u); }
; }
; DI void phase_glu(const Params& p) {
;     ...
;     float b[16]; load16_f(p.s5_glu_b + bcol + ((tid >> 6) & 3) * 64 + (tid & 3) * 16, b);
;     EPI256_BEGIN
;       float y[16], g[16]; load16_bf(ys + (size_t)row * LDP + col, y); bft* gp = G0 + (size_t)row * 2048 + col; load16_bf(gp, g);
; #pragma unroll
;       for (int i = 0; i < 16; ++i) v[i] = y[i] * sigm(v[i] + b[i]) * g[i];
;       store16_bf(gp, v);
	v_lshlrev_b32_e32 v90, 16, v98
	v_and_b32_e32 v94, 0xffff0000, v98
	v_lshlrev_b32_e32 v87, 16, v95
	v_and_b32_e32 v89, 0xffff0000, v95
	v_lshlrev_b32_e32 v91, 16, v99
	v_and_b32_e32 v95, 0xffff0000, v99
	v_rcp_f32_e32 v93, v93
	v_pk_add_f32 v[98:99], v[104:105], 1.0 op_sel_hi:[1,0]
	v_rcp_f32_e32 v92, v92
	s_nop 0
	v_pk_mul_f32 v[86:87], v[92:93], v[86:87]
	v_pk_mul_f32 v[86:87], v[86:87], v[90:91]
	v_rcp_f32_e32 v91, v99
	v_and_b32_e32 v99, 0xffff0000, v101
	v_rcp_f32_e32 v90, v98
	s_nop 0
	v_pk_mul_f32 v[88:89], v[90:91], v[88:89]
	v_lshlrev_b32_e32 v91, 16, v97
	v_lshlrev_b32_e32 v90, 16, v96
	v_and_b32_e32 v93, 0xffff0000, v97
	v_and_b32_e32 v92, 0xffff0000, v96
	v_pk_add_f32 v[96:97], v[106:107], 1.0 op_sel_hi:[1,0]
	v_pk_mul_f32 v[88:89], v[88:89], v[94:95]
	v_lshlrev_b32_e32 v94, 16, v100
	v_and_b32_e32 v98, 0xffff0000, v100
	v_lshlrev_b32_e32 v95, 16, v101
	v_rcp_f32_e32 v97, v97
	v_pk_add_f32 v[100:101], v[108:109], 1.0 op_sel_hi:[1,0]
	v_rcp_f32_e32 v96, v96
	s_nop 0
	v_pk_mul_f32 v[90:91], v[96:97], v[90:91]
	v_pk_mul_f32 v[90:91], v[90:91], v[94:95]
	v_rcp_f32_e32 v95, v101
	v_rcp_f32_e32 v94, v100
	s_nop 0
	v_pk_mul_f32 v[92:93], v[94:95], v[92:93]
	v_bfe_u32 v94, v89, 16, 1
	v_pk_mul_f32 v[92:93], v[92:93], v[98:99]
	v_bfe_u32 v95, v88, 16, 1
	v_add3_u32 v94, v89, v94, s24
	v_bfe_u32 v89, v87, 16, 1
	v_add3_u32 v95, v88, v95, s24
	v_bfe_u32 v88, v86, 16, 1
	v_add3_u32 v87, v87, v89, s24
	v_add3_u32 v86, v86, v88, s24
	v_cvt_pk_bf16_f32 v89, v91, v93
	v_cvt_pk_bf16_f32 v88, v90, v92
	v_lshrrev_b32_e32 v87, 16, v87
	v_and_or_b32 v87, v94, s22, v87
	v_lshrrev_b32_e32 v86, 16, v86
	v_and_or_b32 v86, v95, s22, v86
	v_rcp_f32_e32 v85, v85
	s_waitcnt vmcnt(1)
	v_lshlrev_b32_e32 v91, 16, v73
	v_rcp_f32_e32 v84, v84
	v_lshlrev_b32_e32 v90, 16, v72
	v_pk_mul_f32 v[84:85], v[84:85], v[90:91]
	v_rcp_f32_e32 v83, v83
	s_waitcnt vmcnt(0)
	v_lshlrev_b32_e32 v93, 16, v69
	v_lshlrev_b32_e32 v92, 16, v68
	v_pk_mul_f32 v[84:85], v[84:85], v[92:93]
	v_rcp_f32_e32 v82, v82
	v_and_b32_e32 v73, 0xffff0000, v73
	v_and_b32_e32 v72, 0xffff0000, v72
	v_and_b32_e32 v69, 0xffff0000, v69
	v_rcp_f32_e32 v81, v81
	v_and_b32_e32 v68, 0xffff0000, v68
	v_div_scale_f32 v3, s[0:1], v79, v79, 1.0
	v_rcp_f32_e32 v90, v3
	v_pk_mul_f32 v[72:73], v[82:83], v[72:73]
	v_rcp_f32_e32 v80, v80
	v_pk_mul_f32 v[68:69], v[72:73], v[68:69]
	v_fma_f32 v0, -v3, v90, 1.0
	v_lshlrev_b32_e32 v73, 16, v75
	v_lshlrev_b32_e32 v72, 16, v74
	v_fmac_f32_e32 v90, v0, v90
	v_div_scale_f32 v0, vcc, 1.0, v79, 1.0
	v_pk_mul_f32 v[72:73], v[80:81], v[72:73]
	v_mul_f32_e32 v80, v0, v90
	v_fma_f32 v81, -v3, v80, v0
	v_fmac_f32_e32 v80, v81, v90
	v_fma_f32 v0, -v3, v80, v0
	v_div_scale_f32 v3, s[0:1], v78, v78, 1.0
	v_rcp_f32_e32 v81, v3
	v_div_fmas_f32 v0, v0, v90, v80
	v_div_fixup_f32 v79, v0, v79, 1.0
	v_lshlrev_b32_e32 v83, 16, v71
	v_fma_f32 v0, -v3, v81, 1.0
	v_fmac_f32_e32 v81, v0, v81
	v_div_scale_f32 v0, vcc, 1.0, v78, 1.0
	v_lshlrev_b32_e32 v82, 16, v70
	v_mul_f32_e32 v80, v0, v81
	v_pk_mul_f32 v[72:73], v[72:73], v[82:83]
	v_fma_f32 v82, -v3, v80, v0
	v_fmac_f32_e32 v80, v82, v81
	v_fma_f32 v0, -v3, v80, v0
	v_div_fmas_f32 v0, v0, v81, v80
	v_and_b32_e32 v75, 0xffff0000, v75
	v_and_b32_e32 v74, 0xffff0000, v74
	v_div_fixup_f32 v78, v0, v78, 1.0
	v_and_b32_e32 v71, 0xffff0000, v71
	v_and_b32_e32 v70, 0xffff0000, v70
	v_pk_mul_f32 v[74:75], v[78:79], v[74:75]
	s_nop 0
	v_pk_mul_f32 v[70:71], v[74:75], v[70:71]
	v_bfe_u32 v0, v71, 16, 1
	v_bfe_u32 v3, v70, 16, 1
	v_add3_u32 v3, v70, v3, s24
	v_add3_u32 v0, v71, v0, s24
	v_bfe_u32 v74, v72, 16, 1
	v_bfe_u32 v75, v73, 16, 1
	v_add3_u32 v73, v73, v75, s24
	v_add3_u32 v72, v72, v74, s24
	v_lshrrev_b32_e32 v70, 16, v72
	v_lshrrev_b32_e32 v71, 16, v73
	v_and_or_b32 v71, v0, s22, v71
	v_and_or_b32 v70, v3, s22, v70
	v_cvt_pk_bf16_f32 v69, v85, v69
	v_cvt_pk_bf16_f32 v68, v84, v68
	global_store_dwordx4 v[76:77], v[86:89], off
	global_store_dwordx4 v[76:77], v[68:71], off offset:16
	ds_write2_b32 v155, v60, v64 offset1:16
	ds_write2_b32 v155, v61, v65 offset0:68 offset1:84
	ds_write2_b32 v155, v62, v66 offset0:136 offset1:152
	ds_write2_b32 v155, v63, v67 offset0:204 offset1:220
	ds_write2_b32 v155, v52, v56 offset0:32 offset1:48
	ds_write2_b32 v155, v53, v57 offset0:100 offset1:116
	ds_write2_b32 v155, v54, v58 offset0:168 offset1:184
	ds_write2_b32 v155, v55, v59 offset0:236 offset1:252
	s_waitcnt lgkmcnt(0)
	v_or_b32_e32 v52, 0x50, v2
	ds_read_b128 v[62:65], v154
	ds_read_b128 v[66:69], v154 offset:16
	ds_read_b128 v[70:73], v154 offset:32
	ds_read_b128 v[74:77], v154 offset:48
	v_mad_i64_i32 v[54:55], s[0:1], v52, s4, v[148:149]
	v_ashrrev_i32_e32 v53, 31, v52
	global_load_dwordx4 v[78:81], v[54:55], off
	v_lshlrev_b64 v[52:53], 12, v[52:53]
	v_lshl_add_u64 v[60:61], v[140:141], 0, v[52:53]
	global_load_dwordx4 v[82:85], v[60:61], off
	global_load_dwordx4 v[56:59], v[54:55], off offset:16
	s_nop 0
	global_load_dwordx4 v[52:55], v[60:61], off offset:16
	s_waitcnt lgkmcnt(3)
	v_add_f32_e32 v0, v48, v62
	v_mul_f32_e32 v0, 0xbfb8aa3b, v0
	v_exp_f32_e32 v86, v0
	v_add_f32_e32 v0, v49, v63
	v_mul_f32_e32 v0, 0xbfb8aa3b, v0
	v_exp_f32_e32 v88, v0
	v_add_f32_e32 v0, v50, v64
	v_mul_f32_e32 v0, 0xbfb8aa3b, v0
	v_exp_f32_e32 v87, v0
	v_add_f32_e32 v0, v51, v65
	v_mul_f32_e32 v0, 0xbfb8aa3b, v0
	v_exp_f32_e32 v89, v0
	s_waitcnt lgkmcnt(2)
	v_add_f32_e32 v0, v44, v66
	v_mul_f32_e32 v0, 0xbfb8aa3b, v0
	v_exp_f32_e32 v90, v0
	v_add_f32_e32 v0, v45, v67
	v_mul_f32_e32 v0, 0xbfb8aa3b, v0
	v_exp_f32_e32 v92, v0
	v_add_f32_e32 v0, v46, v68
	v_mul_f32_e32 v0, 0xbfb8aa3b, v0
	v_exp_f32_e32 v91, v0
	v_add_f32_e32 v0, v47, v69
	v_mul_f32_e32 v0, 0xbfb8aa3b, v0
	v_exp_f32_e32 v93, v0
	s_waitcnt lgkmcnt(1)
; DI unsigned pack2(float a, float b) { return (unsigned)f2bf(a) | ((unsigned)f2bf(b) << 16); }
; DI float sigm(float x) { return 1.f / (1.f + __expf(-x)); }
; DI void store16_bf(bft* dst, const float (&v)[16]) {
;   u32x4 o0 = {pack2(v[0], v[1]), pack2(v[2], v[3]), pack2(v[4], v[5]), pack2(v[6], v[7])}, o1 = {pack2(v[8], v[9]), pack2(v[10], v[11]), pack2(v[12], v[13]), pack2(v[14], v[15])};
;   *(u32x4*)dst = o0; *(u32x4*)(dst + 8) = o1;
; }
; DI void load16_bf(const bft* src, float (&v)[16]) {
;   u32x4 w0 = *(const u32x4*)src, w1 = *(const u32x4*)(src + 8);
; #pragma unroll
;   for (int i = 0; i < 4; ++i) { v[2 * i] = __uint_as_float(w0[i] << 16); v[2 * i + 1] = __uint_as_float(w0[i] & 0xffff0000u); v[8 + 2 * i] = __uint_as_float(w1[i] << 16); v[8 + 2 * i + 1] = __uint_as_float(w1[i] & 0xffff0000u); }
; }
; DI void phase_glu(const Params& p) {
;     ...
;     float b[16]; load16_f(p.s5_glu_b + bcol + ((tid >> 6) & 3) * 64 + (tid & 3) * 16, b);
;     EPI256_BEGIN
;       float y[16], g[16]; load16_bf(ys + (size_t)row * LDP + col, y); bft* gp = G0 + (size_t)row * 2048 + col; load16_bf(gp, g);
; #pragma unroll
;       for (int i = 0; i < 16; ++i) v[i] = y[i] * sigm(v[i] + b[i]) * g[i];
;       store16_bf(gp, v);
	v_add_f32_e32 v0, v24, v70
	v_mul_f32_e32 v0, 0xbfb8aa3b, v0
	v_exp_f32_e32 v68, v0
	v_add_f32_e32 v0, v25, v71
	v_mul_f32_e32 v0, 0xbfb8aa3b, v0
	v_exp_f32_e32 v66, v0
	v_add_f32_e32 v0, v26, v72
	v_mul_f32_e32 v0, 0xbfb8aa3b, v0
	v_exp_f32_e32 v69, v0
	v_add_f32_e32 v0, v27, v73
	v_mul_f32_e32 v0, 0xbfb8aa3b, v0
	v_exp_f32_e32 v67, v0
	s_waitcnt lgkmcnt(0)
	v_add_f32_e32 v0, v20, v74
	v_mul_f32_e32 v0, 0xbfb8aa3b, v0
	v_exp_f32_e32 v64, v0
	v_add_f32_e32 v0, v21, v75
	v_mul_f32_e32 v0, 0xbfb8aa3b, v0
	v_exp_f32_e32 v62, v0
	v_add_f32_e32 v0, v22, v76
	v_mul_f32_e32 v0, 0xbfb8aa3b, v0
	v_exp_f32_e32 v65, v0
	v_add_f32_e32 v0, v23, v77
	v_mul_f32_e32 v0, 0xbfb8aa3b, v0
	v_pk_add_f32 v[76:77], v[86:87], 1.0 op_sel_hi:[1,0]
	v_exp_f32_e32 v63, v0
	v_pk_add_f32 v[68:69], v[68:69], 1.0 op_sel_hi:[1,0]
	v_pk_add_f32 v[66:67], v[66:67], 1.0 op_sel_hi:[1,0]
	v_pk_add_f32 v[64:65], v[64:65], 1.0 op_sel_hi:[1,0]
	v_pk_add_f32 v[62:63], v[62:63], 1.0 op_sel_hi:[1,0]
	s_waitcnt vmcnt(3)
	v_lshlrev_b32_e32 v70, 16, v78
	v_and_b32_e32 v72, 0xffff0000, v78
	s_waitcnt vmcnt(2)
	v_lshlrev_b32_e32 v74, 16, v82
	v_and_b32_e32 v78, 0xffff0000, v82
	v_lshlrev_b32_e32 v71, 16, v79
	v_and_b32_e32 v73, 0xffff0000, v79
	v_lshlrev_b32_e32 v75, 16, v83
	v_and_b32_e32 v79, 0xffff0000, v83
	v_rcp_f32_e32 v77, v77
	v_pk_add_f32 v[82:83], v[88:89], 1.0 op_sel_hi:[1,0]
	v_rcp_f32_e32 v76, v76
	s_nop 0
	v_pk_mul_f32 v[70:71], v[76:77], v[70:71]
	v_pk_mul_f32 v[70:71], v[70:71], v[74:75]
	v_rcp_f32_e32 v75, v83
	v_and_b32_e32 v83, 0xffff0000, v85
	v_rcp_f32_e32 v74, v82
	s_nop 0
	v_pk_mul_f32 v[72:73], v[74:75], v[72:73]
	v_lshlrev_b32_e32 v75, 16, v81
	v_lshlrev_b32_e32 v74, 16, v80
	v_and_b32_e32 v77, 0xffff0000, v81
	v_and_b32_e32 v76, 0xffff0000, v80
	v_pk_add_f32 v[80:81], v[90:91], 1.0 op_sel_hi:[1,0]
	v_pk_mul_f32 v[72:73], v[72:73], v[78:79]
	v_lshlrev_b32_e32 v78, 16, v84
	v_and_b32_e32 v82, 0xffff0000, v84
	v_lshlrev_b32_e32 v79, 16, v85
	v_rcp_f32_e32 v81, v81
	v_pk_add_f32 v[84:85], v[92:93], 1.0 op_sel_hi:[1,0]
	v_rcp_f32_e32 v80, v80
	s_nop 0
	v_pk_mul_f32 v[74:75], v[80:81], v[74:75]
	v_pk_mul_f32 v[74:75], v[74:75], v[78:79]
	v_rcp_f32_e32 v79, v85
	v_rcp_f32_e32 v78, v84
	s_nop 0
	v_pk_mul_f32 v[76:77], v[78:79], v[76:77]
	v_bfe_u32 v78, v73, 16, 1
	v_pk_mul_f32 v[76:77], v[76:77], v[82:83]
	v_bfe_u32 v79, v72, 16, 1
	v_add3_u32 v78, v73, v78, s24
	v_bfe_u32 v73, v71, 16, 1
	v_add3_u32 v79, v72, v79, s24
	v_bfe_u32 v72, v70, 16, 1
	v_add3_u32 v71, v71, v73, s24
	v_add3_u32 v70, v70, v72, s24
	v_cvt_pk_bf16_f32 v73, v75, v77
	v_cvt_pk_bf16_f32 v72, v74, v76
	v_lshrrev_b32_e32 v71, 16, v71
	v_and_or_b32 v71, v78, s22, v71
	v_lshrrev_b32_e32 v70, 16, v70
	v_and_or_b32 v70, v79, s22, v70
	v_rcp_f32_e32 v69, v69
	s_waitcnt vmcnt(1)
	v_lshlrev_b32_e32 v75, 16, v57
	v_rcp_f32_e32 v68, v68
	v_lshlrev_b32_e32 v74, 16, v56
	v_pk_mul_f32 v[68:69], v[68:69], v[74:75]
	v_rcp_f32_e32 v67, v67
	s_waitcnt vmcnt(0)
	v_lshlrev_b32_e32 v77, 16, v53
	v_lshlrev_b32_e32 v76, 16, v52
	v_pk_mul_f32 v[68:69], v[68:69], v[76:77]
	v_rcp_f32_e32 v66, v66
	v_and_b32_e32 v57, 0xffff0000, v57
	v_and_b32_e32 v56, 0xffff0000, v56
	v_and_b32_e32 v53, 0xffff0000, v53
	v_rcp_f32_e32 v65, v65
	v_and_b32_e32 v52, 0xffff0000, v52
	v_div_scale_f32 v3, s[0:1], v63, v63, 1.0
	v_rcp_f32_e32 v74, v3
	v_pk_mul_f32 v[56:57], v[66:67], v[56:57]
	v_rcp_f32_e32 v64, v64
	v_pk_mul_f32 v[52:53], v[56:57], v[52:53]
	v_fma_f32 v0, -v3, v74, 1.0
	v_lshlrev_b32_e32 v57, 16, v59
	v_lshlrev_b32_e32 v56, 16, v58
	v_fmac_f32_e32 v74, v0, v74
	v_div_scale_f32 v0, vcc, 1.0, v63, 1.0
	v_pk_mul_f32 v[56:57], v[64:65], v[56:57]
	v_mul_f32_e32 v64, v0, v74
	v_fma_f32 v65, -v3, v64, v0
	v_fmac_f32_e32 v64, v65, v74
	v_fma_f32 v0, -v3, v64, v0
	v_div_scale_f32 v3, s[0:1], v62, v62, 1.0
	v_rcp_f32_e32 v65, v3
	v_div_fmas_f32 v0, v0, v74, v64
	v_div_fixup_f32 v63, v0, v63, 1.0
	v_lshlrev_b32_e32 v67, 16, v55
	v_fma_f32 v0, -v3, v65, 1.0
	v_fmac_f32_e32 v65, v0, v65
	v_div_scale_f32 v0, vcc, 1.0, v62, 1.0
	v_lshlrev_b32_e32 v66, 16, v54
	v_mul_f32_e32 v64, v0, v65
	v_pk_mul_f32 v[56:57], v[56:57], v[66:67]
	v_fma_f32 v66, -v3, v64, v0
	v_fmac_f32_e32 v64, v66, v65
	v_fma_f32 v0, -v3, v64, v0
	v_div_fmas_f32 v0, v0, v65, v64
	v_and_b32_e32 v59, 0xffff0000, v59
	v_and_b32_e32 v58, 0xffff0000, v58
	v_div_fixup_f32 v62, v0, v62, 1.0
	v_and_b32_e32 v55, 0xffff0000, v55
	v_and_b32_e32 v54, 0xffff0000, v54
	v_pk_mul_f32 v[58:59], v[62:63], v[58:59]
	s_nop 0
	v_pk_mul_f32 v[54:55], v[58:59], v[54:55]
	v_bfe_u32 v0, v55, 16, 1
	v_bfe_u32 v3, v54, 16, 1
	v_add3_u32 v3, v54, v3, s24
	v_add3_u32 v0, v55, v0, s24
	v_bfe_u32 v58, v56, 16, 1
	v_bfe_u32 v59, v57, 16, 1
	v_add3_u32 v57, v57, v59, s24
	v_add3_u32 v56, v56, v58, s24
	v_lshrrev_b32_e32 v54, 16, v56
	v_lshrrev_b32_e32 v55, 16, v57
	v_and_or_b32 v55, v0, s22, v55
	v_and_or_b32 v54, v3, s22, v54
	v_cvt_pk_bf16_f32 v53, v69, v53
	v_cvt_pk_bf16_f32 v52, v68, v52
	global_store_dwordx4 v[60:61], v[70:73], off
	global_store_dwordx4 v[60:61], v[52:55], off offset:16
	ds_write2_b32 v155, v36, v40 offset1:16
	ds_write2_b32 v155, v37, v41 offset0:68 offset1:84
	ds_write2_b32 v155, v38, v42 offset0:136 offset1:152
	ds_write2_b32 v155, v39, v43 offset0:204 offset1:220
	ds_write2_b32 v155, v28, v32 offset0:32 offset1:48
	ds_write2_b32 v155, v29, v33 offset0:100 offset1:116
	ds_write2_b32 v155, v30, v34 offset0:168 offset1:184
	ds_write2_b32 v155, v31, v35 offset0:236 offset1:252
	s_waitcnt lgkmcnt(0)
; DI unsigned pack2(float a, float b) { return (unsigned)f2bf(a) | ((unsigned)f2bf(b) << 16); }
; DI float sigm(float x) { return 1.f / (1.f + __expf(-x)); }
; DI void store16_bf(bft* dst, const float (&v)[16]) {
;   u32x4 o0 = {pack2(v[0], v[1]), pack2(v[2], v[3]), pack2(v[4], v[5]), pack2(v[6], v[7])}, o1 = {pack2(v[8], v[9]), pack2(v[10], v[11]), pack2(v[12], v[13]), pack2(v[14], v[15])};
;   *(u32x4*)dst = o0; *(u32x4*)(dst + 8) = o1;
; }
; DI void load16_bf(const bft* src, float (&v)[16]) {
;   u32x4 w0 = *(const u32x4*)src, w1 = *(const u32x4*)(src + 8);
; #pragma unroll
;   for (int i = 0; i < 4; ++i) { v[2 * i] = __uint_as_float(w0[i] << 16); v[2 * i + 1] = __uint_as_float(w0[i] & 0xffff0000u); v[8 + 2 * i] = __uint_as_float(w1[i] << 16); v[8 + 2 * i + 1] = __uint_as_float(w1[i] & 0xffff0000u); }
; }
; DI void phase_glu(const Params& p) {
;     ...
;     float b[16]; load16_f(p.s5_glu_b + bcol + ((tid >> 6) & 3) * 64 + (tid & 3) * 16, b);
;     EPI256_BEGIN
;       float y[16], g[16]; load16_bf(ys + (size_t)row * LDP + col, y); bft* gp = G0 + (size_t)row * 2048 + col; load16_bf(gp, g);
; #pragma unroll
;       for (int i = 0; i < 16; ++i) v[i] = y[i] * sigm(v[i] + b[i]) * g[i];
;       store16_bf(gp, v);
	v_or_b32_e32 v28, 0x60, v2
	ds_read_b128 v[38:41], v154
	ds_read_b128 v[52:55], v154 offset:16
	ds_read_b128 v[56:59], v154 offset:32
	ds_read_b128 v[60:63], v154 offset:48
	v_mad_i64_i32 v[30:31], s[0:1], v28, s4, v[148:149]
	global_load_dwordx4 v[64:67], v[30:31], off
	v_ashrrev_i32_e32 v29, 31, v28
	v_lshlrev_b64 v[28:29], 12, v[28:29]
	v_lshl_add_u64 v[36:37], v[140:141], 0, v[28:29]
	global_load_dwordx4 v[68:71], v[36:37], off
	global_load_dwordx4 v[32:35], v[30:31], off offset:16
	s_nop 0
	global_load_dwordx4 v[28:31], v[36:37], off offset:16
	s_waitcnt lgkmcnt(3)
	v_add_f32_e32 v0, v48, v38
	v_mul_f32_e32 v0, 0xbfb8aa3b, v0
	v_exp_f32_e32 v72, v0
	v_add_f32_e32 v0, v49, v39
	v_mul_f32_e32 v0, 0xbfb8aa3b, v0
	v_exp_f32_e32 v74, v0
	v_add_f32_e32 v0, v50, v40
	v_mul_f32_e32 v0, 0xbfb8aa3b, v0
	v_exp_f32_e32 v73, v0
	v_add_f32_e32 v0, v51, v41
	v_mul_f32_e32 v0, 0xbfb8aa3b, v0
	v_exp_f32_e32 v75, v0
	s_waitcnt lgkmcnt(2)
	v_add_f32_e32 v0, v44, v52
	v_mul_f32_e32 v0, 0xbfb8aa3b, v0
	v_exp_f32_e32 v76, v0
	v_add_f32_e32 v0, v45, v53
	v_mul_f32_e32 v0, 0xbfb8aa3b, v0
	v_exp_f32_e32 v78, v0
	v_add_f32_e32 v0, v46, v54
	v_mul_f32_e32 v0, 0xbfb8aa3b, v0
	v_exp_f32_e32 v77, v0
	v_add_f32_e32 v0, v47, v55
	v_mul_f32_e32 v0, 0xbfb8aa3b, v0
	v_exp_f32_e32 v79, v0
	s_waitcnt lgkmcnt(1)
	v_add_f32_e32 v0, v24, v56
	v_mul_f32_e32 v0, 0xbfb8aa3b, v0
	v_exp_f32_e32 v52, v0
	v_add_f32_e32 v0, v25, v57
	v_mul_f32_e32 v0, 0xbfb8aa3b, v0
	v_exp_f32_e32 v42, v0
	v_add_f32_e32 v0, v26, v58
	v_mul_f32_e32 v0, 0xbfb8aa3b, v0
	v_exp_f32_e32 v53, v0
	v_add_f32_e32 v0, v27, v59
	v_mul_f32_e32 v0, 0xbfb8aa3b, v0
	v_exp_f32_e32 v43, v0
	s_waitcnt lgkmcnt(0)
	v_add_f32_e32 v0, v20, v60
	v_mul_f32_e32 v0, 0xbfb8aa3b, v0
	v_exp_f32_e32 v40, v0
	v_add_f32_e32 v0, v21, v61
	v_mul_f32_e32 v0, 0xbfb8aa3b, v0
	v_exp_f32_e32 v38, v0
	v_add_f32_e32 v0, v22, v62
	v_mul_f32_e32 v0, 0xbfb8aa3b, v0
	v_exp_f32_e32 v41, v0
	v_add_f32_e32 v0, v23, v63
	v_mul_f32_e32 v0, 0xbfb8aa3b, v0
	v_pk_add_f32 v[60:61], v[72:73], 1.0 op_sel_hi:[1,0]
	v_exp_f32_e32 v39, v0
	v_pk_add_f32 v[52:53], v[52:53], 1.0 op_sel_hi:[1,0]
	v_pk_add_f32 v[42:43], v[42:43], 1.0 op_sel_hi:[1,0]
	v_pk_add_f32 v[40:41], v[40:41], 1.0 op_sel_hi:[1,0]
	v_pk_add_f32 v[38:39], v[38:39], 1.0 op_sel_hi:[1,0]
	v_or_b32_e32 v2, 0x70, v2
	s_waitcnt vmcnt(3)
	v_lshlrev_b32_e32 v54, 16, v64
	v_and_b32_e32 v56, 0xffff0000, v64
	v_lshlrev_b32_e32 v55, 16, v65
	v_and_b32_e32 v57, 0xffff0000, v65
	s_waitcnt vmcnt(2)
	v_lshlrev_b32_e32 v58, 16, v68
	v_and_b32_e32 v62, 0xffff0000, v68
	v_rcp_f32_e32 v61, v61
	v_lshlrev_b32_e32 v59, 16, v69
	v_pk_add_f32 v[64:65], v[74:75], 1.0 op_sel_hi:[1,0]
	v_rcp_f32_e32 v60, v60
	s_nop 0
	v_pk_mul_f32 v[54:55], v[60:61], v[54:55]
	v_and_b32_e32 v63, 0xffff0000, v69
	v_pk_mul_f32 v[54:55], v[54:55], v[58:59]
	v_rcp_f32_e32 v59, v65
	v_rcp_f32_e32 v58, v64
	v_pk_add_f32 v[64:65], v[76:77], 1.0 op_sel_hi:[1,0]
	v_pk_mul_f32 v[56:57], v[58:59], v[56:57]
	v_pk_mul_f32 v[56:57], v[56:57], v[62:63]
	v_lshlrev_b32_e32 v58, 16, v66
	v_and_b32_e32 v60, 0xffff0000, v66
	v_lshlrev_b32_e32 v62, 16, v70
	v_and_b32_e32 v66, 0xffff0000, v70
	v_rcp_f32_e32 v65, v65
	v_lshlrev_b32_e32 v59, 16, v67
	v_pk_add_f32 v[68:69], v[78:79], 1.0 op_sel_hi:[1,0]
	v_rcp_f32_e32 v64, v64
	v_lshlrev_b32_e32 v63, 16, v71
	v_pk_mul_f32 v[58:59], v[64:65], v[58:59]
	v_pk_mul_f32 v[58:59], v[58:59], v[62:63]
	v_rcp_f32_e32 v63, v69
	v_and_b32_e32 v61, 0xffff0000, v67
	v_rcp_f32_e32 v62, v68
	v_and_b32_e32 v67, 0xffff0000, v71
	v_pk_mul_f32 v[60:61], v[62:63], v[60:61]
	v_bfe_u32 v62, v57, 16, 1
	v_pk_mul_f32 v[60:61], v[60:61], v[66:67]
	v_bfe_u32 v63, v56, 16, 1
	v_add3_u32 v62, v57, v62, s24
	v_bfe_u32 v57, v55, 16, 1
	v_add3_u32 v63, v56, v63, s24
	v_bfe_u32 v56, v54, 16, 1
	v_add3_u32 v55, v55, v57, s24
	v_add3_u32 v54, v54, v56, s24
	v_cvt_pk_bf16_f32 v57, v59, v61
	v_cvt_pk_bf16_f32 v56, v58, v60
	v_lshrrev_b32_e32 v55, 16, v55
	v_and_or_b32 v55, v62, s22, v55
	v_lshrrev_b32_e32 v54, 16, v54
	v_and_or_b32 v54, v63, s22, v54
	v_rcp_f32_e32 v53, v53
	s_waitcnt vmcnt(1)
	v_lshlrev_b32_e32 v59, 16, v33
	v_rcp_f32_e32 v52, v52
	v_lshlrev_b32_e32 v58, 16, v32
	v_pk_mul_f32 v[52:53], v[52:53], v[58:59]
	v_rcp_f32_e32 v43, v43
	s_waitcnt vmcnt(0)
	v_lshlrev_b32_e32 v61, 16, v29
	v_lshlrev_b32_e32 v60, 16, v28
	v_pk_mul_f32 v[52:53], v[52:53], v[60:61]
	v_rcp_f32_e32 v42, v42
	v_and_b32_e32 v33, 0xffff0000, v33
	v_and_b32_e32 v32, 0xffff0000, v32
	v_and_b32_e32 v29, 0xffff0000, v29
	v_rcp_f32_e32 v41, v41
	v_and_b32_e32 v28, 0xffff0000, v28
	v_div_scale_f32 v3, s[0:1], v39, v39, 1.0
	v_rcp_f32_e32 v58, v3
	v_pk_mul_f32 v[32:33], v[42:43], v[32:33]
	v_rcp_f32_e32 v40, v40
	v_pk_mul_f32 v[28:29], v[32:33], v[28:29]
	v_fma_f32 v0, -v3, v58, 1.0
	v_lshlrev_b32_e32 v33, 16, v35
	v_lshlrev_b32_e32 v32, 16, v34
	v_fmac_f32_e32 v58, v0, v58
	v_div_scale_f32 v0, vcc, 1.0, v39, 1.0
	v_pk_mul_f32 v[32:33], v[40:41], v[32:33]
	v_mul_f32_e32 v40, v0, v58
	v_fma_f32 v41, -v3, v40, v0
	v_fmac_f32_e32 v40, v41, v58
	v_fma_f32 v0, -v3, v40, v0
	v_div_scale_f32 v3, s[0:1], v38, v38, 1.0
	v_rcp_f32_e32 v41, v3
	v_div_fmas_f32 v0, v0, v58, v40
	v_div_fixup_f32 v39, v0, v39, 1.0
	v_lshlrev_b32_e32 v43, 16, v31
	v_fma_f32 v0, -v3, v41, 1.0
	v_fmac_f32_e32 v41, v0, v41
	v_div_scale_f32 v0, vcc, 1.0, v38, 1.0
	v_lshlrev_b32_e32 v42, 16, v30
	v_mul_f32_e32 v40, v0, v41
	v_pk_mul_f32 v[32:33], v[32:33], v[42:43]
	v_fma_f32 v42, -v3, v40, v0
	v_fmac_f32_e32 v40, v42, v41
	v_fma_f32 v0, -v3, v40, v0
	v_div_fmas_f32 v0, v0, v41, v40
	v_and_b32_e32 v35, 0xffff0000, v35
	v_and_b32_e32 v34, 0xffff0000, v34
	v_div_fixup_f32 v38, v0, v38, 1.0
	v_and_b32_e32 v31, 0xffff0000, v31
	v_and_b32_e32 v30, 0xffff0000, v30
	v_pk_mul_f32 v[34:35], v[38:39], v[34:35]
	s_nop 0
	v_pk_mul_f32 v[30:31], v[34:35], v[30:31]
	v_bfe_u32 v0, v31, 16, 1
	v_bfe_u32 v3, v30, 16, 1
	v_add3_u32 v3, v30, v3, s24
	v_add3_u32 v0, v31, v0, s24
	v_bfe_u32 v34, v32, 16, 1
	v_bfe_u32 v35, v33, 16, 1
	v_add3_u32 v33, v33, v35, s24
	v_add3_u32 v32, v32, v34, s24
	v_lshrrev_b32_e32 v30, 16, v32
	v_lshrrev_b32_e32 v31, 16, v33
	v_and_or_b32 v31, v0, s22, v31
	v_and_or_b32 v30, v3, s22, v30
	v_cvt_pk_bf16_f32 v29, v53, v29
	v_cvt_pk_bf16_f32 v28, v52, v28
	global_store_dwordx4 v[36:37], v[54:57], off
	global_store_dwordx4 v[36:37], v[28:31], off offset:16
	ds_write2_b32 v155, v12, v16 offset1:16
	ds_write2_b32 v155, v13, v17 offset0:68 offset1:84
	ds_write2_b32 v155, v14, v18 offset0:136 offset1:152
	ds_write2_b32 v155, v15, v19 offset0:204 offset1:220
	ds_write2_b32 v155, v4, v8 offset0:32 offset1:48
	ds_write2_b32 v155, v5, v9 offset0:100 offset1:116
	ds_write2_b32 v155, v6, v10 offset0:168 offset1:184
	ds_write2_b32 v155, v7, v11 offset0:236 offset1:252
	s_waitcnt lgkmcnt(0)
; DI unsigned pack2(float a, float b) { return (unsigned)f2bf(a) | ((unsigned)f2bf(b) << 16); }
; DI float sigm(float x) { return 1.f / (1.f + __expf(-x)); }
; DI void store16_bf(bft* dst, const float (&v)[16]) {
;   u32x4 o0 = {pack2(v[0], v[1]), pack2(v[2], v[3]), pack2(v[4], v[5]), pack2(v[6], v[7])}, o1 = {pack2(v[8], v[9]), pack2(v[10], v[11]), pack2(v[12], v[13]), pack2(v[14], v[15])};
;   *(u32x4*)dst = o0; *(u32x4*)(dst + 8) = o1;
; }
; DI void load16_bf(const bft* src, float (&v)[16]) {
;   u32x4 w0 = *(const u32x4*)src, w1 = *(const u32x4*)(src + 8);
; #pragma unroll
;   for (int i = 0; i < 4; ++i) { v[2 * i] = __uint_as_float(w0[i] << 16); v[2 * i + 1] = __uint_as_float(w0[i] & 0xffff0000u); v[8 + 2 * i] = __uint_as_float(w1[i] << 16); v[8 + 2 * i + 1] = __uint_as_float(w1[i] & 0xffff0000u); }
; }
; DI void phase_glu(const Params& p) {
;     ...
;     float b[16]; load16_f(p.s5_glu_b + bcol + ((tid >> 6) & 3) * 64 + (tid & 3) * 16, b);
;     EPI256_BEGIN
;       float y[16], g[16]; load16_bf(ys + (size_t)row * LDP + col, y); bft* gp = G0 + (size_t)row * 2048 + col; load16_bf(gp, g);
; #pragma unroll
;       for (int i = 0; i < 16; ++i) v[i] = y[i] * sigm(v[i] + b[i]) * g[i];
;       store16_bf(gp, v);
	ds_read_b128 v[12:15], v154
	ds_read_b128 v[16:19], v154 offset:16
	ds_read_b128 v[28:31], v154 offset:32
	ds_read_b128 v[32:35], v154 offset:48
	v_mad_i64_i32 v[4:5], s[0:1], v2, s4, v[148:149]
	global_load_dwordx4 v[36:39], v[4:5], off
	v_ashrrev_i32_e32 v3, 31, v2
	v_lshlrev_b64 v[2:3], 12, v[2:3]
	v_lshl_add_u64 v[10:11], v[140:141], 0, v[2:3]
	global_load_dwordx4 v[40:43], v[10:11], off
	global_load_dwordx4 v[6:9], v[4:5], off offset:16
	s_nop 0
	global_load_dwordx4 v[2:5], v[10:11], off offset:16
	s_waitcnt lgkmcnt(3)
	v_add_f32_e32 v0, v48, v12
	v_mul_f32_e32 v0, 0xbfb8aa3b, v0
	v_exp_f32_e32 v48, v0
	v_add_f32_e32 v0, v49, v13
	v_mul_f32_e32 v0, 0xbfb8aa3b, v0
	v_exp_f32_e32 v52, v0
	v_add_f32_e32 v0, v50, v14
	v_mul_f32_e32 v0, 0xbfb8aa3b, v0
	v_exp_f32_e32 v49, v0
	v_add_f32_e32 v0, v51, v15
	v_mul_f32_e32 v0, 0xbfb8aa3b, v0
	v_exp_f32_e32 v53, v0
	s_waitcnt lgkmcnt(2)
	v_add_f32_e32 v0, v44, v16
	v_mul_f32_e32 v0, 0xbfb8aa3b, v0
	v_exp_f32_e32 v44, v0
	v_add_f32_e32 v0, v45, v17
	v_mul_f32_e32 v0, 0xbfb8aa3b, v0
	v_exp_f32_e32 v50, v0
	v_add_f32_e32 v0, v46, v18
	v_mul_f32_e32 v0, 0xbfb8aa3b, v0
	v_exp_f32_e32 v45, v0
	v_add_f32_e32 v0, v47, v19
	v_mul_f32_e32 v0, 0xbfb8aa3b, v0
	v_exp_f32_e32 v51, v0
	s_waitcnt lgkmcnt(1)
	v_add_f32_e32 v0, v24, v28
	v_mul_f32_e32 v0, 0xbfb8aa3b, v0
	v_exp_f32_e32 v18, v0
	v_add_f32_e32 v0, v25, v29
	v_mul_f32_e32 v0, 0xbfb8aa3b, v0
	v_exp_f32_e32 v16, v0
	v_add_f32_e32 v0, v26, v30
	v_mul_f32_e32 v0, 0xbfb8aa3b, v0
	v_exp_f32_e32 v19, v0
	v_add_f32_e32 v0, v27, v31
	v_mul_f32_e32 v0, 0xbfb8aa3b, v0
	v_exp_f32_e32 v17, v0
	s_waitcnt lgkmcnt(0)
	v_add_f32_e32 v0, v20, v32
	v_mul_f32_e32 v0, 0xbfb8aa3b, v0
	v_exp_f32_e32 v14, v0
	v_add_f32_e32 v0, v21, v33
	v_mul_f32_e32 v0, 0xbfb8aa3b, v0
	v_exp_f32_e32 v12, v0
	v_add_f32_e32 v0, v22, v34
	v_mul_f32_e32 v0, 0xbfb8aa3b, v0
	v_exp_f32_e32 v15, v0
	v_add_f32_e32 v0, v23, v35
	v_mul_f32_e32 v0, 0xbfb8aa3b, v0
	v_pk_add_f32 v[26:27], v[48:49], 1.0 op_sel_hi:[1,0]
	v_exp_f32_e32 v13, v0
	v_pk_add_f32 v[18:19], v[18:19], 1.0 op_sel_hi:[1,0]
	v_pk_add_f32 v[16:17], v[16:17], 1.0 op_sel_hi:[1,0]
	v_pk_add_f32 v[14:15], v[14:15], 1.0 op_sel_hi:[1,0]
	v_rcp_f32_e32 v27, v27
	v_pk_add_f32 v[12:13], v[12:13], 1.0 op_sel_hi:[1,0]
	v_pk_add_f32 v[30:31], v[52:53], 1.0 op_sel_hi:[1,0]
	s_waitcnt vmcnt(3)
	v_lshlrev_b32_e32 v21, 16, v37
	v_lshlrev_b32_e32 v20, 16, v36
	v_rcp_f32_e32 v26, v26
	s_waitcnt vmcnt(2)
	v_lshlrev_b32_e32 v25, 16, v41
	v_lshlrev_b32_e32 v24, 16, v40
	v_pk_mul_f32 v[20:21], v[26:27], v[20:21]
	v_pk_mul_f32 v[20:21], v[20:21], v[24:25]
	v_rcp_f32_e32 v25, v31
	v_rcp_f32_e32 v24, v30
	v_pk_add_f32 v[30:31], v[44:45], 1.0 op_sel_hi:[1,0]
	v_and_b32_e32 v22, 0xffff0000, v36
	v_and_b32_e32 v23, 0xffff0000, v37
	v_and_b32_e32 v29, 0xffff0000, v41
	v_and_b32_e32 v28, 0xffff0000, v40
	v_rcp_f32_e32 v31, v31
	v_pk_mul_f32 v[22:23], v[24:25], v[22:23]
	v_pk_add_f32 v[34:35], v[50:51], 1.0 op_sel_hi:[1,0]
	v_lshlrev_b32_e32 v25, 16, v39
	v_lshlrev_b32_e32 v24, 16, v38
	v_rcp_f32_e32 v30, v30
	v_pk_mul_f32 v[22:23], v[22:23], v[28:29]
	v_lshlrev_b32_e32 v29, 16, v43
	v_lshlrev_b32_e32 v28, 16, v42
	v_pk_mul_f32 v[24:25], v[30:31], v[24:25]
	v_pk_mul_f32 v[24:25], v[24:25], v[28:29]
	v_rcp_f32_e32 v29, v35
	v_and_b32_e32 v27, 0xffff0000, v39
	v_and_b32_e32 v26, 0xffff0000, v38
	v_rcp_f32_e32 v28, v34
	v_and_b32_e32 v33, 0xffff0000, v43
	v_and_b32_e32 v32, 0xffff0000, v42
	v_pk_mul_f32 v[26:27], v[28:29], v[26:27]
	v_bfe_u32 v30, v22, 16, 1
	v_pk_mul_f32 v[26:27], v[26:27], v[32:33]
	v_bfe_u32 v29, v23, 16, 1
	v_bfe_u32 v28, v26, 16, 1
	v_add3_u32 v30, v22, v30, s24
	v_add3_u32 v22, v26, v28, s24
	v_add3_u32 v29, v23, v29, s24
	v_bfe_u32 v23, v20, 16, 1
	v_add3_u32 v20, v20, v23, s24
	v_cvt_pk_bf16_f32 v23, v25, v27
	v_bfe_u32 v26, v21, 16, 1
	v_add3_u32 v21, v21, v26, s24
	v_lshrrev_b32_e32 v21, 16, v21
	v_and_or_b32 v21, v29, s22, v21
	v_lshrrev_b32_e32 v20, 16, v20
	v_and_or_b32 v20, v30, s22, v20
	v_rcp_f32_e32 v19, v19
	v_bfe_u32 v27, v24, 16, 1
	v_add3_u32 v24, v24, v27, s24
	v_lshrrev_b32_e32 v24, 16, v24
	v_rcp_f32_e32 v18, v18
	v_and_or_b32 v22, v22, s22, v24
	s_waitcnt vmcnt(1)
	v_lshlrev_b32_e32 v25, 16, v7
	v_lshlrev_b32_e32 v24, 16, v6
	v_pk_mul_f32 v[18:19], v[18:19], v[24:25]
	s_waitcnt vmcnt(0)
	v_lshlrev_b32_e32 v27, 16, v3
	v_lshlrev_b32_e32 v26, 16, v2
	v_pk_mul_f32 v[18:19], v[18:19], v[26:27]
	v_rcp_f32_e32 v17, v17
	v_rcp_f32_e32 v16, v16
	v_and_b32_e32 v7, 0xffff0000, v7
	v_and_b32_e32 v6, 0xffff0000, v6
	v_and_b32_e32 v3, 0xffff0000, v3
	v_rcp_f32_e32 v15, v15
	v_and_b32_e32 v2, 0xffff0000, v2
	v_pk_mul_f32 v[6:7], v[16:17], v[6:7]
	v_rcp_f32_e32 v14, v14
	v_pk_mul_f32 v[2:3], v[6:7], v[2:3]
	v_lshlrev_b32_e32 v7, 16, v9
	v_lshlrev_b32_e32 v6, 16, v8
	v_pk_mul_f32 v[6:7], v[14:15], v[6:7]
	v_lshlrev_b32_e32 v17, 16, v5
	v_lshlrev_b32_e32 v16, 16, v4
	v_div_scale_f32 v15, s[0:1], v12, v12, 1.0
	v_pk_mul_f32 v[6:7], v[6:7], v[16:17]
	v_rcp_f32_e32 v16, v15
	v_rcp_f32_e32 v13, v13
	v_fma_f32 v0, -v15, v16, 1.0
	v_fmac_f32_e32 v16, v0, v16
	v_div_scale_f32 v0, vcc, 1.0, v12, 1.0
	v_mul_f32_e32 v14, v0, v16
	v_fma_f32 v17, -v15, v14, v0
	v_fmac_f32_e32 v14, v17, v16
	v_fma_f32 v0, -v15, v14, v0
	v_div_fmas_f32 v0, v0, v16, v14
	v_and_b32_e32 v9, 0xffff0000, v9
	v_and_b32_e32 v8, 0xffff0000, v8
	v_div_fixup_f32 v12, v0, v12, 1.0
	v_and_b32_e32 v5, 0xffff0000, v5
	v_and_b32_e32 v4, 0xffff0000, v4
	v_pk_mul_f32 v[8:9], v[12:13], v[8:9]
	v_pk_mul_f32 v[4:5], v[8:9], v[4:5]
	v_bfe_u32 v0, v5, 16, 1
	v_add3_u32 v0, v5, v0, s24
	v_bfe_u32 v12, v7, 16, 1
	v_add3_u32 v7, v7, v12, s24
	v_lshrrev_b32_e32 v5, 16, v7
	s_mov_b64 s[0:1], 0
	v_and_or_b32 v5, v0, s22, v5
	v_cvt_pk_bf16_f32 v4, v6, v4
	v_cvt_pk_bf16_f32 v3, v19, v3
	v_cvt_pk_bf16_f32 v2, v18, v2
	global_store_dwordx4 v[10:11], v[20:23], off
	global_store_dwordx4 v[10:11], v[2:5], off offset:16

; DI unsigned pack2(float a, float b) { return (unsigned)f2bf(a) | ((unsigned)f2bf(b) << 16); }
; DI void convert_p(const Params& p, int layer) {
;     ...
;   for (long i = gid; i < (long)T * 256 / 4; i += gsz) { long e = i * 4; f32x4 v = e < (long)TP * 256 ? *(const f32x4*)(pp + e) : *(const f32x4*)(ps + (e - (long)TP * 256));
;     u32x2 w = {pack2(v[0], v[1]), pack2(v[2], v[3])}; *(u32x2*)(pb + e) = w; }
.LBB0_907:
	v_lshl_add_u64 v[6:7], s[8:9], 0, v[2:3]
	v_lshl_add_u64 v[8:9], s[10:11], 0, v[2:3]
	v_cmp_gt_i64_e32 vcc, s[18:19], v[0:1]
	v_lshl_add_u64 v[0:1], v[0:1], 0, s[6:7]
	v_lshl_add_u64 v[2:3], v[2:3], 0, s[12:13]
	v_cndmask_b32_e32 v7, v9, v7, vcc
	v_cndmask_b32_e32 v6, v8, v6, vcc
	global_load_dwordx4 v[6:9], v[6:7], off
	v_cmp_lt_i64_e32 vcc, s[20:21], v[0:1]
	s_or_b64 s[16:17], vcc, s[16:17]
	s_waitcnt vmcnt(0)
	v_cvt_pk_bf16_f32 v6, v6, v7
	v_cvt_pk_bf16_f32 v7, v8, v9
	global_store_dwordx2 v[4:5], v[6:7], off
	v_lshl_add_u64 v[4:5], v[4:5], 0, s[14:15]
	s_andn2_b64 exec, exec, s[16:17]
	s_cbranch_execnz .LBB0_907

; DI unsigned pack2(float a, float b) { return (unsigned)f2bf(a) | ((unsigned)f2bf(b) << 16); }
; DI void store16_bf(bft* dst, const float (&v)[16]) {
;   u32x4 o0 = {pack2(v[0], v[1]), pack2(v[2], v[3]), pack2(v[4], v[5]), pack2(v[6], v[7])}, o1 = {pack2(v[8], v[9]), pack2(v[10], v[11]), pack2(v[12], v[13]), pack2(v[14], v[15])};
;   *(u32x4*)dst = o0; *(u32x4*)(dst + 8) = o1;
; }
; DI void load16_bf(const bft* src, float (&v)[16]) {
;   u32x4 w0 = *(const u32x4*)src, w1 = *(const u32x4*)(src + 8);
; #pragma unroll
;   for (int i = 0; i < 4; ++i) { v[2 * i] = __uint_as_float(w0[i] << 16); v[2 * i + 1] = __uint_as_float(w0[i] & 0xffff0000u); v[8 + 2 * i] = __uint_as_float(w1[i] << 16); v[8 + 2 * i + 1] = __uint_as_float(w1[i] & 0xffff0000u); }
; }
; DI void load16_f(const float* src, float (&v)[16]) {
; #pragma unroll
;   for (int i = 0; i < 4; ++i) { f32x4 t = *(const f32x4*)(src + 4 * i); v[4 * i] = t[0]; v[4 * i + 1] = t[1]; v[4 * i + 2] = t[2]; v[4 * i + 3] = t[3]; }
; }
; DI void store16_f(float* dst, const float (&v)[16]) {
; #pragma unroll
;   for (int i = 0; i < 4; ++i) { f32x4 t = {v[4 * i], v[4 * i + 1], v[4 * i + 2], v[4 * i + 3]}; *(f32x4*)(dst + 4 * i) = t; }
; }
; DI void phase_outproj0(const Params& p) {
;     ...
;     EPI256_BEGIN
;       float x[16]; load16_f(xrow(p, row) + col, x);
; #pragma unroll
;       for (int i = 0; i < 16; ++i) v[i] += x[i];
;       store16_f(p.out + (size_t)row * 1024 + col, v); store16_bf(hb + (size_t)row * 1024 + col, v);
.LBB0_961:
	v_lshrrev_b32_e32 v2, 6, v149
	v_lshrrev_b32_e32 v132, 2, v149
	v_and_b32_e32 v3, 15, v149
	v_mul_lo_u32 v2, v2, s27
	v_and_b32_e32 v132, 12, v132
	v_add_u32_e32 v2, s33, v2
	v_lshlrev_b32_e32 v3, 2, v3
	v_mul_u32_u24_e32 v132, 0x110, v132
	v_add3_u32 v134, v2, v3, v132
	v_bfe_u32 v3, v149, 2, 4
	v_and_b32_e32 v133, 48, v150
	v_mul_u32_u24_e32 v132, 0x110, v3
	v_lshlrev_b32_e32 v135, 2, v133
	v_add3_u32 v135, v2, v132, v135
	v_ashrrev_i32_e32 v2, 1, v149
	v_and_b32_e32 v0, 0xc0, v149
	v_and_b32_e32 v2, 0xffffff80, v2
	v_add_u32_e32 v2, s37, v2
	v_or3_b32 v144, v0, s36, v133
	v_or_b32_e32 v132, v2, v3
	v_lshlrev_b32_e32 v0, 1, v144
	v_lshl_add_u64 v[2:3], s[16:17], 0, v[0:1]
	v_add_u32_e32 v0, 0xffffc000, v132
	v_ashrrev_i32_e32 v133, 31, v132
	v_cmp_gt_i32_e32 vcc, s30, v132
	s_waitcnt vmcnt(0)
	s_barrier
	ds_write2_b32 v134, v128, v124 offset1:16
	ds_write2_b32 v134, v129, v125 offset0:68 offset1:84
	ds_write2_b32 v134, v130, v126 offset0:136 offset1:152
	ds_write2_b32 v134, v131, v127 offset0:204 offset1:220
	ds_write2_b32 v134, v120, v116 offset0:32 offset1:48
	ds_write2_b32 v134, v121, v117 offset0:100 offset1:116
	ds_write2_b32 v134, v122, v118 offset0:168 offset1:184
	ds_write2_b32 v134, v123, v119 offset0:236 offset1:252
	v_cndmask_b32_e32 v141, 0, v133, vcc
	v_cndmask_b32_e32 v140, v0, v132, vcc
	v_mov_b32_e32 v116, s15
	v_mov_b32_e32 v117, s13
	v_mov_b32_e32 v118, s14
	v_mov_b32_e32 v119, s12
	v_cndmask_b32_e32 v143, v116, v117, vcc
	v_cndmask_b32_e32 v142, v118, v119, vcc
	v_lshlrev_b64 v[140:141], 12, v[140:141]
	s_waitcnt lgkmcnt(0)
	v_lshl_add_u64 v[140:141], v[142:143], 0, v[140:141]
	v_lshlrev_b32_e32 v0, 2, v144
	ds_read_b128 v[120:123], v135
	ds_read_b128 v[124:127], v135 offset:16
	ds_read_b128 v[128:131], v135 offset:32
	ds_read_b128 v[136:139], v135 offset:48
	v_lshl_add_u64 v[154:155], v[140:141], 0, v[0:1]
	global_load_dwordx4 v[140:143], v[154:155], off
	global_load_dwordx4 v[144:147], v[154:155], off offset:16
	global_load_dwordx4 v[150:153], v[154:155], off offset:32
	s_nop 0
	global_load_dwordx4 v[154:157], v[154:155], off offset:48
	v_lshlrev_b64 v[158:159], 12, v[132:133]
	v_lshl_add_u64 v[158:159], s[8:9], 0, v[158:159]
	v_lshlrev_b64 v[160:161], 11, v[132:133]
	v_lshl_add_u64 v[158:159], v[158:159], 0, v[0:1]
	v_lshl_add_u64 v[160:161], v[2:3], 0, v[160:161]
	s_add_i32 s2, s2, 1
	s_add_i32 s3, s3, 1
	s_mov_b64 s[22:23], 0
	s_waitcnt vmcnt(3) lgkmcnt(3)
	v_pk_add_f32 v[122:123], v[122:123], v[142:143]
	v_pk_add_f32 v[120:121], v[120:121], v[140:141]
	s_waitcnt vmcnt(2) lgkmcnt(2)
	v_pk_add_f32 v[126:127], v[126:127], v[146:147]
	v_pk_add_f32 v[124:125], v[124:125], v[144:145]
	v_bfe_u32 v133, v127, 16, 1
	v_bfe_u32 v140, v123, 16, 1
	v_bfe_u32 v142, v121, 16, 1
	v_bfe_u32 v143, v122, 16, 1
	v_bfe_u32 v144, v126, 16, 1
	v_bfe_u32 v145, v120, 16, 1
	s_waitcnt vmcnt(1) lgkmcnt(1)
	v_pk_add_f32 v[130:131], v[130:131], v[152:153]
	v_pk_add_f32 v[128:129], v[128:129], v[150:151]
	s_waitcnt vmcnt(0) lgkmcnt(0)
	v_pk_add_f32 v[138:139], v[138:139], v[156:157]
	v_pk_add_f32 v[136:137], v[136:137], v[154:155]
	global_store_dwordx4 v[158:159], v[120:123], off
	global_store_dwordx4 v[158:159], v[124:127], off offset:16
	global_store_dwordx4 v[158:159], v[128:131], off offset:32
	global_store_dwordx4 v[158:159], v[136:139], off offset:48
	s_nop 4
	v_add3_u32 v140, v123, v140, s31
	v_add3_u32 v123, v127, v133, s31
	v_add3_u32 v127, v121, v142, s31
	v_add3_u32 v121, v126, v144, s31
	v_add3_u32 v122, v122, v143, s31
	v_add3_u32 v120, v120, v145, s31
	v_lshrrev_b32_e32 v122, 16, v122
	v_lshrrev_b32_e32 v121, 16, v121
	v_lshrrev_b32_e32 v120, 16, v120
	v_and_or_b32 v123, v123, s26, v121
	v_and_or_b32 v121, v140, s26, v122
	v_cvt_pk_bf16_f32 v122, v124, v125
	v_and_or_b32 v120, v127, s26, v120
	v_bfe_u32 v125, v131, 16, 1
	v_add3_u32 v125, v131, v125, s31
	v_bfe_u32 v127, v130, 16, 1
	v_add3_u32 v127, v130, v127, s31
	v_lshrrev_b32_e32 v133, 16, v127
	v_or_b32_e32 v140, 16, v132
	v_cvt_pk_bf16_f32 v127, v138, v139
	v_and_or_b32 v125, v125, s26, v133
	v_cvt_pk_bf16_f32 v126, v136, v137
	v_cvt_pk_bf16_f32 v124, v128, v129
	global_store_dwordx4 v[160:161], v[120:123], off
	global_store_dwordx4 v[160:161], v[124:127], off offset:16
	v_ashrrev_i32_e32 v141, 31, v140
	v_add_u32_e32 v120, 0xffffc010, v132
	v_cmp_gt_i32_e32 vcc, s30, v140
	ds_write2_b32 v134, v112, v108 offset1:16
	ds_write2_b32 v134, v113, v109 offset0:68 offset1:84
	ds_write2_b32 v134, v114, v110 offset0:136 offset1:152
	ds_write2_b32 v134, v115, v111 offset0:204 offset1:220
	ds_write2_b32 v134, v104, v100 offset0:32 offset1:48
	ds_write2_b32 v134, v105, v101 offset0:100 offset1:116
	ds_write2_b32 v134, v106, v102 offset0:168 offset1:184
	ds_write2_b32 v134, v107, v103 offset0:236 offset1:252
	v_cndmask_b32_e32 v121, 0, v141, vcc
	v_cndmask_b32_e32 v120, v120, v140, vcc
	v_cndmask_b32_e32 v123, v116, v117, vcc
	v_cndmask_b32_e32 v122, v118, v119, vcc
	v_lshlrev_b64 v[120:121], 12, v[120:121]
	s_waitcnt lgkmcnt(0)
	v_lshl_add_u64 v[120:121], v[122:123], 0, v[120:121]
	ds_read_b128 v[100:103], v135
	ds_read_b128 v[104:107], v135 offset:16
	ds_read_b128 v[108:111], v135 offset:32
	ds_read_b128 v[112:115], v135 offset:48
	v_lshl_add_u64 v[136:137], v[120:121], 0, v[0:1]
	global_load_dwordx4 v[120:123], v[136:137], off
	global_load_dwordx4 v[124:127], v[136:137], off offset:16
	global_load_dwordx4 v[128:131], v[136:137], off offset:32
	s_nop 0
	global_load_dwordx4 v[136:139], v[136:137], off offset:48
	v_lshlrev_b64 v[142:143], 12, v[140:141]
	v_lshl_add_u64 v[142:143], s[8:9], 0, v[142:143]
	v_lshl_add_u64 v[142:143], v[142:143], 0, v[0:1]
	v_lshlrev_b64 v[140:141], 11, v[140:141]
	v_lshl_add_u64 v[140:141], v[2:3], 0, v[140:141]
	s_waitcnt vmcnt(3) lgkmcnt(3)
; DI unsigned pack2(float a, float b) { return (unsigned)f2bf(a) | ((unsigned)f2bf(b) << 16); }
; DI void store16_bf(bft* dst, const float (&v)[16]) {
;   u32x4 o0 = {pack2(v[0], v[1]), pack2(v[2], v[3]), pack2(v[4], v[5]), pack2(v[6], v[7])}, o1 = {pack2(v[8], v[9]), pack2(v[10], v[11]), pack2(v[12], v[13]), pack2(v[14], v[15])};
;   *(u32x4*)dst = o0; *(u32x4*)(dst + 8) = o1;
; }
; DI void load16_bf(const bft* src, float (&v)[16]) {
;   u32x4 w0 = *(const u32x4*)src, w1 = *(const u32x4*)(src + 8);
; #pragma unroll
;   for (int i = 0; i < 4; ++i) { v[2 * i] = __uint_as_float(w0[i] << 16); v[2 * i + 1] = __uint_as_float(w0[i] & 0xffff0000u); v[8 + 2 * i] = __uint_as_float(w1[i] << 16); v[8 + 2 * i + 1] = __uint_as_float(w1[i] & 0xffff0000u); }
; }
; DI void load16_f(const float* src, float (&v)[16]) {
; #pragma unroll
;   for (int i = 0; i < 4; ++i) { f32x4 t = *(const f32x4*)(src + 4 * i); v[4 * i] = t[0]; v[4 * i + 1] = t[1]; v[4 * i + 2] = t[2]; v[4 * i + 3] = t[3]; }
; }
; DI void store16_f(float* dst, const float (&v)[16]) {
; #pragma unroll
;   for (int i = 0; i < 4; ++i) { f32x4 t = {v[4 * i], v[4 * i + 1], v[4 * i + 2], v[4 * i + 3]}; *(f32x4*)(dst + 4 * i) = t; }
; }
; DI void phase_outproj0(const Params& p) {
;     ...
;     EPI256_BEGIN
;       float x[16]; load16_f(xrow(p, row) + col, x);
; #pragma unroll
;       for (int i = 0; i < 16; ++i) v[i] += x[i];
;       store16_f(p.out + (size_t)row * 1024 + col, v); store16_bf(hb + (size_t)row * 1024 + col, v);
	v_pk_add_f32 v[102:103], v[102:103], v[122:123]
	v_pk_add_f32 v[100:101], v[100:101], v[120:121]
	s_waitcnt vmcnt(2) lgkmcnt(2)
	v_pk_add_f32 v[106:107], v[106:107], v[126:127]
	v_pk_add_f32 v[104:105], v[104:105], v[124:125]
	v_bfe_u32 v120, v107, 16, 1
	v_bfe_u32 v121, v103, 16, 1
	v_bfe_u32 v122, v105, 16, 1
	v_bfe_u32 v123, v101, 16, 1
	s_waitcnt vmcnt(1) lgkmcnt(1)
	v_pk_add_f32 v[110:111], v[110:111], v[130:131]
	v_pk_add_f32 v[108:109], v[108:109], v[128:129]
	s_waitcnt vmcnt(0) lgkmcnt(0)
	v_pk_add_f32 v[114:115], v[114:115], v[138:139]
	v_pk_add_f32 v[112:113], v[112:113], v[136:137]
	global_store_dwordx4 v[142:143], v[100:103], off
	global_store_dwordx4 v[142:143], v[104:107], off offset:16
	global_store_dwordx4 v[142:143], v[108:111], off offset:32
	global_store_dwordx4 v[142:143], v[112:115], off offset:48
	v_add3_u32 v121, v103, v121, s31
	v_add3_u32 v103, v107, v120, s31
	v_add3_u32 v107, v101, v123, s31
	v_add3_u32 v105, v105, v122, s31
	v_bfe_u32 v101, v102, 16, 1
	v_bfe_u32 v120, v106, 16, 1
	v_bfe_u32 v122, v100, 16, 1
	v_bfe_u32 v123, v104, 16, 1
	v_add3_u32 v106, v106, v120, s31
	v_add3_u32 v101, v102, v101, s31
	v_add3_u32 v102, v104, v123, s31
	v_add3_u32 v100, v100, v122, s31
	v_lshrrev_b32_e32 v104, 16, v106
	v_lshrrev_b32_e32 v100, 16, v100
	v_lshrrev_b32_e32 v102, 16, v102
	v_and_or_b32 v103, v103, s26, v104
	v_and_or_b32 v102, v105, s26, v102
	v_and_or_b32 v100, v107, s26, v100
	v_bfe_u32 v104, v115, 16, 1
	v_bfe_u32 v105, v111, 16, 1
	v_bfe_u32 v106, v113, 16, 1
	v_add3_u32 v105, v111, v105, s31
	v_add3_u32 v104, v115, v104, s31
	v_add3_u32 v106, v113, v106, s31
	v_bfe_u32 v107, v110, 16, 1
	v_bfe_u32 v111, v114, 16, 1
	v_bfe_u32 v115, v112, 16, 1
	v_lshrrev_b32_e32 v101, 16, v101
	v_add3_u32 v111, v114, v111, s31
	v_add3_u32 v107, v110, v107, s31
	v_add3_u32 v110, v112, v115, s31
	v_and_or_b32 v101, v121, s26, v101
	v_lshrrev_b32_e32 v112, 16, v107
	v_lshrrev_b32_e32 v107, 16, v111
	v_lshrrev_b32_e32 v110, 16, v110
	v_or_b32_e32 v120, 32, v132
	v_and_or_b32 v107, v104, s26, v107
	v_and_or_b32 v105, v105, s26, v112
	v_and_or_b32 v106, v106, s26, v110
	v_cvt_pk_bf16_f32 v104, v108, v109
	global_store_dwordx4 v[140:141], v[100:103], off
	global_store_dwordx4 v[140:141], v[104:107], off offset:16
	v_ashrrev_i32_e32 v121, 31, v120
	v_add_u32_e32 v100, 0xffffc020, v132
	v_cmp_gt_i32_e32 vcc, s30, v120
	ds_write2_b32 v134, v96, v92 offset1:16
	ds_write2_b32 v134, v97, v93 offset0:68 offset1:84
	ds_write2_b32 v134, v98, v94 offset0:136 offset1:152
	ds_write2_b32 v134, v99, v95 offset0:204 offset1:220
	ds_write2_b32 v134, v88, v84 offset0:32 offset1:48
	ds_write2_b32 v134, v89, v85 offset0:100 offset1:116
	ds_write2_b32 v134, v90, v86 offset0:168 offset1:184
	ds_write2_b32 v134, v91, v87 offset0:236 offset1:252
	v_cndmask_b32_e32 v101, 0, v121, vcc
	v_cndmask_b32_e32 v100, v100, v120, vcc
	v_cndmask_b32_e32 v103, v116, v117, vcc
	v_cndmask_b32_e32 v102, v118, v119, vcc
	v_lshlrev_b64 v[100:101], 12, v[100:101]
	s_waitcnt lgkmcnt(0)
	v_lshl_add_u64 v[100:101], v[102:103], 0, v[100:101]
	ds_read_b128 v[84:87], v135
	ds_read_b128 v[88:91], v135 offset:16
	ds_read_b128 v[92:95], v135 offset:32
	ds_read_b128 v[96:99], v135 offset:48
	v_lshl_add_u64 v[112:113], v[100:101], 0, v[0:1]
	global_load_dwordx4 v[100:103], v[112:113], off
	global_load_dwordx4 v[104:107], v[112:113], off offset:16
	global_load_dwordx4 v[108:111], v[112:113], off offset:32
	s_nop 0
	global_load_dwordx4 v[112:115], v[112:113], off offset:48
	v_lshlrev_b64 v[122:123], 12, v[120:121]
	v_lshl_add_u64 v[122:123], s[8:9], 0, v[122:123]
	v_lshl_add_u64 v[122:123], v[122:123], 0, v[0:1]
	v_lshlrev_b64 v[120:121], 11, v[120:121]
	s_waitcnt vmcnt(3) lgkmcnt(3)
	v_pk_add_f32 v[86:87], v[86:87], v[102:103]
	v_pk_add_f32 v[84:85], v[84:85], v[100:101]
	s_waitcnt vmcnt(2) lgkmcnt(2)
	v_pk_add_f32 v[90:91], v[90:91], v[106:107]
	v_pk_add_f32 v[88:89], v[88:89], v[104:105]
	v_bfe_u32 v102, v91, 16, 1
	v_bfe_u32 v103, v87, 16, 1
	v_bfe_u32 v104, v89, 16, 1
	v_bfe_u32 v105, v85, 16, 1
	s_waitcnt vmcnt(1) lgkmcnt(1)
	v_pk_add_f32 v[94:95], v[94:95], v[110:111]
	v_pk_add_f32 v[92:93], v[92:93], v[108:109]
	s_waitcnt vmcnt(0) lgkmcnt(0)
	v_pk_add_f32 v[98:99], v[98:99], v[114:115]
	v_pk_add_f32 v[96:97], v[96:97], v[112:113]
	global_store_dwordx4 v[122:123], v[84:87], off
	global_store_dwordx4 v[122:123], v[88:91], off offset:16
	global_store_dwordx4 v[122:123], v[92:95], off offset:32
	global_store_dwordx4 v[122:123], v[96:99], off offset:48
	v_add3_u32 v103, v87, v103, s31
	v_add3_u32 v87, v91, v102, s31
	v_add3_u32 v91, v85, v105, s31
	v_add3_u32 v89, v89, v104, s31
	v_bfe_u32 v85, v86, 16, 1
	v_bfe_u32 v102, v90, 16, 1
	v_bfe_u32 v104, v84, 16, 1
	v_bfe_u32 v105, v88, 16, 1
	v_add3_u32 v90, v90, v102, s31
	v_add3_u32 v85, v86, v85, s31
	v_add3_u32 v86, v88, v105, s31
	v_add3_u32 v84, v84, v104, s31
	v_lshrrev_b32_e32 v88, 16, v90
	v_lshrrev_b32_e32 v84, 16, v84
	v_lshrrev_b32_e32 v86, 16, v86
	v_and_or_b32 v87, v87, s26, v88
	v_and_or_b32 v86, v89, s26, v86
	v_and_or_b32 v84, v91, s26, v84
	v_bfe_u32 v88, v99, 16, 1
	v_bfe_u32 v89, v95, 16, 1
	v_bfe_u32 v90, v97, 16, 1
	v_add3_u32 v89, v95, v89, s31
	v_add3_u32 v88, v99, v88, s31
	v_add3_u32 v90, v97, v90, s31
	v_bfe_u32 v91, v94, 16, 1
	v_bfe_u32 v95, v98, 16, 1
	v_bfe_u32 v99, v96, 16, 1
	v_lshrrev_b32_e32 v85, 16, v85
	v_add3_u32 v95, v98, v95, s31
	v_add3_u32 v91, v94, v91, s31
	v_add3_u32 v94, v96, v99, s31
	v_lshl_add_u64 v[100:101], v[2:3], 0, v[120:121]
	v_and_or_b32 v85, v103, s26, v85
	v_lshrrev_b32_e32 v96, 16, v91
	v_lshrrev_b32_e32 v91, 16, v95
	v_lshrrev_b32_e32 v94, 16, v94
	v_and_or_b32 v91, v88, s26, v91
	v_and_or_b32 v89, v89, s26, v96
	v_and_or_b32 v90, v90, s26, v94
	v_cvt_pk_bf16_f32 v88, v92, v93
	global_store_dwordx4 v[100:101], v[84:87], off
	global_store_dwordx4 v[100:101], v[88:91], off offset:16
	v_or_b32_e32 v100, 48, v132
	v_add_u32_e32 v84, 0xffffc030, v132
	v_ashrrev_i32_e32 v101, 31, v100
	v_cmp_gt_i32_e32 vcc, s30, v100
	ds_write2_b32 v134, v80, v76 offset1:16
	ds_write2_b32 v134, v81, v77 offset0:68 offset1:84
	ds_write2_b32 v134, v82, v78 offset0:136 offset1:152
	ds_write2_b32 v134, v83, v79 offset0:204 offset1:220
	ds_write2_b32 v134, v72, v68 offset0:32 offset1:48
	ds_write2_b32 v134, v73, v69 offset0:100 offset1:116
	ds_write2_b32 v134, v74, v70 offset0:168 offset1:184
	ds_write2_b32 v134, v75, v71 offset0:236 offset1:252
	v_cndmask_b32_e32 v85, 0, v101, vcc
	v_cndmask_b32_e32 v84, v84, v100, vcc
	v_cndmask_b32_e32 v87, v116, v117, vcc
	v_cndmask_b32_e32 v86, v118, v119, vcc
	v_lshlrev_b64 v[84:85], 12, v[84:85]
	s_waitcnt lgkmcnt(0)
; DI unsigned pack2(float a, float b) { return (unsigned)f2bf(a) | ((unsigned)f2bf(b) << 16); }
;   const int lane = tid & 63, wid = tid >> 6, fr = lane & 15, fq = lane >> 4;
;   float* stg = (float*)(smem + PATCH) + wid * (16 * 68);
;   asm volatile("" ::: "memory");
; #pragma unroll
;   for (int n = 0; n < 4; ++n)
; #pragma unroll
;     for (int j = 0; j < 4; ++j) stg[(fq * 4 + j) * 68 + n * 16 + fr] = am[n][j];
;   asm volatile("s_waitcnt lgkmcnt(0)" ::: "memory");
;   const float* rp = stg + (lane >> 2) * 68 + (lane & 3) * 16;
; #pragma unroll
;   for (int i = 0; i < 4; ++i) { f32x4 t = *(const f32x4*)(rp + i * 4); v[4 * i] = t[0]; v[4 * i + 1] = t[1]; v[4 * i + 2] = t[2]; v[4 * i + 3] = t[3]; }
;   asm volatile("" ::: "memory");
; }
; DI void store16_bf(bft* dst, const float (&v)[16]) {
;   u32x4 o0 = {pack2(v[0], v[1]), pack2(v[2], v[3]), pack2(v[4], v[5]), pack2(v[6], v[7])}, o1 = {pack2(v[8], v[9]), pack2(v[10], v[11]), pack2(v[12], v[13]), pack2(v[14], v[15])};
;   *(u32x4*)dst = o0; *(u32x4*)(dst + 8) = o1;
; }
; DI void load16_bf(const bft* src, float (&v)[16]) {
;   u32x4 w0 = *(const u32x4*)src, w1 = *(const u32x4*)(src + 8);
; #pragma unroll
;   for (int i = 0; i < 4; ++i) { v[2 * i] = __uint_as_float(w0[i] << 16); v[2 * i + 1] = __uint_as_float(w0[i] & 0xffff0000u); v[8 + 2 * i] = __uint_as_float(w1[i] << 16); v[8 + 2 * i + 1] = __uint_as_float(w1[i] & 0xffff0000u); }
; }
; DI void load16_f(const float* src, float (&v)[16]) {
; #pragma unroll
;   for (int i = 0; i < 4; ++i) { f32x4 t = *(const f32x4*)(src + 4 * i); v[4 * i] = t[0]; v[4 * i + 1] = t[1]; v[4 * i + 2] = t[2]; v[4 * i + 3] = t[3]; }
; }
; DI void store16_f(float* dst, const float (&v)[16]) {
; #pragma unroll
;   for (int i = 0; i < 4; ++i) { f32x4 t = {v[4 * i], v[4 * i + 1], v[4 * i + 2], v[4 * i + 3]}; *(f32x4*)(dst + 4 * i) = t; }
; }
; DI void phase_outproj0(const Params& p) {
;     ...
;     EPI256_BEGIN
;       float x[16]; load16_f(xrow(p, row) + col, x);
; #pragma unroll
;       for (int i = 0; i < 16; ++i) v[i] += x[i];
;       store16_f(p.out + (size_t)row * 1024 + col, v); store16_bf(hb + (size_t)row * 1024 + col, v);
;     EPI_END
	v_lshl_add_u64 v[84:85], v[86:87], 0, v[84:85]
	ds_read_b128 v[68:71], v135
	ds_read_b128 v[72:75], v135 offset:16
	ds_read_b128 v[76:79], v135 offset:32
	ds_read_b128 v[80:83], v135 offset:48
	v_lshl_add_u64 v[96:97], v[84:85], 0, v[0:1]
	global_load_dwordx4 v[84:87], v[96:97], off
	global_load_dwordx4 v[88:91], v[96:97], off offset:16
	global_load_dwordx4 v[92:95], v[96:97], off offset:32
	s_nop 0
	global_load_dwordx4 v[96:99], v[96:97], off offset:48
	s_waitcnt vmcnt(3) lgkmcnt(3)
	v_pk_add_f32 v[68:69], v[68:69], v[84:85]
	v_lshlrev_b64 v[84:85], 12, v[100:101]
	v_pk_add_f32 v[70:71], v[70:71], v[86:87]
	s_waitcnt vmcnt(2) lgkmcnt(2)
	v_pk_add_f32 v[74:75], v[74:75], v[90:91]
	v_pk_add_f32 v[72:73], v[72:73], v[88:89]
	v_lshl_add_u64 v[84:85], s[8:9], 0, v[84:85]
	v_lshl_add_u64 v[84:85], v[84:85], 0, v[0:1]
	v_bfe_u32 v86, v75, 16, 1
	v_bfe_u32 v87, v71, 16, 1
	v_bfe_u32 v88, v73, 16, 1
	v_bfe_u32 v89, v69, 16, 1
	s_waitcnt vmcnt(1) lgkmcnt(1)
	v_pk_add_f32 v[78:79], v[78:79], v[94:95]
	v_pk_add_f32 v[76:77], v[76:77], v[92:93]
	s_waitcnt vmcnt(0) lgkmcnt(0)
	v_pk_add_f32 v[82:83], v[82:83], v[98:99]
	v_pk_add_f32 v[80:81], v[80:81], v[96:97]
	global_store_dwordx4 v[84:85], v[68:71], off
	global_store_dwordx4 v[84:85], v[72:75], off offset:16
	global_store_dwordx4 v[84:85], v[76:79], off offset:32
	global_store_dwordx4 v[84:85], v[80:83], off offset:48
	v_add3_u32 v87, v71, v87, s31
	v_add3_u32 v71, v75, v86, s31
	v_add3_u32 v75, v69, v89, s31
	v_add3_u32 v73, v73, v88, s31
	v_bfe_u32 v69, v70, 16, 1
	v_bfe_u32 v86, v74, 16, 1
	v_bfe_u32 v88, v68, 16, 1
	v_bfe_u32 v89, v72, 16, 1
	v_add3_u32 v74, v74, v86, s31
	v_add3_u32 v69, v70, v69, s31
	v_add3_u32 v70, v72, v89, s31
	v_add3_u32 v68, v68, v88, s31
	v_lshrrev_b32_e32 v72, 16, v74
	v_lshrrev_b32_e32 v68, 16, v68
	v_lshrrev_b32_e32 v70, 16, v70
	v_and_or_b32 v71, v71, s26, v72
	v_and_or_b32 v70, v73, s26, v70
	v_and_or_b32 v68, v75, s26, v68
	v_bfe_u32 v72, v83, 16, 1
	v_bfe_u32 v73, v79, 16, 1
	v_bfe_u32 v74, v81, 16, 1
	v_add3_u32 v73, v79, v73, s31
	v_add3_u32 v72, v83, v72, s31
	v_add3_u32 v74, v81, v74, s31
	v_bfe_u32 v75, v78, 16, 1
	v_bfe_u32 v79, v82, 16, 1
	v_bfe_u32 v83, v80, 16, 1
	v_lshlrev_b64 v[84:85], 11, v[100:101]
	v_lshrrev_b32_e32 v69, 16, v69
	v_add3_u32 v79, v82, v79, s31
	v_add3_u32 v75, v78, v75, s31
	v_add3_u32 v78, v80, v83, s31
	v_lshl_add_u64 v[84:85], v[2:3], 0, v[84:85]
	v_and_or_b32 v69, v87, s26, v69
	v_lshrrev_b32_e32 v80, 16, v75
	v_lshrrev_b32_e32 v75, 16, v79
	v_lshrrev_b32_e32 v78, 16, v78
	v_and_or_b32 v75, v72, s26, v75
	v_and_or_b32 v73, v73, s26, v80
	v_and_or_b32 v74, v74, s26, v78
	v_cvt_pk_bf16_f32 v72, v76, v77
	global_store_dwordx4 v[84:85], v[68:71], off
	global_store_dwordx4 v[84:85], v[72:75], off offset:16
	v_or_b32_e32 v84, 64, v132
	v_add_u32_e32 v68, 0xffffc040, v132
	v_ashrrev_i32_e32 v85, 31, v84
	v_cmp_gt_i32_e32 vcc, s30, v84
	ds_write2_b32 v134, v64, v60 offset1:16
	ds_write2_b32 v134, v65, v61 offset0:68 offset1:84
	ds_write2_b32 v134, v66, v62 offset0:136 offset1:152
	ds_write2_b32 v134, v67, v63 offset0:204 offset1:220
	ds_write2_b32 v134, v56, v52 offset0:32 offset1:48
	ds_write2_b32 v134, v57, v53 offset0:100 offset1:116
	ds_write2_b32 v134, v58, v54 offset0:168 offset1:184
	ds_write2_b32 v134, v59, v55 offset0:236 offset1:252
	v_cndmask_b32_e32 v69, 0, v85, vcc
	v_cndmask_b32_e32 v68, v68, v84, vcc
	v_cndmask_b32_e32 v71, v116, v117, vcc
	v_cndmask_b32_e32 v70, v118, v119, vcc
	v_lshlrev_b64 v[68:69], 12, v[68:69]
	s_waitcnt lgkmcnt(0)
	v_lshl_add_u64 v[68:69], v[70:71], 0, v[68:69]
	ds_read_b128 v[52:55], v135
	ds_read_b128 v[56:59], v135 offset:16
	ds_read_b128 v[60:63], v135 offset:32
	ds_read_b128 v[64:67], v135 offset:48
	v_lshl_add_u64 v[80:81], v[68:69], 0, v[0:1]
	global_load_dwordx4 v[68:71], v[80:81], off
	global_load_dwordx4 v[72:75], v[80:81], off offset:16
	global_load_dwordx4 v[76:79], v[80:81], off offset:32
	s_nop 0
	global_load_dwordx4 v[80:83], v[80:81], off offset:48
	s_waitcnt vmcnt(3) lgkmcnt(3)
	v_pk_add_f32 v[52:53], v[52:53], v[68:69]
	v_lshlrev_b64 v[68:69], 12, v[84:85]
	v_pk_add_f32 v[54:55], v[54:55], v[70:71]
	s_waitcnt vmcnt(2) lgkmcnt(2)
	v_pk_add_f32 v[58:59], v[58:59], v[74:75]
	v_pk_add_f32 v[56:57], v[56:57], v[72:73]
	v_lshl_add_u64 v[68:69], s[8:9], 0, v[68:69]
	v_lshl_add_u64 v[68:69], v[68:69], 0, v[0:1]
	v_bfe_u32 v70, v59, 16, 1
	v_bfe_u32 v71, v55, 16, 1
	v_bfe_u32 v72, v57, 16, 1
	v_bfe_u32 v73, v53, 16, 1
	s_waitcnt vmcnt(1) lgkmcnt(1)
	v_pk_add_f32 v[62:63], v[62:63], v[78:79]
	v_pk_add_f32 v[60:61], v[60:61], v[76:77]
	s_waitcnt vmcnt(0) lgkmcnt(0)
; DI unsigned pack2(float a, float b) { return (unsigned)f2bf(a) | ((unsigned)f2bf(b) << 16); }
;   const int lane = tid & 63, wid = tid >> 6, fr = lane & 15, fq = lane >> 4;
;   float* stg = (float*)(smem + PATCH) + wid * (16 * 68);
;   asm volatile("" ::: "memory");
; #pragma unroll
;   for (int n = 0; n < 4; ++n)
; #pragma unroll
;     for (int j = 0; j < 4; ++j) stg[(fq * 4 + j) * 68 + n * 16 + fr] = am[n][j];
;   asm volatile("s_waitcnt lgkmcnt(0)" ::: "memory");
;   const float* rp = stg + (lane >> 2) * 68 + (lane & 3) * 16;
; #pragma unroll
;   for (int i = 0; i < 4; ++i) { f32x4 t = *(const f32x4*)(rp + i * 4); v[4 * i] = t[0]; v[4 * i + 1] = t[1]; v[4 * i + 2] = t[2]; v[4 * i + 3] = t[3]; }
;   asm volatile("" ::: "memory");
; }
; DI void store16_bf(bft* dst, const float (&v)[16]) {
;   u32x4 o0 = {pack2(v[0], v[1]), pack2(v[2], v[3]), pack2(v[4], v[5]), pack2(v[6], v[7])}, o1 = {pack2(v[8], v[9]), pack2(v[10], v[11]), pack2(v[12], v[13]), pack2(v[14], v[15])};
;   *(u32x4*)dst = o0; *(u32x4*)(dst + 8) = o1;
; }
; DI void load16_bf(const bft* src, float (&v)[16]) {
;   u32x4 w0 = *(const u32x4*)src, w1 = *(const u32x4*)(src + 8);
; #pragma unroll
;   for (int i = 0; i < 4; ++i) { v[2 * i] = __uint_as_float(w0[i] << 16); v[2 * i + 1] = __uint_as_float(w0[i] & 0xffff0000u); v[8 + 2 * i] = __uint_as_float(w1[i] << 16); v[8 + 2 * i + 1] = __uint_as_float(w1[i] & 0xffff0000u); }
; }
; DI void load16_f(const float* src, float (&v)[16]) {
; #pragma unroll
;   for (int i = 0; i < 4; ++i) { f32x4 t = *(const f32x4*)(src + 4 * i); v[4 * i] = t[0]; v[4 * i + 1] = t[1]; v[4 * i + 2] = t[2]; v[4 * i + 3] = t[3]; }
; }
; DI void store16_f(float* dst, const float (&v)[16]) {
; #pragma unroll
;   for (int i = 0; i < 4; ++i) { f32x4 t = {v[4 * i], v[4 * i + 1], v[4 * i + 2], v[4 * i + 3]}; *(f32x4*)(dst + 4 * i) = t; }
; }
; DI void phase_outproj0(const Params& p) {
;     ...
;     EPI256_BEGIN
;       float x[16]; load16_f(xrow(p, row) + col, x);
; #pragma unroll
;       for (int i = 0; i < 16; ++i) v[i] += x[i];
;       store16_f(p.out + (size_t)row * 1024 + col, v); store16_bf(hb + (size_t)row * 1024 + col, v);
;     EPI_END
	v_pk_add_f32 v[66:67], v[66:67], v[82:83]
	v_pk_add_f32 v[64:65], v[64:65], v[80:81]
	global_store_dwordx4 v[68:69], v[52:55], off
	global_store_dwordx4 v[68:69], v[56:59], off offset:16
	global_store_dwordx4 v[68:69], v[60:63], off offset:32
	global_store_dwordx4 v[68:69], v[64:67], off offset:48
	v_add3_u32 v71, v55, v71, s31
	v_add3_u32 v55, v59, v70, s31
	v_add3_u32 v59, v53, v73, s31
	v_add3_u32 v57, v57, v72, s31
	v_bfe_u32 v53, v54, 16, 1
	v_bfe_u32 v70, v58, 16, 1
	v_bfe_u32 v72, v52, 16, 1
	v_bfe_u32 v73, v56, 16, 1
	v_add3_u32 v58, v58, v70, s31
	v_add3_u32 v53, v54, v53, s31
	v_add3_u32 v54, v56, v73, s31
	v_add3_u32 v52, v52, v72, s31
	v_lshrrev_b32_e32 v56, 16, v58
	v_lshrrev_b32_e32 v52, 16, v52
	v_lshrrev_b32_e32 v54, 16, v54
	v_and_or_b32 v55, v55, s26, v56
	v_and_or_b32 v54, v57, s26, v54
	v_and_or_b32 v52, v59, s26, v52
	v_bfe_u32 v56, v67, 16, 1
	v_bfe_u32 v57, v63, 16, 1
	v_bfe_u32 v58, v65, 16, 1
	v_add3_u32 v57, v63, v57, s31
	v_add3_u32 v56, v67, v56, s31
	v_add3_u32 v58, v65, v58, s31
	v_bfe_u32 v59, v62, 16, 1
	v_bfe_u32 v63, v66, 16, 1
	v_bfe_u32 v67, v64, 16, 1
	v_lshlrev_b64 v[68:69], 11, v[84:85]
	v_lshrrev_b32_e32 v53, 16, v53
	v_add3_u32 v63, v66, v63, s31
	v_add3_u32 v59, v62, v59, s31
	v_add3_u32 v62, v64, v67, s31
	v_lshl_add_u64 v[68:69], v[2:3], 0, v[68:69]
	v_and_or_b32 v53, v71, s26, v53
	v_lshrrev_b32_e32 v64, 16, v59
	v_lshrrev_b32_e32 v59, 16, v63
	v_lshrrev_b32_e32 v62, 16, v62
	v_and_or_b32 v59, v56, s26, v59
	v_and_or_b32 v57, v57, s26, v64
	v_and_or_b32 v58, v58, s26, v62
	v_cvt_pk_bf16_f32 v56, v60, v61
	global_store_dwordx4 v[68:69], v[52:55], off
	global_store_dwordx4 v[68:69], v[56:59], off offset:16
	v_or_b32_e32 v68, 0x50, v132
	v_add_u32_e32 v52, 0xffffc050, v132
	v_ashrrev_i32_e32 v69, 31, v68
	v_cmp_gt_i32_e32 vcc, s30, v68
	ds_write2_b32 v134, v48, v44 offset1:16
	ds_write2_b32 v134, v49, v45 offset0:68 offset1:84
	ds_write2_b32 v134, v50, v46 offset0:136 offset1:152
	ds_write2_b32 v134, v51, v47 offset0:204 offset1:220
	ds_write2_b32 v134, v40, v36 offset0:32 offset1:48
	ds_write2_b32 v134, v41, v37 offset0:100 offset1:116
	ds_write2_b32 v134, v42, v38 offset0:168 offset1:184
	ds_write2_b32 v134, v43, v39 offset0:236 offset1:252
	v_cndmask_b32_e32 v53, 0, v69, vcc
	v_cndmask_b32_e32 v52, v52, v68, vcc
	v_cndmask_b32_e32 v55, v116, v117, vcc
	v_cndmask_b32_e32 v54, v118, v119, vcc
	v_lshlrev_b64 v[52:53], 12, v[52:53]
	s_waitcnt lgkmcnt(0)
	v_lshl_add_u64 v[52:53], v[54:55], 0, v[52:53]
	ds_read_b128 v[36:39], v135
	ds_read_b128 v[40:43], v135 offset:16
	ds_read_b128 v[44:47], v135 offset:32
	ds_read_b128 v[48:51], v135 offset:48
	v_lshl_add_u64 v[64:65], v[52:53], 0, v[0:1]
	global_load_dwordx4 v[52:55], v[64:65], off
	global_load_dwordx4 v[56:59], v[64:65], off offset:16
	global_load_dwordx4 v[60:63], v[64:65], off offset:32
	s_nop 0
	global_load_dwordx4 v[64:67], v[64:65], off offset:48
	s_waitcnt vmcnt(3) lgkmcnt(3)
	v_pk_add_f32 v[36:37], v[36:37], v[52:53]
	v_lshlrev_b64 v[52:53], 12, v[68:69]
	v_pk_add_f32 v[38:39], v[38:39], v[54:55]
	s_waitcnt vmcnt(2) lgkmcnt(2)
	v_pk_add_f32 v[42:43], v[42:43], v[58:59]
	v_pk_add_f32 v[40:41], v[40:41], v[56:57]
	v_lshl_add_u64 v[52:53], s[8:9], 0, v[52:53]
	v_lshl_add_u64 v[52:53], v[52:53], 0, v[0:1]
	v_bfe_u32 v54, v43, 16, 1
	v_bfe_u32 v55, v39, 16, 1
	v_bfe_u32 v56, v41, 16, 1
	v_bfe_u32 v57, v37, 16, 1
	s_waitcnt vmcnt(1) lgkmcnt(1)
	v_pk_add_f32 v[46:47], v[46:47], v[62:63]
	v_pk_add_f32 v[44:45], v[44:45], v[60:61]
	s_waitcnt vmcnt(0) lgkmcnt(0)
	v_pk_add_f32 v[50:51], v[50:51], v[66:67]
	v_pk_add_f32 v[48:49], v[48:49], v[64:65]
	global_store_dwordx4 v[52:53], v[36:39], off
	global_store_dwordx4 v[52:53], v[40:43], off offset:16
	global_store_dwordx4 v[52:53], v[44:47], off offset:32
	global_store_dwordx4 v[52:53], v[48:51], off offset:48
	v_add3_u32 v55, v39, v55, s31
	v_add3_u32 v39, v43, v54, s31
	v_add3_u32 v43, v37, v57, s31
	v_add3_u32 v41, v41, v56, s31
	v_bfe_u32 v37, v38, 16, 1
	v_bfe_u32 v54, v42, 16, 1
	v_bfe_u32 v56, v36, 16, 1
	v_bfe_u32 v57, v40, 16, 1
	v_add3_u32 v42, v42, v54, s31
	v_add3_u32 v37, v38, v37, s31
	v_add3_u32 v38, v40, v57, s31
	v_add3_u32 v36, v36, v56, s31
	v_lshrrev_b32_e32 v40, 16, v42
	v_lshrrev_b32_e32 v36, 16, v36
	v_lshrrev_b32_e32 v38, 16, v38
	v_and_or_b32 v39, v39, s26, v40
	v_and_or_b32 v38, v41, s26, v38
	v_and_or_b32 v36, v43, s26, v36
	v_bfe_u32 v40, v51, 16, 1
	v_bfe_u32 v41, v47, 16, 1
	v_bfe_u32 v42, v49, 16, 1
	v_add3_u32 v41, v47, v41, s31
	v_add3_u32 v40, v51, v40, s31
	v_add3_u32 v42, v49, v42, s31
	v_bfe_u32 v43, v46, 16, 1
	v_bfe_u32 v47, v50, 16, 1
	v_bfe_u32 v51, v48, 16, 1
	v_lshlrev_b64 v[52:53], 11, v[68:69]
	v_lshrrev_b32_e32 v37, 16, v37
	v_add3_u32 v47, v50, v47, s31
	v_add3_u32 v43, v46, v43, s31
	v_add3_u32 v46, v48, v51, s31
	v_lshl_add_u64 v[52:53], v[2:3], 0, v[52:53]
	v_and_or_b32 v37, v55, s26, v37
	v_lshrrev_b32_e32 v48, 16, v43
	v_lshrrev_b32_e32 v43, 16, v47
	v_lshrrev_b32_e32 v46, 16, v46
	v_and_or_b32 v43, v40, s26, v43
	v_and_or_b32 v41, v41, s26, v48
	v_and_or_b32 v42, v42, s26, v46
	v_cvt_pk_bf16_f32 v40, v44, v45
	global_store_dwordx4 v[52:53], v[36:39], off
	global_store_dwordx4 v[52:53], v[40:43], off offset:16
	v_or_b32_e32 v52, 0x60, v132
	v_add_u32_e32 v36, 0xffffc060, v132
	v_ashrrev_i32_e32 v53, 31, v52
	v_cmp_gt_i32_e32 vcc, s30, v52
	ds_write2_b32 v134, v32, v28 offset1:16
	ds_write2_b32 v134, v33, v29 offset0:68 offset1:84
	ds_write2_b32 v134, v34, v30 offset0:136 offset1:152
	ds_write2_b32 v134, v35, v31 offset0:204 offset1:220
	ds_write2_b32 v134, v24, v20 offset0:32 offset1:48
	ds_write2_b32 v134, v25, v21 offset0:100 offset1:116
	ds_write2_b32 v134, v26, v22 offset0:168 offset1:184
	ds_write2_b32 v134, v27, v23 offset0:236 offset1:252
	v_cndmask_b32_e32 v37, 0, v53, vcc
	v_cndmask_b32_e32 v36, v36, v52, vcc
	v_cndmask_b32_e32 v39, v116, v117, vcc
	v_cndmask_b32_e32 v38, v118, v119, vcc
	v_lshlrev_b64 v[36:37], 12, v[36:37]
	s_waitcnt lgkmcnt(0)
; DI unsigned pack2(float a, float b) { return (unsigned)f2bf(a) | ((unsigned)f2bf(b) << 16); }
;   const int lane = tid & 63, wid = tid >> 6, fr = lane & 15, fq = lane >> 4;
;   float* stg = (float*)(smem + PATCH) + wid * (16 * 68);
;   asm volatile("" ::: "memory");
; #pragma unroll
;   for (int n = 0; n < 4; ++n)
; #pragma unroll
;     for (int j = 0; j < 4; ++j) stg[(fq * 4 + j) * 68 + n * 16 + fr] = am[n][j];
;   asm volatile("s_waitcnt lgkmcnt(0)" ::: "memory");
;   const float* rp = stg + (lane >> 2) * 68 + (lane & 3) * 16;
; #pragma unroll
;   for (int i = 0; i < 4; ++i) { f32x4 t = *(const f32x4*)(rp + i * 4); v[4 * i] = t[0]; v[4 * i + 1] = t[1]; v[4 * i + 2] = t[2]; v[4 * i + 3] = t[3]; }
;   asm volatile("" ::: "memory");
; }
; DI void store16_bf(bft* dst, const float (&v)[16]) {
;   u32x4 o0 = {pack2(v[0], v[1]), pack2(v[2], v[3]), pack2(v[4], v[5]), pack2(v[6], v[7])}, o1 = {pack2(v[8], v[9]), pack2(v[10], v[11]), pack2(v[12], v[13]), pack2(v[14], v[15])};
;   *(u32x4*)dst = o0; *(u32x4*)(dst + 8) = o1;
; }
; DI void load16_bf(const bft* src, float (&v)[16]) {
;   u32x4 w0 = *(const u32x4*)src, w1 = *(const u32x4*)(src + 8);
; #pragma unroll
;   for (int i = 0; i < 4; ++i) { v[2 * i] = __uint_as_float(w0[i] << 16); v[2 * i + 1] = __uint_as_float(w0[i] & 0xffff0000u); v[8 + 2 * i] = __uint_as_float(w1[i] << 16); v[8 + 2 * i + 1] = __uint_as_float(w1[i] & 0xffff0000u); }
; }
; DI void load16_f(const float* src, float (&v)[16]) {
; #pragma unroll
;   for (int i = 0; i < 4; ++i) { f32x4 t = *(const f32x4*)(src + 4 * i); v[4 * i] = t[0]; v[4 * i + 1] = t[1]; v[4 * i + 2] = t[2]; v[4 * i + 3] = t[3]; }
; }
; DI void store16_f(float* dst, const float (&v)[16]) {
; #pragma unroll
;   for (int i = 0; i < 4; ++i) { f32x4 t = {v[4 * i], v[4 * i + 1], v[4 * i + 2], v[4 * i + 3]}; *(f32x4*)(dst + 4 * i) = t; }
; }
; DI void phase_outproj0(const Params& p) {
;     ...
;     EPI256_BEGIN
;       float x[16]; load16_f(xrow(p, row) + col, x);
; #pragma unroll
;       for (int i = 0; i < 16; ++i) v[i] += x[i];
;       store16_f(p.out + (size_t)row * 1024 + col, v); store16_bf(hb + (size_t)row * 1024 + col, v);
;     EPI_END
	v_lshl_add_u64 v[36:37], v[38:39], 0, v[36:37]
	ds_read_b128 v[20:23], v135
	ds_read_b128 v[24:27], v135 offset:16
	ds_read_b128 v[28:31], v135 offset:32
	ds_read_b128 v[32:35], v135 offset:48
	v_lshl_add_u64 v[48:49], v[36:37], 0, v[0:1]
	global_load_dwordx4 v[36:39], v[48:49], off
	global_load_dwordx4 v[40:43], v[48:49], off offset:16
	global_load_dwordx4 v[44:47], v[48:49], off offset:32
	s_nop 0
	global_load_dwordx4 v[48:51], v[48:49], off offset:48
	s_waitcnt vmcnt(3) lgkmcnt(3)
	v_pk_add_f32 v[20:21], v[20:21], v[36:37]
	v_lshlrev_b64 v[36:37], 12, v[52:53]
	v_pk_add_f32 v[22:23], v[22:23], v[38:39]
	s_waitcnt vmcnt(2) lgkmcnt(2)
	v_pk_add_f32 v[26:27], v[26:27], v[42:43]
	v_pk_add_f32 v[24:25], v[24:25], v[40:41]
	v_lshl_add_u64 v[36:37], s[8:9], 0, v[36:37]
	v_lshl_add_u64 v[36:37], v[36:37], 0, v[0:1]
	v_bfe_u32 v38, v27, 16, 1
	v_bfe_u32 v39, v23, 16, 1
	v_bfe_u32 v40, v25, 16, 1
	v_bfe_u32 v41, v21, 16, 1
	s_waitcnt vmcnt(1) lgkmcnt(1)
	v_pk_add_f32 v[30:31], v[30:31], v[46:47]
	v_pk_add_f32 v[28:29], v[28:29], v[44:45]
	s_waitcnt vmcnt(0) lgkmcnt(0)
	v_pk_add_f32 v[34:35], v[34:35], v[50:51]
	v_pk_add_f32 v[32:33], v[32:33], v[48:49]
	global_store_dwordx4 v[36:37], v[20:23], off
	global_store_dwordx4 v[36:37], v[24:27], off offset:16
	global_store_dwordx4 v[36:37], v[28:31], off offset:32
	global_store_dwordx4 v[36:37], v[32:35], off offset:48
	v_add3_u32 v39, v23, v39, s31
	v_add3_u32 v23, v27, v38, s31
	v_add3_u32 v27, v21, v41, s31
	v_add3_u32 v25, v25, v40, s31
	v_bfe_u32 v21, v22, 16, 1
	v_bfe_u32 v38, v26, 16, 1
	v_bfe_u32 v40, v20, 16, 1
	v_bfe_u32 v41, v24, 16, 1
	v_add3_u32 v26, v26, v38, s31
	v_add3_u32 v21, v22, v21, s31
	v_add3_u32 v22, v24, v41, s31
	v_add3_u32 v20, v20, v40, s31
	v_lshrrev_b32_e32 v24, 16, v26
	v_lshrrev_b32_e32 v20, 16, v20
	v_lshrrev_b32_e32 v22, 16, v22
	v_and_or_b32 v23, v23, s26, v24
	v_and_or_b32 v22, v25, s26, v22
	v_and_or_b32 v20, v27, s26, v20
	v_bfe_u32 v24, v35, 16, 1
	v_bfe_u32 v25, v31, 16, 1
	v_bfe_u32 v26, v33, 16, 1
	v_add3_u32 v25, v31, v25, s31
	v_add3_u32 v24, v35, v24, s31
	v_add3_u32 v26, v33, v26, s31
	v_bfe_u32 v27, v30, 16, 1
	v_bfe_u32 v31, v34, 16, 1
	v_bfe_u32 v35, v32, 16, 1
	v_lshlrev_b64 v[36:37], 11, v[52:53]
	v_lshrrev_b32_e32 v21, 16, v21
	v_add3_u32 v31, v34, v31, s31
	v_add3_u32 v27, v30, v27, s31
	v_add3_u32 v30, v32, v35, s31
	v_lshl_add_u64 v[36:37], v[2:3], 0, v[36:37]
	v_and_or_b32 v21, v39, s26, v21
	v_lshrrev_b32_e32 v32, 16, v27
	v_lshrrev_b32_e32 v27, 16, v31
	v_lshrrev_b32_e32 v30, 16, v30
	v_and_or_b32 v27, v24, s26, v27
	v_and_or_b32 v25, v25, s26, v32
	v_and_or_b32 v26, v26, s26, v30
	v_cvt_pk_bf16_f32 v24, v28, v29
	global_store_dwordx4 v[36:37], v[20:23], off
	global_store_dwordx4 v[36:37], v[24:27], off offset:16
	v_or_b32_e32 v36, 0x70, v132
	v_add_u32_e32 v20, 0xffffc070, v132
	v_ashrrev_i32_e32 v37, 31, v36
	v_cmp_gt_i32_e32 vcc, s30, v36
	ds_write2_b32 v134, v16, v12 offset1:16
	ds_write2_b32 v134, v17, v13 offset0:68 offset1:84
	ds_write2_b32 v134, v18, v14 offset0:136 offset1:152
	ds_write2_b32 v134, v19, v15 offset0:204 offset1:220
	ds_write2_b32 v134, v8, v4 offset0:32 offset1:48
	ds_write2_b32 v134, v9, v5 offset0:100 offset1:116
	ds_write2_b32 v134, v10, v6 offset0:168 offset1:184
	ds_write2_b32 v134, v11, v7 offset0:236 offset1:252
	v_cndmask_b32_e32 v21, 0, v37, vcc
	v_cndmask_b32_e32 v20, v20, v36, vcc
	v_cndmask_b32_e32 v23, v116, v117, vcc
	v_cndmask_b32_e32 v22, v118, v119, vcc
	v_lshlrev_b64 v[20:21], 12, v[20:21]
	s_waitcnt lgkmcnt(0)
	v_lshl_add_u64 v[20:21], v[22:23], 0, v[20:21]
	ds_read_b128 v[4:7], v135
	ds_read_b128 v[8:11], v135 offset:16
	ds_read_b128 v[12:15], v135 offset:32
	ds_read_b128 v[16:19], v135 offset:48
	v_lshl_add_u64 v[32:33], v[20:21], 0, v[0:1]
	global_load_dwordx4 v[20:23], v[32:33], off
	global_load_dwordx4 v[24:27], v[32:33], off offset:16
	global_load_dwordx4 v[28:31], v[32:33], off offset:32
	s_nop 0
	global_load_dwordx4 v[32:35], v[32:33], off offset:48
	s_waitcnt vmcnt(3) lgkmcnt(3)
	v_pk_add_f32 v[4:5], v[4:5], v[20:21]
	v_lshlrev_b64 v[20:21], 12, v[36:37]
	v_lshl_add_u64 v[20:21], s[8:9], 0, v[20:21]
	v_pk_add_f32 v[6:7], v[6:7], v[22:23]
	v_lshl_add_u64 v[20:21], v[20:21], 0, v[0:1]
	s_waitcnt vmcnt(2) lgkmcnt(2)
	v_pk_add_f32 v[10:11], v[10:11], v[26:27]
	v_pk_add_f32 v[8:9], v[8:9], v[24:25]
	s_waitcnt vmcnt(1) lgkmcnt(1)
	v_pk_add_f32 v[14:15], v[14:15], v[30:31]
	v_pk_add_f32 v[12:13], v[12:13], v[28:29]
	s_waitcnt vmcnt(0) lgkmcnt(0)
	v_pk_add_f32 v[18:19], v[18:19], v[34:35]
	v_pk_add_f32 v[16:17], v[16:17], v[32:33]
	global_store_dwordx4 v[20:21], v[4:7], off
	global_store_dwordx4 v[20:21], v[8:11], off offset:16
	global_store_dwordx4 v[20:21], v[12:15], off offset:32
	global_store_dwordx4 v[20:21], v[16:19], off offset:48
	v_lshlrev_b64 v[20:21], 11, v[36:37]
	v_lshl_add_u64 v[20:21], v[2:3], 0, v[20:21]
	v_bfe_u32 v0, v11, 16, 1
	v_bfe_u32 v3, v9, 16, 1
	v_bfe_u32 v2, v7, 16, 1
	v_bfe_u32 v22, v5, 16, 1
	v_add3_u32 v0, v11, v0, s31
	v_add3_u32 v9, v9, v3, s31
	v_bfe_u32 v3, v6, 16, 1
	v_bfe_u32 v11, v4, 16, 1
	v_add3_u32 v2, v7, v2, s31
	v_add3_u32 v7, v5, v22, s31
	v_bfe_u32 v22, v8, 16, 1
	v_add3_u32 v3, v6, v3, s31
	v_add3_u32 v4, v4, v11, s31
	v_bfe_u32 v5, v10, 16, 1
	v_add3_u32 v6, v8, v22, s31
	v_lshrrev_b32_e32 v3, 16, v3
	v_lshrrev_b32_e32 v8, 16, v4
	v_add3_u32 v5, v10, v5, s31
	v_lshrrev_b32_e32 v4, 16, v6
	v_and_or_b32 v3, v2, s26, v3
	v_and_or_b32 v2, v7, s26, v8
	v_lshrrev_b32_e32 v5, 16, v5
	v_and_or_b32 v4, v9, s26, v4
	v_and_or_b32 v5, v0, s26, v5
	v_cvt_pk_bf16_f32 v9, v18, v19
	v_cvt_pk_bf16_f32 v7, v14, v15
	v_cvt_pk_bf16_f32 v8, v16, v17
	v_cvt_pk_bf16_f32 v6, v12, v13
	global_store_dwordx4 v[20:21], v[2:5], off
	global_store_dwordx4 v[20:21], v[6:9], off offset:16

; DI float sigm(float x) { return 1.f / (1.f + __expf(-x)); }
;   const int lane = tid & 63, wid = tid >> 6, fr = lane & 15, fq = lane >> 4;
;   float* stg = (float*)(smem + PATCH) + wid * (16 * 68);
;   asm volatile("" ::: "memory");
; #pragma unroll
;   for (int n = 0; n < 4; ++n)
; #pragma unroll
;     for (int j = 0; j < 4; ++j) stg[(fq * 4 + j) * 68 + n * 16 + fr] = am[n][j];
;   asm volatile("s_waitcnt lgkmcnt(0)" ::: "memory");
;   const float* rp = stg + (lane >> 2) * 68 + (lane & 3) * 16;
; #pragma unroll
;   for (int i = 0; i < 4; ++i) { f32x4 t = *(const f32x4*)(rp + i * 4); v[4 * i] = t[0]; v[4 * i + 1] = t[1]; v[4 * i + 2] = t[2]; v[4 * i + 3] = t[3]; }
;   asm volatile("" ::: "memory");
; }
; DI void phase_ple(const Params& p, int layer, const bft* hbin, bft* hbout, int ldo, float* ssq) {
;     ...
;     EPI_BEGIN
;       float v2[16]; epi_stage(tid, acc2[m], v2); float h[16]; float* hp = p.out + (size_t)row * 1024 + col; load16_f(hp, h); float ss = 0.f;
; #pragma unroll
;       for (int i = 0; i < 16; ++i) { h[i] += sigm(v[i]) * v2[i]; ss += h[i] * h[i]; }
.LBB0_1046:
	v_lshrrev_b32_e32 v129, 6, v143
	s_movk_i32 s0, 0x1100
	v_lshrrev_b32_e32 v130, 2, v143
	v_mul_lo_u32 v129, v129, s0
	v_and_b32_e32 v130, 12, v130
	v_add_u32_e32 v129, s39, v129
	v_lshlrev_b32_e32 v131, 2, v148
	v_mul_u32_u24_e32 v130, 0x110, v130
	v_add3_u32 v140, v129, v131, v130
	v_bfe_u32 v130, v143, 2, 4
	v_and_b32_e32 v132, 48, v144
	v_mul_u32_u24_e32 v131, 0x110, v130
	v_lshlrev_b32_e32 v132, 2, v132
	v_add3_u32 v141, v129, v131, v132
	v_ashrrev_i32_e32 v129, 1, v143
	v_and_b32_e32 v129, 0xffffffc0, v129
	s_waitcnt vmcnt(0)
	s_barrier
	v_add_u32_e32 v129, s27, v129
	v_and_b32_e32 v138, 3, v143
	ds_write2_b32 v140, v92, v88 offset1:16
	ds_write2_b32 v140, v93, v89 offset0:68 offset1:84
	ds_write2_b32 v140, v94, v90 offset0:136 offset1:152
	ds_write2_b32 v140, v95, v91 offset0:204 offset1:220
	ds_write2_b32 v140, v84, v80 offset0:32 offset1:48
	ds_write2_b32 v140, v85, v81 offset0:100 offset1:116
	ds_write2_b32 v140, v86, v82 offset0:168 offset1:184
	ds_write2_b32 v140, v87, v83 offset0:236 offset1:252
	v_and_b32_e32 v128, 64, v143
	v_or_b32_e32 v136, v129, v130
	v_lshlrev_b32_e32 v129, 4, v138
	s_waitcnt lgkmcnt(0)
	v_or3_b32 v139, v129, v128, s26
	ds_read_b128 v[84:87], v141
	ds_read_b128 v[144:147], v141 offset:16
	ds_read_b128 v[128:131], v141 offset:32
	ds_read_b128 v[92:95], v141 offset:48
	v_ashrrev_i32_e32 v137, 31, v136
	v_lshlrev_b32_e32 v132, 1, v139
	ds_write2_b32 v140, v124, v120 offset1:16
	ds_write2_b32 v140, v125, v121 offset0:68 offset1:84
	ds_write2_b32 v140, v126, v122 offset0:136 offset1:152
	ds_write2_b32 v140, v127, v123 offset0:204 offset1:220
	ds_write2_b32 v140, v116, v112 offset0:32 offset1:48
	ds_write2_b32 v140, v117, v113 offset0:100 offset1:116
	ds_write2_b32 v140, v118, v114 offset0:168 offset1:184
	ds_write2_b32 v140, v119, v115 offset0:236 offset1:252
	v_lshlrev_b64 v[88:89], 12, v[136:137]
	v_lshl_add_u64 v[134:135], s[16:17], 0, v[132:133]
	s_waitcnt lgkmcnt(0)
	v_lshl_add_u64 v[88:89], s[12:13], 0, v[88:89]
	v_lshlrev_b32_e32 v132, 2, v139
	ds_read_b128 v[120:123], v141
	ds_read_b128 v[148:151], v141 offset:16
	ds_read_b128 v[112:115], v141 offset:32
	ds_read_b128 v[80:83], v141 offset:48
	v_lshl_add_u64 v[124:125], v[88:89], 0, v[132:133]
	global_load_dwordx4 v[152:155], v[124:125], off
	global_load_dwordx4 v[156:159], v[124:125], off offset:16
	s_waitcnt lgkmcnt(14)
	v_mul_f32_e32 v84, 0xbfb8aa3b, v84
	v_mul_f32_e32 v85, 0xbfb8aa3b, v85
	v_exp_f32_e32 v84, v84
	v_exp_f32_e32 v85, v85
	v_cmp_eq_u32_e64 s[8:9], 0, v138
	v_mul_f32_e32 v86, 0xbfb8aa3b, v86
	v_mul_f32_e32 v87, 0xbfb8aa3b, v87
	v_pk_add_f32 v[84:85], v[84:85], 1.0 op_sel_hi:[1,0]
	v_exp_f32_e32 v86, v86
	v_exp_f32_e32 v87, v87
	global_load_dwordx4 v[88:91], v[124:125], off offset:48
	global_load_dwordx4 v[116:119], v[124:125], off offset:32
	s_waitcnt lgkmcnt(13)
	v_mul_f32_e32 v128, 0xbfb8aa3b, v128
	v_rcp_f32_e32 v85, v85
	v_pk_add_f32 v[86:87], v[86:87], 1.0 op_sel_hi:[1,0]
	v_rcp_f32_e32 v84, v84
	v_mul_f32_e32 v129, 0xbfb8aa3b, v129
	v_exp_f32_e32 v128, v128
	v_exp_f32_e32 v129, v129
	v_mul_f32_e32 v130, 0xbfb8aa3b, v130
	v_mul_f32_e32 v131, 0xbfb8aa3b, v131
	v_exp_f32_e32 v130, v130
	v_pk_add_f32 v[128:129], v[128:129], 1.0 op_sel_hi:[1,0]
	v_exp_f32_e32 v131, v131
	s_waitcnt lgkmcnt(12)
	v_mul_f32_e32 v92, 0xbfb8aa3b, v92
	v_mul_f32_e32 v93, 0xbfb8aa3b, v93
	v_exp_f32_e32 v92, v92
	v_pk_add_f32 v[130:131], v[130:131], 1.0 op_sel_hi:[1,0]
	v_exp_f32_e32 v93, v93
	v_mul_f32_e32 v94, 0xbfb8aa3b, v94
	v_mul_f32_e32 v95, 0xbfb8aa3b, v95
	v_exp_f32_e32 v94, v94
	v_pk_add_f32 v[92:93], v[92:93], 1.0 op_sel_hi:[1,0]
	v_exp_f32_e32 v95, v95
	s_waitcnt vmcnt(3) lgkmcnt(3)
	v_pk_fma_f32 v[84:85], v[84:85], v[120:121], v[152:153]
	v_rcp_f32_e32 v87, v87
	v_mul_f32_e32 v120, 0xbfb8aa3b, v144
	v_mul_f32_e32 v121, 0xbfb8aa3b, v145
	v_exp_f32_e32 v120, v120
	v_exp_f32_e32 v121, v121
	v_rcp_f32_e32 v86, v86
	v_pk_add_f32 v[120:121], v[120:121], 1.0 op_sel_hi:[1,0]
	v_pk_fma_f32 v[86:87], v[86:87], v[122:123], v[154:155]
	v_pk_add_f32 v[94:95], v[94:95], 1.0 op_sel_hi:[1,0]
	v_pk_mul_f32 v[126:127], v[84:85], v[84:85]
	v_pk_mul_f32 v[138:139], v[86:87], v[86:87]
	v_rcp_f32_e32 v121, v121
	v_mul_f32_e32 v122, 0xbfb8aa3b, v146
	v_mul_f32_e32 v123, 0xbfb8aa3b, v147
	v_exp_f32_e32 v122, v122
	v_exp_f32_e32 v123, v123
	v_rcp_f32_e32 v120, v120
	v_pk_add_f32 v[122:123], v[122:123], 1.0 op_sel_hi:[1,0]
	s_waitcnt vmcnt(2) lgkmcnt(2)
	v_pk_fma_f32 v[120:121], v[120:121], v[148:149], v[156:157]
	v_pk_mul_f32 v[144:145], v[120:121], v[120:121]
	v_rcp_f32_e32 v123, v123
	v_rcp_f32_e32 v122, v122
	s_nop 0
	v_pk_fma_f32 v[122:123], v[122:123], v[150:151], v[158:159]
	v_rcp_f32_e32 v129, v129
	v_pk_mul_f32 v[146:147], v[122:123], v[122:123]
	v_rcp_f32_e32 v128, v128
	s_waitcnt vmcnt(0) lgkmcnt(1)
	v_pk_fma_f32 v[112:113], v[128:129], v[112:113], v[116:117]
	v_rcp_f32_e32 v129, v131
	v_pk_mul_f32 v[116:117], v[112:113], v[112:113]
	v_rcp_f32_e32 v128, v130
	s_nop 0
	v_pk_fma_f32 v[114:115], v[128:129], v[114:115], v[118:119]
	v_rcp_f32_e32 v93, v93
	v_pk_mul_f32 v[118:119], v[114:115], v[114:115]
	v_div_scale_f32 v129, s[0:1], v95, v95, 1.0
	v_rcp_f32_e32 v130, v129
	v_rcp_f32_e32 v92, v92
	s_waitcnt lgkmcnt(0)
; DI unsigned pack2(float a, float b) { return (unsigned)f2bf(a) | ((unsigned)f2bf(b) << 16); }
; DI float sigm(float x) { return 1.f / (1.f + __expf(-x)); }
;   const int lane = tid & 63, wid = tid >> 6, fr = lane & 15, fq = lane >> 4;
;   float* stg = (float*)(smem + PATCH) + wid * (16 * 68);
;   asm volatile("" ::: "memory");
; #pragma unroll
;   for (int n = 0; n < 4; ++n)
; #pragma unroll
;     for (int j = 0; j < 4; ++j) stg[(fq * 4 + j) * 68 + n * 16 + fr] = am[n][j];
;   asm volatile("s_waitcnt lgkmcnt(0)" ::: "memory");
;   const float* rp = stg + (lane >> 2) * 68 + (lane & 3) * 16;
; #pragma unroll
;   for (int i = 0; i < 4; ++i) { f32x4 t = *(const f32x4*)(rp + i * 4); v[4 * i] = t[0]; v[4 * i + 1] = t[1]; v[4 * i + 2] = t[2]; v[4 * i + 3] = t[3]; }
;   asm volatile("" ::: "memory");
; }
; DI void store16_bf(bft* dst, const float (&v)[16]) {
;   u32x4 o0 = {pack2(v[0], v[1]), pack2(v[2], v[3]), pack2(v[4], v[5]), pack2(v[6], v[7])}, o1 = {pack2(v[8], v[9]), pack2(v[10], v[11]), pack2(v[12], v[13]), pack2(v[14], v[15])};
;   *(u32x4*)dst = o0; *(u32x4*)(dst + 8) = o1;
; }
; DI void phase_ple(const Params& p, int layer, const bft* hbin, bft* hbout, int ldo, float* ssq) {
;     ...
;     EPI_BEGIN
;       float v2[16]; epi_stage(tid, acc2[m], v2); float h[16]; float* hp = p.out + (size_t)row * 1024 + col; load16_f(hp, h); float ss = 0.f;
; #pragma unroll
;       for (int i = 0; i < 16; ++i) { h[i] += sigm(v[i]) * v2[i]; ss += h[i] * h[i]; }
;       store16_f(hp, h); if (hbout) store16_bf(hbout + (size_t)row * ldo + col, h);
;       ss += __shfl_xor(ss, 1); ss += __shfl_xor(ss, 2);
;       if ((lane & 3) == 0) atomicAdd(ssq + row, ss);
;     EPI_END
	v_pk_fma_f32 v[80:81], v[92:93], v[80:81], v[88:89]
	v_fma_f32 v92, -v129, v130, 1.0
	v_fmac_f32_e32 v130, v92, v130
	v_div_scale_f32 v92, vcc, 1.0, v95, 1.0
	v_mul_f32_e32 v93, v92, v130
	v_fma_f32 v128, -v129, v93, v92
	v_fmac_f32_e32 v93, v128, v130
	v_div_scale_f32 v128, s[0:1], v94, v94, 1.0
	v_fma_f32 v92, -v129, v93, v92
	v_rcp_f32_e32 v129, v128
	v_div_fmas_f32 v92, v92, v130, v93
	v_div_fixup_f32 v93, v92, v95, 1.0
	v_pk_mul_f32 v[88:89], v[80:81], v[80:81]
	v_fma_f32 v92, -v128, v129, 1.0
	v_fmac_f32_e32 v129, v92, v129
	v_div_scale_f32 v92, vcc, 1.0, v94, 1.0
	v_mul_f32_e32 v95, v92, v129
	v_fma_f32 v130, -v128, v95, v92
	v_fmac_f32_e32 v95, v130, v129
	v_fma_f32 v92, -v128, v95, v92
	v_div_fmas_f32 v92, v92, v129, v95
	v_div_fixup_f32 v92, v92, v94, 1.0
	v_pk_fma_f32 v[82:83], v[92:93], v[82:83], v[90:91]
	v_add_f32_e32 v92, v126, v127
	v_add_f32_e32 v92, v138, v92
	v_add_f32_e32 v92, v139, v92
	v_add_f32_e32 v92, v144, v92
	v_add_f32_e32 v92, v145, v92
	v_add_f32_e32 v92, v146, v92
	v_add_f32_e32 v92, v147, v92
	v_add_f32_e32 v92, v116, v92
	v_add_f32_e32 v92, v117, v92
	v_add_f32_e32 v92, v118, v92
	v_add_f32_e32 v92, v119, v92
	v_add_f32_e32 v88, v88, v92
	v_pk_mul_f32 v[90:91], v[82:83], v[82:83]
	v_add_f32_e32 v88, v89, v88
	v_add_f32_e32 v88, v90, v88
	v_add_f32_e32 v89, v91, v88
	v_bfe_u32 v94, v87, 16, 1
	global_store_dwordx4 v[124:125], v[84:87], off
	global_store_dwordx4 v[124:125], v[120:123], off offset:16
	global_store_dwordx4 v[124:125], v[112:115], off offset:32
	global_store_dwordx4 v[124:125], v[80:83], off offset:48
	v_add3_u32 v94, v87, v94, s24
	v_bfe_u32 v90, v86, 16, 1
	v_add3_u32 v86, v86, v90, s24
	v_lshrrev_b32_e32 v90, 16, v86
	v_cvt_pk_bf16_f32 v86, v120, v121
	v_cvt_pk_bf16_f32 v84, v84, v85
	v_cvt_pk_bf16_f32 v87, v122, v123
	v_and_or_b32 v85, v94, s25, v90
	v_bfe_u32 v90, v113, 16, 1
	v_add3_u32 v91, v113, v90, s24
	v_bfe_u32 v88, v114, 16, 1
	v_bfe_u32 v95, v112, 16, 1
	v_add3_u32 v88, v114, v88, s24
	v_and_b32_e32 v90, 64, v181
	v_add3_u32 v95, v112, v95, s24
	v_lshrrev_b32_e32 v112, 16, v88
	v_xor_b32_e32 v88, 1, v181
	v_add_u32_e32 v113, 64, v90
	v_cmp_lt_i32_e32 vcc, v88, v113
	s_nop 4
	v_cvt_pk_bf16_f32 v90, v80, v81
	s_nop 4
	v_cndmask_b32_e32 v88, v181, v88, vcc
	v_lshlrev_b32_e32 v119, 2, v88
	ds_bpermute_b32 v114, v119, v89
	v_xor_b32_e32 v81, 2, v181
	v_cmp_lt_i32_e32 vcc, v81, v113
	v_bfe_u32 v94, v115, 16, 1
	v_mad_i64_i32 v[92:93], s[0:1], v136, s4, v[134:135]
	v_cndmask_b32_e32 v81, v181, v81, vcc
	s_waitcnt lgkmcnt(0)
	v_add_f32_e32 v80, v89, v114
	v_lshlrev_b32_e32 v118, 2, v81
	ds_bpermute_b32 v81, v118, v80
	v_add3_u32 v94, v115, v94, s24
	v_lshrrev_b32_e32 v88, 16, v95
	v_and_or_b32 v88, v91, s25, v88
	v_cvt_pk_bf16_f32 v91, v82, v83
	v_and_or_b32 v89, v94, s25, v112
	global_store_dwordx4 v[92:93], v[84:87], off
	global_store_dwordx4 v[92:93], v[88:91], off offset:16
	s_and_saveexec_b64 s[0:1], s[8:9]
	s_cbranch_execz .LBB0_1048
	s_waitcnt lgkmcnt(0)
	v_add_f32_e32 v82, v80, v81
	v_lshl_add_u64 v[80:81], v[136:137], 2, s[18:19]
	global_atomic_add_f32 v[80:81], v82, off
.LBB0_1048:
	s_or_b64 exec, exec, s[0:1]
	ds_write2_b32 v140, v76, v72 offset1:16
	ds_write2_b32 v140, v77, v73 offset0:68 offset1:84
	ds_write2_b32 v140, v78, v74 offset0:136 offset1:152
	ds_write2_b32 v140, v79, v75 offset0:204 offset1:220
	ds_write2_b32 v140, v68, v64 offset0:32 offset1:48
	ds_write2_b32 v140, v69, v65 offset0:100 offset1:116
	ds_write2_b32 v140, v70, v66 offset0:168 offset1:184
	ds_write2_b32 v140, v71, v67 offset0:236 offset1:252
	s_waitcnt lgkmcnt(0)
	v_or_b32_e32 v116, 16, v136
	ds_read_b128 v[120:123], v141
	ds_read_b128 v[112:115], v141 offset:16
	ds_read_b128 v[88:91], v141 offset:32
	ds_read_b128 v[76:79], v141 offset:48
	v_ashrrev_i32_e32 v117, 31, v116
	ds_write2_b32 v140, v108, v104 offset1:16
	ds_write2_b32 v140, v109, v105 offset0:68 offset1:84
	ds_write2_b32 v140, v110, v106 offset0:136 offset1:152
	ds_write2_b32 v140, v111, v107 offset0:204 offset1:220
	ds_write2_b32 v140, v100, v96 offset0:32 offset1:48
	ds_write2_b32 v140, v101, v97 offset0:100 offset1:116
	ds_write2_b32 v140, v102, v98 offset0:168 offset1:184
	ds_write2_b32 v140, v103, v99 offset0:236 offset1:252
	v_lshlrev_b64 v[68:69], 12, v[116:117]
	s_waitcnt lgkmcnt(0)
	v_lshl_add_u64 v[68:69], s[12:13], 0, v[68:69]
	ds_read_b128 v[72:75], v141
	ds_read_b128 v[92:95], v141 offset:16
	s_waitcnt lgkmcnt(14)
	ds_read_b128 v[80:83], v141 offset:32
	ds_read_b128 v[64:67], v141 offset:48
	v_lshl_add_u64 v[104:105], v[68:69], 0, v[132:133]
	global_load_dwordx4 v[68:71], v[104:105], off offset:48
	global_load_dwordx4 v[84:87], v[104:105], off offset:32
	global_load_dwordx4 v[96:99], v[104:105], off offset:16
	global_load_dwordx4 v[100:103], v[104:105], off
	s_waitcnt lgkmcnt(14)
	v_mul_f32_e32 v106, 0xbfb8aa3b, v120
	v_mul_f32_e32 v107, 0xbfb8aa3b, v121
	v_exp_f32_e32 v106, v106
	v_exp_f32_e32 v107, v107
	s_waitcnt lgkmcnt(13)
	v_mul_f32_e32 v88, 0xbfb8aa3b, v88
	v_mul_f32_e32 v89, 0xbfb8aa3b, v89
	v_exp_f32_e32 v88, v88
	v_pk_add_f32 v[106:107], v[106:107], 1.0 op_sel_hi:[1,0]
	v_exp_f32_e32 v89, v89
	s_nop 0
	v_pk_add_f32 v[88:89], v[88:89], 1.0 op_sel_hi:[1,0]
	s_waitcnt lgkmcnt(12)
	v_mul_f32_e32 v76, 0xbfb8aa3b, v76
	v_mul_f32_e32 v77, 0xbfb8aa3b, v77
	v_rcp_f32_e32 v107, v107
	v_exp_f32_e32 v76, v76
	v_exp_f32_e32 v77, v77
	v_rcp_f32_e32 v106, v106
	v_pk_add_f32 v[76:77], v[76:77], 1.0 op_sel_hi:[1,0]
	s_waitcnt vmcnt(0) lgkmcnt(3)
; DI unsigned pack2(float a, float b) { return (unsigned)f2bf(a) | ((unsigned)f2bf(b) << 16); }
; DI float sigm(float x) { return 1.f / (1.f + __expf(-x)); }
;   const int lane = tid & 63, wid = tid >> 6, fr = lane & 15, fq = lane >> 4;
;   float* stg = (float*)(smem + PATCH) + wid * (16 * 68);
;   asm volatile("" ::: "memory");
; #pragma unroll
;   for (int n = 0; n < 4; ++n)
; #pragma unroll
;     for (int j = 0; j < 4; ++j) stg[(fq * 4 + j) * 68 + n * 16 + fr] = am[n][j];
;   asm volatile("s_waitcnt lgkmcnt(0)" ::: "memory");
;   const float* rp = stg + (lane >> 2) * 68 + (lane & 3) * 16;
; #pragma unroll
;   for (int i = 0; i < 4; ++i) { f32x4 t = *(const f32x4*)(rp + i * 4); v[4 * i] = t[0]; v[4 * i + 1] = t[1]; v[4 * i + 2] = t[2]; v[4 * i + 3] = t[3]; }
;   asm volatile("" ::: "memory");
; }
; DI void store16_bf(bft* dst, const float (&v)[16]) {
;   u32x4 o0 = {pack2(v[0], v[1]), pack2(v[2], v[3]), pack2(v[4], v[5]), pack2(v[6], v[7])}, o1 = {pack2(v[8], v[9]), pack2(v[10], v[11]), pack2(v[12], v[13]), pack2(v[14], v[15])};
;   *(u32x4*)dst = o0; *(u32x4*)(dst + 8) = o1;
; }
; DI void phase_ple(const Params& p, int layer, const bft* hbin, bft* hbout, int ldo, float* ssq) {
;     ...
;     EPI_BEGIN
;       float v2[16]; epi_stage(tid, acc2[m], v2); float h[16]; float* hp = p.out + (size_t)row * 1024 + col; load16_f(hp, h); float ss = 0.f;
; #pragma unroll
;       for (int i = 0; i < 16; ++i) { h[i] += sigm(v[i]) * v2[i]; ss += h[i] * h[i]; }
;       store16_f(hp, h); if (hbout) store16_bf(hbout + (size_t)row * ldo + col, h);
;       ss += __shfl_xor(ss, 1); ss += __shfl_xor(ss, 2);
;       if ((lane & 3) == 0) atomicAdd(ssq + row, ss);
;     EPI_END
	v_pk_fma_f32 v[72:73], v[106:107], v[72:73], v[100:101]
	v_mul_f32_e32 v106, 0xbfb8aa3b, v122
	v_mul_f32_e32 v107, 0xbfb8aa3b, v123
	v_exp_f32_e32 v106, v106
	v_exp_f32_e32 v107, v107
	v_pk_mul_f32 v[100:101], v[72:73], v[72:73]
	v_pk_add_f32 v[106:107], v[106:107], 1.0 op_sel_hi:[1,0]
	s_nop 0
	s_nop 0
	v_rcp_f32_e32 v107, v107
	s_nop 0
	v_rcp_f32_e32 v106, v106
	s_nop 0
	v_pk_fma_f32 v[74:75], v[106:107], v[74:75], v[102:103]
	v_mul_f32_e32 v106, 0xbfb8aa3b, v112
	v_mul_f32_e32 v107, 0xbfb8aa3b, v113
	v_exp_f32_e32 v106, v106
	v_exp_f32_e32 v107, v107
	v_pk_mul_f32 v[102:103], v[74:75], v[74:75]
	v_pk_add_f32 v[106:107], v[106:107], 1.0 op_sel_hi:[1,0]
	s_nop 0
	s_nop 0
	v_rcp_f32_e32 v107, v107
	s_nop 0
	v_rcp_f32_e32 v106, v106
	s_waitcnt lgkmcnt(2)
	v_pk_fma_f32 v[92:93], v[106:107], v[92:93], v[96:97]
	v_mul_f32_e32 v106, 0xbfb8aa3b, v114
	v_mul_f32_e32 v107, 0xbfb8aa3b, v115
	v_exp_f32_e32 v106, v106
	v_exp_f32_e32 v107, v107
	v_pk_mul_f32 v[96:97], v[92:93], v[92:93]
	v_pk_add_f32 v[106:107], v[106:107], 1.0 op_sel_hi:[1,0]
	s_nop 0
	s_nop 0
	v_rcp_f32_e32 v107, v107
	s_nop 0
	v_rcp_f32_e32 v106, v106
	s_nop 0
	v_pk_fma_f32 v[94:95], v[106:107], v[94:95], v[98:99]
	v_pk_mul_f32 v[98:99], v[94:95], v[94:95]
	v_rcp_f32_e32 v89, v89
	s_nop 0
	v_rcp_f32_e32 v88, v88
	s_waitcnt lgkmcnt(1)
	v_pk_fma_f32 v[80:81], v[88:89], v[80:81], v[84:85]
	v_mul_f32_e32 v88, 0xbfb8aa3b, v90
	v_mul_f32_e32 v89, 0xbfb8aa3b, v91
	v_exp_f32_e32 v88, v88
	v_exp_f32_e32 v89, v89
	v_pk_mul_f32 v[84:85], v[80:81], v[80:81]
	v_pk_add_f32 v[88:89], v[88:89], 1.0 op_sel_hi:[1,0]
	s_nop 0
	s_nop 0
	v_rcp_f32_e32 v89, v89
	s_nop 0
	v_rcp_f32_e32 v88, v88
	s_nop 0
	v_pk_fma_f32 v[82:83], v[88:89], v[82:83], v[86:87]
	v_pk_mul_f32 v[86:87], v[82:83], v[82:83]
	v_rcp_f32_e32 v77, v77
	s_nop 0
	v_rcp_f32_e32 v76, v76
	s_waitcnt lgkmcnt(0)
	v_pk_fma_f32 v[64:65], v[76:77], v[64:65], v[68:69]
	v_mul_f32_e32 v76, 0xbfb8aa3b, v78
	v_mul_f32_e32 v77, 0xbfb8aa3b, v79
	v_exp_f32_e32 v76, v76
	v_exp_f32_e32 v77, v77
	v_pk_mul_f32 v[68:69], v[64:65], v[64:65]
	v_pk_add_f32 v[76:77], v[76:77], 1.0 op_sel_hi:[1,0]
	s_nop 0
	s_nop 0
	v_rcp_f32_e32 v77, v77
	v_div_scale_f32 v78, s[0:1], v76, v76, 1.0
	v_rcp_f32_e32 v79, v78
	s_nop 0
	v_fma_f32 v88, -v78, v79, 1.0
	v_fmac_f32_e32 v79, v88, v79
	v_div_scale_f32 v88, vcc, 1.0, v76, 1.0
	v_mul_f32_e32 v89, v88, v79
	v_fma_f32 v90, -v78, v89, v88
	v_fmac_f32_e32 v89, v90, v79
	v_fma_f32 v78, -v78, v89, v88
	v_div_fmas_f32 v78, v78, v79, v89
	v_div_fixup_f32 v76, v78, v76, 1.0
	v_pk_fma_f32 v[66:67], v[76:77], v[66:67], v[70:71]
	v_add_f32_e32 v76, v100, v101
	v_add_f32_e32 v76, v102, v76
	v_add_f32_e32 v76, v103, v76
	v_add_f32_e32 v76, v96, v76
	v_add_f32_e32 v76, v97, v76
	v_add_f32_e32 v76, v98, v76
	v_add_f32_e32 v76, v99, v76
	v_add_f32_e32 v76, v84, v76
	v_add_f32_e32 v76, v85, v76
	v_add_f32_e32 v76, v86, v76
	v_add_f32_e32 v76, v87, v76
	v_add_f32_e32 v68, v68, v76
	v_pk_mul_f32 v[70:71], v[66:67], v[66:67]
	v_add_f32_e32 v68, v69, v68
	v_add_f32_e32 v68, v70, v68
	v_bfe_u32 v69, v73, 16, 1
	v_add_f32_e32 v78, v71, v68
	global_store_dwordx4 v[104:105], v[72:75], off
	global_store_dwordx4 v[104:105], v[92:95], off offset:16
	global_store_dwordx4 v[104:105], v[80:83], off offset:32
	global_store_dwordx4 v[104:105], v[64:67], off offset:48
	s_nop 4
	v_add3_u32 v69, v73, v69, s24
	v_bfe_u32 v79, v72, 16, 1
	v_add3_u32 v72, v72, v79, s24
	v_lshrrev_b32_e32 v72, 16, v72
	v_cvt_pk_bf16_f32 v71, v94, v95
	v_cvt_pk_bf16_f32 v70, v92, v93
	v_and_or_b32 v68, v69, s25, v72
	v_cvt_pk_bf16_f32 v69, v74, v75
	v_bfe_u32 v74, v67, 16, 1
	v_add3_u32 v67, v67, v74, s24
	v_bfe_u32 v74, v66, 16, 1
	v_add3_u32 v66, v66, v74, s24
	v_mad_i64_i32 v[76:77], s[0:1], v116, s4, v[134:135]
	v_lshrrev_b32_e32 v74, 16, v66
	v_cvt_pk_bf16_f32 v66, v64, v65
	v_cvt_pk_bf16_f32 v64, v80, v81
	v_and_or_b32 v67, v67, s25, v74
	v_cvt_pk_bf16_f32 v65, v82, v83
	global_store_dwordx4 v[76:77], v[68:71], off
	global_store_dwordx4 v[76:77], v[64:67], off offset:16
	ds_bpermute_b32 v64, v119, v78
	s_waitcnt lgkmcnt(0)
	v_add_f32_e32 v64, v78, v64
	ds_bpermute_b32 v65, v118, v64
	s_and_saveexec_b64 s[0:1], s[8:9]
	s_cbranch_execz .LBB0_1050
	s_waitcnt lgkmcnt(0)
	v_add_f32_e32 v66, v64, v65
	v_lshl_add_u64 v[64:65], v[116:117], 2, s[18:19]
	global_atomic_add_f32 v[64:65], v66, off
; DI unsigned pack2(float a, float b) { return (unsigned)f2bf(a) | ((unsigned)f2bf(b) << 16); }
; DI float sigm(float x) { return 1.f / (1.f + __expf(-x)); }
;   const int lane = tid & 63, wid = tid >> 6, fr = lane & 15, fq = lane >> 4;
;   float* stg = (float*)(smem + PATCH) + wid * (16 * 68);
;   asm volatile("" ::: "memory");
; #pragma unroll
;   for (int n = 0; n < 4; ++n)
; #pragma unroll
;     for (int j = 0; j < 4; ++j) stg[(fq * 4 + j) * 68 + n * 16 + fr] = am[n][j];
;   asm volatile("s_waitcnt lgkmcnt(0)" ::: "memory");
;   const float* rp = stg + (lane >> 2) * 68 + (lane & 3) * 16;
; #pragma unroll
;   for (int i = 0; i < 4; ++i) { f32x4 t = *(const f32x4*)(rp + i * 4); v[4 * i] = t[0]; v[4 * i + 1] = t[1]; v[4 * i + 2] = t[2]; v[4 * i + 3] = t[3]; }
;   asm volatile("" ::: "memory");
; }
; DI void store16_bf(bft* dst, const float (&v)[16]) {
;   u32x4 o0 = {pack2(v[0], v[1]), pack2(v[2], v[3]), pack2(v[4], v[5]), pack2(v[6], v[7])}, o1 = {pack2(v[8], v[9]), pack2(v[10], v[11]), pack2(v[12], v[13]), pack2(v[14], v[15])};
;   *(u32x4*)dst = o0; *(u32x4*)(dst + 8) = o1;
; }
; DI void phase_ple(const Params& p, int layer, const bft* hbin, bft* hbout, int ldo, float* ssq) {
;     ...
;     EPI_BEGIN
;       float v2[16]; epi_stage(tid, acc2[m], v2); float h[16]; float* hp = p.out + (size_t)row * 1024 + col; load16_f(hp, h); float ss = 0.f;
; #pragma unroll
;       for (int i = 0; i < 16; ++i) { h[i] += sigm(v[i]) * v2[i]; ss += h[i] * h[i]; }
;       store16_f(hp, h); if (hbout) store16_bf(hbout + (size_t)row * ldo + col, h);
;       ss += __shfl_xor(ss, 1); ss += __shfl_xor(ss, 2);
;       if ((lane & 3) == 0) atomicAdd(ssq + row, ss);
;     EPI_END
.LBB0_1050:
	s_or_b64 exec, exec, s[0:1]
	ds_write2_b32 v140, v44, v40 offset1:16
	ds_write2_b32 v140, v45, v41 offset0:68 offset1:84
	ds_write2_b32 v140, v46, v42 offset0:136 offset1:152
	ds_write2_b32 v140, v47, v43 offset0:204 offset1:220
	ds_write2_b32 v140, v36, v32 offset0:32 offset1:48
	ds_write2_b32 v140, v37, v33 offset0:100 offset1:116
	ds_write2_b32 v140, v38, v34 offset0:168 offset1:184
	ds_write2_b32 v140, v39, v35 offset0:236 offset1:252
	s_waitcnt lgkmcnt(0)
	v_or_b32_e32 v76, 32, v136
	ds_read_b128 v[80:83], v141
	ds_read_b128 v[68:71], v141 offset:16
	s_waitcnt lgkmcnt(10)
	ds_read_b128 v[64:67], v141 offset:32
	ds_read_b128 v[44:47], v141 offset:48
	v_ashrrev_i32_e32 v77, 31, v76
	ds_write2_b32 v140, v60, v56 offset1:16
	ds_write2_b32 v140, v61, v57 offset0:68 offset1:84
	ds_write2_b32 v140, v62, v58 offset0:136 offset1:152
	ds_write2_b32 v140, v63, v59 offset0:204 offset1:220
	ds_write2_b32 v140, v52, v48 offset0:32 offset1:48
	ds_write2_b32 v140, v53, v49 offset0:100 offset1:116
	ds_write2_b32 v140, v54, v50 offset0:168 offset1:184
	ds_write2_b32 v140, v55, v51 offset0:236 offset1:252
	v_lshlrev_b64 v[36:37], 12, v[76:77]
	s_waitcnt lgkmcnt(0)
	v_lshl_add_u64 v[36:37], s[12:13], 0, v[36:37]
	ds_read_b128 v[40:43], v141
	ds_read_b128 v[56:59], v141 offset:16
	ds_read_b128 v[48:51], v141 offset:32
	ds_read_b128 v[32:35], v141 offset:48
	v_lshl_add_u64 v[78:79], v[36:37], 0, v[132:133]
	global_load_dwordx4 v[36:39], v[78:79], off offset:48
	global_load_dwordx4 v[52:55], v[78:79], off offset:32
	global_load_dwordx4 v[60:63], v[78:79], off offset:16
	global_load_dwordx4 v[72:75], v[78:79], off
	s_waitcnt lgkmcnt(14)
	v_mul_f32_e32 v80, 0xbfb8aa3b, v80
	v_mul_f32_e32 v81, 0xbfb8aa3b, v81
	v_exp_f32_e32 v80, v80
	v_exp_f32_e32 v81, v81
	v_mul_f32_e32 v68, 0xbfb8aa3b, v68
	v_mul_f32_e32 v69, 0xbfb8aa3b, v69
	v_exp_f32_e32 v68, v68
	v_pk_add_f32 v[80:81], v[80:81], 1.0 op_sel_hi:[1,0]
	v_exp_f32_e32 v69, v69
	s_nop 0
	v_pk_add_f32 v[68:69], v[68:69], 1.0 op_sel_hi:[1,0]
	s_waitcnt lgkmcnt(13)
	v_mul_f32_e32 v64, 0xbfb8aa3b, v64
	v_mul_f32_e32 v65, 0xbfb8aa3b, v65
	v_rcp_f32_e32 v81, v81
	v_exp_f32_e32 v64, v64
	v_exp_f32_e32 v65, v65
	s_waitcnt lgkmcnt(12)
	v_mul_f32_e32 v44, 0xbfb8aa3b, v44
	v_rcp_f32_e32 v80, v80
	v_pk_add_f32 v[64:65], v[64:65], 1.0 op_sel_hi:[1,0]
	v_mul_f32_e32 v45, 0xbfb8aa3b, v45
	v_exp_f32_e32 v44, v44
	v_exp_f32_e32 v45, v45
	s_waitcnt vmcnt(0) lgkmcnt(3)
	v_pk_fma_f32 v[40:41], v[80:81], v[40:41], v[72:73]
	v_mul_f32_e32 v80, 0xbfb8aa3b, v82
	v_mul_f32_e32 v81, 0xbfb8aa3b, v83
	v_exp_f32_e32 v80, v80
	v_exp_f32_e32 v81, v81
	v_pk_add_f32 v[44:45], v[44:45], 1.0 op_sel_hi:[1,0]
	v_pk_mul_f32 v[72:73], v[40:41], v[40:41]
	v_pk_add_f32 v[80:81], v[80:81], 1.0 op_sel_hi:[1,0]
	s_nop 0
	s_nop 0
	v_rcp_f32_e32 v81, v81
	s_nop 0
	v_rcp_f32_e32 v80, v80
	s_nop 0
	v_pk_fma_f32 v[42:43], v[80:81], v[42:43], v[74:75]
	v_pk_mul_f32 v[74:75], v[42:43], v[42:43]
	v_rcp_f32_e32 v69, v69
	s_nop 0
	v_rcp_f32_e32 v68, v68
	s_waitcnt lgkmcnt(2)
	v_pk_fma_f32 v[56:57], v[68:69], v[56:57], v[60:61]
	v_mul_f32_e32 v68, 0xbfb8aa3b, v70
	v_mul_f32_e32 v69, 0xbfb8aa3b, v71
	v_exp_f32_e32 v68, v68
	v_exp_f32_e32 v69, v69
	v_pk_mul_f32 v[60:61], v[56:57], v[56:57]
	v_pk_add_f32 v[68:69], v[68:69], 1.0 op_sel_hi:[1,0]
	s_nop 0
	s_nop 0
	v_rcp_f32_e32 v69, v69
	s_nop 0
	v_rcp_f32_e32 v68, v68
	s_nop 0
	v_pk_fma_f32 v[58:59], v[68:69], v[58:59], v[62:63]
	v_pk_mul_f32 v[62:63], v[58:59], v[58:59]
	v_rcp_f32_e32 v65, v65
	s_nop 0
	v_rcp_f32_e32 v64, v64
	s_waitcnt lgkmcnt(1)
	v_pk_fma_f32 v[48:49], v[64:65], v[48:49], v[52:53]
	v_mul_f32_e32 v64, 0xbfb8aa3b, v66
	v_mul_f32_e32 v65, 0xbfb8aa3b, v67
	v_exp_f32_e32 v64, v64
	v_exp_f32_e32 v65, v65
	v_pk_mul_f32 v[52:53], v[48:49], v[48:49]
	v_pk_add_f32 v[64:65], v[64:65], 1.0 op_sel_hi:[1,0]
	s_nop 0
	s_nop 0
	v_rcp_f32_e32 v65, v65
	s_nop 0
	v_rcp_f32_e32 v64, v64
	s_nop 0
	v_pk_fma_f32 v[50:51], v[64:65], v[50:51], v[54:55]
	v_pk_mul_f32 v[54:55], v[50:51], v[50:51]
	v_rcp_f32_e32 v45, v45
	s_nop 0
	v_rcp_f32_e32 v44, v44
	s_waitcnt lgkmcnt(0)
	v_pk_fma_f32 v[32:33], v[44:45], v[32:33], v[36:37]
	v_mul_f32_e32 v44, 0xbfb8aa3b, v46
	v_mul_f32_e32 v45, 0xbfb8aa3b, v47
	v_exp_f32_e32 v44, v44
	v_exp_f32_e32 v45, v45
	v_pk_mul_f32 v[36:37], v[32:33], v[32:33]
	v_pk_add_f32 v[44:45], v[44:45], 1.0 op_sel_hi:[1,0]
	s_nop 0
	s_nop 0
	v_rcp_f32_e32 v45, v45
	v_div_scale_f32 v46, s[0:1], v44, v44, 1.0
	v_rcp_f32_e32 v47, v46
	s_nop 0
	v_fma_f32 v64, -v46, v47, 1.0
	v_fmac_f32_e32 v47, v64, v47
	v_div_scale_f32 v64, vcc, 1.0, v44, 1.0
	v_mul_f32_e32 v65, v64, v47
	v_fma_f32 v66, -v46, v65, v64
	v_fmac_f32_e32 v65, v66, v47
	v_fma_f32 v46, -v46, v65, v64
	v_div_fmas_f32 v46, v46, v47, v65
	v_div_fixup_f32 v44, v46, v44, 1.0
	v_pk_fma_f32 v[34:35], v[44:45], v[34:35], v[38:39]
	v_add_f32_e32 v44, v72, v73
	v_add_f32_e32 v44, v74, v44
	v_add_f32_e32 v44, v75, v44
	v_add_f32_e32 v44, v60, v44
	v_add_f32_e32 v44, v61, v44
	v_add_f32_e32 v44, v62, v44
	v_add_f32_e32 v44, v63, v44
	v_add_f32_e32 v44, v52, v44
	v_add_f32_e32 v44, v53, v44
	v_add_f32_e32 v44, v54, v44
	v_add_f32_e32 v44, v55, v44
	v_add_f32_e32 v36, v36, v44
	v_pk_mul_f32 v[38:39], v[34:35], v[34:35]
	v_add_f32_e32 v36, v37, v36
	v_add_f32_e32 v36, v38, v36
	v_bfe_u32 v37, v41, 16, 1
	v_add_f32_e32 v46, v39, v36
	global_store_dwordx4 v[78:79], v[40:43], off
	global_store_dwordx4 v[78:79], v[56:59], off offset:16
	global_store_dwordx4 v[78:79], v[48:51], off offset:32
	global_store_dwordx4 v[78:79], v[32:35], off offset:48
	s_nop 4
	v_add3_u32 v37, v41, v37, s24
	v_bfe_u32 v47, v40, 16, 1
	v_add3_u32 v40, v40, v47, s24
	v_lshrrev_b32_e32 v40, 16, v40
	v_cvt_pk_bf16_f32 v39, v58, v59
	v_cvt_pk_bf16_f32 v38, v56, v57
	v_and_or_b32 v36, v37, s25, v40
	v_cvt_pk_bf16_f32 v37, v42, v43
	v_bfe_u32 v42, v35, 16, 1
	v_add3_u32 v35, v35, v42, s24
	v_bfe_u32 v42, v34, 16, 1
	v_add3_u32 v34, v34, v42, s24
	v_mad_i64_i32 v[44:45], s[0:1], v76, s4, v[134:135]
	v_lshrrev_b32_e32 v42, 16, v34
	v_cvt_pk_bf16_f32 v34, v32, v33
	v_cvt_pk_bf16_f32 v32, v48, v49
	v_and_or_b32 v35, v35, s25, v42
	v_cvt_pk_bf16_f32 v33, v50, v51
	global_store_dwordx4 v[44:45], v[36:39], off
	global_store_dwordx4 v[44:45], v[32:35], off offset:16
	ds_bpermute_b32 v32, v119, v46
	s_waitcnt lgkmcnt(0)
	v_add_f32_e32 v32, v46, v32
	ds_bpermute_b32 v33, v118, v32
	s_and_saveexec_b64 s[0:1], s[8:9]
	s_cbranch_execz .LBB0_1052
	s_waitcnt lgkmcnt(0)
	v_add_f32_e32 v34, v32, v33
	v_lshl_add_u64 v[32:33], v[76:77], 2, s[18:19]
	global_atomic_add_f32 v[32:33], v34, off
; DI unsigned pack2(float a, float b) { return (unsigned)f2bf(a) | ((unsigned)f2bf(b) << 16); }
; DI float sigm(float x) { return 1.f / (1.f + __expf(-x)); }
;   const int lane = tid & 63, wid = tid >> 6, fr = lane & 15, fq = lane >> 4;
;   float* stg = (float*)(smem + PATCH) + wid * (16 * 68);
;   asm volatile("" ::: "memory");
; #pragma unroll
;   for (int n = 0; n < 4; ++n)
; #pragma unroll
;     for (int j = 0; j < 4; ++j) stg[(fq * 4 + j) * 68 + n * 16 + fr] = am[n][j];
;   asm volatile("s_waitcnt lgkmcnt(0)" ::: "memory");
;   const float* rp = stg + (lane >> 2) * 68 + (lane & 3) * 16;
; #pragma unroll
;   for (int i = 0; i < 4; ++i) { f32x4 t = *(const f32x4*)(rp + i * 4); v[4 * i] = t[0]; v[4 * i + 1] = t[1]; v[4 * i + 2] = t[2]; v[4 * i + 3] = t[3]; }
;   asm volatile("" ::: "memory");
; }
; DI void store16_bf(bft* dst, const float (&v)[16]) {
;   u32x4 o0 = {pack2(v[0], v[1]), pack2(v[2], v[3]), pack2(v[4], v[5]), pack2(v[6], v[7])}, o1 = {pack2(v[8], v[9]), pack2(v[10], v[11]), pack2(v[12], v[13]), pack2(v[14], v[15])};
;   *(u32x4*)dst = o0; *(u32x4*)(dst + 8) = o1;
; }
; DI void phase_ple(const Params& p, int layer, const bft* hbin, bft* hbout, int ldo, float* ssq) {
;     ...
;     EPI_BEGIN
;       float v2[16]; epi_stage(tid, acc2[m], v2); float h[16]; float* hp = p.out + (size_t)row * 1024 + col; load16_f(hp, h); float ss = 0.f;
; #pragma unroll
;       for (int i = 0; i < 16; ++i) { h[i] += sigm(v[i]) * v2[i]; ss += h[i] * h[i]; }
;       store16_f(hp, h); if (hbout) store16_bf(hbout + (size_t)row * ldo + col, h);
;       ss += __shfl_xor(ss, 1); ss += __shfl_xor(ss, 2);
;       if ((lane & 3) == 0) atomicAdd(ssq + row, ss);
;     EPI_END
.LBB0_1052:
	s_or_b64 exec, exec, s[0:1]
	ds_write2_b32 v140, v8, v4 offset1:16
	ds_write2_b32 v140, v9, v5 offset0:68 offset1:84
	ds_write2_b32 v140, v10, v6 offset0:136 offset1:152
	ds_write2_b32 v140, v11, v7 offset0:204 offset1:220
	ds_write2_b32 v140, v0, v12 offset0:32 offset1:48
	ds_write2_b32 v140, v1, v13 offset0:100 offset1:116
	ds_write2_b32 v140, v2, v14 offset0:168 offset1:184
	ds_write2_b32 v140, v3, v15 offset0:236 offset1:252
	s_waitcnt lgkmcnt(0)
	v_or_b32_e32 v44, 48, v136
	ds_read_b128 v[48:51], v141
	ds_read_b128 v[36:39], v141 offset:16
	s_waitcnt lgkmcnt(10)
	ds_read_b128 v[32:35], v141 offset:32
	ds_read_b128 v[12:15], v141 offset:48
	v_ashrrev_i32_e32 v45, 31, v44
	ds_write2_b32 v140, v24, v20 offset1:16
	ds_write2_b32 v140, v25, v21 offset0:68 offset1:84
	ds_write2_b32 v140, v26, v22 offset0:136 offset1:152
	ds_write2_b32 v140, v27, v23 offset0:204 offset1:220
	ds_write2_b32 v140, v16, v28 offset0:32 offset1:48
	ds_write2_b32 v140, v17, v29 offset0:100 offset1:116
	ds_write2_b32 v140, v18, v30 offset0:168 offset1:184
	ds_write2_b32 v140, v19, v31 offset0:236 offset1:252
	v_lshlrev_b64 v[4:5], 12, v[44:45]
	s_waitcnt lgkmcnt(0)
	v_lshl_add_u64 v[4:5], s[12:13], 0, v[4:5]
	ds_read_b128 v[8:11], v141
	ds_read_b128 v[24:27], v141 offset:16
	ds_read_b128 v[16:19], v141 offset:32
	ds_read_b128 v[0:3], v141 offset:48
	v_lshl_add_u64 v[46:47], v[4:5], 0, v[132:133]
	global_load_dwordx4 v[4:7], v[46:47], off offset:48
	global_load_dwordx4 v[20:23], v[46:47], off offset:32
	global_load_dwordx4 v[28:31], v[46:47], off offset:16
	global_load_dwordx4 v[40:43], v[46:47], off
	s_waitcnt lgkmcnt(14)
	v_mul_f32_e32 v48, 0xbfb8aa3b, v48
	v_mul_f32_e32 v49, 0xbfb8aa3b, v49
	v_exp_f32_e32 v48, v48
	v_exp_f32_e32 v49, v49
	v_mul_f32_e32 v36, 0xbfb8aa3b, v36
	v_mul_f32_e32 v37, 0xbfb8aa3b, v37
	v_exp_f32_e32 v36, v36
	v_pk_add_f32 v[48:49], v[48:49], 1.0 op_sel_hi:[1,0]
	v_exp_f32_e32 v37, v37
	s_nop 0
	v_pk_add_f32 v[36:37], v[36:37], 1.0 op_sel_hi:[1,0]
	s_waitcnt lgkmcnt(13)
	v_mul_f32_e32 v32, 0xbfb8aa3b, v32
	v_mul_f32_e32 v33, 0xbfb8aa3b, v33
	v_rcp_f32_e32 v49, v49
	v_exp_f32_e32 v32, v32
	v_exp_f32_e32 v33, v33
	s_waitcnt lgkmcnt(12)
	v_mul_f32_e32 v12, 0xbfb8aa3b, v12
	v_rcp_f32_e32 v48, v48
	v_pk_add_f32 v[32:33], v[32:33], 1.0 op_sel_hi:[1,0]
	v_mul_f32_e32 v13, 0xbfb8aa3b, v13
	v_exp_f32_e32 v12, v12
	v_exp_f32_e32 v13, v13
	s_waitcnt vmcnt(0) lgkmcnt(3)
	v_pk_fma_f32 v[8:9], v[48:49], v[8:9], v[40:41]
	v_mul_f32_e32 v48, 0xbfb8aa3b, v50
	v_mul_f32_e32 v49, 0xbfb8aa3b, v51
	v_exp_f32_e32 v48, v48
	v_exp_f32_e32 v49, v49
	v_pk_add_f32 v[12:13], v[12:13], 1.0 op_sel_hi:[1,0]
	v_pk_mul_f32 v[40:41], v[8:9], v[8:9]
	v_pk_add_f32 v[48:49], v[48:49], 1.0 op_sel_hi:[1,0]
	s_nop 0
	s_nop 0
	v_rcp_f32_e32 v49, v49
	s_nop 0
	v_rcp_f32_e32 v48, v48
	s_nop 0
	v_pk_fma_f32 v[10:11], v[48:49], v[10:11], v[42:43]
	v_pk_mul_f32 v[42:43], v[10:11], v[10:11]
	v_rcp_f32_e32 v37, v37
	s_nop 0
	v_rcp_f32_e32 v36, v36
	s_waitcnt lgkmcnt(2)
	v_pk_fma_f32 v[24:25], v[36:37], v[24:25], v[28:29]
	v_mul_f32_e32 v36, 0xbfb8aa3b, v38
	v_mul_f32_e32 v37, 0xbfb8aa3b, v39
	v_exp_f32_e32 v36, v36
	v_exp_f32_e32 v37, v37
	v_pk_mul_f32 v[28:29], v[24:25], v[24:25]
	v_pk_add_f32 v[36:37], v[36:37], 1.0 op_sel_hi:[1,0]
	s_nop 0
	s_nop 0
	v_rcp_f32_e32 v37, v37
	s_nop 0
	v_rcp_f32_e32 v36, v36
	s_nop 0
	v_pk_fma_f32 v[26:27], v[36:37], v[26:27], v[30:31]
	v_pk_mul_f32 v[30:31], v[26:27], v[26:27]
	v_rcp_f32_e32 v33, v33
	s_nop 0
	v_rcp_f32_e32 v32, v32
	s_waitcnt lgkmcnt(1)
	v_pk_fma_f32 v[16:17], v[32:33], v[16:17], v[20:21]
	v_mul_f32_e32 v32, 0xbfb8aa3b, v34
	v_mul_f32_e32 v33, 0xbfb8aa3b, v35
	v_exp_f32_e32 v32, v32
	v_exp_f32_e32 v33, v33
	v_pk_mul_f32 v[20:21], v[16:17], v[16:17]
	v_pk_add_f32 v[32:33], v[32:33], 1.0 op_sel_hi:[1,0]
	s_nop 0
	s_nop 0
	v_rcp_f32_e32 v33, v33
	s_nop 0
	v_rcp_f32_e32 v32, v32
	s_nop 0
	v_pk_fma_f32 v[18:19], v[32:33], v[18:19], v[22:23]
	v_pk_mul_f32 v[22:23], v[18:19], v[18:19]
	v_rcp_f32_e32 v13, v13
	s_nop 0
	v_rcp_f32_e32 v12, v12
	s_waitcnt lgkmcnt(0)
	v_pk_fma_f32 v[0:1], v[12:13], v[0:1], v[4:5]
	v_mul_f32_e32 v12, 0xbfb8aa3b, v14
	v_mul_f32_e32 v13, 0xbfb8aa3b, v15
	v_exp_f32_e32 v12, v12
	v_exp_f32_e32 v13, v13
	v_pk_mul_f32 v[4:5], v[0:1], v[0:1]
	v_pk_add_f32 v[12:13], v[12:13], 1.0 op_sel_hi:[1,0]
	s_nop 0
	s_nop 0
	v_rcp_f32_e32 v13, v13
	v_div_scale_f32 v14, s[0:1], v12, v12, 1.0
	v_rcp_f32_e32 v15, v14
	s_nop 0
	v_fma_f32 v32, -v14, v15, 1.0
	v_fmac_f32_e32 v15, v32, v15
	v_div_scale_f32 v32, vcc, 1.0, v12, 1.0
	v_mul_f32_e32 v33, v32, v15
	v_fma_f32 v34, -v14, v33, v32
	v_fmac_f32_e32 v33, v34, v15
	v_fma_f32 v14, -v14, v33, v32
	v_div_fmas_f32 v14, v14, v15, v33
	v_div_fixup_f32 v12, v14, v12, 1.0
	v_pk_fma_f32 v[2:3], v[12:13], v[2:3], v[6:7]
	v_add_f32_e32 v12, v40, v41
	v_add_f32_e32 v12, v42, v12
	v_add_f32_e32 v12, v43, v12
	v_add_f32_e32 v12, v28, v12
	v_add_f32_e32 v12, v29, v12
	v_add_f32_e32 v12, v30, v12
	v_add_f32_e32 v12, v31, v12
	v_add_f32_e32 v12, v20, v12
	v_add_f32_e32 v12, v21, v12
	v_add_f32_e32 v12, v22, v12
	v_add_f32_e32 v12, v23, v12
	v_add_f32_e32 v4, v4, v12
	v_pk_mul_f32 v[6:7], v[2:3], v[2:3]
	v_add_f32_e32 v4, v5, v4
	v_add_f32_e32 v4, v6, v4
	v_bfe_u32 v5, v9, 16, 1
	v_add_f32_e32 v14, v7, v4
	global_store_dwordx4 v[46:47], v[8:11], off
	global_store_dwordx4 v[46:47], v[24:27], off offset:16
	global_store_dwordx4 v[46:47], v[16:19], off offset:32
	global_store_dwordx4 v[46:47], v[0:3], off offset:48
	s_nop 4
	v_add3_u32 v5, v9, v5, s24
	v_bfe_u32 v15, v8, 16, 1
	v_add3_u32 v8, v8, v15, s24
	v_lshrrev_b32_e32 v8, 16, v8
	v_cvt_pk_bf16_f32 v7, v26, v27
	v_cvt_pk_bf16_f32 v6, v24, v25
	v_and_or_b32 v4, v5, s25, v8
	v_cvt_pk_bf16_f32 v5, v10, v11
	v_bfe_u32 v10, v3, 16, 1
	v_add3_u32 v3, v3, v10, s24
	v_bfe_u32 v10, v2, 16, 1
	v_add3_u32 v2, v2, v10, s24
	v_mad_i64_i32 v[12:13], s[0:1], v44, s4, v[134:135]
	v_lshrrev_b32_e32 v10, 16, v2
	v_cvt_pk_bf16_f32 v2, v0, v1
	v_cvt_pk_bf16_f32 v0, v16, v17
	v_and_or_b32 v3, v3, s25, v10
	v_cvt_pk_bf16_f32 v1, v18, v19
	global_store_dwordx4 v[12:13], v[4:7], off
	global_store_dwordx4 v[12:13], v[0:3], off offset:16
	ds_bpermute_b32 v0, v119, v14
	s_waitcnt lgkmcnt(0)
	v_add_f32_e32 v0, v14, v0
	ds_bpermute_b32 v1, v118, v0
	s_and_saveexec_b64 s[0:1], s[8:9]
	s_cbranch_execz .LBB0_1027
	s_waitcnt lgkmcnt(0)
	v_add_f32_e32 v2, v0, v1
	v_lshl_add_u64 v[0:1], v[44:45], 2, s[18:19]
	global_atomic_add_f32 v[0:1], v2, off
	s_branch .LBB0_1027

; DI unsigned pack2(float a, float b) { return (unsigned)f2bf(a) | ((unsigned)f2bf(b) << 16); }
; DI void convert_p(const Params& p, int layer) {
;     ...
;   const long gsz = (long)gridDim.x * NTHR, gid = (long)blockIdx.x * NTHR + tix_;
;   const float* pp = p.p_prompt + (size_t)layer * TP * 256; const float* ps = p.p_sample + (size_t)layer * (T - TP) * 256;
;   for (long i = gid; i < (long)T * 256 / 4; i += gsz) { long e = i * 4; f32x4 v = e < (long)TP * 256 ? *(const f32x4*)(pp + e) : *(const f32x4*)(ps + (e - (long)TP * 256));
;     u32x2 w = {pack2(v[0], v[1]), pack2(v[2], v[3])}; *(u32x2*)(pb + e) = w; }
; }
.LBB0_1108:
	v_lshl_add_u64 v[6:7], s[8:9], 0, v[2:3]
	v_lshl_add_u64 v[8:9], s[10:11], 0, v[2:3]
	v_cmp_gt_i64_e32 vcc, s[20:21], v[0:1]
	v_lshl_add_u64 v[0:1], v[0:1], 0, s[6:7]
	v_lshl_add_u64 v[2:3], v[2:3], 0, s[14:15]
	v_cndmask_b32_e32 v7, v9, v7, vcc
	v_cndmask_b32_e32 v6, v8, v6, vcc
	global_load_dwordx4 v[6:9], v[6:7], off
	v_cmp_lt_i64_e32 vcc, s[22:23], v[0:1]
	s_or_b64 s[18:19], vcc, s[18:19]
	s_waitcnt vmcnt(0)
	v_cvt_pk_bf16_f32 v6, v6, v7
	v_cvt_pk_bf16_f32 v7, v8, v9
	global_store_dwordx2 v[4:5], v[6:7], off
	v_lshl_add_u64 v[4:5], v[4:5], 0, s[16:17]
	s_andn2_b64 exec, exec, s[18:19]
	s_cbranch_execnz .LBB0_1108

; DI unsigned pack2(float a, float b) { return (unsigned)f2bf(a) | ((unsigned)f2bf(b) << 16); }
; DI float siluf(float x) { return x * sigm(x); }
; DI void store16_bf(bft* dst, const float (&v)[16]) {
;   u32x4 o0 = {pack2(v[0], v[1]), pack2(v[2], v[3]), pack2(v[4], v[5]), pack2(v[6], v[7])}, o1 = {pack2(v[8], v[9]), pack2(v[10], v[11]), pack2(v[12], v[13]), pack2(v[14], v[15])};
;   *(u32x4*)dst = o0; *(u32x4*)(dst + 8) = o1;
; }
; DI void phase_inproj1(const Params& p, int ch) {
;     ...
;     EPI256_BEGIN
;       float rs = rsqrtf(ssq1[row] * (1.f / 1024) + EPS);
; #pragma unroll
;       for (int i = 0; i < 16; ++i) { v[i] *= rs; if (isgate) v[i] = siluf(v[i]); }
;       store16_bf(Z + (size_t)row * 1024 + col, v);
.LBB0_1128:
	v_cvt_pk_bf16_f32 v13, v12, v13
	v_cvt_pk_bf16_f32 v12, v10, v11
	v_cvt_pk_bf16_f32 v11, v15, v16
	v_cvt_pk_bf16_f32 v10, v0, v14
	v_bfe_u32 v0, v5, 16, 1
	v_add3_u32 v0, v5, v0, s27
	v_bfe_u32 v16, v4, 16, 1
	v_lshlrev_b64 v[18:19], 11, v[18:19]
	v_add3_u32 v4, v4, v16, s27
	v_lshl_add_u64 v[18:19], v[116:117], 0, v[18:19]
	v_lshrrev_b32_e32 v4, 16, v4
	s_add_i32 s12, s12, 1
	s_add_i32 s13, s13, 1
	s_mov_b64 s[0:1], 0
	v_and_or_b32 v5, v0, s71, v4
	v_cvt_pk_bf16_f32 v4, v2, v3
	v_cvt_pk_bf16_f32 v3, v8, v9
	v_cvt_pk_bf16_f32 v2, v6, v7
	global_store_dwordx4 v[18:19], v[10:13], off
	global_store_dwordx4 v[18:19], v[2:5], off offset:16

; DI unsigned pack2(float a, float b) { return (unsigned)f2bf(a) | ((unsigned)f2bf(b) << 16); }
; DI float siluf(float x) { return x * sigm(x); }
;   const int lane = tid & 63, wid = tid >> 6, fr = lane & 15, fq = lane >> 4;
;   float* stg = (float*)(smem + PATCH) + wid * (16 * 68);
;   asm volatile("" ::: "memory");
; #pragma unroll
;   for (int n = 0; n < 4; ++n)
; #pragma unroll
;     for (int j = 0; j < 4; ++j) stg[(fq * 4 + j) * 68 + n * 16 + fr] = am[n][j];
;   asm volatile("s_waitcnt lgkmcnt(0)" ::: "memory");
;   const float* rp = stg + (lane >> 2) * 68 + (lane & 3) * 16;
; #pragma unroll
;   for (int i = 0; i < 4; ++i) { f32x4 t = *(const f32x4*)(rp + i * 4); v[4 * i] = t[0]; v[4 * i + 1] = t[1]; v[4 * i + 2] = t[2]; v[4 * i + 3] = t[3]; }
;   asm volatile("" ::: "memory");
; }
; DI void store16_bf(bft* dst, const float (&v)[16]) {
;   u32x4 o0 = {pack2(v[0], v[1]), pack2(v[2], v[3]), pack2(v[4], v[5]), pack2(v[6], v[7])}, o1 = {pack2(v[8], v[9]), pack2(v[10], v[11]), pack2(v[12], v[13]), pack2(v[14], v[15])};
;   *(u32x4*)dst = o0; *(u32x4*)(dst + 8) = o1;
; }
; DI void phase_inproj1(const Params& p, int ch) {
;     ...
;     EPI256_BEGIN
;       float rs = rsqrtf(ssq1[row] * (1.f / 1024) + EPS);
; #pragma unroll
;       for (int i = 0; i < 16; ++i) { v[i] *= rs; if (isgate) v[i] = siluf(v[i]); }
;       store16_bf(Z + (size_t)row * 1024 + col, v);
.LBB0_1159:
	v_and_b32_e32 v116, 0xc0, v157
	v_or3_b32 v0, v116, s14, v0
	v_lshlrev_b32_e32 v0, 1, v0
	v_lshl_add_u64 v[116:117], s[76:77], 0, v[0:1]
	v_lshlrev_b64 v[136:137], 11, v[132:133]
	v_bfe_u32 v0, v127, 16, 1
	v_add3_u32 v0, v127, v0, s27
	v_bfe_u32 v139, v126, 16, 1
	v_add3_u32 v126, v126, v139, s27
	v_lshrrev_b32_e32 v126, 16, v126
	v_and_or_b32 v127, v0, s71, v126
	v_cvt_pk_bf16_f32 v126, v124, v125
	v_cvt_pk_bf16_f32 v125, v128, v129
	v_cvt_pk_bf16_f32 v124, v2, v3
	v_bfe_u32 v0, v119, 16, 1
	v_bfe_u32 v3, v123, 16, 1
	v_bfe_u32 v128, v121, 16, 1
	v_add3_u32 v128, v121, v128, s27
	v_add3_u32 v3, v123, v3, s27
	v_add3_u32 v0, v119, v0, s27
	v_bfe_u32 v119, v120, 16, 1
	v_bfe_u32 v121, v122, 16, 1
	v_bfe_u32 v129, v118, 16, 1
	v_add3_u32 v118, v118, v129, s27
	v_add3_u32 v121, v122, v121, s27
	v_add3_u32 v119, v120, v119, s27
	v_lshl_add_u64 v[136:137], v[116:117], 0, v[136:137]
	v_lshrrev_b32_e32 v122, 16, v119
	v_lshrrev_b32_e32 v119, 16, v121
	v_lshrrev_b32_e32 v118, 16, v118
	v_and_or_b32 v121, v0, s71, v118
	v_cvt_pk_bf16_f32 v120, v130, v131
	v_and_or_b32 v119, v3, s71, v119
	v_and_or_b32 v118, v128, s71, v122
	global_store_dwordx4 v[136:137], v[124:127], off
	global_store_dwordx4 v[136:137], v[118:121], off offset:16
	ds_write2_b32 v134, v112, v108 offset1:16
	ds_write2_b32 v134, v113, v109 offset0:68 offset1:84
	ds_write2_b32 v134, v114, v110 offset0:136 offset1:152
	ds_write2_b32 v134, v115, v111 offset0:204 offset1:220
	ds_write2_b32 v134, v104, v100 offset0:32 offset1:48
	ds_write2_b32 v134, v105, v101 offset0:100 offset1:116
	ds_write2_b32 v134, v106, v102 offset0:168 offset1:184
	ds_write2_b32 v134, v107, v103 offset0:236 offset1:252
	v_or_b32_e32 v2, 16, v132
	s_waitcnt lgkmcnt(0)
	v_ashrrev_i32_e32 v3, 31, v2
	ds_read_b128 v[112:115], v135
	ds_read_b128 v[108:111], v135 offset:16
	ds_read_b128 v[104:107], v135 offset:32
	ds_read_b128 v[100:103], v135 offset:48
	v_lshl_add_u64 v[118:119], v[2:3], 2, s[78:79]
	global_load_dword v0, v[118:119], off
	s_waitcnt vmcnt(0)
	v_fmamk_f32 v0, v0, 0x3a800000, v148
	v_mul_f32_e32 v118, 0x4b800000, v0
	v_cmp_gt_f32_e32 vcc, s86, v0
	s_nop 1
	v_cndmask_b32_e32 v0, v0, v118, vcc
	v_rsq_f32_e32 v0, v0
	s_nop 0
	v_mul_f32_e32 v118, 0x45800000, v0
	v_cndmask_b32_e32 v118, v0, v118, vcc
	s_and_b64 vcc, exec, s[8:9]
	s_waitcnt lgkmcnt(3)
	v_mul_f32_e32 v0, v112, v118
	s_cbranch_vccz .LBB0_1291
	s_and_b64 vcc, exec, s[8:9]
	v_mul_f32_e32 v112, v113, v118
	s_cbranch_vccz .LBB0_1292

; DI unsigned pack2(float a, float b) { return (unsigned)f2bf(a) | ((unsigned)f2bf(b) << 16); }
; DI float siluf(float x) { return x * sigm(x); }
;   const int lane = tid & 63, wid = tid >> 6, fr = lane & 15, fq = lane >> 4;
;   float* stg = (float*)(smem + PATCH) + wid * (16 * 68);
;   asm volatile("" ::: "memory");
; #pragma unroll
;   for (int n = 0; n < 4; ++n)
; #pragma unroll
;     for (int j = 0; j < 4; ++j) stg[(fq * 4 + j) * 68 + n * 16 + fr] = am[n][j];
;   asm volatile("s_waitcnt lgkmcnt(0)" ::: "memory");
;   const float* rp = stg + (lane >> 2) * 68 + (lane & 3) * 16;
; #pragma unroll
;   for (int i = 0; i < 4; ++i) { f32x4 t = *(const f32x4*)(rp + i * 4); v[4 * i] = t[0]; v[4 * i + 1] = t[1]; v[4 * i + 2] = t[2]; v[4 * i + 3] = t[3]; }
;   asm volatile("" ::: "memory");
; }
; DI void store16_bf(bft* dst, const float (&v)[16]) {
;   u32x4 o0 = {pack2(v[0], v[1]), pack2(v[2], v[3]), pack2(v[4], v[5]), pack2(v[6], v[7])}, o1 = {pack2(v[8], v[9]), pack2(v[10], v[11]), pack2(v[12], v[13]), pack2(v[14], v[15])};
;   *(u32x4*)dst = o0; *(u32x4*)(dst + 8) = o1;
; }
; DI void phase_inproj1(const Params& p, int ch) {
;     ...
;     EPI256_BEGIN
;       float rs = rsqrtf(ssq1[row] * (1.f / 1024) + EPS);
; #pragma unroll
;       for (int i = 0; i < 16; ++i) { v[i] *= rs; if (isgate) v[i] = siluf(v[i]); }
;       store16_bf(Z + (size_t)row * 1024 + col, v);
.LBB0_1176:
	v_cvt_pk_bf16_f32 v111, v110, v111
	v_cvt_pk_bf16_f32 v110, v108, v109
	v_cvt_pk_bf16_f32 v109, v113, v114
	v_cvt_pk_bf16_f32 v108, v0, v112
	v_bfe_u32 v0, v103, 16, 1
	v_add3_u32 v0, v103, v0, s27
	v_bfe_u32 v114, v102, 16, 1
	v_lshlrev_b64 v[2:3], 11, v[2:3]
	v_add3_u32 v102, v102, v114, s27
	v_lshl_add_u64 v[2:3], v[116:117], 0, v[2:3]
	v_lshrrev_b32_e32 v102, 16, v102
	v_and_or_b32 v103, v0, s71, v102
	v_cvt_pk_bf16_f32 v102, v100, v101
	v_cvt_pk_bf16_f32 v101, v106, v107
	v_cvt_pk_bf16_f32 v100, v104, v105
	global_store_dwordx4 v[2:3], v[108:111], off
	global_store_dwordx4 v[2:3], v[100:103], off offset:16
	ds_write2_b32 v134, v96, v92 offset1:16
	ds_write2_b32 v134, v97, v93 offset0:68 offset1:84
	ds_write2_b32 v134, v98, v94 offset0:136 offset1:152
	ds_write2_b32 v134, v99, v95 offset0:204 offset1:220
	ds_write2_b32 v134, v88, v84 offset0:32 offset1:48
	ds_write2_b32 v134, v89, v85 offset0:100 offset1:116
	ds_write2_b32 v134, v90, v86 offset0:168 offset1:184
	ds_write2_b32 v134, v91, v87 offset0:236 offset1:252
	v_or_b32_e32 v2, 32, v132
	s_waitcnt lgkmcnt(0)
	v_ashrrev_i32_e32 v3, 31, v2
	ds_read_b128 v[96:99], v135
	ds_read_b128 v[92:95], v135 offset:16
	ds_read_b128 v[88:91], v135 offset:32
	ds_read_b128 v[84:87], v135 offset:48
	v_lshl_add_u64 v[100:101], v[2:3], 2, s[78:79]
	global_load_dword v0, v[100:101], off
	s_waitcnt vmcnt(0)
	v_fmamk_f32 v0, v0, 0x3a800000, v148
	v_mul_f32_e32 v100, 0x4b800000, v0
	v_cmp_gt_f32_e32 vcc, s86, v0
	s_nop 1
	v_cndmask_b32_e32 v0, v0, v100, vcc
	v_rsq_f32_e32 v0, v0
	s_nop 0
	v_mul_f32_e32 v100, 0x45800000, v0
	v_cndmask_b32_e32 v100, v0, v100, vcc
	s_and_b64 vcc, exec, s[8:9]
	s_waitcnt lgkmcnt(3)
	v_mul_f32_e32 v0, v96, v100
	s_cbranch_vccz .LBB0_1306
	s_and_b64 vcc, exec, s[8:9]
	v_mul_f32_e32 v96, v97, v100
	s_cbranch_vccz .LBB0_1307

; DI unsigned pack2(float a, float b) { return (unsigned)f2bf(a) | ((unsigned)f2bf(b) << 16); }
; DI float siluf(float x) { return x * sigm(x); }
;   const int lane = tid & 63, wid = tid >> 6, fr = lane & 15, fq = lane >> 4;
;   float* stg = (float*)(smem + PATCH) + wid * (16 * 68);
;   asm volatile("" ::: "memory");
; #pragma unroll
;   for (int n = 0; n < 4; ++n)
; #pragma unroll
;     for (int j = 0; j < 4; ++j) stg[(fq * 4 + j) * 68 + n * 16 + fr] = am[n][j];
;   asm volatile("s_waitcnt lgkmcnt(0)" ::: "memory");
;   const float* rp = stg + (lane >> 2) * 68 + (lane & 3) * 16;
; #pragma unroll
;   for (int i = 0; i < 4; ++i) { f32x4 t = *(const f32x4*)(rp + i * 4); v[4 * i] = t[0]; v[4 * i + 1] = t[1]; v[4 * i + 2] = t[2]; v[4 * i + 3] = t[3]; }
;   asm volatile("" ::: "memory");
; }
; DI void store16_bf(bft* dst, const float (&v)[16]) {
;   u32x4 o0 = {pack2(v[0], v[1]), pack2(v[2], v[3]), pack2(v[4], v[5]), pack2(v[6], v[7])}, o1 = {pack2(v[8], v[9]), pack2(v[10], v[11]), pack2(v[12], v[13]), pack2(v[14], v[15])};
;   *(u32x4*)dst = o0; *(u32x4*)(dst + 8) = o1;
; }
; DI void phase_inproj1(const Params& p, int ch) {
;     ...
;     EPI256_BEGIN
;       float rs = rsqrtf(ssq1[row] * (1.f / 1024) + EPS);
; #pragma unroll
;       for (int i = 0; i < 16; ++i) { v[i] *= rs; if (isgate) v[i] = siluf(v[i]); }
;       store16_bf(Z + (size_t)row * 1024 + col, v);
.LBB0_1193:
	v_cvt_pk_bf16_f32 v95, v94, v95
	v_cvt_pk_bf16_f32 v94, v92, v93
	v_cvt_pk_bf16_f32 v93, v97, v98
	v_cvt_pk_bf16_f32 v92, v0, v96
	v_bfe_u32 v0, v87, 16, 1
	v_add3_u32 v0, v87, v0, s27
	v_bfe_u32 v98, v86, 16, 1
	v_lshlrev_b64 v[2:3], 11, v[2:3]
	v_add3_u32 v86, v86, v98, s27
	v_lshl_add_u64 v[2:3], v[116:117], 0, v[2:3]
	v_lshrrev_b32_e32 v86, 16, v86
	v_and_or_b32 v87, v0, s71, v86
	v_cvt_pk_bf16_f32 v86, v84, v85
	v_cvt_pk_bf16_f32 v85, v90, v91
	v_cvt_pk_bf16_f32 v84, v88, v89
	global_store_dwordx4 v[2:3], v[92:95], off
	global_store_dwordx4 v[2:3], v[84:87], off offset:16
	ds_write2_b32 v134, v80, v76 offset1:16
	ds_write2_b32 v134, v81, v77 offset0:68 offset1:84
	ds_write2_b32 v134, v82, v78 offset0:136 offset1:152
	ds_write2_b32 v134, v83, v79 offset0:204 offset1:220
	ds_write2_b32 v134, v72, v68 offset0:32 offset1:48
	ds_write2_b32 v134, v73, v69 offset0:100 offset1:116
	ds_write2_b32 v134, v74, v70 offset0:168 offset1:184
	ds_write2_b32 v134, v75, v71 offset0:236 offset1:252
	v_or_b32_e32 v2, 48, v132
	s_waitcnt lgkmcnt(0)
	v_ashrrev_i32_e32 v3, 31, v2
	ds_read_b128 v[80:83], v135
	ds_read_b128 v[76:79], v135 offset:16
	ds_read_b128 v[72:75], v135 offset:32
	ds_read_b128 v[68:71], v135 offset:48
	v_lshl_add_u64 v[84:85], v[2:3], 2, s[78:79]
	global_load_dword v0, v[84:85], off
	s_waitcnt vmcnt(0)
	v_fmamk_f32 v0, v0, 0x3a800000, v148
	v_mul_f32_e32 v84, 0x4b800000, v0
	v_cmp_gt_f32_e32 vcc, s86, v0
	s_nop 1
	v_cndmask_b32_e32 v0, v0, v84, vcc
	v_rsq_f32_e32 v0, v0
	s_nop 0
	v_mul_f32_e32 v84, 0x45800000, v0
	v_cndmask_b32_e32 v84, v0, v84, vcc
	s_and_b64 vcc, exec, s[8:9]
	s_waitcnt lgkmcnt(3)
	v_mul_f32_e32 v0, v80, v84
	s_cbranch_vccz .LBB0_1321
	s_and_b64 vcc, exec, s[8:9]
	v_mul_f32_e32 v80, v81, v84
	s_cbranch_vccz .LBB0_1322

; DI unsigned pack2(float a, float b) { return (unsigned)f2bf(a) | ((unsigned)f2bf(b) << 16); }
; DI float siluf(float x) { return x * sigm(x); }
;   const int lane = tid & 63, wid = tid >> 6, fr = lane & 15, fq = lane >> 4;
;   float* stg = (float*)(smem + PATCH) + wid * (16 * 68);
;   asm volatile("" ::: "memory");
; #pragma unroll
;   for (int n = 0; n < 4; ++n)
; #pragma unroll
;     for (int j = 0; j < 4; ++j) stg[(fq * 4 + j) * 68 + n * 16 + fr] = am[n][j];
;   asm volatile("s_waitcnt lgkmcnt(0)" ::: "memory");
;   const float* rp = stg + (lane >> 2) * 68 + (lane & 3) * 16;
; #pragma unroll
;   for (int i = 0; i < 4; ++i) { f32x4 t = *(const f32x4*)(rp + i * 4); v[4 * i] = t[0]; v[4 * i + 1] = t[1]; v[4 * i + 2] = t[2]; v[4 * i + 3] = t[3]; }
;   asm volatile("" ::: "memory");
; }
; DI void store16_bf(bft* dst, const float (&v)[16]) {
;   u32x4 o0 = {pack2(v[0], v[1]), pack2(v[2], v[3]), pack2(v[4], v[5]), pack2(v[6], v[7])}, o1 = {pack2(v[8], v[9]), pack2(v[10], v[11]), pack2(v[12], v[13]), pack2(v[14], v[15])};
;   *(u32x4*)dst = o0; *(u32x4*)(dst + 8) = o1;
; }
; DI void phase_inproj1(const Params& p, int ch) {
;     ...
;     EPI256_BEGIN
;       float rs = rsqrtf(ssq1[row] * (1.f / 1024) + EPS);
; #pragma unroll
;       for (int i = 0; i < 16; ++i) { v[i] *= rs; if (isgate) v[i] = siluf(v[i]); }
;       store16_bf(Z + (size_t)row * 1024 + col, v);
.LBB0_1210:
	v_cvt_pk_bf16_f32 v79, v78, v79
	v_cvt_pk_bf16_f32 v78, v76, v77
	v_cvt_pk_bf16_f32 v77, v81, v82
	v_cvt_pk_bf16_f32 v76, v0, v80
	v_bfe_u32 v0, v71, 16, 1
	v_add3_u32 v0, v71, v0, s27
	v_bfe_u32 v82, v70, 16, 1
	v_lshlrev_b64 v[2:3], 11, v[2:3]
	v_add3_u32 v70, v70, v82, s27
	v_lshl_add_u64 v[2:3], v[116:117], 0, v[2:3]
	v_lshrrev_b32_e32 v70, 16, v70
	v_and_or_b32 v71, v0, s71, v70
	v_cvt_pk_bf16_f32 v70, v68, v69
	v_cvt_pk_bf16_f32 v69, v74, v75
	v_cvt_pk_bf16_f32 v68, v72, v73
	global_store_dwordx4 v[2:3], v[76:79], off
	global_store_dwordx4 v[2:3], v[68:71], off offset:16
	ds_write2_b32 v134, v64, v60 offset1:16
	ds_write2_b32 v134, v65, v61 offset0:68 offset1:84
	ds_write2_b32 v134, v66, v62 offset0:136 offset1:152
	ds_write2_b32 v134, v67, v63 offset0:204 offset1:220
	ds_write2_b32 v134, v56, v52 offset0:32 offset1:48
	ds_write2_b32 v134, v57, v53 offset0:100 offset1:116
	ds_write2_b32 v134, v58, v54 offset0:168 offset1:184
	ds_write2_b32 v134, v59, v55 offset0:236 offset1:252
	v_or_b32_e32 v2, 64, v132
	s_waitcnt lgkmcnt(0)
	v_ashrrev_i32_e32 v3, 31, v2
	ds_read_b128 v[64:67], v135
	ds_read_b128 v[60:63], v135 offset:16
	ds_read_b128 v[56:59], v135 offset:32
	ds_read_b128 v[52:55], v135 offset:48
	v_lshl_add_u64 v[68:69], v[2:3], 2, s[78:79]
	global_load_dword v0, v[68:69], off
	s_waitcnt vmcnt(0)
	v_fmamk_f32 v0, v0, 0x3a800000, v148
	v_mul_f32_e32 v68, 0x4b800000, v0
	v_cmp_gt_f32_e32 vcc, s86, v0
	s_nop 1
	v_cndmask_b32_e32 v0, v0, v68, vcc
	v_rsq_f32_e32 v0, v0
	s_nop 0
	v_mul_f32_e32 v68, 0x45800000, v0
	v_cndmask_b32_e32 v68, v0, v68, vcc
	s_and_b64 vcc, exec, s[8:9]
	s_waitcnt lgkmcnt(3)
	v_mul_f32_e32 v0, v64, v68
	s_cbranch_vccz .LBB0_1336
	s_and_b64 vcc, exec, s[8:9]
	v_mul_f32_e32 v64, v65, v68
	s_cbranch_vccz .LBB0_1337

; DI unsigned pack2(float a, float b) { return (unsigned)f2bf(a) | ((unsigned)f2bf(b) << 16); }
; DI float siluf(float x) { return x * sigm(x); }
;   const int lane = tid & 63, wid = tid >> 6, fr = lane & 15, fq = lane >> 4;
;   float* stg = (float*)(smem + PATCH) + wid * (16 * 68);
;   asm volatile("" ::: "memory");
; #pragma unroll
;   for (int n = 0; n < 4; ++n)
; #pragma unroll
;     for (int j = 0; j < 4; ++j) stg[(fq * 4 + j) * 68 + n * 16 + fr] = am[n][j];
;   asm volatile("s_waitcnt lgkmcnt(0)" ::: "memory");
;   const float* rp = stg + (lane >> 2) * 68 + (lane & 3) * 16;
; #pragma unroll
;   for (int i = 0; i < 4; ++i) { f32x4 t = *(const f32x4*)(rp + i * 4); v[4 * i] = t[0]; v[4 * i + 1] = t[1]; v[4 * i + 2] = t[2]; v[4 * i + 3] = t[3]; }
;   asm volatile("" ::: "memory");
; }
; DI void store16_bf(bft* dst, const float (&v)[16]) {
;   u32x4 o0 = {pack2(v[0], v[1]), pack2(v[2], v[3]), pack2(v[4], v[5]), pack2(v[6], v[7])}, o1 = {pack2(v[8], v[9]), pack2(v[10], v[11]), pack2(v[12], v[13]), pack2(v[14], v[15])};
;   *(u32x4*)dst = o0; *(u32x4*)(dst + 8) = o1;
; }
; DI void phase_inproj1(const Params& p, int ch) {
;     ...
;     EPI256_BEGIN
;       float rs = rsqrtf(ssq1[row] * (1.f / 1024) + EPS);
; #pragma unroll
;       for (int i = 0; i < 16; ++i) { v[i] *= rs; if (isgate) v[i] = siluf(v[i]); }
;       store16_bf(Z + (size_t)row * 1024 + col, v);
.LBB0_1227:
	v_cvt_pk_bf16_f32 v63, v62, v63
	v_cvt_pk_bf16_f32 v62, v60, v61
	v_cvt_pk_bf16_f32 v61, v65, v66
	v_cvt_pk_bf16_f32 v60, v0, v64
	v_bfe_u32 v0, v55, 16, 1
	v_add3_u32 v0, v55, v0, s27
	v_bfe_u32 v66, v54, 16, 1
	v_lshlrev_b64 v[2:3], 11, v[2:3]
	v_add3_u32 v54, v54, v66, s27
	v_lshl_add_u64 v[2:3], v[116:117], 0, v[2:3]
	v_lshrrev_b32_e32 v54, 16, v54
	v_and_or_b32 v55, v0, s71, v54
	v_cvt_pk_bf16_f32 v54, v52, v53
	v_cvt_pk_bf16_f32 v53, v58, v59
	v_cvt_pk_bf16_f32 v52, v56, v57
	global_store_dwordx4 v[2:3], v[60:63], off
	global_store_dwordx4 v[2:3], v[52:55], off offset:16
	ds_write2_b32 v134, v48, v44 offset1:16
	ds_write2_b32 v134, v49, v45 offset0:68 offset1:84
	ds_write2_b32 v134, v50, v46 offset0:136 offset1:152
	ds_write2_b32 v134, v51, v47 offset0:204 offset1:220
	ds_write2_b32 v134, v40, v36 offset0:32 offset1:48
	ds_write2_b32 v134, v41, v37 offset0:100 offset1:116
	ds_write2_b32 v134, v42, v38 offset0:168 offset1:184
	ds_write2_b32 v134, v43, v39 offset0:236 offset1:252
	v_or_b32_e32 v2, 0x50, v132
	s_waitcnt lgkmcnt(0)
	v_ashrrev_i32_e32 v3, 31, v2
	ds_read_b128 v[48:51], v135
	ds_read_b128 v[44:47], v135 offset:16
	ds_read_b128 v[40:43], v135 offset:32
	ds_read_b128 v[36:39], v135 offset:48
	v_lshl_add_u64 v[52:53], v[2:3], 2, s[78:79]
	global_load_dword v0, v[52:53], off
	s_waitcnt vmcnt(0)
	v_fmamk_f32 v0, v0, 0x3a800000, v148
	v_mul_f32_e32 v52, 0x4b800000, v0
	v_cmp_gt_f32_e32 vcc, s86, v0
	s_nop 1
	v_cndmask_b32_e32 v0, v0, v52, vcc
	v_rsq_f32_e32 v0, v0
	s_nop 0
	v_mul_f32_e32 v52, 0x45800000, v0
	v_cndmask_b32_e32 v52, v0, v52, vcc
	s_and_b64 vcc, exec, s[8:9]
	s_waitcnt lgkmcnt(3)
	v_mul_f32_e32 v0, v48, v52
	s_cbranch_vccz .LBB0_1351
	s_and_b64 vcc, exec, s[8:9]
	v_mul_f32_e32 v48, v49, v52
	s_cbranch_vccz .LBB0_1352

; DI unsigned pack2(float a, float b) { return (unsigned)f2bf(a) | ((unsigned)f2bf(b) << 16); }
; DI float siluf(float x) { return x * sigm(x); }
;   const int lane = tid & 63, wid = tid >> 6, fr = lane & 15, fq = lane >> 4;
;   float* stg = (float*)(smem + PATCH) + wid * (16 * 68);
;   asm volatile("" ::: "memory");
; #pragma unroll
;   for (int n = 0; n < 4; ++n)
; #pragma unroll
;     for (int j = 0; j < 4; ++j) stg[(fq * 4 + j) * 68 + n * 16 + fr] = am[n][j];
;   asm volatile("s_waitcnt lgkmcnt(0)" ::: "memory");
;   const float* rp = stg + (lane >> 2) * 68 + (lane & 3) * 16;
; #pragma unroll
;   for (int i = 0; i < 4; ++i) { f32x4 t = *(const f32x4*)(rp + i * 4); v[4 * i] = t[0]; v[4 * i + 1] = t[1]; v[4 * i + 2] = t[2]; v[4 * i + 3] = t[3]; }
;   asm volatile("" ::: "memory");
; }
; DI void store16_bf(bft* dst, const float (&v)[16]) {
;   u32x4 o0 = {pack2(v[0], v[1]), pack2(v[2], v[3]), pack2(v[4], v[5]), pack2(v[6], v[7])}, o1 = {pack2(v[8], v[9]), pack2(v[10], v[11]), pack2(v[12], v[13]), pack2(v[14], v[15])};
;   *(u32x4*)dst = o0; *(u32x4*)(dst + 8) = o1;
; }
; DI void phase_inproj1(const Params& p, int ch) {
;     ...
;     EPI256_BEGIN
;       float rs = rsqrtf(ssq1[row] * (1.f / 1024) + EPS);
; #pragma unroll
;       for (int i = 0; i < 16; ++i) { v[i] *= rs; if (isgate) v[i] = siluf(v[i]); }
;       store16_bf(Z + (size_t)row * 1024 + col, v);
.LBB0_1244:
	v_cvt_pk_bf16_f32 v47, v46, v47
	v_cvt_pk_bf16_f32 v46, v44, v45
	v_cvt_pk_bf16_f32 v45, v49, v50
	v_cvt_pk_bf16_f32 v44, v0, v48
	v_bfe_u32 v0, v39, 16, 1
	v_add3_u32 v0, v39, v0, s27
	v_bfe_u32 v50, v38, 16, 1
	v_lshlrev_b64 v[2:3], 11, v[2:3]
	v_add3_u32 v38, v38, v50, s27
	v_lshl_add_u64 v[2:3], v[116:117], 0, v[2:3]
	v_lshrrev_b32_e32 v38, 16, v38
	v_and_or_b32 v39, v0, s71, v38
	v_cvt_pk_bf16_f32 v38, v36, v37
	v_cvt_pk_bf16_f32 v37, v42, v43
	v_cvt_pk_bf16_f32 v36, v40, v41
	global_store_dwordx4 v[2:3], v[44:47], off
	global_store_dwordx4 v[2:3], v[36:39], off offset:16
	ds_write2_b32 v134, v32, v28 offset1:16
	ds_write2_b32 v134, v33, v29 offset0:68 offset1:84
	ds_write2_b32 v134, v34, v30 offset0:136 offset1:152
	ds_write2_b32 v134, v35, v31 offset0:204 offset1:220
	ds_write2_b32 v134, v24, v20 offset0:32 offset1:48
	ds_write2_b32 v134, v25, v21 offset0:100 offset1:116
	ds_write2_b32 v134, v26, v22 offset0:168 offset1:184
	ds_write2_b32 v134, v27, v23 offset0:236 offset1:252
	v_or_b32_e32 v2, 0x60, v132
	s_waitcnt lgkmcnt(0)
	v_ashrrev_i32_e32 v3, 31, v2
	ds_read_b128 v[32:35], v135
	ds_read_b128 v[28:31], v135 offset:16
	ds_read_b128 v[24:27], v135 offset:32
	ds_read_b128 v[20:23], v135 offset:48
	v_lshl_add_u64 v[36:37], v[2:3], 2, s[78:79]
	global_load_dword v0, v[36:37], off
	s_waitcnt vmcnt(0)
	v_fmamk_f32 v0, v0, 0x3a800000, v148
	v_mul_f32_e32 v36, 0x4b800000, v0
	v_cmp_gt_f32_e32 vcc, s86, v0
	s_nop 1
	v_cndmask_b32_e32 v0, v0, v36, vcc
	v_rsq_f32_e32 v0, v0
	s_nop 0
	v_mul_f32_e32 v36, 0x45800000, v0
	v_cndmask_b32_e32 v36, v0, v36, vcc
	s_and_b64 vcc, exec, s[8:9]
	s_waitcnt lgkmcnt(3)
	v_mul_f32_e32 v0, v32, v36
	s_cbranch_vccz .LBB0_1366
	s_and_b64 vcc, exec, s[8:9]
	v_mul_f32_e32 v32, v33, v36
	s_cbranch_vccz .LBB0_1367

; DI unsigned pack2(float a, float b) { return (unsigned)f2bf(a) | ((unsigned)f2bf(b) << 16); }
; DI float siluf(float x) { return x * sigm(x); }
;   const int lane = tid & 63, wid = tid >> 6, fr = lane & 15, fq = lane >> 4;
;   float* stg = (float*)(smem + PATCH) + wid * (16 * 68);
;   asm volatile("" ::: "memory");
; #pragma unroll
;   for (int n = 0; n < 4; ++n)
; #pragma unroll
;     for (int j = 0; j < 4; ++j) stg[(fq * 4 + j) * 68 + n * 16 + fr] = am[n][j];
;   asm volatile("s_waitcnt lgkmcnt(0)" ::: "memory");
;   const float* rp = stg + (lane >> 2) * 68 + (lane & 3) * 16;
; #pragma unroll
;   for (int i = 0; i < 4; ++i) { f32x4 t = *(const f32x4*)(rp + i * 4); v[4 * i] = t[0]; v[4 * i + 1] = t[1]; v[4 * i + 2] = t[2]; v[4 * i + 3] = t[3]; }
;   asm volatile("" ::: "memory");
; }
; DI void store16_bf(bft* dst, const float (&v)[16]) {
;   u32x4 o0 = {pack2(v[0], v[1]), pack2(v[2], v[3]), pack2(v[4], v[5]), pack2(v[6], v[7])}, o1 = {pack2(v[8], v[9]), pack2(v[10], v[11]), pack2(v[12], v[13]), pack2(v[14], v[15])};
;   *(u32x4*)dst = o0; *(u32x4*)(dst + 8) = o1;
; }
; DI void phase_inproj1(const Params& p, int ch) {
;     ...
;     EPI256_BEGIN
;       float rs = rsqrtf(ssq1[row] * (1.f / 1024) + EPS);
; #pragma unroll
;       for (int i = 0; i < 16; ++i) { v[i] *= rs; if (isgate) v[i] = siluf(v[i]); }
;       store16_bf(Z + (size_t)row * 1024 + col, v);
.LBB0_1261:
	v_cvt_pk_bf16_f32 v31, v30, v31
	v_cvt_pk_bf16_f32 v30, v28, v29
	v_cvt_pk_bf16_f32 v29, v33, v34
	v_cvt_pk_bf16_f32 v28, v0, v32
	v_bfe_u32 v0, v23, 16, 1
	v_add3_u32 v0, v23, v0, s27
	v_bfe_u32 v34, v22, 16, 1
	v_lshlrev_b64 v[2:3], 11, v[2:3]
	v_add3_u32 v22, v22, v34, s27
	v_lshl_add_u64 v[2:3], v[116:117], 0, v[2:3]
	v_lshrrev_b32_e32 v22, 16, v22
	v_and_or_b32 v23, v0, s71, v22
	v_cvt_pk_bf16_f32 v22, v20, v21
	v_cvt_pk_bf16_f32 v21, v26, v27
	v_cvt_pk_bf16_f32 v20, v24, v25
	global_store_dwordx4 v[2:3], v[28:31], off
	global_store_dwordx4 v[2:3], v[20:23], off offset:16
	ds_write2_b32 v134, v16, v12 offset1:16
	ds_write2_b32 v134, v17, v13 offset0:68 offset1:84
	ds_write2_b32 v134, v18, v14 offset0:136 offset1:152
	ds_write2_b32 v134, v19, v15 offset0:204 offset1:220
	ds_write2_b32 v134, v8, v4 offset0:32 offset1:48
	ds_write2_b32 v134, v9, v5 offset0:100 offset1:116
	ds_write2_b32 v134, v10, v6 offset0:168 offset1:184
	ds_write2_b32 v134, v11, v7 offset0:236 offset1:252
	v_or_b32_e32 v18, 0x70, v132
	s_waitcnt lgkmcnt(0)
	v_ashrrev_i32_e32 v19, 31, v18
	ds_read_b128 v[14:17], v135
	ds_read_b128 v[10:13], v135 offset:16
	ds_read_b128 v[6:9], v135 offset:32
	ds_read_b128 v[2:5], v135 offset:48
	v_lshl_add_u64 v[20:21], v[18:19], 2, s[78:79]
	global_load_dword v0, v[20:21], off
	s_waitcnt vmcnt(0)
	v_fmamk_f32 v0, v0, 0x3a800000, v148
	v_mul_f32_e32 v20, 0x4b800000, v0
	v_cmp_gt_f32_e32 vcc, s86, v0
	s_nop 1
	v_cndmask_b32_e32 v0, v0, v20, vcc
	v_rsq_f32_e32 v0, v0
	s_nop 0
	v_mul_f32_e32 v20, 0x45800000, v0
	v_cndmask_b32_e32 v20, v0, v20, vcc
	s_and_b64 vcc, exec, s[8:9]
	s_waitcnt lgkmcnt(3)
	v_mul_f32_e32 v0, v14, v20
	s_cbranch_vccz .LBB0_1381
	s_and_b64 vcc, exec, s[8:9]
	v_mul_f32_e32 v14, v15, v20
	s_cbranch_vccz .LBB0_1382

; DI unsigned pack2(float a, float b) { return (unsigned)f2bf(a) | ((unsigned)f2bf(b) << 16); }
; DI void phase_vx(const Params& p, int ch) {
;     ...
;     { int cl = tid >> 1, th = (tid & 1) * 32; bft* dst = vxT + (size_t)cl * T + tok0 + th;
; #pragma unroll
;       for (int q = 0; q < 4; ++q) { u32x4 o;
; #pragma unroll
;         for (int k = 0; k < 4; ++k) o[k] = pack2(tile[(th + q * 8 + 2 * k) * 257 + cl], tile[(th + q * 8 + 2 * k + 1) * 257 + cl]);
;         *(u32x4*)(dst + q * 8) = o; } }
.LBB0_1468:
	s_waitcnt lgkmcnt(0)
	s_barrier
	ds_read_b32 v0, v93
	ds_read_b32 v66, v98 offset:1028
	s_ashr_i32 s1, s0, 31
	v_lshl_add_u64 v[70:71], s[0:1], 1, v[94:95]
	s_add_i32 s12, s12, s28
	s_waitcnt lgkmcnt(1)
	s_waitcnt lgkmcnt(0)
	v_cvt_pk_bf16_f32 v66, v0, v66
	ds_read_b32 v0, v93 offset:2056
	ds_read_b32 v67, v98 offset:3084
	s_cmpk_gt_i32 s12, 0x2ff
	s_waitcnt lgkmcnt(1)
	s_waitcnt lgkmcnt(0)
	v_cvt_pk_bf16_f32 v67, v0, v67
	ds_read_b32 v0, v93 offset:4112
	ds_read_b32 v68, v98 offset:5140
	s_waitcnt lgkmcnt(1)
	s_waitcnt lgkmcnt(0)
	v_cvt_pk_bf16_f32 v68, v0, v68
	ds_read_b32 v0, v93 offset:6168
	ds_read_b32 v69, v98 offset:7196
	s_waitcnt lgkmcnt(1)
	s_waitcnt lgkmcnt(0)
	v_cvt_pk_bf16_f32 v69, v0, v69
	global_store_dwordx4 v[70:71], v[66:69], off
	ds_read_b32 v0, v93 offset:8224
	ds_read_b32 v66, v98 offset:9252
	s_waitcnt lgkmcnt(1)
	s_waitcnt lgkmcnt(0)
	v_cvt_pk_bf16_f32 v66, v0, v66
	ds_read_b32 v0, v93 offset:10280
	ds_read_b32 v67, v98 offset:11308
	s_waitcnt lgkmcnt(1)
	s_waitcnt lgkmcnt(0)
	v_cvt_pk_bf16_f32 v67, v0, v67
	ds_read_b32 v0, v93 offset:12336
	ds_read_b32 v68, v98 offset:13364
	s_waitcnt lgkmcnt(1)
	s_waitcnt lgkmcnt(0)
	v_cvt_pk_bf16_f32 v68, v0, v68
	ds_read_b32 v0, v93 offset:14392
	ds_read_b32 v69, v98 offset:15420
	s_waitcnt lgkmcnt(1)
	s_waitcnt lgkmcnt(0)
	v_cvt_pk_bf16_f32 v69, v0, v69
	global_store_dwordx4 v[70:71], v[66:69], off offset:16
	ds_read_b32 v0, v93 offset:16448
	ds_read_b32 v66, v98 offset:17476
	s_waitcnt lgkmcnt(1)
	s_waitcnt lgkmcnt(0)
	v_cvt_pk_bf16_f32 v66, v0, v66
	ds_read_b32 v0, v93 offset:18504
	ds_read_b32 v67, v98 offset:19532
	s_waitcnt lgkmcnt(1)
	s_waitcnt lgkmcnt(0)
	v_cvt_pk_bf16_f32 v67, v0, v67
	ds_read_b32 v0, v93 offset:20560
	ds_read_b32 v68, v98 offset:21588
	s_waitcnt lgkmcnt(1)
	s_waitcnt lgkmcnt(0)
	v_cvt_pk_bf16_f32 v68, v0, v68
	ds_read_b32 v0, v93 offset:22616
	ds_read_b32 v69, v98 offset:23644
	s_waitcnt lgkmcnt(1)
	s_waitcnt lgkmcnt(0)
	v_cvt_pk_bf16_f32 v69, v0, v69
	global_store_dwordx4 v[70:71], v[66:69], off offset:32
	ds_read_b32 v0, v93 offset:24672
	ds_read_b32 v66, v98 offset:25700
	s_waitcnt lgkmcnt(1)
	s_waitcnt lgkmcnt(0)
	v_cvt_pk_bf16_f32 v66, v0, v66
	ds_read_b32 v0, v93 offset:26728
	ds_read_b32 v67, v98 offset:27756
	s_waitcnt lgkmcnt(1)
	s_waitcnt lgkmcnt(0)
	v_cvt_pk_bf16_f32 v67, v0, v67
	ds_read_b32 v0, v93 offset:28784
	ds_read_b32 v68, v98 offset:29812
	s_waitcnt lgkmcnt(1)
	s_waitcnt lgkmcnt(0)
	v_cvt_pk_bf16_f32 v68, v0, v68
	ds_read_b32 v0, v93 offset:30840
	ds_read_b32 v69, v98 offset:31868
	s_waitcnt lgkmcnt(1)
	s_waitcnt lgkmcnt(0)
	v_cvt_pk_bf16_f32 v69, v0, v69
	global_store_dwordx4 v[70:71], v[66:69], off offset:48
	s_barrier
	s_cbranch_scc1 .LBB0_1536

; DI unsigned pack2(float a, float b) { return (unsigned)f2bf(a) | ((unsigned)f2bf(b) << 16); }
; DI float2 twid(float r) { return float2{__builtin_amdgcn_cosf(r), -__builtin_amdgcn_sinf(r)}; }
; DI void fftconv2_item(bft* x, const float2* kh) {
;     ...
;   for (int ii = 2 * tid; ii < 2 * L; ii += 2 * NTHR) { const int sel = ii >= L ? 1 : 0, i = ii - sel * L; bft* xa = x + sel * 2 * L; bft* xb = xa + L; float2* z = z0 + sel * N;
;     float2 v0 = z[i], v1 = z[i + 1];
;     float2 c0 = cmulc(z[L + i], twid((float)i * (1.f / N))), c1 = cmulc(z[L + i + 1], twid((float)(i + 1) * (1.f / N))); v0.x += c0.x; v0.y += c0.y; v1.x += c1.x; v1.y += c1.y;
;     *(unsigned*)(xa + i) = pack2(v0.x, v1.x); *(unsigned*)(xb + i) = pack2(v0.y, v1.y); }
.LBB0_1624:
	v_cmp_lt_i32_e32 vcc, s31, v74
	s_nop 1
	v_cndmask_b32_e32 v0, 0, v154, vcc
	v_cndmask_b32_e32 v2, 0, v155, vcc
	v_add_u32_e32 v10, v0, v74
	v_lshlrev_b32_e32 v0, 1, v2
	v_lshl_add_u64 v[12:13], s[14:15], 0, v[0:1]
	v_lshlrev_b32_e32 v0, 3, v2
	v_lshlrev_b32_e32 v2, 3, v10
	v_add3_u32 v0, 16, v0, v2
	ds_read_b128 v[2:5], v0
	ds_read_b128 v[6:9], v0 offset:32768
	v_cvt_f32_i32_e32 v0, v10
	v_add_u32_e32 v14, 1, v10
	v_ashrrev_i32_e32 v11, 31, v10
	v_mul_f32_e32 v0, 0x39000000, v0
	v_cos_f32_e32 v15, v0
	v_sin_f32_e32 v0, v0
	s_waitcnt lgkmcnt(0)
	v_mul_f32_e32 v16, v0, v7
	v_mul_f32_e32 v7, v15, v7
	v_fmac_f32_e32 v7, v6, v0
	v_cvt_f32_i32_e32 v0, v14
	v_fma_f32 v16, v6, v15, -v16
	v_add_f32_e32 v7, v3, v7
	v_mul_f32_e32 v0, 0x39000000, v0
	v_cos_f32_e32 v6, v0
	v_sin_f32_e32 v0, v0
	s_nop 0
	v_mul_f32_e32 v14, v0, v9
	v_fma_f32 v14, v6, v8, -v14
	v_mul_f32_e32 v6, v6, v9
	v_fmac_f32_e32 v6, v0, v8
	v_add_f32_e32 v0, v2, v16
	v_add_f32_e32 v2, v4, v14
	v_cvt_pk_bf16_f32 v0, v0, v2
	v_lshl_add_u64 v[2:3], v[10:11], 1, v[12:13]
	v_add_f32_e32 v4, v5, v6
	global_store_dword v[2:3], v0, off
	v_add_co_u32_e32 v2, vcc, 0x2000, v2
	v_cvt_pk_bf16_f32 v0, v7, v4
	s_nop 0
	v_addc_co_u32_e32 v3, vcc, 0, v3, vcc
	global_store_dword v[2:3], v0, off
	v_add_u32_e32 v0, 0x400, v74
	v_cmp_lt_i32_e32 vcc, s4, v74
	s_or_b64 s[10:11], vcc, s[10:11]
	v_mov_b32_e32 v74, v0
	s_andn2_b64 exec, exec, s[10:11]
	s_cbranch_execnz .LBB0_1624

; DI unsigned pack2(float a, float b) { return (unsigned)f2bf(a) | ((unsigned)f2bf(b) << 16); }
; DI float2 twid(float r) { return float2{__builtin_amdgcn_cosf(r), -__builtin_amdgcn_sinf(r)}; }
; DI void bfly_inv(float2 s0, float2 s1, float2 s2, float2 s3, float r, float2& o0, float2& o1, float2& o2, float2& o3) {
;   float2 w1 = twid(r), w2 = cmul(w1, w1), w3 = cmul(w2, w1);
;   float2 c0 = s0, c1 = cmulc(s1, w1), c2 = cmulc(s2, w2), c3 = cmulc(s3, w3);
;   float2 t0 = {c0.x + c2.x, c0.y + c2.y}, t1 = {c0.x - c2.x, c0.y - c2.y}, t2 = {c1.x + c3.x, c1.y + c3.y}, t3 = {c1.x - c3.x, c1.y - c3.y};
;   o0 = float2{t0.x + t2.x, t0.y + t2.y}; o2 = float2{t0.x - t2.x, t0.y - t2.y}; o1 = float2{t1.x - t3.y, t1.y + t3.x}; o3 = float2{t1.x + t3.y, t1.y - t3.x};
; }
; template <int LOGN> DI void fftconv_item(bft* xa, bft* xb, const float2* kh) {
;     ...
;     constexpr int Q = N / 4;
;     for (int i = 2 * tid; i < Q; i += 2 * NTHR) { float2 r0[2], r1[2];
; #pragma unroll
;       for (int e = 0; e < 2; ++e) { float2 o2, o3; bfly_inv(z[i + e], z[i + e + Q], z[i + e + 2 * Q], z[i + e + 3 * Q], (float)(i + e) * (1.f / N), r0[e], r1[e], o2, o3); }
;       *(unsigned*)(xa + i) = pack2(r0[0].x, r0[1].x); *(unsigned*)(xb + i) = pack2(r0[0].y, r0[1].y);
;       *(unsigned*)(xa + Q + i) = pack2(r1[0].x, r1[1].x); *(unsigned*)(xb + Q + i) = pack2(r1[0].y, r1[1].y); }
.LBB0_1656:
	v_add_u32_e32 v3, 0x10000, v0
	ds_read_b128 v[6:9], v0
	ds_read_b128 v[10:13], v0 offset:32768
	ds_read_b128 v[14:17], v3
	v_add_u32_e32 v3, 0x18000, v0
	ds_read_b128 v[18:21], v3
	v_cvt_f32_i32_e32 v3, v2
	v_add_u32_e32 v0, 0x2000, v0
	v_mul_f32_e32 v3, 0x38800000, v3
	v_cos_f32_e32 v22, v3
	v_sin_f32_e32 v3, v3
	s_nop 0
	v_mul_f32_e32 v23, v3, v3
	v_fma_f32 v23, v22, v22, -v23
	v_mul_f32_e64 v24, v22, -v3
	v_add_f32_e32 v24, v24, v24
	v_mul_f32_e32 v26, v3, v23
	s_waitcnt lgkmcnt(2)
	v_mul_f32_e32 v27, v3, v11
	v_mul_f32_e32 v11, v22, v11
	v_mul_f32_e32 v25, v3, v24
	v_fma_f32 v26, v22, v24, -v26
	v_fma_f32 v27, v22, v10, -v27
	v_fmac_f32_e32 v11, v3, v10
	s_waitcnt lgkmcnt(1)
	v_mul_f32_e32 v3, v24, v15
	v_mul_f32_e32 v10, v24, v14
	v_fmac_f32_e32 v25, v22, v23
	v_fmac_f32_e32 v3, v23, v14
	v_fma_f32 v10, v23, v15, -v10
	s_waitcnt lgkmcnt(0)
	v_mul_f32_e32 v14, v26, v19
	v_mul_f32_e32 v15, v26, v18
	v_fmac_f32_e32 v14, v25, v18
	v_fma_f32 v15, v25, v19, -v15
	v_add_f32_e32 v18, v6, v3
	v_add_f32_e32 v19, v7, v10
	v_sub_f32_e32 v3, v6, v3
	v_sub_f32_e32 v6, v7, v10
	v_add_f32_e32 v7, v27, v14
	v_add_f32_e32 v10, v11, v15
	v_sub_f32_e32 v14, v27, v14
	v_sub_f32_e32 v11, v11, v15
	v_sub_f32_e32 v3, v3, v11
	v_add_f32_e32 v11, v6, v14
	v_add_u32_e32 v6, 1, v2
	v_cvt_f32_i32_e32 v6, v6
	v_add_f32_e32 v7, v18, v7
	v_add_f32_e32 v10, v19, v10
	v_mul_f32_e32 v6, 0x38800000, v6
	v_cos_f32_e32 v14, v6
	v_sin_f32_e32 v6, v6
	s_nop 0
	v_mul_f32_e32 v15, v6, v6
	v_fma_f32 v15, v14, v14, -v15
	v_mul_f32_e64 v18, v14, -v6
	v_add_f32_e32 v18, v18, v18
	v_mul_f32_e32 v22, v6, v15
	v_mul_f32_e32 v23, v6, v13
	v_mul_f32_e32 v13, v14, v13
	v_mul_f32_e32 v19, v6, v18
	v_fma_f32 v22, v14, v18, -v22
	v_fma_f32 v23, v14, v12, -v23
	v_fmac_f32_e32 v13, v6, v12
	v_mul_f32_e32 v6, v18, v17
	v_mul_f32_e32 v12, v18, v16
	v_fmac_f32_e32 v19, v14, v15
	v_fmac_f32_e32 v6, v15, v16
	v_fma_f32 v12, v15, v17, -v12
	v_mul_f32_e32 v14, v22, v21
	v_mul_f32_e32 v15, v22, v20
	v_fmac_f32_e32 v14, v19, v20
	v_fma_f32 v15, v19, v21, -v15
	v_add_f32_e32 v16, v8, v6
	v_add_f32_e32 v17, v9, v12
	v_sub_f32_e32 v6, v8, v6
	v_sub_f32_e32 v8, v9, v12
	v_add_f32_e32 v9, v23, v14
	v_add_f32_e32 v12, v13, v15
	v_sub_f32_e32 v13, v13, v15
	v_add_f32_e32 v9, v16, v9
	v_sub_f32_e32 v13, v6, v13
	v_cvt_pk_bf16_f32 v6, v7, v9
	v_add_f32_e32 v12, v17, v12
	global_store_dword v[4:5], v6, off
	v_cvt_pk_bf16_f32 v9, v10, v12
	v_add_co_u32_e32 v6, vcc, s29, v4
	v_sub_f32_e32 v14, v23, v14
	s_nop 0
	v_addc_co_u32_e32 v7, vcc, 0, v5, vcc
	global_store_dword v[6:7], v9, off
	v_cvt_pk_bf16_f32 v3, v3, v13
	v_add_co_u32_e32 v6, vcc, s24, v4
	v_add_f32_e32 v8, v8, v14
	s_nop 0
	v_addc_co_u32_e32 v7, vcc, 0, v5, vcc
	global_store_dword v[6:7], v3, off
	v_cvt_pk_bf16_f32 v3, v11, v8
	v_add_co_u32_e32 v6, vcc, 0x6000, v4
	s_nop 1
	v_addc_co_u32_e32 v7, vcc, 0, v5, vcc
	global_store_dword v[6:7], v3, off
	v_add_u32_e32 v3, 0x400, v2
	v_cmp_lt_i32_e32 vcc, s87, v2
	v_lshl_add_u64 v[4:5], v[4:5], 0, s[6:7]
	s_or_b64 s[10:11], vcc, s[10:11]
	v_mov_b32_e32 v2, v3
	s_andn2_b64 exec, exec, s[10:11]
	s_cbranch_execnz .LBB0_1656
	s_branch .LBB0_1592

; DI unsigned pack2(float a, float b) { return (unsigned)f2bf(a) | ((unsigned)f2bf(b) << 16); }
; DI void phase_gate(const Params& p, int ch) {
;     ...
;     for (int rr = 0; rr < 4; ++rr) { int e = tid + rr * 512; int tl = e >> 5, cg = e & 31; int tok = tok0 + tl, cc = cg * 8, c = ch * 256 + cc; int pos = tok_pos(tok), L = tok_len(tok);
;       const bft* zr = Z + (size_t)tok * 1024; u32x4 zero = {0, 0, 0, 0};
;       u32x4 xm = pos > 0 ? *(const u32x4*)(zr - 1024 + cc) : zero, x0 = *(const u32x4*)(zr + cc), xp = pos < L - 1 ? *(const u32x4*)(zr + 1024 + cc) : zero, gt = *(const u32x4*)(zr + 768 + cc);
;       float o[8];
; #pragma unroll
;       for (int i = 0; i < 8; ++i) { int sh = (i & 1) ? 0 : 16; unsigned msk = 0xffff0000u; int w = i >> 1;
;         float a = __uint_as_float((xm[w] << sh) & msk), b = __uint_as_float((x0[w] << sh) & msk), d = __uint_as_float((xp[w] << sh) & msk), g = __uint_as_float((gt[w] << sh) & msk);
;         float xc = a * w0[0][i] + b * w0[1][i] + d * w0[2][i] + b0[i];
;         o[i] = tile[(cc + i) * 65 + tl] * xc * g; }
;       u32x4 w = {pack2(o[0], o[1]), pack2(o[2], o[3]), pack2(o[4], o[5]), pack2(o[6], o[7])};
;       *(u32x4*)(G1 + (size_t)tok * 1024 + cc) = w; }
.LBB0_1710:
	s_or_b64 exec, exec, s[8:9]
	global_load_dwordx4 v[60:63], v[54:55], off offset:1536
	v_lshl_add_u32 v0, v58, 2, v56
	ds_read2_b32 v[72:73], v0 offset1:65
	ds_read2_b32 v[74:75], v0 offset0:130 offset1:195
	v_add_u32_e32 v0, 0x400, v0
	s_waitcnt vmcnt(1)
	v_lshlrev_b32_e32 v65, 16, v41
	v_lshlrev_b32_e32 v64, 16, v40
	ds_read2_b32 v[76:77], v0 offset0:4 offset1:69
	ds_read2_b32 v[78:79], v0 offset0:134 offset1:199
	v_lshlrev_b32_e32 v59, 16, v37
	v_lshlrev_b32_e32 v58, 16, v36
	v_and_b32_e32 v41, 0xffff0000, v41
	v_and_b32_e32 v40, 0xffff0000, v40
	v_lshlrev_b32_e32 v71, 16, v43
	v_lshlrev_b32_e32 v70, 16, v42
	v_and_b32_e32 v43, 0xffff0000, v43
	v_and_b32_e32 v42, 0xffff0000, v42
	v_pk_mul_f32 v[64:65], v[18:19], v[64:65]
	v_lshlrev_b32_e32 v54, 16, v32
	v_lshlrev_b32_e32 v55, 16, v33
	v_and_b32_e32 v37, 0xffff0000, v37
	v_and_b32_e32 v36, 0xffff0000, v36
	v_lshlrev_b32_e32 v69, 16, v39
	v_lshlrev_b32_e32 v68, 16, v38
	v_and_b32_e32 v39, 0xffff0000, v39
	v_and_b32_e32 v38, 0xffff0000, v38
	v_pk_mul_f32 v[40:41], v[12:13], v[40:41]
	v_pk_mul_f32 v[70:71], v[26:27], v[70:71]
	v_pk_mul_f32 v[42:43], v[20:21], v[42:43]
	v_pk_fma_f32 v[58:59], v[6:7], v[58:59], v[64:65]
	v_and_b32_e32 v32, 0xffff0000, v32
	v_and_b32_e32 v33, 0xffff0000, v33
	v_lshlrev_b32_e32 v66, 16, v34
	v_and_b32_e32 v34, 0xffff0000, v34
	v_lshlrev_b32_e32 v67, 16, v35
	v_and_b32_e32 v35, 0xffff0000, v35
	v_pk_fma_f32 v[36:37], v[52:53], v[36:37], v[40:41]
	v_pk_fma_f32 v[40:41], v[14:15], v[68:69], v[70:71]
	v_pk_fma_f32 v[38:39], v[8:9], v[38:39], v[42:43]
	v_pk_fma_f32 v[42:43], v[22:23], v[54:55], v[58:59]
	v_pk_fma_f32 v[32:33], v[16:17], v[32:33], v[36:37]
	v_pk_fma_f32 v[36:37], v[30:31], v[66:67], v[40:41]
	v_pk_fma_f32 v[34:35], v[24:25], v[34:35], v[38:39]
	v_pk_add_f32 v[38:39], v[2:3], v[42:43]
	s_waitcnt lgkmcnt(3)
	v_mov_b32_e32 v40, v72
	s_waitcnt lgkmcnt(2)
	v_mov_b32_e32 v41, v74
	v_pk_add_f32 v[36:37], v[10:11], v[36:37]
	v_pk_add_f32 v[34:35], v[4:5], v[34:35]
	v_pk_mul_f32 v[38:39], v[40:41], v[38:39]
	s_waitcnt lgkmcnt(1)
	v_mov_b32_e32 v40, v76
	s_waitcnt lgkmcnt(0)
	v_mov_b32_e32 v41, v78
	v_mov_b32_e32 v78, v77
	v_pk_add_f32 v[32:33], v[50:51], v[32:33]
	v_mov_b32_e32 v74, v73
	v_pk_mul_f32 v[36:37], v[40:41], v[36:37]
	v_pk_mul_f32 v[34:35], v[34:35], v[78:79]
	v_pk_mul_f32 v[32:33], v[74:75], v[32:33]
	v_lshlrev_b64 v[28:29], 10, v[28:29]
	s_addk_i32 s1, 0x200
	v_lshl_add_u64 v[28:29], v[28:29], 1, v[48:49]
	s_cmpk_eq_i32 s1, 0x800
	s_waitcnt vmcnt(0)
	v_lshlrev_b32_e32 v41, 16, v61
	v_lshlrev_b32_e32 v40, 16, v60
	v_lshlrev_b32_e32 v55, 16, v63
	v_lshlrev_b32_e32 v54, 16, v62
	v_and_b32_e32 v59, 0xffff0000, v63
	v_and_b32_e32 v58, 0xffff0000, v62
	v_and_b32_e32 v43, 0xffff0000, v61
	v_and_b32_e32 v42, 0xffff0000, v60
	v_pk_mul_f32 v[38:39], v[38:39], v[40:41]
	v_pk_mul_f32 v[36:37], v[36:37], v[54:55]
	v_pk_mul_f32 v[34:35], v[34:35], v[58:59]
	v_pk_mul_f32 v[32:33], v[32:33], v[42:43]
	v_bfe_u32 v0, v35, 16, 1
	v_bfe_u32 v58, v37, 16, 1
	v_add3_u32 v0, v35, v0, s27
	v_add3_u32 v35, v37, v58, s27
	v_lshrrev_b32_e32 v35, 16, v35
	v_and_or_b32 v35, v0, s71, v35
	v_cvt_pk_bf16_f32 v34, v36, v34
	v_cvt_pk_bf16_f32 v33, v39, v33
	v_cvt_pk_bf16_f32 v32, v38, v32
	global_store_dwordx4 v[28:29], v[32:35], off
	s_cbranch_scc1 .LBB0_1708

; DI unsigned pack2(float a, float b) { return (unsigned)f2bf(a) | ((unsigned)f2bf(b) << 16); }
;   const int lane = tid & 63, wid = tid >> 6, fr = lane & 15, fq = lane >> 4;
;   float* stg = (float*)(smem + PATCH) + wid * (16 * 68);
;   asm volatile("" ::: "memory");
; #pragma unroll
;   for (int n = 0; n < 4; ++n)
; #pragma unroll
;     for (int j = 0; j < 4; ++j) stg[(fq * 4 + j) * 68 + n * 16 + fr] = am[n][j];
;   asm volatile("s_waitcnt lgkmcnt(0)" ::: "memory");
;   const float* rp = stg + (lane >> 2) * 68 + (lane & 3) * 16;
; #pragma unroll
;   for (int i = 0; i < 4; ++i) { f32x4 t = *(const f32x4*)(rp + i * 4); v[4 * i] = t[0]; v[4 * i + 1] = t[1]; v[4 * i + 2] = t[2]; v[4 * i + 3] = t[3]; }
;   asm volatile("" ::: "memory");
; }
; DI void store16_bf(bft* dst, const float (&v)[16]) {
;   u32x4 o0 = {pack2(v[0], v[1]), pack2(v[2], v[3]), pack2(v[4], v[5]), pack2(v[6], v[7])}, o1 = {pack2(v[8], v[9]), pack2(v[10], v[11]), pack2(v[12], v[13]), pack2(v[14], v[15])};
;   *(u32x4*)dst = o0; *(u32x4*)(dst + 8) = o1;
; }
; DI void load16_bf(const bft* src, float (&v)[16]) {
;   u32x4 w0 = *(const u32x4*)src, w1 = *(const u32x4*)(src + 8);
; #pragma unroll
;   for (int i = 0; i < 4; ++i) { v[2 * i] = __uint_as_float(w0[i] << 16); v[2 * i + 1] = __uint_as_float(w0[i] & 0xffff0000u); v[8 + 2 * i] = __uint_as_float(w1[i] << 16); v[8 + 2 * i + 1] = __uint_as_float(w1[i] & 0xffff0000u); }
; }
; DI void load16_f(const float* src, float (&v)[16]) {
; #pragma unroll
;   for (int i = 0; i < 4; ++i) { f32x4 t = *(const f32x4*)(src + 4 * i); v[4 * i] = t[0]; v[4 * i + 1] = t[1]; v[4 * i + 2] = t[2]; v[4 * i + 3] = t[3]; }
; }
; DI void store16_f(float* dst, const float (&v)[16]) {
; #pragma unroll
;   for (int i = 0; i < 4; ++i) { f32x4 t = {v[4 * i], v[4 * i + 1], v[4 * i + 2], v[4 * i + 3]}; *(f32x4*)(dst + 4 * i) = t; }
; }
; DI void phase_outproj1(const Params& p, int hh) {
;     ...
;     EPI256_BEGIN
;       float h[16]; float* hp = p.out + (size_t)row * 1024 + col; load16_f(hp, h);
; #pragma unroll
;       for (int i = 0; i < 16; ++i) h[i] += v[i];
;       store16_f(hp, h); if (hh == 1) store16_bf(hb3 + (size_t)row * 1024 + col, h);
.LBB0_1767:
	v_lshrrev_b32_e32 v2, 6, v149
	v_lshrrev_b32_e32 v132, 2, v149
	v_and_b32_e32 v3, 15, v149
	v_mul_lo_u32 v2, v2, s23
	v_and_b32_e32 v132, 12, v132
	v_add_u32_e32 v2, s33, v2
	v_lshlrev_b32_e32 v3, 2, v3
	v_mul_u32_u24_e32 v132, 0x110, v132
	v_add3_u32 v134, v2, v3, v132
	v_bfe_u32 v3, v149, 2, 4
	v_and_b32_e32 v133, 48, v150
	v_mul_u32_u24_e32 v132, 0x110, v3
	v_lshlrev_b32_e32 v135, 2, v133
	v_add3_u32 v135, v2, v132, v135
	v_ashrrev_i32_e32 v2, 1, v149
	v_and_b32_e32 v2, 0xffffff80, v2
	v_add_u32_e32 v2, s26, v2
	v_and_b32_e32 v0, 0xc0, v149
	v_or_b32_e32 v132, v2, v3
	v_or3_b32 v138, v0, s25, v133
	v_ashrrev_i32_e32 v133, 31, v132
	s_waitcnt vmcnt(0)
	s_barrier
	v_lshlrev_b32_e32 v0, 1, v138
	ds_write2_b32 v134, v128, v124 offset1:16
	ds_write2_b32 v134, v129, v125 offset0:68 offset1:84
	ds_write2_b32 v134, v130, v126 offset0:136 offset1:152
	ds_write2_b32 v134, v131, v127 offset0:204 offset1:220
	ds_write2_b32 v134, v120, v116 offset0:32 offset1:48
	ds_write2_b32 v134, v121, v117 offset0:100 offset1:116
	ds_write2_b32 v134, v122, v118 offset0:168 offset1:184
	ds_write2_b32 v134, v123, v119 offset0:236 offset1:252
	v_lshlrev_b64 v[136:137], 12, v[132:133]
	v_lshl_add_u64 v[2:3], s[6:7], 0, v[0:1]
	s_waitcnt lgkmcnt(0)
	v_lshl_add_u64 v[136:137], s[8:9], 0, v[136:137]
	v_lshlrev_b32_e32 v0, 2, v138
	ds_read_b128 v[116:119], v135
	ds_read_b128 v[120:123], v135 offset:16
	ds_read_b128 v[124:127], v135 offset:32
	ds_read_b128 v[128:131], v135 offset:48
	v_lshl_add_u64 v[154:155], v[136:137], 0, v[0:1]
	global_load_dwordx4 v[136:139], v[154:155], off
	global_load_dwordx4 v[140:143], v[154:155], off offset:16
	global_load_dwordx4 v[144:147], v[154:155], off offset:32
	global_load_dwordx4 v[150:153], v[154:155], off offset:48
	v_lshlrev_b64 v[156:157], 11, v[132:133]
	v_lshl_add_u64 v[156:157], v[2:3], 0, v[156:157]
	s_add_i32 s2, s2, 1
	s_add_i32 s3, s3, 1
	s_mov_b64 s[16:17], 0
	s_waitcnt vmcnt(3) lgkmcnt(3)
	v_pk_add_f32 v[118:119], v[118:119], v[138:139]
	v_pk_add_f32 v[116:117], v[116:117], v[136:137]
	s_waitcnt vmcnt(2) lgkmcnt(2)
	v_pk_add_f32 v[122:123], v[122:123], v[142:143]
	v_pk_add_f32 v[120:121], v[120:121], v[140:141]
	v_bfe_u32 v133, v123, 16, 1
	v_bfe_u32 v136, v119, 16, 1
	v_bfe_u32 v138, v117, 16, 1
	v_bfe_u32 v139, v118, 16, 1
	v_bfe_u32 v140, v122, 16, 1
	v_bfe_u32 v141, v116, 16, 1
	s_waitcnt vmcnt(1) lgkmcnt(1)
	v_pk_add_f32 v[126:127], v[126:127], v[146:147]
	v_pk_add_f32 v[124:125], v[124:125], v[144:145]
	s_waitcnt vmcnt(0) lgkmcnt(0)
	v_pk_add_f32 v[130:131], v[130:131], v[152:153]
	v_pk_add_f32 v[128:129], v[128:129], v[150:151]
	global_store_dwordx4 v[154:155], v[116:119], off
	global_store_dwordx4 v[154:155], v[120:123], off offset:16
	global_store_dwordx4 v[154:155], v[124:127], off offset:32
	global_store_dwordx4 v[154:155], v[128:131], off offset:48
	s_nop 4
	v_add3_u32 v136, v119, v136, s24
	v_add3_u32 v119, v123, v133, s24
	v_add3_u32 v123, v117, v138, s24
	v_add3_u32 v117, v122, v140, s24
	v_add3_u32 v118, v118, v139, s24
	v_add3_u32 v116, v116, v141, s24
	v_bfe_u32 v143, v131, 16, 1
	v_bfe_u32 v144, v127, 16, 1
	v_bfe_u32 v145, v129, 16, 1
	v_bfe_u32 v146, v125, 16, 1
	v_lshrrev_b32_e32 v118, 16, v118
	v_lshrrev_b32_e32 v117, 16, v117
	v_lshrrev_b32_e32 v116, 16, v116
	v_add3_u32 v122, v127, v144, s24
	v_add3_u32 v127, v131, v143, s24
	v_and_or_b32 v119, v119, s22, v117
	v_and_or_b32 v117, v136, s22, v118
	v_cvt_pk_bf16_f32 v118, v120, v121
	v_and_or_b32 v116, v123, s22, v116
	v_add3_u32 v120, v125, v146, s24
	v_add3_u32 v125, v129, v145, s24
	v_bfe_u32 v121, v126, 16, 1
	v_bfe_u32 v123, v130, 16, 1
	v_bfe_u32 v129, v124, 16, 1
	v_bfe_u32 v131, v128, 16, 1
	v_add3_u32 v123, v130, v123, s24
	v_add3_u32 v121, v126, v121, s24
	v_add3_u32 v126, v128, v131, s24
	v_add3_u32 v124, v124, v129, s24
	v_lshrrev_b32_e32 v121, 16, v121
	v_lshrrev_b32_e32 v123, 16, v123
	v_lshrrev_b32_e32 v124, 16, v124
	v_lshrrev_b32_e32 v126, 16, v126
	v_or_b32_e32 v136, 16, v132
	v_and_or_b32 v123, v127, s22, v123
	v_and_or_b32 v121, v122, s22, v121
	v_and_or_b32 v122, v125, s22, v126
	v_and_or_b32 v120, v120, s22, v124
	global_store_dwordx4 v[156:157], v[116:119], off
	global_store_dwordx4 v[156:157], v[120:123], off offset:16
	v_ashrrev_i32_e32 v137, 31, v136
	ds_write2_b32 v134, v112, v108 offset1:16
	ds_write2_b32 v134, v113, v109 offset0:68 offset1:84
	ds_write2_b32 v134, v114, v110 offset0:136 offset1:152
	ds_write2_b32 v134, v115, v111 offset0:204 offset1:220
	ds_write2_b32 v134, v104, v100 offset0:32 offset1:48
	ds_write2_b32 v134, v105, v101 offset0:100 offset1:116
	ds_write2_b32 v134, v106, v102 offset0:168 offset1:184
	ds_write2_b32 v134, v107, v103 offset0:236 offset1:252
	v_lshlrev_b64 v[116:117], 12, v[136:137]
	s_waitcnt lgkmcnt(0)
	v_lshl_add_u64 v[116:117], s[8:9], 0, v[116:117]
	ds_read_b128 v[100:103], v135
	ds_read_b128 v[104:107], v135 offset:16
	ds_read_b128 v[108:111], v135 offset:32
	ds_read_b128 v[112:115], v135 offset:48
	v_lshl_add_u64 v[138:139], v[116:117], 0, v[0:1]
	global_load_dwordx4 v[116:119], v[138:139], off
	global_load_dwordx4 v[120:123], v[138:139], off offset:16
	global_load_dwordx4 v[124:127], v[138:139], off offset:32
	global_load_dwordx4 v[128:131], v[138:139], off offset:48
	v_lshlrev_b64 v[136:137], 11, v[136:137]
	v_lshl_add_u64 v[136:137], v[2:3], 0, v[136:137]
	s_waitcnt vmcnt(3) lgkmcnt(3)
	v_pk_add_f32 v[102:103], v[102:103], v[118:119]
	v_pk_add_f32 v[100:101], v[100:101], v[116:117]
	s_waitcnt vmcnt(2) lgkmcnt(2)
	v_pk_add_f32 v[106:107], v[106:107], v[122:123]
	v_pk_add_f32 v[104:105], v[104:105], v[120:121]
	v_bfe_u32 v116, v107, 16, 1
	v_bfe_u32 v117, v103, 16, 1
	v_bfe_u32 v119, v101, 16, 1
	v_bfe_u32 v120, v102, 16, 1
	v_bfe_u32 v121, v106, 16, 1
	v_bfe_u32 v122, v100, 16, 1
	s_waitcnt vmcnt(1) lgkmcnt(1)
; DI unsigned pack2(float a, float b) { return (unsigned)f2bf(a) | ((unsigned)f2bf(b) << 16); }
;   const int lane = tid & 63, wid = tid >> 6, fr = lane & 15, fq = lane >> 4;
;   float* stg = (float*)(smem + PATCH) + wid * (16 * 68);
;   asm volatile("" ::: "memory");
; #pragma unroll
;   for (int n = 0; n < 4; ++n)
; #pragma unroll
;     for (int j = 0; j < 4; ++j) stg[(fq * 4 + j) * 68 + n * 16 + fr] = am[n][j];
;   asm volatile("s_waitcnt lgkmcnt(0)" ::: "memory");
;   const float* rp = stg + (lane >> 2) * 68 + (lane & 3) * 16;
; #pragma unroll
;   for (int i = 0; i < 4; ++i) { f32x4 t = *(const f32x4*)(rp + i * 4); v[4 * i] = t[0]; v[4 * i + 1] = t[1]; v[4 * i + 2] = t[2]; v[4 * i + 3] = t[3]; }
;   asm volatile("" ::: "memory");
; }
; DI void store16_bf(bft* dst, const float (&v)[16]) {
;   u32x4 o0 = {pack2(v[0], v[1]), pack2(v[2], v[3]), pack2(v[4], v[5]), pack2(v[6], v[7])}, o1 = {pack2(v[8], v[9]), pack2(v[10], v[11]), pack2(v[12], v[13]), pack2(v[14], v[15])};
;   *(u32x4*)dst = o0; *(u32x4*)(dst + 8) = o1;
; }
; DI void load16_bf(const bft* src, float (&v)[16]) {
;   u32x4 w0 = *(const u32x4*)src, w1 = *(const u32x4*)(src + 8);
; #pragma unroll
;   for (int i = 0; i < 4; ++i) { v[2 * i] = __uint_as_float(w0[i] << 16); v[2 * i + 1] = __uint_as_float(w0[i] & 0xffff0000u); v[8 + 2 * i] = __uint_as_float(w1[i] << 16); v[8 + 2 * i + 1] = __uint_as_float(w1[i] & 0xffff0000u); }
; }
; DI void load16_f(const float* src, float (&v)[16]) {
; #pragma unroll
;   for (int i = 0; i < 4; ++i) { f32x4 t = *(const f32x4*)(src + 4 * i); v[4 * i] = t[0]; v[4 * i + 1] = t[1]; v[4 * i + 2] = t[2]; v[4 * i + 3] = t[3]; }
; }
; DI void store16_f(float* dst, const float (&v)[16]) {
; #pragma unroll
;   for (int i = 0; i < 4; ++i) { f32x4 t = {v[4 * i], v[4 * i + 1], v[4 * i + 2], v[4 * i + 3]}; *(f32x4*)(dst + 4 * i) = t; }
; }
; DI void phase_outproj1(const Params& p, int hh) {
;     ...
;     EPI256_BEGIN
;       float h[16]; float* hp = p.out + (size_t)row * 1024 + col; load16_f(hp, h);
; #pragma unroll
;       for (int i = 0; i < 16; ++i) h[i] += v[i];
;       store16_f(hp, h); if (hh == 1) store16_bf(hb3 + (size_t)row * 1024 + col, h);
	v_pk_add_f32 v[110:111], v[110:111], v[126:127]
	v_pk_add_f32 v[108:109], v[108:109], v[124:125]
	s_waitcnt vmcnt(0) lgkmcnt(0)
	v_pk_add_f32 v[114:115], v[114:115], v[130:131]
	v_pk_add_f32 v[112:113], v[112:113], v[128:129]
	global_store_dwordx4 v[138:139], v[100:103], off
	global_store_dwordx4 v[138:139], v[104:107], off offset:16
	global_store_dwordx4 v[138:139], v[108:111], off offset:32
	global_store_dwordx4 v[138:139], v[112:115], off offset:48
	s_nop 4
	v_add3_u32 v117, v103, v117, s24
	v_add3_u32 v103, v107, v116, s24
	v_add3_u32 v107, v101, v119, s24
	v_add3_u32 v101, v106, v121, s24
	v_add3_u32 v102, v102, v120, s24
	v_add3_u32 v100, v100, v122, s24
	v_bfe_u32 v124, v115, 16, 1
	v_bfe_u32 v125, v111, 16, 1
	v_bfe_u32 v126, v113, 16, 1
	v_lshrrev_b32_e32 v102, 16, v102
	v_lshrrev_b32_e32 v101, 16, v101
	v_lshrrev_b32_e32 v100, 16, v100
	v_add3_u32 v106, v111, v125, s24
	v_add3_u32 v111, v115, v124, s24
	v_and_or_b32 v103, v103, s22, v101
	v_and_or_b32 v101, v117, s22, v102
	v_cvt_pk_bf16_f32 v102, v104, v105
	v_and_or_b32 v100, v107, s22, v100
	v_add3_u32 v104, v113, v126, s24
	v_bfe_u32 v105, v110, 16, 1
	v_bfe_u32 v107, v114, 16, 1
	v_bfe_u32 v115, v112, 16, 1
	v_add3_u32 v107, v114, v107, s24
	v_add3_u32 v105, v110, v105, s24
	v_add3_u32 v110, v112, v115, s24
	v_lshrrev_b32_e32 v105, 16, v105
	v_lshrrev_b32_e32 v107, 16, v107
	v_lshrrev_b32_e32 v110, 16, v110
	v_or_b32_e32 v116, 32, v132
	v_and_or_b32 v107, v111, s22, v107
	v_and_or_b32 v105, v106, s22, v105
	v_and_or_b32 v106, v104, s22, v110
	v_cvt_pk_bf16_f32 v104, v108, v109
	global_store_dwordx4 v[136:137], v[100:103], off
	global_store_dwordx4 v[136:137], v[104:107], off offset:16
	v_ashrrev_i32_e32 v117, 31, v116
	ds_write2_b32 v134, v96, v92 offset1:16
	ds_write2_b32 v134, v97, v93 offset0:68 offset1:84
	ds_write2_b32 v134, v98, v94 offset0:136 offset1:152
	ds_write2_b32 v134, v99, v95 offset0:204 offset1:220
	ds_write2_b32 v134, v88, v84 offset0:32 offset1:48
	ds_write2_b32 v134, v89, v85 offset0:100 offset1:116
	ds_write2_b32 v134, v90, v86 offset0:168 offset1:184
	ds_write2_b32 v134, v91, v87 offset0:236 offset1:252
	v_lshlrev_b64 v[100:101], 12, v[116:117]
	s_waitcnt lgkmcnt(0)
	v_lshl_add_u64 v[100:101], s[8:9], 0, v[100:101]
	ds_read_b128 v[84:87], v135
	ds_read_b128 v[88:91], v135 offset:16
	ds_read_b128 v[92:95], v135 offset:32
	ds_read_b128 v[96:99], v135 offset:48
	v_lshl_add_u64 v[118:119], v[100:101], 0, v[0:1]
	global_load_dwordx4 v[100:103], v[118:119], off
	global_load_dwordx4 v[104:107], v[118:119], off offset:16
	global_load_dwordx4 v[108:111], v[118:119], off offset:32
	global_load_dwordx4 v[112:115], v[118:119], off offset:48
	v_lshlrev_b64 v[116:117], 11, v[116:117]
	v_lshl_add_u64 v[116:117], v[2:3], 0, v[116:117]
	s_waitcnt vmcnt(3) lgkmcnt(3)
	v_pk_add_f32 v[86:87], v[86:87], v[102:103]
	v_pk_add_f32 v[84:85], v[84:85], v[100:101]
	s_waitcnt vmcnt(2) lgkmcnt(2)
	v_pk_add_f32 v[90:91], v[90:91], v[106:107]
	v_pk_add_f32 v[88:89], v[88:89], v[104:105]
	v_bfe_u32 v100, v91, 16, 1
	v_bfe_u32 v101, v87, 16, 1
	v_bfe_u32 v103, v85, 16, 1
	v_bfe_u32 v104, v86, 16, 1
	v_bfe_u32 v105, v90, 16, 1
	v_bfe_u32 v106, v84, 16, 1
	s_waitcnt vmcnt(1) lgkmcnt(1)
	v_pk_add_f32 v[94:95], v[94:95], v[110:111]
	v_pk_add_f32 v[92:93], v[92:93], v[108:109]
	s_waitcnt vmcnt(0) lgkmcnt(0)
	v_pk_add_f32 v[98:99], v[98:99], v[114:115]
	v_pk_add_f32 v[96:97], v[96:97], v[112:113]
	global_store_dwordx4 v[118:119], v[84:87], off
	global_store_dwordx4 v[118:119], v[88:91], off offset:16
	global_store_dwordx4 v[118:119], v[92:95], off offset:32
	global_store_dwordx4 v[118:119], v[96:99], off offset:48
	s_nop 4
	v_add3_u32 v101, v87, v101, s24
	v_add3_u32 v87, v91, v100, s24
	v_add3_u32 v91, v85, v103, s24
	v_add3_u32 v85, v90, v105, s24
	v_add3_u32 v86, v86, v104, s24
	v_add3_u32 v84, v84, v106, s24
	v_bfe_u32 v108, v99, 16, 1
	v_bfe_u32 v109, v95, 16, 1
	v_lshrrev_b32_e32 v86, 16, v86
	v_lshrrev_b32_e32 v85, 16, v85
	v_lshrrev_b32_e32 v84, 16, v84
	v_add3_u32 v90, v95, v109, s24
	v_add3_u32 v95, v99, v108, s24
	v_and_or_b32 v87, v87, s22, v85
	v_and_or_b32 v85, v101, s22, v86
	v_cvt_pk_bf16_f32 v86, v88, v89
	v_and_or_b32 v84, v91, s22, v84
	v_bfe_u32 v88, v94, 16, 1
	v_bfe_u32 v89, v98, 16, 1
	v_add3_u32 v89, v98, v89, s24
	v_add3_u32 v88, v94, v88, s24
	v_lshrrev_b32_e32 v88, 16, v88
	v_lshrrev_b32_e32 v89, 16, v89
	v_or_b32_e32 v100, 48, v132
	v_and_or_b32 v91, v95, s22, v89
	v_and_or_b32 v89, v90, s22, v88
	v_cvt_pk_bf16_f32 v90, v96, v97
	v_cvt_pk_bf16_f32 v88, v92, v93
	global_store_dwordx4 v[116:117], v[84:87], off
	global_store_dwordx4 v[116:117], v[88:91], off offset:16
	v_ashrrev_i32_e32 v101, 31, v100
	ds_write2_b32 v134, v80, v76 offset1:16
	ds_write2_b32 v134, v81, v77 offset0:68 offset1:84
	ds_write2_b32 v134, v82, v78 offset0:136 offset1:152
	ds_write2_b32 v134, v83, v79 offset0:204 offset1:220
	ds_write2_b32 v134, v72, v68 offset0:32 offset1:48
	ds_write2_b32 v134, v73, v69 offset0:100 offset1:116
	ds_write2_b32 v134, v74, v70 offset0:168 offset1:184
	ds_write2_b32 v134, v75, v71 offset0:236 offset1:252
	v_lshlrev_b64 v[84:85], 12, v[100:101]
	s_waitcnt lgkmcnt(0)
	v_lshl_add_u64 v[84:85], s[8:9], 0, v[84:85]
	ds_read_b128 v[68:71], v135
	ds_read_b128 v[72:75], v135 offset:16
	ds_read_b128 v[76:79], v135 offset:32
	ds_read_b128 v[80:83], v135 offset:48
	v_lshl_add_u64 v[102:103], v[84:85], 0, v[0:1]
	global_load_dwordx4 v[84:87], v[102:103], off
	global_load_dwordx4 v[88:91], v[102:103], off offset:16
	global_load_dwordx4 v[92:95], v[102:103], off offset:32
	global_load_dwordx4 v[96:99], v[102:103], off offset:48
	v_lshlrev_b64 v[100:101], 11, v[100:101]
	v_lshl_add_u64 v[100:101], v[2:3], 0, v[100:101]
	s_waitcnt vmcnt(3) lgkmcnt(3)
; DI unsigned pack2(float a, float b) { return (unsigned)f2bf(a) | ((unsigned)f2bf(b) << 16); }
;   const int lane = tid & 63, wid = tid >> 6, fr = lane & 15, fq = lane >> 4;
;   float* stg = (float*)(smem + PATCH) + wid * (16 * 68);
;   asm volatile("" ::: "memory");
; #pragma unroll
;   for (int n = 0; n < 4; ++n)
; #pragma unroll
;     for (int j = 0; j < 4; ++j) stg[(fq * 4 + j) * 68 + n * 16 + fr] = am[n][j];
;   asm volatile("s_waitcnt lgkmcnt(0)" ::: "memory");
;   const float* rp = stg + (lane >> 2) * 68 + (lane & 3) * 16;
; #pragma unroll
;   for (int i = 0; i < 4; ++i) { f32x4 t = *(const f32x4*)(rp + i * 4); v[4 * i] = t[0]; v[4 * i + 1] = t[1]; v[4 * i + 2] = t[2]; v[4 * i + 3] = t[3]; }
;   asm volatile("" ::: "memory");
; }
; DI void store16_bf(bft* dst, const float (&v)[16]) {
;   u32x4 o0 = {pack2(v[0], v[1]), pack2(v[2], v[3]), pack2(v[4], v[5]), pack2(v[6], v[7])}, o1 = {pack2(v[8], v[9]), pack2(v[10], v[11]), pack2(v[12], v[13]), pack2(v[14], v[15])};
;   *(u32x4*)dst = o0; *(u32x4*)(dst + 8) = o1;
; }
; DI void load16_bf(const bft* src, float (&v)[16]) {
;   u32x4 w0 = *(const u32x4*)src, w1 = *(const u32x4*)(src + 8);
; #pragma unroll
;   for (int i = 0; i < 4; ++i) { v[2 * i] = __uint_as_float(w0[i] << 16); v[2 * i + 1] = __uint_as_float(w0[i] & 0xffff0000u); v[8 + 2 * i] = __uint_as_float(w1[i] << 16); v[8 + 2 * i + 1] = __uint_as_float(w1[i] & 0xffff0000u); }
; }
; DI void load16_f(const float* src, float (&v)[16]) {
; #pragma unroll
;   for (int i = 0; i < 4; ++i) { f32x4 t = *(const f32x4*)(src + 4 * i); v[4 * i] = t[0]; v[4 * i + 1] = t[1]; v[4 * i + 2] = t[2]; v[4 * i + 3] = t[3]; }
; }
; DI void store16_f(float* dst, const float (&v)[16]) {
; #pragma unroll
;   for (int i = 0; i < 4; ++i) { f32x4 t = {v[4 * i], v[4 * i + 1], v[4 * i + 2], v[4 * i + 3]}; *(f32x4*)(dst + 4 * i) = t; }
; }
; DI void phase_outproj1(const Params& p, int hh) {
;     ...
;     EPI256_BEGIN
;       float h[16]; float* hp = p.out + (size_t)row * 1024 + col; load16_f(hp, h);
; #pragma unroll
;       for (int i = 0; i < 16; ++i) h[i] += v[i];
;       store16_f(hp, h); if (hh == 1) store16_bf(hb3 + (size_t)row * 1024 + col, h);
	v_pk_add_f32 v[70:71], v[70:71], v[86:87]
	v_pk_add_f32 v[68:69], v[68:69], v[84:85]
	s_waitcnt vmcnt(2) lgkmcnt(2)
	v_pk_add_f32 v[74:75], v[74:75], v[90:91]
	v_pk_add_f32 v[72:73], v[72:73], v[88:89]
	v_bfe_u32 v84, v75, 16, 1
	v_bfe_u32 v85, v71, 16, 1
	v_bfe_u32 v87, v69, 16, 1
	v_bfe_u32 v88, v70, 16, 1
	v_bfe_u32 v89, v74, 16, 1
	v_bfe_u32 v90, v68, 16, 1
	s_waitcnt vmcnt(1) lgkmcnt(1)
	v_pk_add_f32 v[78:79], v[78:79], v[94:95]
	v_pk_add_f32 v[76:77], v[76:77], v[92:93]
	s_waitcnt vmcnt(0) lgkmcnt(0)
	v_pk_add_f32 v[82:83], v[82:83], v[98:99]
	v_pk_add_f32 v[80:81], v[80:81], v[96:97]
	global_store_dwordx4 v[102:103], v[68:71], off
	global_store_dwordx4 v[102:103], v[72:75], off offset:16
	global_store_dwordx4 v[102:103], v[76:79], off offset:32
	global_store_dwordx4 v[102:103], v[80:83], off offset:48
	s_nop 4
	v_add3_u32 v85, v71, v85, s24
	v_add3_u32 v71, v75, v84, s24
	v_add3_u32 v75, v69, v87, s24
	v_add3_u32 v69, v74, v89, s24
	v_add3_u32 v70, v70, v88, s24
	v_add3_u32 v68, v68, v90, s24
	v_lshrrev_b32_e32 v70, 16, v70
	v_lshrrev_b32_e32 v69, 16, v69
	v_lshrrev_b32_e32 v68, 16, v68
	v_bfe_u32 v96, v78, 16, 1
	v_and_or_b32 v71, v71, s22, v69
	v_and_or_b32 v69, v85, s22, v70
	v_cvt_pk_bf16_f32 v70, v72, v73
	v_and_or_b32 v68, v75, s22, v68
	v_bfe_u32 v73, v76, 16, 1
	v_bfe_u32 v93, v79, 16, 1
	v_bfe_u32 v95, v77, 16, 1
	v_add3_u32 v78, v78, v96, s24
	v_add3_u32 v73, v76, v73, s24
	v_add3_u32 v74, v79, v93, s24
	v_add3_u32 v77, v77, v95, s24
	v_lshrrev_b32_e32 v76, 16, v78
	v_lshrrev_b32_e32 v78, 16, v73
	v_or_b32_e32 v84, 64, v132
	v_cvt_pk_bf16_f32 v75, v82, v83
	v_and_or_b32 v73, v74, s22, v76
	v_cvt_pk_bf16_f32 v74, v80, v81
	v_and_or_b32 v72, v77, s22, v78
	global_store_dwordx4 v[100:101], v[68:71], off
	global_store_dwordx4 v[100:101], v[72:75], off offset:16
	v_ashrrev_i32_e32 v85, 31, v84
	ds_write2_b32 v134, v64, v60 offset1:16
	ds_write2_b32 v134, v65, v61 offset0:68 offset1:84
	ds_write2_b32 v134, v66, v62 offset0:136 offset1:152
	ds_write2_b32 v134, v67, v63 offset0:204 offset1:220
	ds_write2_b32 v134, v56, v52 offset0:32 offset1:48
	ds_write2_b32 v134, v57, v53 offset0:100 offset1:116
	ds_write2_b32 v134, v58, v54 offset0:168 offset1:184
	ds_write2_b32 v134, v59, v55 offset0:236 offset1:252
	v_lshlrev_b64 v[68:69], 12, v[84:85]
	s_waitcnt lgkmcnt(0)
	v_lshl_add_u64 v[68:69], s[8:9], 0, v[68:69]
	ds_read_b128 v[52:55], v135
	ds_read_b128 v[56:59], v135 offset:16
	ds_read_b128 v[60:63], v135 offset:32
	ds_read_b128 v[64:67], v135 offset:48
	v_lshl_add_u64 v[86:87], v[68:69], 0, v[0:1]
	global_load_dwordx4 v[68:71], v[86:87], off
	global_load_dwordx4 v[72:75], v[86:87], off offset:16
	global_load_dwordx4 v[76:79], v[86:87], off offset:32
	global_load_dwordx4 v[80:83], v[86:87], off offset:48
	v_lshlrev_b64 v[84:85], 11, v[84:85]
	v_lshl_add_u64 v[84:85], v[2:3], 0, v[84:85]
	s_waitcnt vmcnt(3) lgkmcnt(3)
	v_pk_add_f32 v[54:55], v[54:55], v[70:71]
	v_pk_add_f32 v[52:53], v[52:53], v[68:69]
	s_waitcnt vmcnt(2) lgkmcnt(2)
	v_pk_add_f32 v[58:59], v[58:59], v[74:75]
	v_pk_add_f32 v[56:57], v[56:57], v[72:73]
	v_bfe_u32 v68, v59, 16, 1
	v_bfe_u32 v69, v55, 16, 1
	v_bfe_u32 v71, v53, 16, 1
	v_bfe_u32 v72, v54, 16, 1
	v_bfe_u32 v73, v58, 16, 1
	s_waitcnt vmcnt(1) lgkmcnt(1)
	v_pk_add_f32 v[62:63], v[62:63], v[78:79]
	v_pk_add_f32 v[60:61], v[60:61], v[76:77]
	s_waitcnt vmcnt(0) lgkmcnt(0)
	v_pk_add_f32 v[66:67], v[66:67], v[82:83]
	v_pk_add_f32 v[64:65], v[64:65], v[80:81]
	global_store_dwordx4 v[86:87], v[52:55], off
	global_store_dwordx4 v[86:87], v[56:59], off offset:16
	global_store_dwordx4 v[86:87], v[60:63], off offset:32
	global_store_dwordx4 v[86:87], v[64:67], off offset:48
	s_nop 4
	v_bfe_u32 v74, v52, 16, 1
	v_add3_u32 v69, v55, v69, s24
	v_add3_u32 v55, v59, v68, s24
	v_add3_u32 v59, v53, v71, s24
	v_add3_u32 v53, v58, v73, s24
	v_add3_u32 v54, v54, v72, s24
	v_add3_u32 v52, v52, v74, s24
	v_lshrrev_b32_e32 v54, 16, v54
	v_lshrrev_b32_e32 v53, 16, v53
	v_bfe_u32 v80, v62, 16, 1
	v_lshrrev_b32_e32 v52, 16, v52
	v_and_or_b32 v55, v55, s22, v53
	v_and_or_b32 v53, v69, s22, v54
	v_cvt_pk_bf16_f32 v54, v56, v57
	v_bfe_u32 v56, v60, 16, 1
	v_bfe_u32 v77, v63, 16, 1
	v_bfe_u32 v79, v61, 16, 1
	v_and_or_b32 v52, v59, s22, v52
	v_add3_u32 v62, v62, v80, s24
	v_add3_u32 v56, v60, v56, s24
	v_add3_u32 v58, v63, v77, s24
	v_add3_u32 v61, v61, v79, s24
	v_lshrrev_b32_e32 v60, 16, v62
	v_lshrrev_b32_e32 v56, 16, v56
	v_or_b32_e32 v68, 0x50, v132
	v_cvt_pk_bf16_f32 v59, v66, v67
	v_and_or_b32 v57, v58, s22, v60
	v_cvt_pk_bf16_f32 v58, v64, v65
	v_and_or_b32 v56, v61, s22, v56
	global_store_dwordx4 v[84:85], v[52:55], off
	global_store_dwordx4 v[84:85], v[56:59], off offset:16
	v_ashrrev_i32_e32 v69, 31, v68
	ds_write2_b32 v134, v48, v44 offset1:16
	ds_write2_b32 v134, v49, v45 offset0:68 offset1:84
	ds_write2_b32 v134, v50, v46 offset0:136 offset1:152
	ds_write2_b32 v134, v51, v47 offset0:204 offset1:220
	ds_write2_b32 v134, v40, v36 offset0:32 offset1:48
	ds_write2_b32 v134, v41, v37 offset0:100 offset1:116
	ds_write2_b32 v134, v42, v38 offset0:168 offset1:184
	ds_write2_b32 v134, v43, v39 offset0:236 offset1:252
	v_lshlrev_b64 v[52:53], 12, v[68:69]
	s_waitcnt lgkmcnt(0)
	v_lshl_add_u64 v[52:53], s[8:9], 0, v[52:53]
	ds_read_b128 v[36:39], v135
	ds_read_b128 v[40:43], v135 offset:16
	ds_read_b128 v[44:47], v135 offset:32
	ds_read_b128 v[48:51], v135 offset:48
	v_lshl_add_u64 v[70:71], v[52:53], 0, v[0:1]
	global_load_dwordx4 v[52:55], v[70:71], off
	global_load_dwordx4 v[56:59], v[70:71], off offset:16
	global_load_dwordx4 v[60:63], v[70:71], off offset:32
	global_load_dwordx4 v[64:67], v[70:71], off offset:48
	v_lshlrev_b64 v[68:69], 11, v[68:69]
	v_lshl_add_u64 v[68:69], v[2:3], 0, v[68:69]
	s_waitcnt vmcnt(3) lgkmcnt(3)
; DI unsigned pack2(float a, float b) { return (unsigned)f2bf(a) | ((unsigned)f2bf(b) << 16); }
;   const int lane = tid & 63, wid = tid >> 6, fr = lane & 15, fq = lane >> 4;
;   float* stg = (float*)(smem + PATCH) + wid * (16 * 68);
;   asm volatile("" ::: "memory");
; #pragma unroll
;   for (int n = 0; n < 4; ++n)
; #pragma unroll
;     for (int j = 0; j < 4; ++j) stg[(fq * 4 + j) * 68 + n * 16 + fr] = am[n][j];
;   asm volatile("s_waitcnt lgkmcnt(0)" ::: "memory");
;   const float* rp = stg + (lane >> 2) * 68 + (lane & 3) * 16;
; #pragma unroll
;   for (int i = 0; i < 4; ++i) { f32x4 t = *(const f32x4*)(rp + i * 4); v[4 * i] = t[0]; v[4 * i + 1] = t[1]; v[4 * i + 2] = t[2]; v[4 * i + 3] = t[3]; }
;   asm volatile("" ::: "memory");
; }
; DI void store16_bf(bft* dst, const float (&v)[16]) {
;   u32x4 o0 = {pack2(v[0], v[1]), pack2(v[2], v[3]), pack2(v[4], v[5]), pack2(v[6], v[7])}, o1 = {pack2(v[8], v[9]), pack2(v[10], v[11]), pack2(v[12], v[13]), pack2(v[14], v[15])};
;   *(u32x4*)dst = o0; *(u32x4*)(dst + 8) = o1;
; }
; DI void load16_bf(const bft* src, float (&v)[16]) {
;   u32x4 w0 = *(const u32x4*)src, w1 = *(const u32x4*)(src + 8);
; #pragma unroll
;   for (int i = 0; i < 4; ++i) { v[2 * i] = __uint_as_float(w0[i] << 16); v[2 * i + 1] = __uint_as_float(w0[i] & 0xffff0000u); v[8 + 2 * i] = __uint_as_float(w1[i] << 16); v[8 + 2 * i + 1] = __uint_as_float(w1[i] & 0xffff0000u); }
; }
; DI void load16_f(const float* src, float (&v)[16]) {
; #pragma unroll
;   for (int i = 0; i < 4; ++i) { f32x4 t = *(const f32x4*)(src + 4 * i); v[4 * i] = t[0]; v[4 * i + 1] = t[1]; v[4 * i + 2] = t[2]; v[4 * i + 3] = t[3]; }
; }
; DI void store16_f(float* dst, const float (&v)[16]) {
; #pragma unroll
;   for (int i = 0; i < 4; ++i) { f32x4 t = {v[4 * i], v[4 * i + 1], v[4 * i + 2], v[4 * i + 3]}; *(f32x4*)(dst + 4 * i) = t; }
; }
; DI void phase_outproj1(const Params& p, int hh) {
;     ...
;     EPI256_BEGIN
;       float h[16]; float* hp = p.out + (size_t)row * 1024 + col; load16_f(hp, h);
; #pragma unroll
;       for (int i = 0; i < 16; ++i) h[i] += v[i];
;       store16_f(hp, h); if (hh == 1) store16_bf(hb3 + (size_t)row * 1024 + col, h);
	v_pk_add_f32 v[38:39], v[38:39], v[54:55]
	v_pk_add_f32 v[36:37], v[36:37], v[52:53]
	s_waitcnt vmcnt(2) lgkmcnt(2)
	v_pk_add_f32 v[42:43], v[42:43], v[58:59]
	v_pk_add_f32 v[40:41], v[40:41], v[56:57]
	v_bfe_u32 v52, v43, 16, 1
	v_bfe_u32 v53, v39, 16, 1
	v_bfe_u32 v55, v37, 16, 1
	v_bfe_u32 v56, v38, 16, 1
	v_bfe_u32 v57, v42, 16, 1
	s_waitcnt vmcnt(1) lgkmcnt(1)
	v_pk_add_f32 v[46:47], v[46:47], v[62:63]
	v_pk_add_f32 v[44:45], v[44:45], v[60:61]
	s_waitcnt vmcnt(0) lgkmcnt(0)
	v_pk_add_f32 v[50:51], v[50:51], v[66:67]
	v_pk_add_f32 v[48:49], v[48:49], v[64:65]
	global_store_dwordx4 v[70:71], v[36:39], off
	global_store_dwordx4 v[70:71], v[40:43], off offset:16
	global_store_dwordx4 v[70:71], v[44:47], off offset:32
	global_store_dwordx4 v[70:71], v[48:51], off offset:48
	s_nop 4
	v_bfe_u32 v58, v36, 16, 1
	v_add3_u32 v53, v39, v53, s24
	v_add3_u32 v39, v43, v52, s24
	v_add3_u32 v43, v37, v55, s24
	v_add3_u32 v37, v42, v57, s24
	v_add3_u32 v38, v38, v56, s24
	v_add3_u32 v36, v36, v58, s24
	v_lshrrev_b32_e32 v38, 16, v38
	v_lshrrev_b32_e32 v37, 16, v37
	v_lshrrev_b32_e32 v36, 16, v36
	v_and_or_b32 v39, v39, s22, v37
	v_and_or_b32 v37, v53, s22, v38
	v_cvt_pk_bf16_f32 v38, v40, v41
	v_and_or_b32 v36, v43, s22, v36
	v_or_b32_e32 v52, 0x60, v132
	v_cvt_pk_bf16_f32 v43, v50, v51
	v_cvt_pk_bf16_f32 v41, v46, v47
	v_cvt_pk_bf16_f32 v42, v48, v49
	v_cvt_pk_bf16_f32 v40, v44, v45
	global_store_dwordx4 v[68:69], v[36:39], off
	global_store_dwordx4 v[68:69], v[40:43], off offset:16
	v_ashrrev_i32_e32 v53, 31, v52
	ds_write2_b32 v134, v32, v28 offset1:16
	ds_write2_b32 v134, v33, v29 offset0:68 offset1:84
	ds_write2_b32 v134, v34, v30 offset0:136 offset1:152
	ds_write2_b32 v134, v35, v31 offset0:204 offset1:220
	ds_write2_b32 v134, v24, v20 offset0:32 offset1:48
	ds_write2_b32 v134, v25, v21 offset0:100 offset1:116
	ds_write2_b32 v134, v26, v22 offset0:168 offset1:184
	ds_write2_b32 v134, v27, v23 offset0:236 offset1:252
	v_lshlrev_b64 v[36:37], 12, v[52:53]
	s_waitcnt lgkmcnt(0)
	v_lshl_add_u64 v[36:37], s[8:9], 0, v[36:37]
	ds_read_b128 v[20:23], v135
	ds_read_b128 v[24:27], v135 offset:16
	ds_read_b128 v[28:31], v135 offset:32
	ds_read_b128 v[32:35], v135 offset:48
	v_lshl_add_u64 v[54:55], v[36:37], 0, v[0:1]
	global_load_dwordx4 v[36:39], v[54:55], off
	global_load_dwordx4 v[40:43], v[54:55], off offset:16
	global_load_dwordx4 v[44:47], v[54:55], off offset:32
	global_load_dwordx4 v[48:51], v[54:55], off offset:48
	v_lshlrev_b64 v[52:53], 11, v[52:53]
	v_lshl_add_u64 v[52:53], v[2:3], 0, v[52:53]
	s_waitcnt vmcnt(3) lgkmcnt(3)
	v_pk_add_f32 v[22:23], v[22:23], v[38:39]
	v_pk_add_f32 v[20:21], v[20:21], v[36:37]
	s_waitcnt vmcnt(2) lgkmcnt(2)
	v_pk_add_f32 v[26:27], v[26:27], v[42:43]
	v_pk_add_f32 v[24:25], v[24:25], v[40:41]
	v_bfe_u32 v36, v27, 16, 1
	v_bfe_u32 v37, v23, 16, 1
	v_bfe_u32 v39, v21, 16, 1
	v_bfe_u32 v40, v22, 16, 1
	v_bfe_u32 v41, v26, 16, 1
	v_bfe_u32 v42, v20, 16, 1
	s_waitcnt vmcnt(1) lgkmcnt(1)
	v_pk_add_f32 v[30:31], v[30:31], v[46:47]
	v_pk_add_f32 v[28:29], v[28:29], v[44:45]
	s_waitcnt vmcnt(0) lgkmcnt(0)
; DI unsigned pack2(float a, float b) { return (unsigned)f2bf(a) | ((unsigned)f2bf(b) << 16); }
;   const int lane = tid & 63, wid = tid >> 6, fr = lane & 15, fq = lane >> 4;
;   float* stg = (float*)(smem + PATCH) + wid * (16 * 68);
;   asm volatile("" ::: "memory");
; #pragma unroll
;   for (int n = 0; n < 4; ++n)
; #pragma unroll
;     for (int j = 0; j < 4; ++j) stg[(fq * 4 + j) * 68 + n * 16 + fr] = am[n][j];
;   asm volatile("s_waitcnt lgkmcnt(0)" ::: "memory");
;   const float* rp = stg + (lane >> 2) * 68 + (lane & 3) * 16;
; #pragma unroll
;   for (int i = 0; i < 4; ++i) { f32x4 t = *(const f32x4*)(rp + i * 4); v[4 * i] = t[0]; v[4 * i + 1] = t[1]; v[4 * i + 2] = t[2]; v[4 * i + 3] = t[3]; }
;   asm volatile("" ::: "memory");
; }
; DI void store16_bf(bft* dst, const float (&v)[16]) {
;   u32x4 o0 = {pack2(v[0], v[1]), pack2(v[2], v[3]), pack2(v[4], v[5]), pack2(v[6], v[7])}, o1 = {pack2(v[8], v[9]), pack2(v[10], v[11]), pack2(v[12], v[13]), pack2(v[14], v[15])};
;   *(u32x4*)dst = o0; *(u32x4*)(dst + 8) = o1;
; }
; DI void load16_bf(const bft* src, float (&v)[16]) {
;   u32x4 w0 = *(const u32x4*)src, w1 = *(const u32x4*)(src + 8);
; #pragma unroll
;   for (int i = 0; i < 4; ++i) { v[2 * i] = __uint_as_float(w0[i] << 16); v[2 * i + 1] = __uint_as_float(w0[i] & 0xffff0000u); v[8 + 2 * i] = __uint_as_float(w1[i] << 16); v[8 + 2 * i + 1] = __uint_as_float(w1[i] & 0xffff0000u); }
; }
; DI void load16_f(const float* src, float (&v)[16]) {
; #pragma unroll
;   for (int i = 0; i < 4; ++i) { f32x4 t = *(const f32x4*)(src + 4 * i); v[4 * i] = t[0]; v[4 * i + 1] = t[1]; v[4 * i + 2] = t[2]; v[4 * i + 3] = t[3]; }
; }
; DI void store16_f(float* dst, const float (&v)[16]) {
; #pragma unroll
;   for (int i = 0; i < 4; ++i) { f32x4 t = {v[4 * i], v[4 * i + 1], v[4 * i + 2], v[4 * i + 3]}; *(f32x4*)(dst + 4 * i) = t; }
; }
; DI void phase_outproj1(const Params& p, int hh) {
;     ...
;     EPI256_BEGIN
;       float h[16]; float* hp = p.out + (size_t)row * 1024 + col; load16_f(hp, h);
; #pragma unroll
;       for (int i = 0; i < 16; ++i) h[i] += v[i];
;       store16_f(hp, h); if (hh == 1) store16_bf(hb3 + (size_t)row * 1024 + col, h);
	v_pk_add_f32 v[34:35], v[34:35], v[50:51]
	v_pk_add_f32 v[32:33], v[32:33], v[48:49]
	global_store_dwordx4 v[54:55], v[20:23], off
	global_store_dwordx4 v[54:55], v[24:27], off offset:16
	global_store_dwordx4 v[54:55], v[28:31], off offset:32
	global_store_dwordx4 v[54:55], v[32:35], off offset:48
	s_nop 4
	v_add3_u32 v37, v23, v37, s24
	v_add3_u32 v23, v27, v36, s24
	v_add3_u32 v27, v21, v39, s24
	v_add3_u32 v21, v26, v41, s24
	v_add3_u32 v22, v22, v40, s24
	v_add3_u32 v20, v20, v42, s24
	v_bfe_u32 v48, v30, 16, 1
	v_lshrrev_b32_e32 v22, 16, v22
	v_lshrrev_b32_e32 v21, 16, v21
	v_lshrrev_b32_e32 v20, 16, v20
	v_bfe_u32 v45, v31, 16, 1
	v_and_or_b32 v23, v23, s22, v21
	v_and_or_b32 v21, v37, s22, v22
	v_cvt_pk_bf16_f32 v22, v24, v25
	v_and_or_b32 v20, v27, s22, v20
	v_add3_u32 v25, v30, v48, s24
	v_add3_u32 v26, v31, v45, s24
	v_lshrrev_b32_e32 v25, 16, v25
	v_or_b32_e32 v36, 0x70, v132
	v_cvt_pk_bf16_f32 v27, v34, v35
	v_and_or_b32 v25, v26, s22, v25
	v_cvt_pk_bf16_f32 v26, v32, v33
	v_cvt_pk_bf16_f32 v24, v28, v29
	global_store_dwordx4 v[52:53], v[20:23], off
	global_store_dwordx4 v[52:53], v[24:27], off offset:16
	v_ashrrev_i32_e32 v37, 31, v36
	ds_write2_b32 v134, v16, v12 offset1:16
	ds_write2_b32 v134, v17, v13 offset0:68 offset1:84
	ds_write2_b32 v134, v18, v14 offset0:136 offset1:152
	ds_write2_b32 v134, v19, v15 offset0:204 offset1:220
	ds_write2_b32 v134, v8, v4 offset0:32 offset1:48
	ds_write2_b32 v134, v9, v5 offset0:100 offset1:116
	ds_write2_b32 v134, v10, v6 offset0:168 offset1:184
	ds_write2_b32 v134, v11, v7 offset0:236 offset1:252
	v_lshlrev_b64 v[20:21], 12, v[36:37]
	s_waitcnt lgkmcnt(0)
	v_lshl_add_u64 v[20:21], s[8:9], 0, v[20:21]
	ds_read_b128 v[4:7], v135
	ds_read_b128 v[8:11], v135 offset:16
	ds_read_b128 v[12:15], v135 offset:32
	ds_read_b128 v[16:19], v135 offset:48
	v_lshl_add_u64 v[38:39], v[20:21], 0, v[0:1]
	global_load_dwordx4 v[20:23], v[38:39], off
	global_load_dwordx4 v[24:27], v[38:39], off offset:16
	global_load_dwordx4 v[28:31], v[38:39], off offset:32
	global_load_dwordx4 v[32:35], v[38:39], off offset:48
	v_lshlrev_b64 v[36:37], 11, v[36:37]
	v_lshl_add_u64 v[36:37], v[2:3], 0, v[36:37]
	s_waitcnt vmcnt(3) lgkmcnt(3)
	v_pk_add_f32 v[6:7], v[6:7], v[22:23]
	v_pk_add_f32 v[4:5], v[4:5], v[20:21]
	s_waitcnt vmcnt(2) lgkmcnt(2)
	v_pk_add_f32 v[10:11], v[10:11], v[26:27]
	v_pk_add_f32 v[8:9], v[8:9], v[24:25]
	s_waitcnt vmcnt(1) lgkmcnt(1)
	v_pk_add_f32 v[14:15], v[14:15], v[30:31]
	v_pk_add_f32 v[12:13], v[12:13], v[28:29]
	s_waitcnt vmcnt(0) lgkmcnt(0)
	v_pk_add_f32 v[18:19], v[18:19], v[34:35]
	v_pk_add_f32 v[16:17], v[16:17], v[32:33]
	v_bfe_u32 v2, v7, 16, 1
	v_bfe_u32 v3, v9, 16, 1
	v_bfe_u32 v20, v5, 16, 1
	v_bfe_u32 v21, v6, 16, 1
	v_bfe_u32 v22, v10, 16, 1
	v_bfe_u32 v23, v4, 16, 1
	global_store_dwordx4 v[38:39], v[4:7], off
	global_store_dwordx4 v[38:39], v[8:11], off offset:16
	global_store_dwordx4 v[38:39], v[12:15], off offset:32
	global_store_dwordx4 v[38:39], v[16:19], off offset:48
	v_bfe_u32 v0, v11, 16, 1
	v_bfe_u32 v24, v8, 16, 1
	v_bfe_u32 v26, v15, 16, 1
	v_bfe_u32 v27, v17, 16, 1
	v_bfe_u32 v28, v13, 16, 1
	v_bfe_u32 v30, v18, 16, 1
	v_add3_u32 v2, v7, v2, s24
	v_add3_u32 v7, v5, v20, s24
	v_add3_u32 v9, v9, v3, s24
	v_add3_u32 v3, v10, v22, s24
	v_add3_u32 v5, v6, v21, s24
	v_add3_u32 v4, v4, v23, s24
	v_bfe_u32 v29, v14, 16, 1
	v_bfe_u32 v31, v12, 16, 1
	v_bfe_u32 v32, v16, 16, 1
	v_add3_u32 v0, v11, v0, s24
	v_add3_u32 v6, v8, v24, s24
	v_add3_u32 v8, v15, v26, s24
	v_add3_u32 v11, v13, v28, s24
	v_add3_u32 v13, v17, v27, s24
	v_add3_u32 v15, v18, v30, s24
	v_lshrrev_b32_e32 v17, 16, v5
	v_lshrrev_b32_e32 v3, 16, v3
	v_lshrrev_b32_e32 v18, 16, v4
	v_bfe_u32 v25, v19, 16, 1
	v_lshrrev_b32_e32 v4, 16, v6
	v_and_or_b32 v5, v0, s22, v3
	v_and_or_b32 v3, v2, s22, v17
	v_and_or_b32 v2, v7, s22, v18
	v_add3_u32 v0, v14, v29, s24
	v_add3_u32 v6, v16, v32, s24
	v_add3_u32 v7, v12, v31, s24
	v_add3_u32 v10, v19, v25, s24
	v_and_or_b32 v4, v9, s22, v4
	v_lshrrev_b32_e32 v0, 16, v0
	v_lshrrev_b32_e32 v9, 16, v15
	v_lshrrev_b32_e32 v12, 16, v7
	v_lshrrev_b32_e32 v6, 16, v6
	v_and_or_b32 v9, v10, s22, v9
	v_and_or_b32 v7, v8, s22, v0
	v_and_or_b32 v8, v13, s22, v6
	v_and_or_b32 v6, v11, s22, v12
	global_store_dwordx4 v[36:37], v[2:5], off
	global_store_dwordx4 v[36:37], v[6:9], off offset:16
